# FFN-up GEMM (both layers): four hand-written 128x256 pair-tiles per workgroup (A fragments shared by two column blocks, BK=32 two-stage LDS) plus one compiler 128x128 tile
# speedup vs baseline: 1.0245x; 1.0159x over previous
; #define G_LOAD(S, kt_) do { G_LD1(S##a0, S##b0, 0, kt_); G_LD1(S##a1, S##b1, 1, kt_); G_LD1(S##a2, S##b2, 2, kt_); G_LD1(S##a3, S##b3, 3, kt_); } while (0)
; #define G_STORE(S, buf_) do { G_ST1(S##a0, S##b0, 0, buf_); G_ST1(S##a1, S##b1, 1, buf_); G_ST1(S##a2, S##b2, 2, buf_); G_ST1(S##a3, S##b3, 3, buf_); } while (0)
; template <class AL, class BL>
; DI void gemm_core(AL al, BL bl, int m0, int n0, int K, char* smem, f32x16 (&acc)[2][2]) {
;     ...
;   const int srow = tid >> 3, sch = tid & 7;
;     ...
;   G_LOAD(x, 0);
;   G_STORE(x, 0);
;   G_LOAD(x, 1);
;   G_LOAD(y, (nk > 2) ? 2 : 1);
;   __syncthreads();
;   for (int kt = 0; kt < nk; kt += 2) {
;     G_TILE(0, x, true, (kt + 3 < nk), kt + 3);
; DI void ffn_up_phase(const Params& p, const u16* xb, int ldx, const u16* wupT, u16* hid, char* smem) {
;   const float* rs = (const float*)(p.ws + W_RS);
;   gemm_phase(NT / 128, 32, 1024,
;              [=](int m, int k) { return xb + (long)m * ldx + k; },
;              [=](int n, int k) { return wupT + (long)n * 1024 + k; },
;              [=](const f32x16 (&acc)[2][2], int m0, int n0) {
;                epi_bf16_tile(acc, m0, n0, hid + (long)m0 * 4096 + n0, 4096, smem, [=](int m, int n, float v) {
;                  const float a = fmaxf(v * rs[m], 0.f);
;                  return a * a;
;                });
;              }, smem);
.LBB0_976:
	s_or_b64 exec, exec, s[0:1]
	s_cmpk_lt_i32 s78, 0x1200
	s_cselect_b64 s[58:59], -1, 0
	s_cmpk_gt_i32 s78, 0x11ff
	s_mov_b64 s[2:3], s[70:71]
	s_waitcnt lgkmcnt(0)
	s_barrier
	s_cbranch_scc1 .LBB0_980
	s_add_u32 s8, s70, 0xdc00000
	s_addc_u32 s9, s71, 0
	s_add_u32 s22, s70, 0x4c00000
	s_addc_u32 s23, s71, 0
	s_add_u32 s14, s70, 0x10000
	s_mov_b64 s[12:13], 0x10000
	s_addc_u32 s15, s71, 0
	s_add_i32 s24, s67, 48
	s_lshl_b32 s25, s50, 7
	v_mov_b32_e32 v65, 0
	s_mov_b32 s26, 0x10000
	s_mov_b64 s[16:17], 0x20000
	s_mov_b32 s27, 0x20000
	s_mov_b64 s[18:19], 0x30000
	s_mov_b32 s28, 0x30000
	s_movk_i32 s29, 0x90
	s_mov_b32 s30, 0xfffffc0
	s_movk_i32 s31, 0x110
	s_mov_b32 s33, s78
	v_bfe_u32 v62, v202, 5, 1
	v_and_b32_e32 v63, 31, v202
	v_lshrrev_b32_e32 v64, 7, v202
	v_bfe_u32 v252, v202, 6, 1
	v_lshlrev_b32_e32 v253, 2, v62
	v_lshl_add_u32 v253, v64, 6, v253
	v_mul_u32_u24_e32 v59, 528, v253
	v_lshl_add_u32 v253, v252, 7, v63
	v_lshl_add_u32 v59, v253, 1, v59
	v_lshrrev_b32_e32 v253, 5, v202
	v_mul_u32_u24_e32 v60, 528, v253
	v_lshl_add_u32 v60, v63, 4, v60
	s_mov_b32 s98, s78
.Lfu0_tile:
	s_cmpk_lt_u32 s98, 0x7e0
	s_cbranch_scc1 .Lfu0_main
	s_sub_u32 s34, s98, 0x7e0
	s_mov_b32 s35, 14
	s_branch .Lfu0_go
.Lfu0_main:
	s_mul_hi_u32 s0, s98, 0x38e38e39
	s_lshr_b32 s35, s0, 5
	s_mul_i32 s0, s35, 0x90
	s_sub_u32 s34, s98, s0
.Lfu0_go:
	s_lshl_b32 s0, s34, 7
	v_lshlrev_b32_e32 v253, 2, v62
	v_lshl_add_u32 v253, v64, 6, v253
	v_add_u32_e32 v253, s0, v253
	v_lshlrev_b32_e32 v61, 2, v253
	s_mul_i32 s1, s0, 8192
	s_mul_hi_u32 s2, s0, 8192
	s_add_u32 s20, s22, s1
	s_addc_u32 s21, s23, s2
	s_lshl_b32 s1, s35, 9
	s_add_u32 s20, s20, s1
	s_addc_u32 s21, s21, 0
	v_lshrrev_b32_e32 v253, 5, v202
	v_mul_u32_u24_e32 v227, 8192, v253
	v_lshl_add_u32 v227, v63, 4, v227
	v_lshrrev_b32_e32 v62, 2, v202
	v_and_b32_e32 v63, 3, v202
	v_lshlrev_b32_e32 v63, 4, v63
	v_mul_u32_u24_e32 v58, 80, v62
	v_add_u32_e32 v58, v58, v63
	s_lshl_b32 s0, s34, 7
	v_add_u32_e32 v64, s0, v62
	v_mov_b32_e32 v254, v63
	v_mov_b32_e32 v255, 0
	v_mov_b32_e32 v252, 4096
	v_mad_u64_u32 v[240:241], s[0:1], v64, v252, v[254:255]
	v_lshl_add_u64 v[240:241], v[240:241], 0, s[68:69]
	s_mov_b32 s0, 262144
	s_mov_b32 s1, 0
	v_lshl_add_u64 v[242:243], v[240:241], 0, s[0:1]
	s_lshl_b32 s0, s35, 8
	v_add_u32_e32 v64, s0, v62
	v_mov_b32_e32 v252, 2048
	v_mad_u64_u32 v[244:245], s[0:1], v64, v252, v[254:255]
	v_lshl_add_u64 v[244:245], v[244:245], 0, s[8:9]
	s_mov_b32 s0, 131072
	s_mov_b32 s1, 0
	v_lshl_add_u64 v[246:247], v[244:245], 0, s[0:1]
	v_lshl_add_u64 v[248:249], v[246:247], 0, s[0:1]
	v_lshl_add_u64 v[250:251], v[248:249], 0, s[0:1]
	v_and_b32_e32 v62, 31, v202
	v_bfe_u32 v63, v202, 5, 1
	v_lshrrev_b32_e32 v64, 7, v202
	v_bfe_u32 v252, v202, 6, 1
	v_lshl_add_u32 v253, v64, 6, v62
	v_mul_u32_u24_e32 v56, 80, v253
	v_lshl_add_u32 v56, v63, 4, v56
	v_lshl_add_u32 v253, v252, 7, v62
	v_mul_u32_u24_e32 v57, 80, v253
	v_lshl_add_u32 v57, v63, 4, v57
	v_add_u32_e32 v57, 10240, v57
	global_load_dwordx4 v[32:35], v[240:241], off offset:2048
	global_load_dwordx4 v[36:39], v[242:243], off offset:2048
	global_load_dwordx4 v[40:43], v[244:245], off offset:0
	global_load_dwordx4 v[44:47], v[246:247], off offset:0
	global_load_dwordx4 v[48:51], v[248:249], off offset:0
	global_load_dwordx4 v[52:55], v[250:251], off offset:0
	global_load_dwordx4 v[214:217], v[240:241], off offset:2112
	global_load_dwordx4 v[218:221], v[242:243], off offset:2112
	global_load_dwordx4 v[222:225], v[244:245], off offset:64
	global_load_dwordx4 v[228:231], v[246:247], off offset:64
	global_load_dwordx4 v[232:235], v[248:249], off offset:64
	global_load_dwordx4 v[236:239], v[250:251], off offset:64
	s_waitcnt vmcnt(6)
	ds_write_b128 v58, v[32:35] offset:0
	ds_write_b128 v58, v[36:39] offset:5120
	ds_write_b128 v58, v[40:43] offset:10240
	ds_write_b128 v58, v[44:47] offset:15360
	ds_write_b128 v58, v[48:51] offset:20480
	ds_write_b128 v58, v[52:55] offset:25600
	global_load_dwordx4 v[32:35], v[240:241], off offset:2176
	global_load_dwordx4 v[36:39], v[242:243], off offset:2176
	global_load_dwordx4 v[40:43], v[244:245], off offset:128
	global_load_dwordx4 v[44:47], v[246:247], off offset:128
	global_load_dwordx4 v[48:51], v[248:249], off offset:128
	global_load_dwordx4 v[52:55], v[250:251], off offset:128
	s_waitcnt lgkmcnt(0)
	s_barrier
	ds_read_b128 v[0:3], v56 offset:0
	ds_read_b128 v[4:7], v56 offset:2560
	ds_read_b128 v[8:11], v57 offset:0
	ds_read_b128 v[12:15], v57 offset:2560
	ds_read_b128 v[16:19], v57 offset:5120
	ds_read_b128 v[20:23], v57 offset:7680
	ds_read_b128 v[24:27], v56 offset:32
	ds_read_b128 v[28:31], v56 offset:2592
	s_waitcnt lgkmcnt(4)
	v_mfma_f32_32x32x16_bf16 v[66:81], v[0:3], v[8:11], 0
	v_mfma_f32_32x32x16_bf16 v[82:97], v[0:3], v[12:15], 0
	s_waitcnt vmcnt(6)
	ds_write_b128 v58, v[214:217] offset:30720
	ds_write_b128 v58, v[218:221] offset:35840
	s_waitcnt lgkmcnt(4)
	v_mfma_f32_32x32x16_bf16 v[98:113], v[0:3], v[16:19], 0
	v_mfma_f32_32x32x16_bf16 v[114:129], v[0:3], v[20:23], 0
	ds_read_b128 v[0:3], v57 offset:32
	ds_write_b128 v58, v[222:225] offset:40960
	ds_write_b128 v58, v[228:231] offset:46080
	v_mfma_f32_32x32x16_bf16 v[130:145], v[4:7], v[8:11], 0
	v_mfma_f32_32x32x16_bf16 v[146:161], v[4:7], v[12:15], 0
	ds_write_b128 v58, v[232:235] offset:51200
	ds_write_b128 v58, v[236:239] offset:56320
	v_mfma_f32_32x32x16_bf16 v[162:177], v[4:7], v[16:19], 0
	v_mfma_f32_32x32x16_bf16 v[178:193], v[4:7], v[20:23], 0
	ds_read_b128 v[4:7], v57 offset:2592
	ds_read_b128 v[8:11], v57 offset:5152
	ds_read_b128 v[12:15], v57 offset:7712
	s_waitcnt lgkmcnt(2)
	v_mfma_f32_32x32x16_bf16 v[66:81], v[24:27], v[0:3], v[66:81]
	global_load_dwordx4 v[214:217], v[240:241], off offset:2240
	global_load_dwordx4 v[218:221], v[242:243], off offset:2240
	v_mfma_f32_32x32x16_bf16 v[82:97], v[24:27], v[4:7], v[82:97]
	s_waitcnt lgkmcnt(0)
	v_mfma_f32_32x32x16_bf16 v[98:113], v[24:27], v[8:11], v[98:113]
	global_load_dwordx4 v[222:225], v[244:245], off offset:192
	global_load_dwordx4 v[228:231], v[246:247], off offset:192
	v_mfma_f32_32x32x16_bf16 v[114:129], v[24:27], v[12:15], v[114:129]
	v_mfma_f32_32x32x16_bf16 v[130:145], v[28:31], v[0:3], v[130:145]
	global_load_dwordx4 v[232:235], v[248:249], off offset:192
	global_load_dwordx4 v[236:239], v[250:251], off offset:192
	v_mfma_f32_32x32x16_bf16 v[146:161], v[28:31], v[4:7], v[146:161]
	v_mfma_f32_32x32x16_bf16 v[162:177], v[28:31], v[8:11], v[162:177]
	v_mfma_f32_32x32x16_bf16 v[178:193], v[28:31], v[12:15], v[178:193]
	s_waitcnt lgkmcnt(0)
	s_barrier
; #define G_LOAD(S, kt_) do { G_LD1(S##a0, S##b0, 0, kt_); G_LD1(S##a1, S##b1, 1, kt_); G_LD1(S##a2, S##b2, 2, kt_); G_LD1(S##a3, S##b3, 3, kt_); } while (0)
; #define G_STORE(S, buf_) do { G_ST1(S##a0, S##b0, 0, buf_); G_ST1(S##a1, S##b1, 1, buf_); G_ST1(S##a2, S##b2, 2, buf_); G_ST1(S##a3, S##b3, 3, buf_); } while (0)
; template <class AL, class BL>
; DI void gemm_core(AL al, BL bl, int m0, int n0, int K, char* smem, f32x16 (&acc)[2][2]) {
;     ...
;   G_LOAD(x, 0);
;   G_STORE(x, 0);
;   G_LOAD(x, 1);
;   G_LOAD(y, (nk > 2) ? 2 : 1);
;   __syncthreads();
;   for (int kt = 0; kt < nk; kt += 2) {
;     G_TILE(0, x, true, (kt + 3 < nk), kt + 3);
;     __syncthreads();
;     G_TILE(1, y, (kt + 2 < nk), (kt + 4 < nk), kt + 4);
;     __syncthreads();
;   }
	ds_read_b128 v[0:3], v56 offset:30720
	ds_read_b128 v[4:7], v56 offset:33280
	ds_read_b128 v[8:11], v57 offset:30720
	ds_read_b128 v[12:15], v57 offset:33280
	ds_read_b128 v[16:19], v57 offset:35840
	ds_read_b128 v[20:23], v57 offset:38400
	ds_read_b128 v[24:27], v56 offset:30752
	ds_read_b128 v[28:31], v56 offset:33312
	s_waitcnt lgkmcnt(4)
	v_mfma_f32_32x32x16_bf16 v[66:81], v[0:3], v[8:11], v[66:81]
	v_mfma_f32_32x32x16_bf16 v[82:97], v[0:3], v[12:15], v[82:97]
	s_waitcnt vmcnt(6)
	ds_write_b128 v58, v[32:35] offset:0
	ds_write_b128 v58, v[36:39] offset:5120
	s_waitcnt lgkmcnt(4)
	v_mfma_f32_32x32x16_bf16 v[98:113], v[0:3], v[16:19], v[98:113]
	v_mfma_f32_32x32x16_bf16 v[114:129], v[0:3], v[20:23], v[114:129]
	ds_read_b128 v[0:3], v57 offset:30752
	ds_write_b128 v58, v[40:43] offset:10240
	ds_write_b128 v58, v[44:47] offset:15360
	v_mfma_f32_32x32x16_bf16 v[130:145], v[4:7], v[8:11], v[130:145]
	v_mfma_f32_32x32x16_bf16 v[146:161], v[4:7], v[12:15], v[146:161]
	ds_write_b128 v58, v[48:51] offset:20480
	ds_write_b128 v58, v[52:55] offset:25600
	v_mfma_f32_32x32x16_bf16 v[162:177], v[4:7], v[16:19], v[162:177]
	v_mfma_f32_32x32x16_bf16 v[178:193], v[4:7], v[20:23], v[178:193]
	ds_read_b128 v[4:7], v57 offset:33312
	ds_read_b128 v[8:11], v57 offset:35872
	ds_read_b128 v[12:15], v57 offset:38432
	s_waitcnt lgkmcnt(2)
	v_mfma_f32_32x32x16_bf16 v[66:81], v[24:27], v[0:3], v[66:81]
	global_load_dwordx4 v[32:35], v[240:241], off offset:2304
	global_load_dwordx4 v[36:39], v[242:243], off offset:2304
	v_mfma_f32_32x32x16_bf16 v[82:97], v[24:27], v[4:7], v[82:97]
	s_waitcnt lgkmcnt(0)
	v_mfma_f32_32x32x16_bf16 v[98:113], v[24:27], v[8:11], v[98:113]
	global_load_dwordx4 v[40:43], v[244:245], off offset:256
	global_load_dwordx4 v[44:47], v[246:247], off offset:256
	v_mfma_f32_32x32x16_bf16 v[114:129], v[24:27], v[12:15], v[114:129]
	v_mfma_f32_32x32x16_bf16 v[130:145], v[28:31], v[0:3], v[130:145]
	global_load_dwordx4 v[48:51], v[248:249], off offset:256
	global_load_dwordx4 v[52:55], v[250:251], off offset:256
	v_mfma_f32_32x32x16_bf16 v[146:161], v[28:31], v[4:7], v[146:161]
	v_mfma_f32_32x32x16_bf16 v[162:177], v[28:31], v[8:11], v[162:177]
	v_mfma_f32_32x32x16_bf16 v[178:193], v[28:31], v[12:15], v[178:193]
	s_waitcnt lgkmcnt(0)
	s_barrier
	ds_read_b128 v[0:3], v56 offset:0
	ds_read_b128 v[4:7], v56 offset:2560
	ds_read_b128 v[8:11], v57 offset:0
	ds_read_b128 v[12:15], v57 offset:2560
	ds_read_b128 v[16:19], v57 offset:5120
	ds_read_b128 v[20:23], v57 offset:7680
	ds_read_b128 v[24:27], v56 offset:32
	ds_read_b128 v[28:31], v56 offset:2592
	s_waitcnt lgkmcnt(4)
	v_mfma_f32_32x32x16_bf16 v[66:81], v[0:3], v[8:11], v[66:81]
	v_mfma_f32_32x32x16_bf16 v[82:97], v[0:3], v[12:15], v[82:97]
	s_waitcnt vmcnt(6)
	ds_write_b128 v58, v[214:217] offset:30720
	ds_write_b128 v58, v[218:221] offset:35840
	s_waitcnt lgkmcnt(4)
	v_mfma_f32_32x32x16_bf16 v[98:113], v[0:3], v[16:19], v[98:113]
	v_mfma_f32_32x32x16_bf16 v[114:129], v[0:3], v[20:23], v[114:129]
	ds_read_b128 v[0:3], v57 offset:32
	ds_write_b128 v58, v[222:225] offset:40960
	ds_write_b128 v58, v[228:231] offset:46080
	v_mfma_f32_32x32x16_bf16 v[130:145], v[4:7], v[8:11], v[130:145]
	v_mfma_f32_32x32x16_bf16 v[146:161], v[4:7], v[12:15], v[146:161]
	ds_write_b128 v58, v[232:235] offset:51200
	ds_write_b128 v58, v[236:239] offset:56320
	v_mfma_f32_32x32x16_bf16 v[162:177], v[4:7], v[16:19], v[162:177]
	v_mfma_f32_32x32x16_bf16 v[178:193], v[4:7], v[20:23], v[178:193]
	ds_read_b128 v[4:7], v57 offset:2592
	ds_read_b128 v[8:11], v57 offset:5152
	ds_read_b128 v[12:15], v57 offset:7712
	s_waitcnt lgkmcnt(2)
	v_mfma_f32_32x32x16_bf16 v[66:81], v[24:27], v[0:3], v[66:81]
	global_load_dwordx4 v[214:217], v[240:241], off offset:2368
	global_load_dwordx4 v[218:221], v[242:243], off offset:2368
	v_mfma_f32_32x32x16_bf16 v[82:97], v[24:27], v[4:7], v[82:97]
	s_waitcnt lgkmcnt(0)
	v_mfma_f32_32x32x16_bf16 v[98:113], v[24:27], v[8:11], v[98:113]
	global_load_dwordx4 v[222:225], v[244:245], off offset:320
	global_load_dwordx4 v[228:231], v[246:247], off offset:320
	v_mfma_f32_32x32x16_bf16 v[114:129], v[24:27], v[12:15], v[114:129]
	v_mfma_f32_32x32x16_bf16 v[130:145], v[28:31], v[0:3], v[130:145]
	global_load_dwordx4 v[232:235], v[248:249], off offset:320
	global_load_dwordx4 v[236:239], v[250:251], off offset:320
	v_mfma_f32_32x32x16_bf16 v[146:161], v[28:31], v[4:7], v[146:161]
	v_mfma_f32_32x32x16_bf16 v[162:177], v[28:31], v[8:11], v[162:177]
	v_mfma_f32_32x32x16_bf16 v[178:193], v[28:31], v[12:15], v[178:193]
	s_waitcnt lgkmcnt(0)
	s_barrier
; #define G_LOAD(S, kt_) do { G_LD1(S##a0, S##b0, 0, kt_); G_LD1(S##a1, S##b1, 1, kt_); G_LD1(S##a2, S##b2, 2, kt_); G_LD1(S##a3, S##b3, 3, kt_); } while (0)
; #define G_STORE(S, buf_) do { G_ST1(S##a0, S##b0, 0, buf_); G_ST1(S##a1, S##b1, 1, buf_); G_ST1(S##a2, S##b2, 2, buf_); G_ST1(S##a3, S##b3, 3, buf_); } while (0)
; template <class AL, class BL>
; DI void gemm_core(AL al, BL bl, int m0, int n0, int K, char* smem, f32x16 (&acc)[2][2]) {
;     ...
;   G_LOAD(x, 0);
;   G_STORE(x, 0);
;   G_LOAD(x, 1);
;   G_LOAD(y, (nk > 2) ? 2 : 1);
;   __syncthreads();
;   for (int kt = 0; kt < nk; kt += 2) {
;     G_TILE(0, x, true, (kt + 3 < nk), kt + 3);
;     __syncthreads();
;     G_TILE(1, y, (kt + 2 < nk), (kt + 4 < nk), kt + 4);
;     __syncthreads();
;   }
	ds_read_b128 v[0:3], v56 offset:30720
	ds_read_b128 v[4:7], v56 offset:33280
	ds_read_b128 v[8:11], v57 offset:30720
	ds_read_b128 v[12:15], v57 offset:33280
	ds_read_b128 v[16:19], v57 offset:35840
	ds_read_b128 v[20:23], v57 offset:38400
	ds_read_b128 v[24:27], v56 offset:30752
	ds_read_b128 v[28:31], v56 offset:33312
	s_waitcnt lgkmcnt(4)
	v_mfma_f32_32x32x16_bf16 v[66:81], v[0:3], v[8:11], v[66:81]
	v_mfma_f32_32x32x16_bf16 v[82:97], v[0:3], v[12:15], v[82:97]
	s_waitcnt vmcnt(6)
	ds_write_b128 v58, v[32:35] offset:0
	ds_write_b128 v58, v[36:39] offset:5120
	s_waitcnt lgkmcnt(4)
	v_mfma_f32_32x32x16_bf16 v[98:113], v[0:3], v[16:19], v[98:113]
	v_mfma_f32_32x32x16_bf16 v[114:129], v[0:3], v[20:23], v[114:129]
	ds_read_b128 v[0:3], v57 offset:30752
	ds_write_b128 v58, v[40:43] offset:10240
	ds_write_b128 v58, v[44:47] offset:15360
	v_mfma_f32_32x32x16_bf16 v[130:145], v[4:7], v[8:11], v[130:145]
	v_mfma_f32_32x32x16_bf16 v[146:161], v[4:7], v[12:15], v[146:161]
	ds_write_b128 v58, v[48:51] offset:20480
	ds_write_b128 v58, v[52:55] offset:25600
	v_mfma_f32_32x32x16_bf16 v[162:177], v[4:7], v[16:19], v[162:177]
	v_mfma_f32_32x32x16_bf16 v[178:193], v[4:7], v[20:23], v[178:193]
	ds_read_b128 v[4:7], v57 offset:33312
	ds_read_b128 v[8:11], v57 offset:35872
	ds_read_b128 v[12:15], v57 offset:38432
	s_waitcnt lgkmcnt(2)
	v_mfma_f32_32x32x16_bf16 v[66:81], v[24:27], v[0:3], v[66:81]
	global_load_dwordx4 v[32:35], v[240:241], off offset:2432
	global_load_dwordx4 v[36:39], v[242:243], off offset:2432
	v_mfma_f32_32x32x16_bf16 v[82:97], v[24:27], v[4:7], v[82:97]
	s_waitcnt lgkmcnt(0)
	v_mfma_f32_32x32x16_bf16 v[98:113], v[24:27], v[8:11], v[98:113]
	global_load_dwordx4 v[40:43], v[244:245], off offset:384
	global_load_dwordx4 v[44:47], v[246:247], off offset:384
	v_mfma_f32_32x32x16_bf16 v[114:129], v[24:27], v[12:15], v[114:129]
	v_mfma_f32_32x32x16_bf16 v[130:145], v[28:31], v[0:3], v[130:145]
	global_load_dwordx4 v[48:51], v[248:249], off offset:384
	global_load_dwordx4 v[52:55], v[250:251], off offset:384
	v_mfma_f32_32x32x16_bf16 v[146:161], v[28:31], v[4:7], v[146:161]
	v_mfma_f32_32x32x16_bf16 v[162:177], v[28:31], v[8:11], v[162:177]
	v_mfma_f32_32x32x16_bf16 v[178:193], v[28:31], v[12:15], v[178:193]
	s_waitcnt lgkmcnt(0)
	s_barrier
	ds_read_b128 v[0:3], v56 offset:0
	ds_read_b128 v[4:7], v56 offset:2560
	ds_read_b128 v[8:11], v57 offset:0
	ds_read_b128 v[12:15], v57 offset:2560
	ds_read_b128 v[16:19], v57 offset:5120
	ds_read_b128 v[20:23], v57 offset:7680
	ds_read_b128 v[24:27], v56 offset:32
	ds_read_b128 v[28:31], v56 offset:2592
	s_waitcnt lgkmcnt(4)
	v_mfma_f32_32x32x16_bf16 v[66:81], v[0:3], v[8:11], v[66:81]
	v_mfma_f32_32x32x16_bf16 v[82:97], v[0:3], v[12:15], v[82:97]
	s_waitcnt vmcnt(6)
	ds_write_b128 v58, v[214:217] offset:30720
	ds_write_b128 v58, v[218:221] offset:35840
	s_waitcnt lgkmcnt(4)
	v_mfma_f32_32x32x16_bf16 v[98:113], v[0:3], v[16:19], v[98:113]
	v_mfma_f32_32x32x16_bf16 v[114:129], v[0:3], v[20:23], v[114:129]
	ds_read_b128 v[0:3], v57 offset:32
	ds_write_b128 v58, v[222:225] offset:40960
	ds_write_b128 v58, v[228:231] offset:46080
	v_mfma_f32_32x32x16_bf16 v[130:145], v[4:7], v[8:11], v[130:145]
	v_mfma_f32_32x32x16_bf16 v[146:161], v[4:7], v[12:15], v[146:161]
	ds_write_b128 v58, v[232:235] offset:51200
	ds_write_b128 v58, v[236:239] offset:56320
	v_mfma_f32_32x32x16_bf16 v[162:177], v[4:7], v[16:19], v[162:177]
	v_mfma_f32_32x32x16_bf16 v[178:193], v[4:7], v[20:23], v[178:193]
	ds_read_b128 v[4:7], v57 offset:2592
	ds_read_b128 v[8:11], v57 offset:5152
	ds_read_b128 v[12:15], v57 offset:7712
	s_waitcnt lgkmcnt(2)
	v_mfma_f32_32x32x16_bf16 v[66:81], v[24:27], v[0:3], v[66:81]
	global_load_dwordx4 v[214:217], v[240:241], off offset:2496
	global_load_dwordx4 v[218:221], v[242:243], off offset:2496
	v_mfma_f32_32x32x16_bf16 v[82:97], v[24:27], v[4:7], v[82:97]
	s_waitcnt lgkmcnt(0)
	v_mfma_f32_32x32x16_bf16 v[98:113], v[24:27], v[8:11], v[98:113]
	global_load_dwordx4 v[222:225], v[244:245], off offset:448
	global_load_dwordx4 v[228:231], v[246:247], off offset:448
	v_mfma_f32_32x32x16_bf16 v[114:129], v[24:27], v[12:15], v[114:129]
	v_mfma_f32_32x32x16_bf16 v[130:145], v[28:31], v[0:3], v[130:145]
	global_load_dwordx4 v[232:235], v[248:249], off offset:448
	global_load_dwordx4 v[236:239], v[250:251], off offset:448
	v_mfma_f32_32x32x16_bf16 v[146:161], v[28:31], v[4:7], v[146:161]
	v_mfma_f32_32x32x16_bf16 v[162:177], v[28:31], v[8:11], v[162:177]
	v_mfma_f32_32x32x16_bf16 v[178:193], v[28:31], v[12:15], v[178:193]
	s_waitcnt lgkmcnt(0)
	s_barrier
; #define G_LOAD(S, kt_) do { G_LD1(S##a0, S##b0, 0, kt_); G_LD1(S##a1, S##b1, 1, kt_); G_LD1(S##a2, S##b2, 2, kt_); G_LD1(S##a3, S##b3, 3, kt_); } while (0)
; #define G_STORE(S, buf_) do { G_ST1(S##a0, S##b0, 0, buf_); G_ST1(S##a1, S##b1, 1, buf_); G_ST1(S##a2, S##b2, 2, buf_); G_ST1(S##a3, S##b3, 3, buf_); } while (0)
; template <class AL, class BL>
; DI void gemm_core(AL al, BL bl, int m0, int n0, int K, char* smem, f32x16 (&acc)[2][2]) {
;     ...
;   G_LOAD(x, 0);
;   G_STORE(x, 0);
;   G_LOAD(x, 1);
;   G_LOAD(y, (nk > 2) ? 2 : 1);
;   __syncthreads();
;   for (int kt = 0; kt < nk; kt += 2) {
;     G_TILE(0, x, true, (kt + 3 < nk), kt + 3);
;     __syncthreads();
;     G_TILE(1, y, (kt + 2 < nk), (kt + 4 < nk), kt + 4);
;     __syncthreads();
;   }
	ds_read_b128 v[0:3], v56 offset:30720
	ds_read_b128 v[4:7], v56 offset:33280
	ds_read_b128 v[8:11], v57 offset:30720
	ds_read_b128 v[12:15], v57 offset:33280
	ds_read_b128 v[16:19], v57 offset:35840
	ds_read_b128 v[20:23], v57 offset:38400
	ds_read_b128 v[24:27], v56 offset:30752
	ds_read_b128 v[28:31], v56 offset:33312
	s_waitcnt lgkmcnt(4)
	v_mfma_f32_32x32x16_bf16 v[66:81], v[0:3], v[8:11], v[66:81]
	v_mfma_f32_32x32x16_bf16 v[82:97], v[0:3], v[12:15], v[82:97]
	s_waitcnt vmcnt(6)
	ds_write_b128 v58, v[32:35] offset:0
	ds_write_b128 v58, v[36:39] offset:5120
	s_waitcnt lgkmcnt(4)
	v_mfma_f32_32x32x16_bf16 v[98:113], v[0:3], v[16:19], v[98:113]
	v_mfma_f32_32x32x16_bf16 v[114:129], v[0:3], v[20:23], v[114:129]
	ds_read_b128 v[0:3], v57 offset:30752
	ds_write_b128 v58, v[40:43] offset:10240
	ds_write_b128 v58, v[44:47] offset:15360
	v_mfma_f32_32x32x16_bf16 v[130:145], v[4:7], v[8:11], v[130:145]
	v_mfma_f32_32x32x16_bf16 v[146:161], v[4:7], v[12:15], v[146:161]
	ds_write_b128 v58, v[48:51] offset:20480
	ds_write_b128 v58, v[52:55] offset:25600
	v_mfma_f32_32x32x16_bf16 v[162:177], v[4:7], v[16:19], v[162:177]
	v_mfma_f32_32x32x16_bf16 v[178:193], v[4:7], v[20:23], v[178:193]
	ds_read_b128 v[4:7], v57 offset:33312
	ds_read_b128 v[8:11], v57 offset:35872
	ds_read_b128 v[12:15], v57 offset:38432
	s_waitcnt lgkmcnt(2)
	v_mfma_f32_32x32x16_bf16 v[66:81], v[24:27], v[0:3], v[66:81]
	global_load_dwordx4 v[32:35], v[240:241], off offset:2560
	global_load_dwordx4 v[36:39], v[242:243], off offset:2560
	v_mfma_f32_32x32x16_bf16 v[82:97], v[24:27], v[4:7], v[82:97]
	s_waitcnt lgkmcnt(0)
	v_mfma_f32_32x32x16_bf16 v[98:113], v[24:27], v[8:11], v[98:113]
	global_load_dwordx4 v[40:43], v[244:245], off offset:512
	global_load_dwordx4 v[44:47], v[246:247], off offset:512
	v_mfma_f32_32x32x16_bf16 v[114:129], v[24:27], v[12:15], v[114:129]
	v_mfma_f32_32x32x16_bf16 v[130:145], v[28:31], v[0:3], v[130:145]
	global_load_dwordx4 v[48:51], v[248:249], off offset:512
	global_load_dwordx4 v[52:55], v[250:251], off offset:512
	v_mfma_f32_32x32x16_bf16 v[146:161], v[28:31], v[4:7], v[146:161]
	v_mfma_f32_32x32x16_bf16 v[162:177], v[28:31], v[8:11], v[162:177]
	v_mfma_f32_32x32x16_bf16 v[178:193], v[28:31], v[12:15], v[178:193]
	s_waitcnt lgkmcnt(0)
	s_barrier
	ds_read_b128 v[0:3], v56 offset:0
	ds_read_b128 v[4:7], v56 offset:2560
	ds_read_b128 v[8:11], v57 offset:0
	ds_read_b128 v[12:15], v57 offset:2560
	ds_read_b128 v[16:19], v57 offset:5120
	ds_read_b128 v[20:23], v57 offset:7680
	ds_read_b128 v[24:27], v56 offset:32
	ds_read_b128 v[28:31], v56 offset:2592
	s_waitcnt lgkmcnt(4)
	v_mfma_f32_32x32x16_bf16 v[66:81], v[0:3], v[8:11], v[66:81]
	v_mfma_f32_32x32x16_bf16 v[82:97], v[0:3], v[12:15], v[82:97]
	s_waitcnt vmcnt(6)
	ds_write_b128 v58, v[214:217] offset:30720
	ds_write_b128 v58, v[218:221] offset:35840
	s_waitcnt lgkmcnt(4)
	v_mfma_f32_32x32x16_bf16 v[98:113], v[0:3], v[16:19], v[98:113]
	v_mfma_f32_32x32x16_bf16 v[114:129], v[0:3], v[20:23], v[114:129]
	ds_read_b128 v[0:3], v57 offset:32
	ds_write_b128 v58, v[222:225] offset:40960
	ds_write_b128 v58, v[228:231] offset:46080
	v_mfma_f32_32x32x16_bf16 v[130:145], v[4:7], v[8:11], v[130:145]
	v_mfma_f32_32x32x16_bf16 v[146:161], v[4:7], v[12:15], v[146:161]
	ds_write_b128 v58, v[232:235] offset:51200
	ds_write_b128 v58, v[236:239] offset:56320
	v_mfma_f32_32x32x16_bf16 v[162:177], v[4:7], v[16:19], v[162:177]
	v_mfma_f32_32x32x16_bf16 v[178:193], v[4:7], v[20:23], v[178:193]
	ds_read_b128 v[4:7], v57 offset:2592
	ds_read_b128 v[8:11], v57 offset:5152
	ds_read_b128 v[12:15], v57 offset:7712
	s_waitcnt lgkmcnt(2)
	v_mfma_f32_32x32x16_bf16 v[66:81], v[24:27], v[0:3], v[66:81]
	global_load_dwordx4 v[214:217], v[240:241], off offset:2624
	global_load_dwordx4 v[218:221], v[242:243], off offset:2624
	v_mfma_f32_32x32x16_bf16 v[82:97], v[24:27], v[4:7], v[82:97]
	s_waitcnt lgkmcnt(0)
	v_mfma_f32_32x32x16_bf16 v[98:113], v[24:27], v[8:11], v[98:113]
	global_load_dwordx4 v[222:225], v[244:245], off offset:576
	global_load_dwordx4 v[228:231], v[246:247], off offset:576
	v_mfma_f32_32x32x16_bf16 v[114:129], v[24:27], v[12:15], v[114:129]
	v_mfma_f32_32x32x16_bf16 v[130:145], v[28:31], v[0:3], v[130:145]
	global_load_dwordx4 v[232:235], v[248:249], off offset:576
	global_load_dwordx4 v[236:239], v[250:251], off offset:576
	v_mfma_f32_32x32x16_bf16 v[146:161], v[28:31], v[4:7], v[146:161]
	v_mfma_f32_32x32x16_bf16 v[162:177], v[28:31], v[8:11], v[162:177]
	v_mfma_f32_32x32x16_bf16 v[178:193], v[28:31], v[12:15], v[178:193]
	s_waitcnt lgkmcnt(0)
	s_barrier
; #define G_LOAD(S, kt_) do { G_LD1(S##a0, S##b0, 0, kt_); G_LD1(S##a1, S##b1, 1, kt_); G_LD1(S##a2, S##b2, 2, kt_); G_LD1(S##a3, S##b3, 3, kt_); } while (0)
; #define G_STORE(S, buf_) do { G_ST1(S##a0, S##b0, 0, buf_); G_ST1(S##a1, S##b1, 1, buf_); G_ST1(S##a2, S##b2, 2, buf_); G_ST1(S##a3, S##b3, 3, buf_); } while (0)
; template <class AL, class BL>
; DI void gemm_core(AL al, BL bl, int m0, int n0, int K, char* smem, f32x16 (&acc)[2][2]) {
;     ...
;   G_LOAD(x, 0);
;   G_STORE(x, 0);
;   G_LOAD(x, 1);
;   G_LOAD(y, (nk > 2) ? 2 : 1);
;   __syncthreads();
;   for (int kt = 0; kt < nk; kt += 2) {
;     G_TILE(0, x, true, (kt + 3 < nk), kt + 3);
;     __syncthreads();
;     G_TILE(1, y, (kt + 2 < nk), (kt + 4 < nk), kt + 4);
;     __syncthreads();
;   }
	ds_read_b128 v[0:3], v56 offset:30720
	ds_read_b128 v[4:7], v56 offset:33280
	ds_read_b128 v[8:11], v57 offset:30720
	ds_read_b128 v[12:15], v57 offset:33280
	ds_read_b128 v[16:19], v57 offset:35840
	ds_read_b128 v[20:23], v57 offset:38400
	ds_read_b128 v[24:27], v56 offset:30752
	ds_read_b128 v[28:31], v56 offset:33312
	s_waitcnt lgkmcnt(4)
	v_mfma_f32_32x32x16_bf16 v[66:81], v[0:3], v[8:11], v[66:81]
	v_mfma_f32_32x32x16_bf16 v[82:97], v[0:3], v[12:15], v[82:97]
	s_waitcnt vmcnt(6)
	ds_write_b128 v58, v[32:35] offset:0
	ds_write_b128 v58, v[36:39] offset:5120
	s_waitcnt lgkmcnt(4)
	v_mfma_f32_32x32x16_bf16 v[98:113], v[0:3], v[16:19], v[98:113]
	v_mfma_f32_32x32x16_bf16 v[114:129], v[0:3], v[20:23], v[114:129]
	ds_read_b128 v[0:3], v57 offset:30752
	ds_write_b128 v58, v[40:43] offset:10240
	ds_write_b128 v58, v[44:47] offset:15360
	v_mfma_f32_32x32x16_bf16 v[130:145], v[4:7], v[8:11], v[130:145]
	v_mfma_f32_32x32x16_bf16 v[146:161], v[4:7], v[12:15], v[146:161]
	ds_write_b128 v58, v[48:51] offset:20480
	ds_write_b128 v58, v[52:55] offset:25600
	v_mfma_f32_32x32x16_bf16 v[162:177], v[4:7], v[16:19], v[162:177]
	v_mfma_f32_32x32x16_bf16 v[178:193], v[4:7], v[20:23], v[178:193]
	ds_read_b128 v[4:7], v57 offset:33312
	ds_read_b128 v[8:11], v57 offset:35872
	ds_read_b128 v[12:15], v57 offset:38432
	s_waitcnt lgkmcnt(2)
	v_mfma_f32_32x32x16_bf16 v[66:81], v[24:27], v[0:3], v[66:81]
	global_load_dwordx4 v[32:35], v[240:241], off offset:2688
	global_load_dwordx4 v[36:39], v[242:243], off offset:2688
	v_mfma_f32_32x32x16_bf16 v[82:97], v[24:27], v[4:7], v[82:97]
	s_waitcnt lgkmcnt(0)
	v_mfma_f32_32x32x16_bf16 v[98:113], v[24:27], v[8:11], v[98:113]
	global_load_dwordx4 v[40:43], v[244:245], off offset:640
	global_load_dwordx4 v[44:47], v[246:247], off offset:640
	v_mfma_f32_32x32x16_bf16 v[114:129], v[24:27], v[12:15], v[114:129]
	v_mfma_f32_32x32x16_bf16 v[130:145], v[28:31], v[0:3], v[130:145]
	global_load_dwordx4 v[48:51], v[248:249], off offset:640
	global_load_dwordx4 v[52:55], v[250:251], off offset:640
	v_mfma_f32_32x32x16_bf16 v[146:161], v[28:31], v[4:7], v[146:161]
	v_mfma_f32_32x32x16_bf16 v[162:177], v[28:31], v[8:11], v[162:177]
	v_mfma_f32_32x32x16_bf16 v[178:193], v[28:31], v[12:15], v[178:193]
	s_waitcnt lgkmcnt(0)
	s_barrier
	ds_read_b128 v[0:3], v56 offset:0
	ds_read_b128 v[4:7], v56 offset:2560
	ds_read_b128 v[8:11], v57 offset:0
	ds_read_b128 v[12:15], v57 offset:2560
	ds_read_b128 v[16:19], v57 offset:5120
	ds_read_b128 v[20:23], v57 offset:7680
	ds_read_b128 v[24:27], v56 offset:32
	ds_read_b128 v[28:31], v56 offset:2592
	s_waitcnt lgkmcnt(4)
	v_mfma_f32_32x32x16_bf16 v[66:81], v[0:3], v[8:11], v[66:81]
	v_mfma_f32_32x32x16_bf16 v[82:97], v[0:3], v[12:15], v[82:97]
	s_waitcnt vmcnt(6)
	ds_write_b128 v58, v[214:217] offset:30720
	ds_write_b128 v58, v[218:221] offset:35840
	s_waitcnt lgkmcnt(4)
	v_mfma_f32_32x32x16_bf16 v[98:113], v[0:3], v[16:19], v[98:113]
	v_mfma_f32_32x32x16_bf16 v[114:129], v[0:3], v[20:23], v[114:129]
	ds_read_b128 v[0:3], v57 offset:32
	ds_write_b128 v58, v[222:225] offset:40960
	ds_write_b128 v58, v[228:231] offset:46080
	v_mfma_f32_32x32x16_bf16 v[130:145], v[4:7], v[8:11], v[130:145]
	v_mfma_f32_32x32x16_bf16 v[146:161], v[4:7], v[12:15], v[146:161]
	ds_write_b128 v58, v[232:235] offset:51200
	ds_write_b128 v58, v[236:239] offset:56320
	v_mfma_f32_32x32x16_bf16 v[162:177], v[4:7], v[16:19], v[162:177]
	v_mfma_f32_32x32x16_bf16 v[178:193], v[4:7], v[20:23], v[178:193]
	ds_read_b128 v[4:7], v57 offset:2592
	ds_read_b128 v[8:11], v57 offset:5152
	ds_read_b128 v[12:15], v57 offset:7712
	s_waitcnt lgkmcnt(2)
	v_mfma_f32_32x32x16_bf16 v[66:81], v[24:27], v[0:3], v[66:81]
	global_load_dwordx4 v[214:217], v[240:241], off offset:2752
	global_load_dwordx4 v[218:221], v[242:243], off offset:2752
	v_mfma_f32_32x32x16_bf16 v[82:97], v[24:27], v[4:7], v[82:97]
	s_waitcnt lgkmcnt(0)
	v_mfma_f32_32x32x16_bf16 v[98:113], v[24:27], v[8:11], v[98:113]
	global_load_dwordx4 v[222:225], v[244:245], off offset:704
	global_load_dwordx4 v[228:231], v[246:247], off offset:704
	v_mfma_f32_32x32x16_bf16 v[114:129], v[24:27], v[12:15], v[114:129]
	v_mfma_f32_32x32x16_bf16 v[130:145], v[28:31], v[0:3], v[130:145]
	global_load_dwordx4 v[232:235], v[248:249], off offset:704
	global_load_dwordx4 v[236:239], v[250:251], off offset:704
	v_mfma_f32_32x32x16_bf16 v[146:161], v[28:31], v[4:7], v[146:161]
	v_mfma_f32_32x32x16_bf16 v[162:177], v[28:31], v[8:11], v[162:177]
	v_mfma_f32_32x32x16_bf16 v[178:193], v[28:31], v[12:15], v[178:193]
	s_waitcnt lgkmcnt(0)
	s_barrier
; #define G_LOAD(S, kt_) do { G_LD1(S##a0, S##b0, 0, kt_); G_LD1(S##a1, S##b1, 1, kt_); G_LD1(S##a2, S##b2, 2, kt_); G_LD1(S##a3, S##b3, 3, kt_); } while (0)
; #define G_STORE(S, buf_) do { G_ST1(S##a0, S##b0, 0, buf_); G_ST1(S##a1, S##b1, 1, buf_); G_ST1(S##a2, S##b2, 2, buf_); G_ST1(S##a3, S##b3, 3, buf_); } while (0)
; template <class AL, class BL>
; DI void gemm_core(AL al, BL bl, int m0, int n0, int K, char* smem, f32x16 (&acc)[2][2]) {
;     ...
;   G_LOAD(x, 0);
;   G_STORE(x, 0);
;   G_LOAD(x, 1);
;   G_LOAD(y, (nk > 2) ? 2 : 1);
;   __syncthreads();
;   for (int kt = 0; kt < nk; kt += 2) {
;     G_TILE(0, x, true, (kt + 3 < nk), kt + 3);
;     __syncthreads();
;     G_TILE(1, y, (kt + 2 < nk), (kt + 4 < nk), kt + 4);
;     __syncthreads();
;   }
	ds_read_b128 v[0:3], v56 offset:30720
	ds_read_b128 v[4:7], v56 offset:33280
	ds_read_b128 v[8:11], v57 offset:30720
	ds_read_b128 v[12:15], v57 offset:33280
	ds_read_b128 v[16:19], v57 offset:35840
	ds_read_b128 v[20:23], v57 offset:38400
	ds_read_b128 v[24:27], v56 offset:30752
	ds_read_b128 v[28:31], v56 offset:33312
	s_waitcnt lgkmcnt(4)
	v_mfma_f32_32x32x16_bf16 v[66:81], v[0:3], v[8:11], v[66:81]
	v_mfma_f32_32x32x16_bf16 v[82:97], v[0:3], v[12:15], v[82:97]
	s_waitcnt vmcnt(6)
	ds_write_b128 v58, v[32:35] offset:0
	ds_write_b128 v58, v[36:39] offset:5120
	s_waitcnt lgkmcnt(4)
	v_mfma_f32_32x32x16_bf16 v[98:113], v[0:3], v[16:19], v[98:113]
	v_mfma_f32_32x32x16_bf16 v[114:129], v[0:3], v[20:23], v[114:129]
	ds_read_b128 v[0:3], v57 offset:30752
	ds_write_b128 v58, v[40:43] offset:10240
	ds_write_b128 v58, v[44:47] offset:15360
	v_mfma_f32_32x32x16_bf16 v[130:145], v[4:7], v[8:11], v[130:145]
	v_mfma_f32_32x32x16_bf16 v[146:161], v[4:7], v[12:15], v[146:161]
	ds_write_b128 v58, v[48:51] offset:20480
	ds_write_b128 v58, v[52:55] offset:25600
	v_mfma_f32_32x32x16_bf16 v[162:177], v[4:7], v[16:19], v[162:177]
	v_mfma_f32_32x32x16_bf16 v[178:193], v[4:7], v[20:23], v[178:193]
	ds_read_b128 v[4:7], v57 offset:33312
	ds_read_b128 v[8:11], v57 offset:35872
	ds_read_b128 v[12:15], v57 offset:38432
	s_waitcnt lgkmcnt(2)
	v_mfma_f32_32x32x16_bf16 v[66:81], v[24:27], v[0:3], v[66:81]
	global_load_dwordx4 v[32:35], v[240:241], off offset:2816
	global_load_dwordx4 v[36:39], v[242:243], off offset:2816
	v_mfma_f32_32x32x16_bf16 v[82:97], v[24:27], v[4:7], v[82:97]
	s_waitcnt lgkmcnt(0)
	v_mfma_f32_32x32x16_bf16 v[98:113], v[24:27], v[8:11], v[98:113]
	global_load_dwordx4 v[40:43], v[244:245], off offset:768
	global_load_dwordx4 v[44:47], v[246:247], off offset:768
	v_mfma_f32_32x32x16_bf16 v[114:129], v[24:27], v[12:15], v[114:129]
	v_mfma_f32_32x32x16_bf16 v[130:145], v[28:31], v[0:3], v[130:145]
	global_load_dwordx4 v[48:51], v[248:249], off offset:768
	global_load_dwordx4 v[52:55], v[250:251], off offset:768
	v_mfma_f32_32x32x16_bf16 v[146:161], v[28:31], v[4:7], v[146:161]
	v_mfma_f32_32x32x16_bf16 v[162:177], v[28:31], v[8:11], v[162:177]
	v_mfma_f32_32x32x16_bf16 v[178:193], v[28:31], v[12:15], v[178:193]
	s_waitcnt lgkmcnt(0)
	s_barrier
	ds_read_b128 v[0:3], v56 offset:0
	ds_read_b128 v[4:7], v56 offset:2560
	ds_read_b128 v[8:11], v57 offset:0
	ds_read_b128 v[12:15], v57 offset:2560
	ds_read_b128 v[16:19], v57 offset:5120
	ds_read_b128 v[20:23], v57 offset:7680
	ds_read_b128 v[24:27], v56 offset:32
	ds_read_b128 v[28:31], v56 offset:2592
	s_waitcnt lgkmcnt(4)
	v_mfma_f32_32x32x16_bf16 v[66:81], v[0:3], v[8:11], v[66:81]
	v_mfma_f32_32x32x16_bf16 v[82:97], v[0:3], v[12:15], v[82:97]
	s_waitcnt vmcnt(6)
	ds_write_b128 v58, v[214:217] offset:30720
	ds_write_b128 v58, v[218:221] offset:35840
	s_waitcnt lgkmcnt(4)
	v_mfma_f32_32x32x16_bf16 v[98:113], v[0:3], v[16:19], v[98:113]
	v_mfma_f32_32x32x16_bf16 v[114:129], v[0:3], v[20:23], v[114:129]
	ds_read_b128 v[0:3], v57 offset:32
	ds_write_b128 v58, v[222:225] offset:40960
	ds_write_b128 v58, v[228:231] offset:46080
	v_mfma_f32_32x32x16_bf16 v[130:145], v[4:7], v[8:11], v[130:145]
	v_mfma_f32_32x32x16_bf16 v[146:161], v[4:7], v[12:15], v[146:161]
	ds_write_b128 v58, v[232:235] offset:51200
	ds_write_b128 v58, v[236:239] offset:56320
	v_mfma_f32_32x32x16_bf16 v[162:177], v[4:7], v[16:19], v[162:177]
	v_mfma_f32_32x32x16_bf16 v[178:193], v[4:7], v[20:23], v[178:193]
	ds_read_b128 v[4:7], v57 offset:2592
	ds_read_b128 v[8:11], v57 offset:5152
	ds_read_b128 v[12:15], v57 offset:7712
	s_waitcnt lgkmcnt(2)
	v_mfma_f32_32x32x16_bf16 v[66:81], v[24:27], v[0:3], v[66:81]
	global_load_dwordx4 v[214:217], v[240:241], off offset:2880
	global_load_dwordx4 v[218:221], v[242:243], off offset:2880
	v_mfma_f32_32x32x16_bf16 v[82:97], v[24:27], v[4:7], v[82:97]
	s_waitcnt lgkmcnt(0)
	v_mfma_f32_32x32x16_bf16 v[98:113], v[24:27], v[8:11], v[98:113]
	global_load_dwordx4 v[222:225], v[244:245], off offset:832
	global_load_dwordx4 v[228:231], v[246:247], off offset:832
	v_mfma_f32_32x32x16_bf16 v[114:129], v[24:27], v[12:15], v[114:129]
	v_mfma_f32_32x32x16_bf16 v[130:145], v[28:31], v[0:3], v[130:145]
	global_load_dwordx4 v[232:235], v[248:249], off offset:832
	global_load_dwordx4 v[236:239], v[250:251], off offset:832
	v_mfma_f32_32x32x16_bf16 v[146:161], v[28:31], v[4:7], v[146:161]
	v_mfma_f32_32x32x16_bf16 v[162:177], v[28:31], v[8:11], v[162:177]
	v_mfma_f32_32x32x16_bf16 v[178:193], v[28:31], v[12:15], v[178:193]
	s_waitcnt lgkmcnt(0)
	s_barrier
; #define G_LOAD(S, kt_) do { G_LD1(S##a0, S##b0, 0, kt_); G_LD1(S##a1, S##b1, 1, kt_); G_LD1(S##a2, S##b2, 2, kt_); G_LD1(S##a3, S##b3, 3, kt_); } while (0)
; #define G_STORE(S, buf_) do { G_ST1(S##a0, S##b0, 0, buf_); G_ST1(S##a1, S##b1, 1, buf_); G_ST1(S##a2, S##b2, 2, buf_); G_ST1(S##a3, S##b3, 3, buf_); } while (0)
; template <class AL, class BL>
; DI void gemm_core(AL al, BL bl, int m0, int n0, int K, char* smem, f32x16 (&acc)[2][2]) {
;     ...
;   G_LOAD(x, 0);
;   G_STORE(x, 0);
;   G_LOAD(x, 1);
;   G_LOAD(y, (nk > 2) ? 2 : 1);
;   __syncthreads();
;   for (int kt = 0; kt < nk; kt += 2) {
;     G_TILE(0, x, true, (kt + 3 < nk), kt + 3);
;     __syncthreads();
;     G_TILE(1, y, (kt + 2 < nk), (kt + 4 < nk), kt + 4);
;     __syncthreads();
;   }
	ds_read_b128 v[0:3], v56 offset:30720
	ds_read_b128 v[4:7], v56 offset:33280
	ds_read_b128 v[8:11], v57 offset:30720
	ds_read_b128 v[12:15], v57 offset:33280
	ds_read_b128 v[16:19], v57 offset:35840
	ds_read_b128 v[20:23], v57 offset:38400
	ds_read_b128 v[24:27], v56 offset:30752
	ds_read_b128 v[28:31], v56 offset:33312
	s_waitcnt lgkmcnt(4)
	v_mfma_f32_32x32x16_bf16 v[66:81], v[0:3], v[8:11], v[66:81]
	v_mfma_f32_32x32x16_bf16 v[82:97], v[0:3], v[12:15], v[82:97]
	s_waitcnt vmcnt(6)
	ds_write_b128 v58, v[32:35] offset:0
	ds_write_b128 v58, v[36:39] offset:5120
	s_waitcnt lgkmcnt(4)
	v_mfma_f32_32x32x16_bf16 v[98:113], v[0:3], v[16:19], v[98:113]
	v_mfma_f32_32x32x16_bf16 v[114:129], v[0:3], v[20:23], v[114:129]
	ds_read_b128 v[0:3], v57 offset:30752
	ds_write_b128 v58, v[40:43] offset:10240
	ds_write_b128 v58, v[44:47] offset:15360
	v_mfma_f32_32x32x16_bf16 v[130:145], v[4:7], v[8:11], v[130:145]
	v_mfma_f32_32x32x16_bf16 v[146:161], v[4:7], v[12:15], v[146:161]
	ds_write_b128 v58, v[48:51] offset:20480
	ds_write_b128 v58, v[52:55] offset:25600
	v_mfma_f32_32x32x16_bf16 v[162:177], v[4:7], v[16:19], v[162:177]
	v_mfma_f32_32x32x16_bf16 v[178:193], v[4:7], v[20:23], v[178:193]
	ds_read_b128 v[4:7], v57 offset:33312
	ds_read_b128 v[8:11], v57 offset:35872
	ds_read_b128 v[12:15], v57 offset:38432
	s_waitcnt lgkmcnt(2)
	v_mfma_f32_32x32x16_bf16 v[66:81], v[24:27], v[0:3], v[66:81]
	global_load_dwordx4 v[32:35], v[240:241], off offset:2944
	global_load_dwordx4 v[36:39], v[242:243], off offset:2944
	v_mfma_f32_32x32x16_bf16 v[82:97], v[24:27], v[4:7], v[82:97]
	s_waitcnt lgkmcnt(0)
	v_mfma_f32_32x32x16_bf16 v[98:113], v[24:27], v[8:11], v[98:113]
	global_load_dwordx4 v[40:43], v[244:245], off offset:896
	global_load_dwordx4 v[44:47], v[246:247], off offset:896
	v_mfma_f32_32x32x16_bf16 v[114:129], v[24:27], v[12:15], v[114:129]
	v_mfma_f32_32x32x16_bf16 v[130:145], v[28:31], v[0:3], v[130:145]
	global_load_dwordx4 v[48:51], v[248:249], off offset:896
	global_load_dwordx4 v[52:55], v[250:251], off offset:896
	v_mfma_f32_32x32x16_bf16 v[146:161], v[28:31], v[4:7], v[146:161]
	v_mfma_f32_32x32x16_bf16 v[162:177], v[28:31], v[8:11], v[162:177]
	v_mfma_f32_32x32x16_bf16 v[178:193], v[28:31], v[12:15], v[178:193]
	s_waitcnt lgkmcnt(0)
	s_barrier
	ds_read_b128 v[0:3], v56 offset:0
	ds_read_b128 v[4:7], v56 offset:2560
	ds_read_b128 v[8:11], v57 offset:0
	ds_read_b128 v[12:15], v57 offset:2560
	ds_read_b128 v[16:19], v57 offset:5120
	ds_read_b128 v[20:23], v57 offset:7680
	ds_read_b128 v[24:27], v56 offset:32
	ds_read_b128 v[28:31], v56 offset:2592
	s_waitcnt lgkmcnt(4)
	v_mfma_f32_32x32x16_bf16 v[66:81], v[0:3], v[8:11], v[66:81]
	v_mfma_f32_32x32x16_bf16 v[82:97], v[0:3], v[12:15], v[82:97]
	s_waitcnt vmcnt(6)
	ds_write_b128 v58, v[214:217] offset:30720
	ds_write_b128 v58, v[218:221] offset:35840
	s_waitcnt lgkmcnt(4)
	v_mfma_f32_32x32x16_bf16 v[98:113], v[0:3], v[16:19], v[98:113]
	v_mfma_f32_32x32x16_bf16 v[114:129], v[0:3], v[20:23], v[114:129]
	ds_read_b128 v[0:3], v57 offset:32
	ds_write_b128 v58, v[222:225] offset:40960
	ds_write_b128 v58, v[228:231] offset:46080
	v_mfma_f32_32x32x16_bf16 v[130:145], v[4:7], v[8:11], v[130:145]
	v_mfma_f32_32x32x16_bf16 v[146:161], v[4:7], v[12:15], v[146:161]
	ds_write_b128 v58, v[232:235] offset:51200
	ds_write_b128 v58, v[236:239] offset:56320
	v_mfma_f32_32x32x16_bf16 v[162:177], v[4:7], v[16:19], v[162:177]
	v_mfma_f32_32x32x16_bf16 v[178:193], v[4:7], v[20:23], v[178:193]
	ds_read_b128 v[4:7], v57 offset:2592
	ds_read_b128 v[8:11], v57 offset:5152
	ds_read_b128 v[12:15], v57 offset:7712
	s_waitcnt lgkmcnt(2)
	v_mfma_f32_32x32x16_bf16 v[66:81], v[24:27], v[0:3], v[66:81]
	global_load_dwordx4 v[214:217], v[240:241], off offset:3008
	global_load_dwordx4 v[218:221], v[242:243], off offset:3008
	v_mfma_f32_32x32x16_bf16 v[82:97], v[24:27], v[4:7], v[82:97]
	s_waitcnt lgkmcnt(0)
	v_mfma_f32_32x32x16_bf16 v[98:113], v[24:27], v[8:11], v[98:113]
	global_load_dwordx4 v[222:225], v[244:245], off offset:960
	global_load_dwordx4 v[228:231], v[246:247], off offset:960
	v_mfma_f32_32x32x16_bf16 v[114:129], v[24:27], v[12:15], v[114:129]
	v_mfma_f32_32x32x16_bf16 v[130:145], v[28:31], v[0:3], v[130:145]
	global_load_dwordx4 v[232:235], v[248:249], off offset:960
	global_load_dwordx4 v[236:239], v[250:251], off offset:960
	v_mfma_f32_32x32x16_bf16 v[146:161], v[28:31], v[4:7], v[146:161]
	v_mfma_f32_32x32x16_bf16 v[162:177], v[28:31], v[8:11], v[162:177]
	v_mfma_f32_32x32x16_bf16 v[178:193], v[28:31], v[12:15], v[178:193]
	s_waitcnt lgkmcnt(0)
	s_barrier
; #define G_LOAD(S, kt_) do { G_LD1(S##a0, S##b0, 0, kt_); G_LD1(S##a1, S##b1, 1, kt_); G_LD1(S##a2, S##b2, 2, kt_); G_LD1(S##a3, S##b3, 3, kt_); } while (0)
; #define G_STORE(S, buf_) do { G_ST1(S##a0, S##b0, 0, buf_); G_ST1(S##a1, S##b1, 1, buf_); G_ST1(S##a2, S##b2, 2, buf_); G_ST1(S##a3, S##b3, 3, buf_); } while (0)
; template <class AL, class BL>
; DI void gemm_core(AL al, BL bl, int m0, int n0, int K, char* smem, f32x16 (&acc)[2][2]) {
;     ...
;   G_LOAD(x, 0);
;   G_STORE(x, 0);
;   G_LOAD(x, 1);
;   G_LOAD(y, (nk > 2) ? 2 : 1);
;   __syncthreads();
;   for (int kt = 0; kt < nk; kt += 2) {
;     G_TILE(0, x, true, (kt + 3 < nk), kt + 3);
;     __syncthreads();
;     G_TILE(1, y, (kt + 2 < nk), (kt + 4 < nk), kt + 4);
;     __syncthreads();
;   }
	ds_read_b128 v[0:3], v56 offset:30720
	ds_read_b128 v[4:7], v56 offset:33280
	ds_read_b128 v[8:11], v57 offset:30720
	ds_read_b128 v[12:15], v57 offset:33280
	ds_read_b128 v[16:19], v57 offset:35840
	ds_read_b128 v[20:23], v57 offset:38400
	ds_read_b128 v[24:27], v56 offset:30752
	ds_read_b128 v[28:31], v56 offset:33312
	s_waitcnt lgkmcnt(4)
	v_mfma_f32_32x32x16_bf16 v[66:81], v[0:3], v[8:11], v[66:81]
	v_mfma_f32_32x32x16_bf16 v[82:97], v[0:3], v[12:15], v[82:97]
	s_waitcnt vmcnt(6)
	ds_write_b128 v58, v[32:35] offset:0
	ds_write_b128 v58, v[36:39] offset:5120
	s_waitcnt lgkmcnt(4)
	v_mfma_f32_32x32x16_bf16 v[98:113], v[0:3], v[16:19], v[98:113]
	v_mfma_f32_32x32x16_bf16 v[114:129], v[0:3], v[20:23], v[114:129]
	ds_read_b128 v[0:3], v57 offset:30752
	ds_write_b128 v58, v[40:43] offset:10240
	ds_write_b128 v58, v[44:47] offset:15360
	v_mfma_f32_32x32x16_bf16 v[130:145], v[4:7], v[8:11], v[130:145]
	v_mfma_f32_32x32x16_bf16 v[146:161], v[4:7], v[12:15], v[146:161]
	ds_write_b128 v58, v[48:51] offset:20480
	ds_write_b128 v58, v[52:55] offset:25600
	v_mfma_f32_32x32x16_bf16 v[162:177], v[4:7], v[16:19], v[162:177]
	v_mfma_f32_32x32x16_bf16 v[178:193], v[4:7], v[20:23], v[178:193]
	ds_read_b128 v[4:7], v57 offset:33312
	ds_read_b128 v[8:11], v57 offset:35872
	ds_read_b128 v[12:15], v57 offset:38432
	s_waitcnt lgkmcnt(2)
	v_mfma_f32_32x32x16_bf16 v[66:81], v[24:27], v[0:3], v[66:81]
	global_load_dwordx4 v[32:35], v[240:241], off offset:3072
	global_load_dwordx4 v[36:39], v[242:243], off offset:3072
	v_mfma_f32_32x32x16_bf16 v[82:97], v[24:27], v[4:7], v[82:97]
	s_waitcnt lgkmcnt(0)
	v_mfma_f32_32x32x16_bf16 v[98:113], v[24:27], v[8:11], v[98:113]
	global_load_dwordx4 v[40:43], v[244:245], off offset:1024
	global_load_dwordx4 v[44:47], v[246:247], off offset:1024
	v_mfma_f32_32x32x16_bf16 v[114:129], v[24:27], v[12:15], v[114:129]
	v_mfma_f32_32x32x16_bf16 v[130:145], v[28:31], v[0:3], v[130:145]
	global_load_dwordx4 v[48:51], v[248:249], off offset:1024
	global_load_dwordx4 v[52:55], v[250:251], off offset:1024
	v_mfma_f32_32x32x16_bf16 v[146:161], v[28:31], v[4:7], v[146:161]
	v_mfma_f32_32x32x16_bf16 v[162:177], v[28:31], v[8:11], v[162:177]
	v_mfma_f32_32x32x16_bf16 v[178:193], v[28:31], v[12:15], v[178:193]
	s_waitcnt lgkmcnt(0)
	s_barrier
	ds_read_b128 v[0:3], v56 offset:0
	ds_read_b128 v[4:7], v56 offset:2560
	ds_read_b128 v[8:11], v57 offset:0
	ds_read_b128 v[12:15], v57 offset:2560
	ds_read_b128 v[16:19], v57 offset:5120
	ds_read_b128 v[20:23], v57 offset:7680
	ds_read_b128 v[24:27], v56 offset:32
	ds_read_b128 v[28:31], v56 offset:2592
	s_waitcnt lgkmcnt(4)
	v_mfma_f32_32x32x16_bf16 v[66:81], v[0:3], v[8:11], v[66:81]
	v_mfma_f32_32x32x16_bf16 v[82:97], v[0:3], v[12:15], v[82:97]
	s_waitcnt vmcnt(6)
	ds_write_b128 v58, v[214:217] offset:30720
	ds_write_b128 v58, v[218:221] offset:35840
	s_waitcnt lgkmcnt(4)
	v_mfma_f32_32x32x16_bf16 v[98:113], v[0:3], v[16:19], v[98:113]
	v_mfma_f32_32x32x16_bf16 v[114:129], v[0:3], v[20:23], v[114:129]
	ds_read_b128 v[0:3], v57 offset:32
	ds_write_b128 v58, v[222:225] offset:40960
	ds_write_b128 v58, v[228:231] offset:46080
	v_mfma_f32_32x32x16_bf16 v[130:145], v[4:7], v[8:11], v[130:145]
	v_mfma_f32_32x32x16_bf16 v[146:161], v[4:7], v[12:15], v[146:161]
	ds_write_b128 v58, v[232:235] offset:51200
	ds_write_b128 v58, v[236:239] offset:56320
	v_mfma_f32_32x32x16_bf16 v[162:177], v[4:7], v[16:19], v[162:177]
	v_mfma_f32_32x32x16_bf16 v[178:193], v[4:7], v[20:23], v[178:193]
	ds_read_b128 v[4:7], v57 offset:2592
	ds_read_b128 v[8:11], v57 offset:5152
	ds_read_b128 v[12:15], v57 offset:7712
	s_waitcnt lgkmcnt(2)
	v_mfma_f32_32x32x16_bf16 v[66:81], v[24:27], v[0:3], v[66:81]
	global_load_dwordx4 v[214:217], v[240:241], off offset:3136
	global_load_dwordx4 v[218:221], v[242:243], off offset:3136
	v_mfma_f32_32x32x16_bf16 v[82:97], v[24:27], v[4:7], v[82:97]
	s_waitcnt lgkmcnt(0)
	v_mfma_f32_32x32x16_bf16 v[98:113], v[24:27], v[8:11], v[98:113]
	global_load_dwordx4 v[222:225], v[244:245], off offset:1088
	global_load_dwordx4 v[228:231], v[246:247], off offset:1088
	v_mfma_f32_32x32x16_bf16 v[114:129], v[24:27], v[12:15], v[114:129]
	v_mfma_f32_32x32x16_bf16 v[130:145], v[28:31], v[0:3], v[130:145]
	global_load_dwordx4 v[232:235], v[248:249], off offset:1088
	global_load_dwordx4 v[236:239], v[250:251], off offset:1088
	v_mfma_f32_32x32x16_bf16 v[146:161], v[28:31], v[4:7], v[146:161]
	v_mfma_f32_32x32x16_bf16 v[162:177], v[28:31], v[8:11], v[162:177]
	v_mfma_f32_32x32x16_bf16 v[178:193], v[28:31], v[12:15], v[178:193]
	s_waitcnt lgkmcnt(0)
	s_barrier
; #define G_LOAD(S, kt_) do { G_LD1(S##a0, S##b0, 0, kt_); G_LD1(S##a1, S##b1, 1, kt_); G_LD1(S##a2, S##b2, 2, kt_); G_LD1(S##a3, S##b3, 3, kt_); } while (0)
; #define G_STORE(S, buf_) do { G_ST1(S##a0, S##b0, 0, buf_); G_ST1(S##a1, S##b1, 1, buf_); G_ST1(S##a2, S##b2, 2, buf_); G_ST1(S##a3, S##b3, 3, buf_); } while (0)
; template <class AL, class BL>
; DI void gemm_core(AL al, BL bl, int m0, int n0, int K, char* smem, f32x16 (&acc)[2][2]) {
;     ...
;   G_LOAD(x, 0);
;   G_STORE(x, 0);
;   G_LOAD(x, 1);
;   G_LOAD(y, (nk > 2) ? 2 : 1);
;   __syncthreads();
;   for (int kt = 0; kt < nk; kt += 2) {
;     G_TILE(0, x, true, (kt + 3 < nk), kt + 3);
;     __syncthreads();
;     G_TILE(1, y, (kt + 2 < nk), (kt + 4 < nk), kt + 4);
;     __syncthreads();
;   }
	ds_read_b128 v[0:3], v56 offset:30720
	ds_read_b128 v[4:7], v56 offset:33280
	ds_read_b128 v[8:11], v57 offset:30720
	ds_read_b128 v[12:15], v57 offset:33280
	ds_read_b128 v[16:19], v57 offset:35840
	ds_read_b128 v[20:23], v57 offset:38400
	ds_read_b128 v[24:27], v56 offset:30752
	ds_read_b128 v[28:31], v56 offset:33312
	s_waitcnt lgkmcnt(4)
	v_mfma_f32_32x32x16_bf16 v[66:81], v[0:3], v[8:11], v[66:81]
	v_mfma_f32_32x32x16_bf16 v[82:97], v[0:3], v[12:15], v[82:97]
	s_waitcnt vmcnt(6)
	ds_write_b128 v58, v[32:35] offset:0
	ds_write_b128 v58, v[36:39] offset:5120
	s_waitcnt lgkmcnt(4)
	v_mfma_f32_32x32x16_bf16 v[98:113], v[0:3], v[16:19], v[98:113]
	v_mfma_f32_32x32x16_bf16 v[114:129], v[0:3], v[20:23], v[114:129]
	ds_read_b128 v[0:3], v57 offset:30752
	ds_write_b128 v58, v[40:43] offset:10240
	ds_write_b128 v58, v[44:47] offset:15360
	v_mfma_f32_32x32x16_bf16 v[130:145], v[4:7], v[8:11], v[130:145]
	v_mfma_f32_32x32x16_bf16 v[146:161], v[4:7], v[12:15], v[146:161]
	ds_write_b128 v58, v[48:51] offset:20480
	ds_write_b128 v58, v[52:55] offset:25600
	v_mfma_f32_32x32x16_bf16 v[162:177], v[4:7], v[16:19], v[162:177]
	v_mfma_f32_32x32x16_bf16 v[178:193], v[4:7], v[20:23], v[178:193]
	ds_read_b128 v[4:7], v57 offset:33312
	ds_read_b128 v[8:11], v57 offset:35872
	ds_read_b128 v[12:15], v57 offset:38432
	s_waitcnt lgkmcnt(2)
	v_mfma_f32_32x32x16_bf16 v[66:81], v[24:27], v[0:3], v[66:81]
	global_load_dwordx4 v[32:35], v[240:241], off offset:3200
	global_load_dwordx4 v[36:39], v[242:243], off offset:3200
	v_mfma_f32_32x32x16_bf16 v[82:97], v[24:27], v[4:7], v[82:97]
	s_waitcnt lgkmcnt(0)
	v_mfma_f32_32x32x16_bf16 v[98:113], v[24:27], v[8:11], v[98:113]
	global_load_dwordx4 v[40:43], v[244:245], off offset:1152
	global_load_dwordx4 v[44:47], v[246:247], off offset:1152
	v_mfma_f32_32x32x16_bf16 v[114:129], v[24:27], v[12:15], v[114:129]
	v_mfma_f32_32x32x16_bf16 v[130:145], v[28:31], v[0:3], v[130:145]
	global_load_dwordx4 v[48:51], v[248:249], off offset:1152
	global_load_dwordx4 v[52:55], v[250:251], off offset:1152
	v_mfma_f32_32x32x16_bf16 v[146:161], v[28:31], v[4:7], v[146:161]
	v_mfma_f32_32x32x16_bf16 v[162:177], v[28:31], v[8:11], v[162:177]
	v_mfma_f32_32x32x16_bf16 v[178:193], v[28:31], v[12:15], v[178:193]
	s_waitcnt lgkmcnt(0)
	s_barrier
	ds_read_b128 v[0:3], v56 offset:0
	ds_read_b128 v[4:7], v56 offset:2560
	ds_read_b128 v[8:11], v57 offset:0
	ds_read_b128 v[12:15], v57 offset:2560
	ds_read_b128 v[16:19], v57 offset:5120
	ds_read_b128 v[20:23], v57 offset:7680
	ds_read_b128 v[24:27], v56 offset:32
	ds_read_b128 v[28:31], v56 offset:2592
	s_waitcnt lgkmcnt(4)
	v_mfma_f32_32x32x16_bf16 v[66:81], v[0:3], v[8:11], v[66:81]
	v_mfma_f32_32x32x16_bf16 v[82:97], v[0:3], v[12:15], v[82:97]
	s_waitcnt vmcnt(6)
	ds_write_b128 v58, v[214:217] offset:30720
	ds_write_b128 v58, v[218:221] offset:35840
	s_waitcnt lgkmcnt(4)
	v_mfma_f32_32x32x16_bf16 v[98:113], v[0:3], v[16:19], v[98:113]
	v_mfma_f32_32x32x16_bf16 v[114:129], v[0:3], v[20:23], v[114:129]
	ds_read_b128 v[0:3], v57 offset:32
	ds_write_b128 v58, v[222:225] offset:40960
	ds_write_b128 v58, v[228:231] offset:46080
	v_mfma_f32_32x32x16_bf16 v[130:145], v[4:7], v[8:11], v[130:145]
	v_mfma_f32_32x32x16_bf16 v[146:161], v[4:7], v[12:15], v[146:161]
	ds_write_b128 v58, v[232:235] offset:51200
	ds_write_b128 v58, v[236:239] offset:56320
	v_mfma_f32_32x32x16_bf16 v[162:177], v[4:7], v[16:19], v[162:177]
	v_mfma_f32_32x32x16_bf16 v[178:193], v[4:7], v[20:23], v[178:193]
	ds_read_b128 v[4:7], v57 offset:2592
	ds_read_b128 v[8:11], v57 offset:5152
	ds_read_b128 v[12:15], v57 offset:7712
	s_waitcnt lgkmcnt(2)
	v_mfma_f32_32x32x16_bf16 v[66:81], v[24:27], v[0:3], v[66:81]
	global_load_dwordx4 v[214:217], v[240:241], off offset:3264
	global_load_dwordx4 v[218:221], v[242:243], off offset:3264
	v_mfma_f32_32x32x16_bf16 v[82:97], v[24:27], v[4:7], v[82:97]
	s_waitcnt lgkmcnt(0)
	v_mfma_f32_32x32x16_bf16 v[98:113], v[24:27], v[8:11], v[98:113]
	global_load_dwordx4 v[222:225], v[244:245], off offset:1216
	global_load_dwordx4 v[228:231], v[246:247], off offset:1216
	v_mfma_f32_32x32x16_bf16 v[114:129], v[24:27], v[12:15], v[114:129]
	v_mfma_f32_32x32x16_bf16 v[130:145], v[28:31], v[0:3], v[130:145]
	global_load_dwordx4 v[232:235], v[248:249], off offset:1216
	global_load_dwordx4 v[236:239], v[250:251], off offset:1216
	v_mfma_f32_32x32x16_bf16 v[146:161], v[28:31], v[4:7], v[146:161]
	v_mfma_f32_32x32x16_bf16 v[162:177], v[28:31], v[8:11], v[162:177]
	v_mfma_f32_32x32x16_bf16 v[178:193], v[28:31], v[12:15], v[178:193]
	s_waitcnt lgkmcnt(0)
	s_barrier
; #define G_LOAD(S, kt_) do { G_LD1(S##a0, S##b0, 0, kt_); G_LD1(S##a1, S##b1, 1, kt_); G_LD1(S##a2, S##b2, 2, kt_); G_LD1(S##a3, S##b3, 3, kt_); } while (0)
; #define G_STORE(S, buf_) do { G_ST1(S##a0, S##b0, 0, buf_); G_ST1(S##a1, S##b1, 1, buf_); G_ST1(S##a2, S##b2, 2, buf_); G_ST1(S##a3, S##b3, 3, buf_); } while (0)
; template <class AL, class BL>
; DI void gemm_core(AL al, BL bl, int m0, int n0, int K, char* smem, f32x16 (&acc)[2][2]) {
;     ...
;   G_LOAD(x, 0);
;   G_STORE(x, 0);
;   G_LOAD(x, 1);
;   G_LOAD(y, (nk > 2) ? 2 : 1);
;   __syncthreads();
;   for (int kt = 0; kt < nk; kt += 2) {
;     G_TILE(0, x, true, (kt + 3 < nk), kt + 3);
;     __syncthreads();
;     G_TILE(1, y, (kt + 2 < nk), (kt + 4 < nk), kt + 4);
;     __syncthreads();
;   }
	ds_read_b128 v[0:3], v56 offset:30720
	ds_read_b128 v[4:7], v56 offset:33280
	ds_read_b128 v[8:11], v57 offset:30720
	ds_read_b128 v[12:15], v57 offset:33280
	ds_read_b128 v[16:19], v57 offset:35840
	ds_read_b128 v[20:23], v57 offset:38400
	ds_read_b128 v[24:27], v56 offset:30752
	ds_read_b128 v[28:31], v56 offset:33312
	s_waitcnt lgkmcnt(4)
	v_mfma_f32_32x32x16_bf16 v[66:81], v[0:3], v[8:11], v[66:81]
	v_mfma_f32_32x32x16_bf16 v[82:97], v[0:3], v[12:15], v[82:97]
	s_waitcnt vmcnt(6)
	ds_write_b128 v58, v[32:35] offset:0
	ds_write_b128 v58, v[36:39] offset:5120
	s_waitcnt lgkmcnt(4)
	v_mfma_f32_32x32x16_bf16 v[98:113], v[0:3], v[16:19], v[98:113]
	v_mfma_f32_32x32x16_bf16 v[114:129], v[0:3], v[20:23], v[114:129]
	ds_read_b128 v[0:3], v57 offset:30752
	ds_write_b128 v58, v[40:43] offset:10240
	ds_write_b128 v58, v[44:47] offset:15360
	v_mfma_f32_32x32x16_bf16 v[130:145], v[4:7], v[8:11], v[130:145]
	v_mfma_f32_32x32x16_bf16 v[146:161], v[4:7], v[12:15], v[146:161]
	ds_write_b128 v58, v[48:51] offset:20480
	ds_write_b128 v58, v[52:55] offset:25600
	v_mfma_f32_32x32x16_bf16 v[162:177], v[4:7], v[16:19], v[162:177]
	v_mfma_f32_32x32x16_bf16 v[178:193], v[4:7], v[20:23], v[178:193]
	ds_read_b128 v[4:7], v57 offset:33312
	ds_read_b128 v[8:11], v57 offset:35872
	ds_read_b128 v[12:15], v57 offset:38432
	s_waitcnt lgkmcnt(2)
	v_mfma_f32_32x32x16_bf16 v[66:81], v[24:27], v[0:3], v[66:81]
	global_load_dwordx4 v[32:35], v[240:241], off offset:3328
	global_load_dwordx4 v[36:39], v[242:243], off offset:3328
	v_mfma_f32_32x32x16_bf16 v[82:97], v[24:27], v[4:7], v[82:97]
	s_waitcnt lgkmcnt(0)
	v_mfma_f32_32x32x16_bf16 v[98:113], v[24:27], v[8:11], v[98:113]
	global_load_dwordx4 v[40:43], v[244:245], off offset:1280
	global_load_dwordx4 v[44:47], v[246:247], off offset:1280
	v_mfma_f32_32x32x16_bf16 v[114:129], v[24:27], v[12:15], v[114:129]
	v_mfma_f32_32x32x16_bf16 v[130:145], v[28:31], v[0:3], v[130:145]
	global_load_dwordx4 v[48:51], v[248:249], off offset:1280
	global_load_dwordx4 v[52:55], v[250:251], off offset:1280
	v_mfma_f32_32x32x16_bf16 v[146:161], v[28:31], v[4:7], v[146:161]
	v_mfma_f32_32x32x16_bf16 v[162:177], v[28:31], v[8:11], v[162:177]
	v_mfma_f32_32x32x16_bf16 v[178:193], v[28:31], v[12:15], v[178:193]
	s_waitcnt lgkmcnt(0)
	s_barrier
	ds_read_b128 v[0:3], v56 offset:0
	ds_read_b128 v[4:7], v56 offset:2560
	ds_read_b128 v[8:11], v57 offset:0
	ds_read_b128 v[12:15], v57 offset:2560
	ds_read_b128 v[16:19], v57 offset:5120
	ds_read_b128 v[20:23], v57 offset:7680
	ds_read_b128 v[24:27], v56 offset:32
	ds_read_b128 v[28:31], v56 offset:2592
	s_waitcnt lgkmcnt(4)
	v_mfma_f32_32x32x16_bf16 v[66:81], v[0:3], v[8:11], v[66:81]
	v_mfma_f32_32x32x16_bf16 v[82:97], v[0:3], v[12:15], v[82:97]
	s_waitcnt vmcnt(6)
	ds_write_b128 v58, v[214:217] offset:30720
	ds_write_b128 v58, v[218:221] offset:35840
	s_waitcnt lgkmcnt(4)
	v_mfma_f32_32x32x16_bf16 v[98:113], v[0:3], v[16:19], v[98:113]
	v_mfma_f32_32x32x16_bf16 v[114:129], v[0:3], v[20:23], v[114:129]
	ds_read_b128 v[0:3], v57 offset:32
	ds_write_b128 v58, v[222:225] offset:40960
	ds_write_b128 v58, v[228:231] offset:46080
	v_mfma_f32_32x32x16_bf16 v[130:145], v[4:7], v[8:11], v[130:145]
	v_mfma_f32_32x32x16_bf16 v[146:161], v[4:7], v[12:15], v[146:161]
	ds_write_b128 v58, v[232:235] offset:51200
	ds_write_b128 v58, v[236:239] offset:56320
	v_mfma_f32_32x32x16_bf16 v[162:177], v[4:7], v[16:19], v[162:177]
	v_mfma_f32_32x32x16_bf16 v[178:193], v[4:7], v[20:23], v[178:193]
	ds_read_b128 v[4:7], v57 offset:2592
	ds_read_b128 v[8:11], v57 offset:5152
	ds_read_b128 v[12:15], v57 offset:7712
	s_waitcnt lgkmcnt(2)
	v_mfma_f32_32x32x16_bf16 v[66:81], v[24:27], v[0:3], v[66:81]
	global_load_dwordx4 v[214:217], v[240:241], off offset:3392
	global_load_dwordx4 v[218:221], v[242:243], off offset:3392
	v_mfma_f32_32x32x16_bf16 v[82:97], v[24:27], v[4:7], v[82:97]
	s_waitcnt lgkmcnt(0)
	v_mfma_f32_32x32x16_bf16 v[98:113], v[24:27], v[8:11], v[98:113]
	global_load_dwordx4 v[222:225], v[244:245], off offset:1344
	global_load_dwordx4 v[228:231], v[246:247], off offset:1344
	v_mfma_f32_32x32x16_bf16 v[114:129], v[24:27], v[12:15], v[114:129]
	v_mfma_f32_32x32x16_bf16 v[130:145], v[28:31], v[0:3], v[130:145]
	global_load_dwordx4 v[232:235], v[248:249], off offset:1344
	global_load_dwordx4 v[236:239], v[250:251], off offset:1344
	v_mfma_f32_32x32x16_bf16 v[146:161], v[28:31], v[4:7], v[146:161]
	v_mfma_f32_32x32x16_bf16 v[162:177], v[28:31], v[8:11], v[162:177]
	v_mfma_f32_32x32x16_bf16 v[178:193], v[28:31], v[12:15], v[178:193]
	s_waitcnt lgkmcnt(0)
	s_barrier
; #define G_LOAD(S, kt_) do { G_LD1(S##a0, S##b0, 0, kt_); G_LD1(S##a1, S##b1, 1, kt_); G_LD1(S##a2, S##b2, 2, kt_); G_LD1(S##a3, S##b3, 3, kt_); } while (0)
; #define G_STORE(S, buf_) do { G_ST1(S##a0, S##b0, 0, buf_); G_ST1(S##a1, S##b1, 1, buf_); G_ST1(S##a2, S##b2, 2, buf_); G_ST1(S##a3, S##b3, 3, buf_); } while (0)
; template <class AL, class BL>
; DI void gemm_core(AL al, BL bl, int m0, int n0, int K, char* smem, f32x16 (&acc)[2][2]) {
;     ...
;   G_LOAD(x, 0);
;   G_STORE(x, 0);
;   G_LOAD(x, 1);
;   G_LOAD(y, (nk > 2) ? 2 : 1);
;   __syncthreads();
;   for (int kt = 0; kt < nk; kt += 2) {
;     G_TILE(0, x, true, (kt + 3 < nk), kt + 3);
;     __syncthreads();
;     G_TILE(1, y, (kt + 2 < nk), (kt + 4 < nk), kt + 4);
;     __syncthreads();
;   }
	ds_read_b128 v[0:3], v56 offset:30720
	ds_read_b128 v[4:7], v56 offset:33280
	ds_read_b128 v[8:11], v57 offset:30720
	ds_read_b128 v[12:15], v57 offset:33280
	ds_read_b128 v[16:19], v57 offset:35840
	ds_read_b128 v[20:23], v57 offset:38400
	ds_read_b128 v[24:27], v56 offset:30752
	ds_read_b128 v[28:31], v56 offset:33312
	s_waitcnt lgkmcnt(4)
	v_mfma_f32_32x32x16_bf16 v[66:81], v[0:3], v[8:11], v[66:81]
	v_mfma_f32_32x32x16_bf16 v[82:97], v[0:3], v[12:15], v[82:97]
	s_waitcnt vmcnt(6)
	ds_write_b128 v58, v[32:35] offset:0
	ds_write_b128 v58, v[36:39] offset:5120
	s_waitcnt lgkmcnt(4)
	v_mfma_f32_32x32x16_bf16 v[98:113], v[0:3], v[16:19], v[98:113]
	v_mfma_f32_32x32x16_bf16 v[114:129], v[0:3], v[20:23], v[114:129]
	ds_read_b128 v[0:3], v57 offset:30752
	ds_write_b128 v58, v[40:43] offset:10240
	ds_write_b128 v58, v[44:47] offset:15360
	v_mfma_f32_32x32x16_bf16 v[130:145], v[4:7], v[8:11], v[130:145]
	v_mfma_f32_32x32x16_bf16 v[146:161], v[4:7], v[12:15], v[146:161]
	ds_write_b128 v58, v[48:51] offset:20480
	ds_write_b128 v58, v[52:55] offset:25600
	v_mfma_f32_32x32x16_bf16 v[162:177], v[4:7], v[16:19], v[162:177]
	v_mfma_f32_32x32x16_bf16 v[178:193], v[4:7], v[20:23], v[178:193]
	ds_read_b128 v[4:7], v57 offset:33312
	ds_read_b128 v[8:11], v57 offset:35872
	ds_read_b128 v[12:15], v57 offset:38432
	s_waitcnt lgkmcnt(2)
	v_mfma_f32_32x32x16_bf16 v[66:81], v[24:27], v[0:3], v[66:81]
	global_load_dwordx4 v[32:35], v[240:241], off offset:3456
	global_load_dwordx4 v[36:39], v[242:243], off offset:3456
	v_mfma_f32_32x32x16_bf16 v[82:97], v[24:27], v[4:7], v[82:97]
	s_waitcnt lgkmcnt(0)
	v_mfma_f32_32x32x16_bf16 v[98:113], v[24:27], v[8:11], v[98:113]
	global_load_dwordx4 v[40:43], v[244:245], off offset:1408
	global_load_dwordx4 v[44:47], v[246:247], off offset:1408
	v_mfma_f32_32x32x16_bf16 v[114:129], v[24:27], v[12:15], v[114:129]
	v_mfma_f32_32x32x16_bf16 v[130:145], v[28:31], v[0:3], v[130:145]
	global_load_dwordx4 v[48:51], v[248:249], off offset:1408
	global_load_dwordx4 v[52:55], v[250:251], off offset:1408
	v_mfma_f32_32x32x16_bf16 v[146:161], v[28:31], v[4:7], v[146:161]
	v_mfma_f32_32x32x16_bf16 v[162:177], v[28:31], v[8:11], v[162:177]
	v_mfma_f32_32x32x16_bf16 v[178:193], v[28:31], v[12:15], v[178:193]
	s_waitcnt lgkmcnt(0)
	s_barrier
	ds_read_b128 v[0:3], v56 offset:0
	ds_read_b128 v[4:7], v56 offset:2560
	ds_read_b128 v[8:11], v57 offset:0
	ds_read_b128 v[12:15], v57 offset:2560
	ds_read_b128 v[16:19], v57 offset:5120
	ds_read_b128 v[20:23], v57 offset:7680
	ds_read_b128 v[24:27], v56 offset:32
	ds_read_b128 v[28:31], v56 offset:2592
	s_waitcnt lgkmcnt(4)
	v_mfma_f32_32x32x16_bf16 v[66:81], v[0:3], v[8:11], v[66:81]
	v_mfma_f32_32x32x16_bf16 v[82:97], v[0:3], v[12:15], v[82:97]
	s_waitcnt vmcnt(6)
	ds_write_b128 v58, v[214:217] offset:30720
	ds_write_b128 v58, v[218:221] offset:35840
	s_waitcnt lgkmcnt(4)
	v_mfma_f32_32x32x16_bf16 v[98:113], v[0:3], v[16:19], v[98:113]
	v_mfma_f32_32x32x16_bf16 v[114:129], v[0:3], v[20:23], v[114:129]
	ds_read_b128 v[0:3], v57 offset:32
	ds_write_b128 v58, v[222:225] offset:40960
	ds_write_b128 v58, v[228:231] offset:46080
	v_mfma_f32_32x32x16_bf16 v[130:145], v[4:7], v[8:11], v[130:145]
	v_mfma_f32_32x32x16_bf16 v[146:161], v[4:7], v[12:15], v[146:161]
	ds_write_b128 v58, v[232:235] offset:51200
	ds_write_b128 v58, v[236:239] offset:56320
	v_mfma_f32_32x32x16_bf16 v[162:177], v[4:7], v[16:19], v[162:177]
	v_mfma_f32_32x32x16_bf16 v[178:193], v[4:7], v[20:23], v[178:193]
	ds_read_b128 v[4:7], v57 offset:2592
	ds_read_b128 v[8:11], v57 offset:5152
	ds_read_b128 v[12:15], v57 offset:7712
	s_waitcnt lgkmcnt(2)
	v_mfma_f32_32x32x16_bf16 v[66:81], v[24:27], v[0:3], v[66:81]
	global_load_dwordx4 v[214:217], v[240:241], off offset:3520
	global_load_dwordx4 v[218:221], v[242:243], off offset:3520
	v_mfma_f32_32x32x16_bf16 v[82:97], v[24:27], v[4:7], v[82:97]
	s_waitcnt lgkmcnt(0)
	v_mfma_f32_32x32x16_bf16 v[98:113], v[24:27], v[8:11], v[98:113]
	global_load_dwordx4 v[222:225], v[244:245], off offset:1472
	global_load_dwordx4 v[228:231], v[246:247], off offset:1472
	v_mfma_f32_32x32x16_bf16 v[114:129], v[24:27], v[12:15], v[114:129]
	v_mfma_f32_32x32x16_bf16 v[130:145], v[28:31], v[0:3], v[130:145]
	global_load_dwordx4 v[232:235], v[248:249], off offset:1472
	global_load_dwordx4 v[236:239], v[250:251], off offset:1472
	v_mfma_f32_32x32x16_bf16 v[146:161], v[28:31], v[4:7], v[146:161]
	v_mfma_f32_32x32x16_bf16 v[162:177], v[28:31], v[8:11], v[162:177]
	v_mfma_f32_32x32x16_bf16 v[178:193], v[28:31], v[12:15], v[178:193]
	s_waitcnt lgkmcnt(0)
	s_barrier
; #define G_LOAD(S, kt_) do { G_LD1(S##a0, S##b0, 0, kt_); G_LD1(S##a1, S##b1, 1, kt_); G_LD1(S##a2, S##b2, 2, kt_); G_LD1(S##a3, S##b3, 3, kt_); } while (0)
; #define G_STORE(S, buf_) do { G_ST1(S##a0, S##b0, 0, buf_); G_ST1(S##a1, S##b1, 1, buf_); G_ST1(S##a2, S##b2, 2, buf_); G_ST1(S##a3, S##b3, 3, buf_); } while (0)
; template <class AL, class BL>
; DI void gemm_core(AL al, BL bl, int m0, int n0, int K, char* smem, f32x16 (&acc)[2][2]) {
;     ...
;   G_LOAD(x, 0);
;   G_STORE(x, 0);
;   G_LOAD(x, 1);
;   G_LOAD(y, (nk > 2) ? 2 : 1);
;   __syncthreads();
;   for (int kt = 0; kt < nk; kt += 2) {
;     G_TILE(0, x, true, (kt + 3 < nk), kt + 3);
;     __syncthreads();
;     G_TILE(1, y, (kt + 2 < nk), (kt + 4 < nk), kt + 4);
;     __syncthreads();
;   }
	ds_read_b128 v[0:3], v56 offset:30720
	ds_read_b128 v[4:7], v56 offset:33280
	ds_read_b128 v[8:11], v57 offset:30720
	ds_read_b128 v[12:15], v57 offset:33280
	ds_read_b128 v[16:19], v57 offset:35840
	ds_read_b128 v[20:23], v57 offset:38400
	ds_read_b128 v[24:27], v56 offset:30752
	ds_read_b128 v[28:31], v56 offset:33312
	s_waitcnt lgkmcnt(4)
	v_mfma_f32_32x32x16_bf16 v[66:81], v[0:3], v[8:11], v[66:81]
	v_mfma_f32_32x32x16_bf16 v[82:97], v[0:3], v[12:15], v[82:97]
	s_waitcnt vmcnt(6)
	ds_write_b128 v58, v[32:35] offset:0
	ds_write_b128 v58, v[36:39] offset:5120
	s_waitcnt lgkmcnt(4)
	v_mfma_f32_32x32x16_bf16 v[98:113], v[0:3], v[16:19], v[98:113]
	v_mfma_f32_32x32x16_bf16 v[114:129], v[0:3], v[20:23], v[114:129]
	ds_read_b128 v[0:3], v57 offset:30752
	ds_write_b128 v58, v[40:43] offset:10240
	ds_write_b128 v58, v[44:47] offset:15360
	v_mfma_f32_32x32x16_bf16 v[130:145], v[4:7], v[8:11], v[130:145]
	v_mfma_f32_32x32x16_bf16 v[146:161], v[4:7], v[12:15], v[146:161]
	ds_write_b128 v58, v[48:51] offset:20480
	ds_write_b128 v58, v[52:55] offset:25600
	v_mfma_f32_32x32x16_bf16 v[162:177], v[4:7], v[16:19], v[162:177]
	v_mfma_f32_32x32x16_bf16 v[178:193], v[4:7], v[20:23], v[178:193]
	ds_read_b128 v[4:7], v57 offset:33312
	ds_read_b128 v[8:11], v57 offset:35872
	ds_read_b128 v[12:15], v57 offset:38432
	s_waitcnt lgkmcnt(2)
	v_mfma_f32_32x32x16_bf16 v[66:81], v[24:27], v[0:3], v[66:81]
	global_load_dwordx4 v[32:35], v[240:241], off offset:3584
	global_load_dwordx4 v[36:39], v[242:243], off offset:3584
	v_mfma_f32_32x32x16_bf16 v[82:97], v[24:27], v[4:7], v[82:97]
	s_waitcnt lgkmcnt(0)
	v_mfma_f32_32x32x16_bf16 v[98:113], v[24:27], v[8:11], v[98:113]
	global_load_dwordx4 v[40:43], v[244:245], off offset:1536
	global_load_dwordx4 v[44:47], v[246:247], off offset:1536
	v_mfma_f32_32x32x16_bf16 v[114:129], v[24:27], v[12:15], v[114:129]
	v_mfma_f32_32x32x16_bf16 v[130:145], v[28:31], v[0:3], v[130:145]
	global_load_dwordx4 v[48:51], v[248:249], off offset:1536
	global_load_dwordx4 v[52:55], v[250:251], off offset:1536
	v_mfma_f32_32x32x16_bf16 v[146:161], v[28:31], v[4:7], v[146:161]
	v_mfma_f32_32x32x16_bf16 v[162:177], v[28:31], v[8:11], v[162:177]
	v_mfma_f32_32x32x16_bf16 v[178:193], v[28:31], v[12:15], v[178:193]
	s_waitcnt lgkmcnt(0)
	s_barrier
	ds_read_b128 v[0:3], v56 offset:0
	ds_read_b128 v[4:7], v56 offset:2560
	ds_read_b128 v[8:11], v57 offset:0
	ds_read_b128 v[12:15], v57 offset:2560
	ds_read_b128 v[16:19], v57 offset:5120
	ds_read_b128 v[20:23], v57 offset:7680
	ds_read_b128 v[24:27], v56 offset:32
	ds_read_b128 v[28:31], v56 offset:2592
	s_waitcnt lgkmcnt(4)
	v_mfma_f32_32x32x16_bf16 v[66:81], v[0:3], v[8:11], v[66:81]
	v_mfma_f32_32x32x16_bf16 v[82:97], v[0:3], v[12:15], v[82:97]
	s_waitcnt vmcnt(6)
	ds_write_b128 v58, v[214:217] offset:30720
	ds_write_b128 v58, v[218:221] offset:35840
	s_waitcnt lgkmcnt(4)
	v_mfma_f32_32x32x16_bf16 v[98:113], v[0:3], v[16:19], v[98:113]
	v_mfma_f32_32x32x16_bf16 v[114:129], v[0:3], v[20:23], v[114:129]
	ds_read_b128 v[0:3], v57 offset:32
	ds_write_b128 v58, v[222:225] offset:40960
	ds_write_b128 v58, v[228:231] offset:46080
	v_mfma_f32_32x32x16_bf16 v[130:145], v[4:7], v[8:11], v[130:145]
	v_mfma_f32_32x32x16_bf16 v[146:161], v[4:7], v[12:15], v[146:161]
	ds_write_b128 v58, v[232:235] offset:51200
	ds_write_b128 v58, v[236:239] offset:56320
	v_mfma_f32_32x32x16_bf16 v[162:177], v[4:7], v[16:19], v[162:177]
	v_mfma_f32_32x32x16_bf16 v[178:193], v[4:7], v[20:23], v[178:193]
	ds_read_b128 v[4:7], v57 offset:2592
	ds_read_b128 v[8:11], v57 offset:5152
	ds_read_b128 v[12:15], v57 offset:7712
	s_waitcnt lgkmcnt(2)
	v_mfma_f32_32x32x16_bf16 v[66:81], v[24:27], v[0:3], v[66:81]
	global_load_dwordx4 v[214:217], v[240:241], off offset:3648
	global_load_dwordx4 v[218:221], v[242:243], off offset:3648
	v_mfma_f32_32x32x16_bf16 v[82:97], v[24:27], v[4:7], v[82:97]
	s_waitcnt lgkmcnt(0)
	v_mfma_f32_32x32x16_bf16 v[98:113], v[24:27], v[8:11], v[98:113]
	global_load_dwordx4 v[222:225], v[244:245], off offset:1600
	global_load_dwordx4 v[228:231], v[246:247], off offset:1600
	v_mfma_f32_32x32x16_bf16 v[114:129], v[24:27], v[12:15], v[114:129]
	v_mfma_f32_32x32x16_bf16 v[130:145], v[28:31], v[0:3], v[130:145]
	global_load_dwordx4 v[232:235], v[248:249], off offset:1600
	global_load_dwordx4 v[236:239], v[250:251], off offset:1600
	v_mfma_f32_32x32x16_bf16 v[146:161], v[28:31], v[4:7], v[146:161]
	v_mfma_f32_32x32x16_bf16 v[162:177], v[28:31], v[8:11], v[162:177]
	v_mfma_f32_32x32x16_bf16 v[178:193], v[28:31], v[12:15], v[178:193]
	s_waitcnt lgkmcnt(0)
	s_barrier
; #define G_LOAD(S, kt_) do { G_LD1(S##a0, S##b0, 0, kt_); G_LD1(S##a1, S##b1, 1, kt_); G_LD1(S##a2, S##b2, 2, kt_); G_LD1(S##a3, S##b3, 3, kt_); } while (0)
; #define G_STORE(S, buf_) do { G_ST1(S##a0, S##b0, 0, buf_); G_ST1(S##a1, S##b1, 1, buf_); G_ST1(S##a2, S##b2, 2, buf_); G_ST1(S##a3, S##b3, 3, buf_); } while (0)
; template <class AL, class BL>
; DI void gemm_core(AL al, BL bl, int m0, int n0, int K, char* smem, f32x16 (&acc)[2][2]) {
;     ...
;   G_LOAD(x, 0);
;   G_STORE(x, 0);
;   G_LOAD(x, 1);
;   G_LOAD(y, (nk > 2) ? 2 : 1);
;   __syncthreads();
;   for (int kt = 0; kt < nk; kt += 2) {
;     G_TILE(0, x, true, (kt + 3 < nk), kt + 3);
;     __syncthreads();
;     G_TILE(1, y, (kt + 2 < nk), (kt + 4 < nk), kt + 4);
;     __syncthreads();
;   }
	ds_read_b128 v[0:3], v56 offset:30720
	ds_read_b128 v[4:7], v56 offset:33280
	ds_read_b128 v[8:11], v57 offset:30720
	ds_read_b128 v[12:15], v57 offset:33280
	ds_read_b128 v[16:19], v57 offset:35840
	ds_read_b128 v[20:23], v57 offset:38400
	ds_read_b128 v[24:27], v56 offset:30752
	ds_read_b128 v[28:31], v56 offset:33312
	s_waitcnt lgkmcnt(4)
	v_mfma_f32_32x32x16_bf16 v[66:81], v[0:3], v[8:11], v[66:81]
	v_mfma_f32_32x32x16_bf16 v[82:97], v[0:3], v[12:15], v[82:97]
	s_waitcnt vmcnt(6)
	ds_write_b128 v58, v[32:35] offset:0
	ds_write_b128 v58, v[36:39] offset:5120
	s_waitcnt lgkmcnt(4)
	v_mfma_f32_32x32x16_bf16 v[98:113], v[0:3], v[16:19], v[98:113]
	v_mfma_f32_32x32x16_bf16 v[114:129], v[0:3], v[20:23], v[114:129]
	ds_read_b128 v[0:3], v57 offset:30752
	ds_write_b128 v58, v[40:43] offset:10240
	ds_write_b128 v58, v[44:47] offset:15360
	v_mfma_f32_32x32x16_bf16 v[130:145], v[4:7], v[8:11], v[130:145]
	v_mfma_f32_32x32x16_bf16 v[146:161], v[4:7], v[12:15], v[146:161]
	ds_write_b128 v58, v[48:51] offset:20480
	ds_write_b128 v58, v[52:55] offset:25600
	v_mfma_f32_32x32x16_bf16 v[162:177], v[4:7], v[16:19], v[162:177]
	v_mfma_f32_32x32x16_bf16 v[178:193], v[4:7], v[20:23], v[178:193]
	ds_read_b128 v[4:7], v57 offset:33312
	ds_read_b128 v[8:11], v57 offset:35872
	ds_read_b128 v[12:15], v57 offset:38432
	s_waitcnt lgkmcnt(2)
	v_mfma_f32_32x32x16_bf16 v[66:81], v[24:27], v[0:3], v[66:81]
	global_load_dwordx4 v[32:35], v[240:241], off offset:3712
	global_load_dwordx4 v[36:39], v[242:243], off offset:3712
	v_mfma_f32_32x32x16_bf16 v[82:97], v[24:27], v[4:7], v[82:97]
	s_waitcnt lgkmcnt(0)
	v_mfma_f32_32x32x16_bf16 v[98:113], v[24:27], v[8:11], v[98:113]
	global_load_dwordx4 v[40:43], v[244:245], off offset:1664
	global_load_dwordx4 v[44:47], v[246:247], off offset:1664
	v_mfma_f32_32x32x16_bf16 v[114:129], v[24:27], v[12:15], v[114:129]
	v_mfma_f32_32x32x16_bf16 v[130:145], v[28:31], v[0:3], v[130:145]
	global_load_dwordx4 v[48:51], v[248:249], off offset:1664
	global_load_dwordx4 v[52:55], v[250:251], off offset:1664
	v_mfma_f32_32x32x16_bf16 v[146:161], v[28:31], v[4:7], v[146:161]
	v_mfma_f32_32x32x16_bf16 v[162:177], v[28:31], v[8:11], v[162:177]
	v_mfma_f32_32x32x16_bf16 v[178:193], v[28:31], v[12:15], v[178:193]
	s_waitcnt lgkmcnt(0)
	s_barrier
	ds_read_b128 v[0:3], v56 offset:0
	ds_read_b128 v[4:7], v56 offset:2560
	ds_read_b128 v[8:11], v57 offset:0
	ds_read_b128 v[12:15], v57 offset:2560
	ds_read_b128 v[16:19], v57 offset:5120
	ds_read_b128 v[20:23], v57 offset:7680
	ds_read_b128 v[24:27], v56 offset:32
	ds_read_b128 v[28:31], v56 offset:2592
	s_waitcnt lgkmcnt(4)
	v_mfma_f32_32x32x16_bf16 v[66:81], v[0:3], v[8:11], v[66:81]
	v_mfma_f32_32x32x16_bf16 v[82:97], v[0:3], v[12:15], v[82:97]
	s_waitcnt vmcnt(6)
	ds_write_b128 v58, v[214:217] offset:30720
	ds_write_b128 v58, v[218:221] offset:35840
	s_waitcnt lgkmcnt(4)
	v_mfma_f32_32x32x16_bf16 v[98:113], v[0:3], v[16:19], v[98:113]
	v_mfma_f32_32x32x16_bf16 v[114:129], v[0:3], v[20:23], v[114:129]
	ds_read_b128 v[0:3], v57 offset:32
	ds_write_b128 v58, v[222:225] offset:40960
	ds_write_b128 v58, v[228:231] offset:46080
	v_mfma_f32_32x32x16_bf16 v[130:145], v[4:7], v[8:11], v[130:145]
	v_mfma_f32_32x32x16_bf16 v[146:161], v[4:7], v[12:15], v[146:161]
	ds_write_b128 v58, v[232:235] offset:51200
	ds_write_b128 v58, v[236:239] offset:56320
	v_mfma_f32_32x32x16_bf16 v[162:177], v[4:7], v[16:19], v[162:177]
	v_mfma_f32_32x32x16_bf16 v[178:193], v[4:7], v[20:23], v[178:193]
	ds_read_b128 v[4:7], v57 offset:2592
	ds_read_b128 v[8:11], v57 offset:5152
	ds_read_b128 v[12:15], v57 offset:7712
	s_waitcnt lgkmcnt(2)
	v_mfma_f32_32x32x16_bf16 v[66:81], v[24:27], v[0:3], v[66:81]
	global_load_dwordx4 v[214:217], v[240:241], off offset:3776
	global_load_dwordx4 v[218:221], v[242:243], off offset:3776
	v_mfma_f32_32x32x16_bf16 v[82:97], v[24:27], v[4:7], v[82:97]
	s_waitcnt lgkmcnt(0)
	v_mfma_f32_32x32x16_bf16 v[98:113], v[24:27], v[8:11], v[98:113]
	global_load_dwordx4 v[222:225], v[244:245], off offset:1728
	global_load_dwordx4 v[228:231], v[246:247], off offset:1728
	v_mfma_f32_32x32x16_bf16 v[114:129], v[24:27], v[12:15], v[114:129]
	v_mfma_f32_32x32x16_bf16 v[130:145], v[28:31], v[0:3], v[130:145]
	global_load_dwordx4 v[232:235], v[248:249], off offset:1728
	global_load_dwordx4 v[236:239], v[250:251], off offset:1728
	v_mfma_f32_32x32x16_bf16 v[146:161], v[28:31], v[4:7], v[146:161]
	v_mfma_f32_32x32x16_bf16 v[162:177], v[28:31], v[8:11], v[162:177]
	v_mfma_f32_32x32x16_bf16 v[178:193], v[28:31], v[12:15], v[178:193]
	s_waitcnt lgkmcnt(0)
	s_barrier
; #define G_LOAD(S, kt_) do { G_LD1(S##a0, S##b0, 0, kt_); G_LD1(S##a1, S##b1, 1, kt_); G_LD1(S##a2, S##b2, 2, kt_); G_LD1(S##a3, S##b3, 3, kt_); } while (0)
; #define G_STORE(S, buf_) do { G_ST1(S##a0, S##b0, 0, buf_); G_ST1(S##a1, S##b1, 1, buf_); G_ST1(S##a2, S##b2, 2, buf_); G_ST1(S##a3, S##b3, 3, buf_); } while (0)
; template <class AL, class BL>
; DI void gemm_core(AL al, BL bl, int m0, int n0, int K, char* smem, f32x16 (&acc)[2][2]) {
;     ...
;   G_LOAD(x, 0);
;   G_STORE(x, 0);
;   G_LOAD(x, 1);
;   G_LOAD(y, (nk > 2) ? 2 : 1);
;   __syncthreads();
;   for (int kt = 0; kt < nk; kt += 2) {
;     G_TILE(0, x, true, (kt + 3 < nk), kt + 3);
;     __syncthreads();
;     G_TILE(1, y, (kt + 2 < nk), (kt + 4 < nk), kt + 4);
;     __syncthreads();
;   }
	ds_read_b128 v[0:3], v56 offset:30720
	ds_read_b128 v[4:7], v56 offset:33280
	ds_read_b128 v[8:11], v57 offset:30720
	ds_read_b128 v[12:15], v57 offset:33280
	ds_read_b128 v[16:19], v57 offset:35840
	ds_read_b128 v[20:23], v57 offset:38400
	ds_read_b128 v[24:27], v56 offset:30752
	ds_read_b128 v[28:31], v56 offset:33312
	s_waitcnt lgkmcnt(4)
	v_mfma_f32_32x32x16_bf16 v[66:81], v[0:3], v[8:11], v[66:81]
	v_mfma_f32_32x32x16_bf16 v[82:97], v[0:3], v[12:15], v[82:97]
	s_waitcnt vmcnt(6)
	ds_write_b128 v58, v[32:35] offset:0
	ds_write_b128 v58, v[36:39] offset:5120
	s_waitcnt lgkmcnt(4)
	v_mfma_f32_32x32x16_bf16 v[98:113], v[0:3], v[16:19], v[98:113]
	v_mfma_f32_32x32x16_bf16 v[114:129], v[0:3], v[20:23], v[114:129]
	ds_read_b128 v[0:3], v57 offset:30752
	ds_write_b128 v58, v[40:43] offset:10240
	ds_write_b128 v58, v[44:47] offset:15360
	v_mfma_f32_32x32x16_bf16 v[130:145], v[4:7], v[8:11], v[130:145]
	v_mfma_f32_32x32x16_bf16 v[146:161], v[4:7], v[12:15], v[146:161]
	ds_write_b128 v58, v[48:51] offset:20480
	ds_write_b128 v58, v[52:55] offset:25600
	v_mfma_f32_32x32x16_bf16 v[162:177], v[4:7], v[16:19], v[162:177]
	v_mfma_f32_32x32x16_bf16 v[178:193], v[4:7], v[20:23], v[178:193]
	ds_read_b128 v[4:7], v57 offset:33312
	ds_read_b128 v[8:11], v57 offset:35872
	ds_read_b128 v[12:15], v57 offset:38432
	s_waitcnt lgkmcnt(2)
	v_mfma_f32_32x32x16_bf16 v[66:81], v[24:27], v[0:3], v[66:81]
	global_load_dwordx4 v[32:35], v[240:241], off offset:3840
	global_load_dwordx4 v[36:39], v[242:243], off offset:3840
	v_mfma_f32_32x32x16_bf16 v[82:97], v[24:27], v[4:7], v[82:97]
	s_waitcnt lgkmcnt(0)
	v_mfma_f32_32x32x16_bf16 v[98:113], v[24:27], v[8:11], v[98:113]
	global_load_dwordx4 v[40:43], v[244:245], off offset:1792
	global_load_dwordx4 v[44:47], v[246:247], off offset:1792
	v_mfma_f32_32x32x16_bf16 v[114:129], v[24:27], v[12:15], v[114:129]
	v_mfma_f32_32x32x16_bf16 v[130:145], v[28:31], v[0:3], v[130:145]
	global_load_dwordx4 v[48:51], v[248:249], off offset:1792
	global_load_dwordx4 v[52:55], v[250:251], off offset:1792
	v_mfma_f32_32x32x16_bf16 v[146:161], v[28:31], v[4:7], v[146:161]
	v_mfma_f32_32x32x16_bf16 v[162:177], v[28:31], v[8:11], v[162:177]
	v_mfma_f32_32x32x16_bf16 v[178:193], v[28:31], v[12:15], v[178:193]
	s_waitcnt lgkmcnt(0)
	s_barrier
	ds_read_b128 v[0:3], v56 offset:0
	ds_read_b128 v[4:7], v56 offset:2560
	ds_read_b128 v[8:11], v57 offset:0
	ds_read_b128 v[12:15], v57 offset:2560
	ds_read_b128 v[16:19], v57 offset:5120
	ds_read_b128 v[20:23], v57 offset:7680
	ds_read_b128 v[24:27], v56 offset:32
	ds_read_b128 v[28:31], v56 offset:2592
	s_waitcnt lgkmcnt(4)
	v_mfma_f32_32x32x16_bf16 v[66:81], v[0:3], v[8:11], v[66:81]
	v_mfma_f32_32x32x16_bf16 v[82:97], v[0:3], v[12:15], v[82:97]
	s_waitcnt vmcnt(6)
	ds_write_b128 v58, v[214:217] offset:30720
	ds_write_b128 v58, v[218:221] offset:35840
	s_waitcnt lgkmcnt(4)
	v_mfma_f32_32x32x16_bf16 v[98:113], v[0:3], v[16:19], v[98:113]
	v_mfma_f32_32x32x16_bf16 v[114:129], v[0:3], v[20:23], v[114:129]
	ds_read_b128 v[0:3], v57 offset:32
	ds_write_b128 v58, v[222:225] offset:40960
	ds_write_b128 v58, v[228:231] offset:46080
	v_mfma_f32_32x32x16_bf16 v[130:145], v[4:7], v[8:11], v[130:145]
	v_mfma_f32_32x32x16_bf16 v[146:161], v[4:7], v[12:15], v[146:161]
	ds_write_b128 v58, v[232:235] offset:51200
	ds_write_b128 v58, v[236:239] offset:56320
	v_mfma_f32_32x32x16_bf16 v[162:177], v[4:7], v[16:19], v[162:177]
	v_mfma_f32_32x32x16_bf16 v[178:193], v[4:7], v[20:23], v[178:193]
	ds_read_b128 v[4:7], v57 offset:2592
	ds_read_b128 v[8:11], v57 offset:5152
	ds_read_b128 v[12:15], v57 offset:7712
	s_waitcnt lgkmcnt(2)
	v_mfma_f32_32x32x16_bf16 v[66:81], v[24:27], v[0:3], v[66:81]
	global_load_dwordx4 v[214:217], v[240:241], off offset:3904
	global_load_dwordx4 v[218:221], v[242:243], off offset:3904
	v_mfma_f32_32x32x16_bf16 v[82:97], v[24:27], v[4:7], v[82:97]
	s_waitcnt lgkmcnt(0)
	v_mfma_f32_32x32x16_bf16 v[98:113], v[24:27], v[8:11], v[98:113]
	global_load_dwordx4 v[222:225], v[244:245], off offset:1856
	global_load_dwordx4 v[228:231], v[246:247], off offset:1856
	v_mfma_f32_32x32x16_bf16 v[114:129], v[24:27], v[12:15], v[114:129]
	v_mfma_f32_32x32x16_bf16 v[130:145], v[28:31], v[0:3], v[130:145]
	global_load_dwordx4 v[232:235], v[248:249], off offset:1856
	global_load_dwordx4 v[236:239], v[250:251], off offset:1856
	v_mfma_f32_32x32x16_bf16 v[146:161], v[28:31], v[4:7], v[146:161]
	v_mfma_f32_32x32x16_bf16 v[162:177], v[28:31], v[8:11], v[162:177]
	v_mfma_f32_32x32x16_bf16 v[178:193], v[28:31], v[12:15], v[178:193]
	s_waitcnt lgkmcnt(0)
	s_barrier
; #define G_LOAD(S, kt_) do { G_LD1(S##a0, S##b0, 0, kt_); G_LD1(S##a1, S##b1, 1, kt_); G_LD1(S##a2, S##b2, 2, kt_); G_LD1(S##a3, S##b3, 3, kt_); } while (0)
; #define G_STORE(S, buf_) do { G_ST1(S##a0, S##b0, 0, buf_); G_ST1(S##a1, S##b1, 1, buf_); G_ST1(S##a2, S##b2, 2, buf_); G_ST1(S##a3, S##b3, 3, buf_); } while (0)
; template <class AL, class BL>
; DI void gemm_core(AL al, BL bl, int m0, int n0, int K, char* smem, f32x16 (&acc)[2][2]) {
;     ...
;   G_LOAD(x, 0);
;   G_STORE(x, 0);
;   G_LOAD(x, 1);
;   G_LOAD(y, (nk > 2) ? 2 : 1);
;   __syncthreads();
;   for (int kt = 0; kt < nk; kt += 2) {
;     G_TILE(0, x, true, (kt + 3 < nk), kt + 3);
;     __syncthreads();
;     G_TILE(1, y, (kt + 2 < nk), (kt + 4 < nk), kt + 4);
;     __syncthreads();
;   }
	ds_read_b128 v[0:3], v56 offset:30720
	ds_read_b128 v[4:7], v56 offset:33280
	ds_read_b128 v[8:11], v57 offset:30720
	ds_read_b128 v[12:15], v57 offset:33280
	ds_read_b128 v[16:19], v57 offset:35840
	ds_read_b128 v[20:23], v57 offset:38400
	ds_read_b128 v[24:27], v56 offset:30752
	ds_read_b128 v[28:31], v56 offset:33312
	s_waitcnt lgkmcnt(4)
	v_mfma_f32_32x32x16_bf16 v[66:81], v[0:3], v[8:11], v[66:81]
	v_mfma_f32_32x32x16_bf16 v[82:97], v[0:3], v[12:15], v[82:97]
	s_waitcnt vmcnt(6)
	ds_write_b128 v58, v[32:35] offset:0
	ds_write_b128 v58, v[36:39] offset:5120
	s_waitcnt lgkmcnt(4)
	v_mfma_f32_32x32x16_bf16 v[98:113], v[0:3], v[16:19], v[98:113]
	v_mfma_f32_32x32x16_bf16 v[114:129], v[0:3], v[20:23], v[114:129]
	ds_read_b128 v[0:3], v57 offset:30752
	ds_write_b128 v58, v[40:43] offset:10240
	ds_write_b128 v58, v[44:47] offset:15360
	v_mfma_f32_32x32x16_bf16 v[130:145], v[4:7], v[8:11], v[130:145]
	v_mfma_f32_32x32x16_bf16 v[146:161], v[4:7], v[12:15], v[146:161]
	ds_write_b128 v58, v[48:51] offset:20480
	ds_write_b128 v58, v[52:55] offset:25600
	v_mfma_f32_32x32x16_bf16 v[162:177], v[4:7], v[16:19], v[162:177]
	v_mfma_f32_32x32x16_bf16 v[178:193], v[4:7], v[20:23], v[178:193]
	ds_read_b128 v[4:7], v57 offset:33312
	ds_read_b128 v[8:11], v57 offset:35872
	ds_read_b128 v[12:15], v57 offset:38432
	s_waitcnt lgkmcnt(2)
	v_mfma_f32_32x32x16_bf16 v[66:81], v[24:27], v[0:3], v[66:81]
	global_load_dwordx4 v[32:35], v[240:241], off offset:3968
	global_load_dwordx4 v[36:39], v[242:243], off offset:3968
	v_mfma_f32_32x32x16_bf16 v[82:97], v[24:27], v[4:7], v[82:97]
	s_waitcnt lgkmcnt(0)
	v_mfma_f32_32x32x16_bf16 v[98:113], v[24:27], v[8:11], v[98:113]
	global_load_dwordx4 v[40:43], v[244:245], off offset:1920
	global_load_dwordx4 v[44:47], v[246:247], off offset:1920
	v_mfma_f32_32x32x16_bf16 v[114:129], v[24:27], v[12:15], v[114:129]
	v_mfma_f32_32x32x16_bf16 v[130:145], v[28:31], v[0:3], v[130:145]
	global_load_dwordx4 v[48:51], v[248:249], off offset:1920
	global_load_dwordx4 v[52:55], v[250:251], off offset:1920
	v_mfma_f32_32x32x16_bf16 v[146:161], v[28:31], v[4:7], v[146:161]
	v_mfma_f32_32x32x16_bf16 v[162:177], v[28:31], v[8:11], v[162:177]
	v_mfma_f32_32x32x16_bf16 v[178:193], v[28:31], v[12:15], v[178:193]
	s_waitcnt lgkmcnt(0)
	s_barrier
	ds_read_b128 v[0:3], v56 offset:0
	ds_read_b128 v[4:7], v56 offset:2560
	ds_read_b128 v[8:11], v57 offset:0
	ds_read_b128 v[12:15], v57 offset:2560
	ds_read_b128 v[16:19], v57 offset:5120
	ds_read_b128 v[20:23], v57 offset:7680
	ds_read_b128 v[24:27], v56 offset:32
	ds_read_b128 v[28:31], v56 offset:2592
	s_waitcnt lgkmcnt(4)
	v_mfma_f32_32x32x16_bf16 v[66:81], v[0:3], v[8:11], v[66:81]
	v_mfma_f32_32x32x16_bf16 v[82:97], v[0:3], v[12:15], v[82:97]
	s_waitcnt vmcnt(6)
	ds_write_b128 v58, v[214:217] offset:30720
	ds_write_b128 v58, v[218:221] offset:35840
	s_waitcnt lgkmcnt(4)
	v_mfma_f32_32x32x16_bf16 v[98:113], v[0:3], v[16:19], v[98:113]
	v_mfma_f32_32x32x16_bf16 v[114:129], v[0:3], v[20:23], v[114:129]
	ds_read_b128 v[0:3], v57 offset:32
	ds_write_b128 v58, v[222:225] offset:40960
	ds_write_b128 v58, v[228:231] offset:46080
	v_mfma_f32_32x32x16_bf16 v[130:145], v[4:7], v[8:11], v[130:145]
	v_mfma_f32_32x32x16_bf16 v[146:161], v[4:7], v[12:15], v[146:161]
	ds_write_b128 v58, v[232:235] offset:51200
	ds_write_b128 v58, v[236:239] offset:56320
	v_mfma_f32_32x32x16_bf16 v[162:177], v[4:7], v[16:19], v[162:177]
	v_mfma_f32_32x32x16_bf16 v[178:193], v[4:7], v[20:23], v[178:193]
	ds_read_b128 v[4:7], v57 offset:2592
	ds_read_b128 v[8:11], v57 offset:5152
	ds_read_b128 v[12:15], v57 offset:7712
	s_waitcnt lgkmcnt(2)
	v_mfma_f32_32x32x16_bf16 v[66:81], v[24:27], v[0:3], v[66:81]
	global_load_dwordx4 v[214:217], v[240:241], off offset:4032
	global_load_dwordx4 v[218:221], v[242:243], off offset:4032
	v_mfma_f32_32x32x16_bf16 v[82:97], v[24:27], v[4:7], v[82:97]
	s_waitcnt lgkmcnt(0)
	v_mfma_f32_32x32x16_bf16 v[98:113], v[24:27], v[8:11], v[98:113]
	global_load_dwordx4 v[222:225], v[244:245], off offset:1984
	global_load_dwordx4 v[228:231], v[246:247], off offset:1984
	v_mfma_f32_32x32x16_bf16 v[114:129], v[24:27], v[12:15], v[114:129]
	v_mfma_f32_32x32x16_bf16 v[130:145], v[28:31], v[0:3], v[130:145]
	global_load_dwordx4 v[232:235], v[248:249], off offset:1984
	global_load_dwordx4 v[236:239], v[250:251], off offset:1984
	v_mfma_f32_32x32x16_bf16 v[146:161], v[28:31], v[4:7], v[146:161]
	v_mfma_f32_32x32x16_bf16 v[162:177], v[28:31], v[8:11], v[162:177]
	v_mfma_f32_32x32x16_bf16 v[178:193], v[28:31], v[12:15], v[178:193]
	s_waitcnt lgkmcnt(0)
	s_barrier
	ds_read_b128 v[0:3], v56 offset:30720
	ds_read_b128 v[4:7], v56 offset:33280
	ds_read_b128 v[8:11], v57 offset:30720
	ds_read_b128 v[12:15], v57 offset:33280
	ds_read_b128 v[16:19], v57 offset:35840
	ds_read_b128 v[20:23], v57 offset:38400
	ds_read_b128 v[24:27], v56 offset:30752
	ds_read_b128 v[28:31], v56 offset:33312
	s_waitcnt lgkmcnt(4)
	v_mfma_f32_32x32x16_bf16 v[66:81], v[0:3], v[8:11], v[66:81]
	v_mfma_f32_32x32x16_bf16 v[82:97], v[0:3], v[12:15], v[82:97]
	s_waitcnt vmcnt(6)
	ds_write_b128 v58, v[32:35] offset:0
	ds_write_b128 v58, v[36:39] offset:5120
	s_waitcnt lgkmcnt(4)
	v_mfma_f32_32x32x16_bf16 v[98:113], v[0:3], v[16:19], v[98:113]
	v_mfma_f32_32x32x16_bf16 v[114:129], v[0:3], v[20:23], v[114:129]
	ds_read_b128 v[0:3], v57 offset:30752
	ds_write_b128 v58, v[40:43] offset:10240
	ds_write_b128 v58, v[44:47] offset:15360
	v_mfma_f32_32x32x16_bf16 v[130:145], v[4:7], v[8:11], v[130:145]
	v_mfma_f32_32x32x16_bf16 v[146:161], v[4:7], v[12:15], v[146:161]
	ds_write_b128 v58, v[48:51] offset:20480
	ds_write_b128 v58, v[52:55] offset:25600
	v_mfma_f32_32x32x16_bf16 v[162:177], v[4:7], v[16:19], v[162:177]
	v_mfma_f32_32x32x16_bf16 v[178:193], v[4:7], v[20:23], v[178:193]
	ds_read_b128 v[4:7], v57 offset:33312
	ds_read_b128 v[8:11], v57 offset:35872
	ds_read_b128 v[12:15], v57 offset:38432
	s_waitcnt lgkmcnt(2)
	v_mfma_f32_32x32x16_bf16 v[66:81], v[24:27], v[0:3], v[66:81]
	v_mfma_f32_32x32x16_bf16 v[82:97], v[24:27], v[4:7], v[82:97]
	s_waitcnt lgkmcnt(0)
	v_mfma_f32_32x32x16_bf16 v[98:113], v[24:27], v[8:11], v[98:113]
	v_mfma_f32_32x32x16_bf16 v[114:129], v[24:27], v[12:15], v[114:129]
	v_mfma_f32_32x32x16_bf16 v[130:145], v[28:31], v[0:3], v[130:145]
	v_mfma_f32_32x32x16_bf16 v[146:161], v[28:31], v[4:7], v[146:161]
	v_mfma_f32_32x32x16_bf16 v[162:177], v[28:31], v[8:11], v[162:177]
	v_mfma_f32_32x32x16_bf16 v[178:193], v[28:31], v[12:15], v[178:193]
	s_waitcnt lgkmcnt(0)
	s_barrier
; template <class AL, class BL>
; DI void gemm_core(AL al, BL bl, int m0, int n0, int K, char* smem, f32x16 (&acc)[2][2]) {
;     ...
;   for (int kt = 0; kt < nk; kt += 2) {
;     G_TILE(0, x, true, (kt + 3 < nk), kt + 3);
;     __syncthreads();
;     G_TILE(1, y, (kt + 2 < nk), (kt + 4 < nk), kt + 4);
;     __syncthreads();
;   }
; DI void ffn_up_phase(const Params& p, const u16* xb, int ldx, const u16* wupT, u16* hid, char* smem) {
;     ...
;              [=](const f32x16 (&acc)[2][2], int m0, int n0) {
;                epi_bf16_tile(acc, m0, n0, hid + (long)m0 * 4096 + n0, 4096, smem, [=](int m, int n, float v) {
;                  const float a = fmaxf(v * rs[m], 0.f);
;                  return a * a;
	ds_read_b128 v[0:3], v56 offset:0
	ds_read_b128 v[4:7], v56 offset:2560
	ds_read_b128 v[8:11], v57 offset:0
	ds_read_b128 v[12:15], v57 offset:2560
	ds_read_b128 v[16:19], v57 offset:5120
	ds_read_b128 v[20:23], v57 offset:7680
	ds_read_b128 v[24:27], v56 offset:32
	ds_read_b128 v[28:31], v56 offset:2592
	s_waitcnt lgkmcnt(4)
	v_mfma_f32_32x32x16_bf16 v[66:81], v[0:3], v[8:11], v[66:81]
	v_mfma_f32_32x32x16_bf16 v[82:97], v[0:3], v[12:15], v[82:97]
	s_waitcnt vmcnt(0)
	ds_write_b128 v58, v[214:217] offset:30720
	ds_write_b128 v58, v[218:221] offset:35840
	s_waitcnt lgkmcnt(4)
	v_mfma_f32_32x32x16_bf16 v[98:113], v[0:3], v[16:19], v[98:113]
	v_mfma_f32_32x32x16_bf16 v[114:129], v[0:3], v[20:23], v[114:129]
	ds_read_b128 v[0:3], v57 offset:32
	ds_write_b128 v58, v[222:225] offset:40960
	ds_write_b128 v58, v[228:231] offset:46080
	v_mfma_f32_32x32x16_bf16 v[130:145], v[4:7], v[8:11], v[130:145]
	v_mfma_f32_32x32x16_bf16 v[146:161], v[4:7], v[12:15], v[146:161]
	ds_write_b128 v58, v[232:235] offset:51200
	ds_write_b128 v58, v[236:239] offset:56320
	v_mfma_f32_32x32x16_bf16 v[162:177], v[4:7], v[16:19], v[162:177]
	v_mfma_f32_32x32x16_bf16 v[178:193], v[4:7], v[20:23], v[178:193]
	ds_read_b128 v[4:7], v57 offset:2592
	ds_read_b128 v[8:11], v57 offset:5152
	ds_read_b128 v[12:15], v57 offset:7712
	s_waitcnt lgkmcnt(2)
	v_mfma_f32_32x32x16_bf16 v[66:81], v[24:27], v[0:3], v[66:81]
	v_mfma_f32_32x32x16_bf16 v[82:97], v[24:27], v[4:7], v[82:97]
	s_waitcnt lgkmcnt(0)
	v_mfma_f32_32x32x16_bf16 v[98:113], v[24:27], v[8:11], v[98:113]
	v_mfma_f32_32x32x16_bf16 v[114:129], v[24:27], v[12:15], v[114:129]
	v_mfma_f32_32x32x16_bf16 v[130:145], v[28:31], v[0:3], v[130:145]
	v_mfma_f32_32x32x16_bf16 v[146:161], v[28:31], v[4:7], v[146:161]
	v_mfma_f32_32x32x16_bf16 v[162:177], v[28:31], v[8:11], v[162:177]
	v_mfma_f32_32x32x16_bf16 v[178:193], v[28:31], v[12:15], v[178:193]
	s_waitcnt lgkmcnt(0)
	s_barrier
	ds_read_b128 v[0:3], v56 offset:30720
	ds_read_b128 v[4:7], v56 offset:33280
	ds_read_b128 v[8:11], v57 offset:30720
	ds_read_b128 v[12:15], v57 offset:33280
	ds_read_b128 v[16:19], v57 offset:35840
	ds_read_b128 v[20:23], v57 offset:38400
	ds_read_b128 v[24:27], v56 offset:30752
	ds_read_b128 v[28:31], v56 offset:33312
	s_waitcnt lgkmcnt(4)
	v_mfma_f32_32x32x16_bf16 v[66:81], v[0:3], v[8:11], v[66:81]
	global_load_dword v32, v61, s[14:15] offset:0
	global_load_dword v33, v61, s[14:15] offset:4
	global_load_dword v34, v61, s[14:15] offset:8
	global_load_dword v35, v61, s[14:15] offset:12
	v_mfma_f32_32x32x16_bf16 v[82:97], v[0:3], v[12:15], v[82:97]
	s_waitcnt lgkmcnt(2)
	v_mfma_f32_32x32x16_bf16 v[98:113], v[0:3], v[16:19], v[98:113]
	global_load_dword v36, v61, s[14:15] offset:32
	global_load_dword v37, v61, s[14:15] offset:36
	global_load_dword v38, v61, s[14:15] offset:40
	global_load_dword v39, v61, s[14:15] offset:44
	v_mfma_f32_32x32x16_bf16 v[114:129], v[0:3], v[20:23], v[114:129]
	ds_read_b128 v[0:3], v57 offset:30752
	v_mfma_f32_32x32x16_bf16 v[130:145], v[4:7], v[8:11], v[130:145]
	global_load_dword v40, v61, s[14:15] offset:64
	global_load_dword v41, v61, s[14:15] offset:68
	global_load_dword v42, v61, s[14:15] offset:72
	global_load_dword v43, v61, s[14:15] offset:76
	v_mfma_f32_32x32x16_bf16 v[146:161], v[4:7], v[12:15], v[146:161]
	v_mfma_f32_32x32x16_bf16 v[162:177], v[4:7], v[16:19], v[162:177]
	global_load_dword v44, v61, s[14:15] offset:96
	global_load_dword v45, v61, s[14:15] offset:100
	global_load_dword v46, v61, s[14:15] offset:104
	global_load_dword v47, v61, s[14:15] offset:108
	v_mfma_f32_32x32x16_bf16 v[178:193], v[4:7], v[20:23], v[178:193]
	ds_read_b128 v[4:7], v57 offset:33312
	ds_read_b128 v[8:11], v57 offset:35872
	ds_read_b128 v[12:15], v57 offset:38432
	s_waitcnt lgkmcnt(2)
	v_mfma_f32_32x32x16_bf16 v[66:81], v[24:27], v[0:3], v[66:81]
	global_load_dword v48, v61, s[14:15] offset:128
	global_load_dword v49, v61, s[14:15] offset:132
	global_load_dword v50, v61, s[14:15] offset:136
	global_load_dword v51, v61, s[14:15] offset:140
	v_mfma_f32_32x32x16_bf16 v[82:97], v[24:27], v[4:7], v[82:97]
	s_waitcnt lgkmcnt(0)
	v_mfma_f32_32x32x16_bf16 v[98:113], v[24:27], v[8:11], v[98:113]
	global_load_dword v52, v61, s[14:15] offset:160
	global_load_dword v53, v61, s[14:15] offset:164
	global_load_dword v54, v61, s[14:15] offset:168
	global_load_dword v55, v61, s[14:15] offset:172
	v_mfma_f32_32x32x16_bf16 v[114:129], v[24:27], v[12:15], v[114:129]
	v_mfma_f32_32x32x16_bf16 v[130:145], v[28:31], v[0:3], v[130:145]
	global_load_dword v214, v61, s[14:15] offset:192
	global_load_dword v215, v61, s[14:15] offset:196
	global_load_dword v216, v61, s[14:15] offset:200
	global_load_dword v217, v61, s[14:15] offset:204
	v_mfma_f32_32x32x16_bf16 v[146:161], v[28:31], v[4:7], v[146:161]
	v_mfma_f32_32x32x16_bf16 v[162:177], v[28:31], v[8:11], v[162:177]
	global_load_dword v218, v61, s[14:15] offset:224
	global_load_dword v219, v61, s[14:15] offset:228
	global_load_dword v220, v61, s[14:15] offset:232
	global_load_dword v221, v61, s[14:15] offset:236
	v_mfma_f32_32x32x16_bf16 v[178:193], v[28:31], v[12:15], v[178:193]
	s_waitcnt lgkmcnt(0)
	s_barrier
; DI u16 f2bf(float x) { return (u16)(pack2(x, 0.f) & 0xffffu); }
; DI int opaque_tid() { int t = threadIdx.x; asm volatile("" : "+v"(t)); return t; }
; DI int crow(int i, int h) { return (i & 3) + 8 * (i >> 2) + 4 * h; }
; template <class F>
; DI void epi_bf16_tile(const f32x16 (&acc)[2][2], int m0, int n0, u16* dst0, long ld, char* smem, F f) {
;   const int tid = opaque_tid(), lane = tid & 63, w = tid >> 6, wm = w >> 1, wn = w & 1, h = lane >> 5;
;   u16* T = (u16*)smem;
; #pragma unroll
;   for (int mt = 0; mt < 2; mt++)
; #pragma unroll
;     for (int nt = 0; nt < 2; nt++)
; #pragma unroll
;       for (int i = 0; i < 16; i++) {
;         const int ml = wm * 64 + mt * 32 + crow(i, h), nl = wn * 64 + nt * 32 + (lane & 31);
;         T[ml * 136 + nl] = f2bf(f(m0 + ml, n0 + nl, acc[mt][nt][i]));
;       }
;   __syncthreads();
; DI void ffn_up_phase(const Params& p, const u16* xb, int ldx, const u16* wupT, u16* hid, char* smem) {
;     ...
;              [=](const f32x16 (&acc)[2][2], int m0, int n0) {
;                epi_bf16_tile(acc, m0, n0, hid + (long)m0 * 4096 + n0, 4096, smem, [=](int m, int n, float v) {
;                  const float a = fmaxf(v * rs[m], 0.f);
;                  return a * a;
;                });
	s_nop 7
	s_nop 3
	s_waitcnt vmcnt(0)
	v_mul_f32_e32 v62, v66, v32
	v_max_f32_e32 v62, 0, v62
	v_mul_f32_e32 v62, v62, v62
	v_cvt_pk_bf16_f32 v62, v62, v62
	ds_write_b16 v59, v62 offset:0
	v_mul_f32_e32 v63, v67, v33
	v_max_f32_e32 v63, 0, v63
	v_mul_f32_e32 v63, v63, v63
	v_cvt_pk_bf16_f32 v63, v63, v63
	ds_write_b16 v59, v63 offset:528
	v_mul_f32_e32 v64, v68, v34
	v_max_f32_e32 v64, 0, v64
	v_mul_f32_e32 v64, v64, v64
	v_cvt_pk_bf16_f32 v64, v64, v64
	ds_write_b16 v59, v64 offset:1056
	v_mul_f32_e32 v252, v69, v35
	v_max_f32_e32 v252, 0, v252
	v_mul_f32_e32 v252, v252, v252
	v_cvt_pk_bf16_f32 v252, v252, v252
	ds_write_b16 v59, v252 offset:1584
	v_mul_f32_e32 v62, v70, v36
	v_max_f32_e32 v62, 0, v62
	v_mul_f32_e32 v62, v62, v62
	v_cvt_pk_bf16_f32 v62, v62, v62
	ds_write_b16 v59, v62 offset:4224
	v_mul_f32_e32 v63, v71, v37
	v_max_f32_e32 v63, 0, v63
	v_mul_f32_e32 v63, v63, v63
	v_cvt_pk_bf16_f32 v63, v63, v63
	ds_write_b16 v59, v63 offset:4752
	v_mul_f32_e32 v64, v72, v38
	v_max_f32_e32 v64, 0, v64
	v_mul_f32_e32 v64, v64, v64
	v_cvt_pk_bf16_f32 v64, v64, v64
	ds_write_b16 v59, v64 offset:5280
	v_mul_f32_e32 v252, v73, v39
	v_max_f32_e32 v252, 0, v252
	v_mul_f32_e32 v252, v252, v252
	v_cvt_pk_bf16_f32 v252, v252, v252
	ds_write_b16 v59, v252 offset:5808
	v_mul_f32_e32 v62, v74, v40
	v_max_f32_e32 v62, 0, v62
	v_mul_f32_e32 v62, v62, v62
	v_cvt_pk_bf16_f32 v62, v62, v62
	ds_write_b16 v59, v62 offset:8448
	v_mul_f32_e32 v63, v75, v41
	v_max_f32_e32 v63, 0, v63
	v_mul_f32_e32 v63, v63, v63
	v_cvt_pk_bf16_f32 v63, v63, v63
	ds_write_b16 v59, v63 offset:8976
	v_mul_f32_e32 v64, v76, v42
	v_max_f32_e32 v64, 0, v64
	v_mul_f32_e32 v64, v64, v64
	v_cvt_pk_bf16_f32 v64, v64, v64
	ds_write_b16 v59, v64 offset:9504
	v_mul_f32_e32 v252, v77, v43
	v_max_f32_e32 v252, 0, v252
	v_mul_f32_e32 v252, v252, v252
	v_cvt_pk_bf16_f32 v252, v252, v252
	ds_write_b16 v59, v252 offset:10032
	v_mul_f32_e32 v62, v78, v44
	v_max_f32_e32 v62, 0, v62
	v_mul_f32_e32 v62, v62, v62
	v_cvt_pk_bf16_f32 v62, v62, v62
	ds_write_b16 v59, v62 offset:12672
	v_mul_f32_e32 v63, v79, v45
	v_max_f32_e32 v63, 0, v63
	v_mul_f32_e32 v63, v63, v63
	v_cvt_pk_bf16_f32 v63, v63, v63
	ds_write_b16 v59, v63 offset:13200
	v_mul_f32_e32 v64, v80, v46
	v_max_f32_e32 v64, 0, v64
	v_mul_f32_e32 v64, v64, v64
	v_cvt_pk_bf16_f32 v64, v64, v64
	ds_write_b16 v59, v64 offset:13728
	v_mul_f32_e32 v252, v81, v47
	v_max_f32_e32 v252, 0, v252
	v_mul_f32_e32 v252, v252, v252
	v_cvt_pk_bf16_f32 v252, v252, v252
	ds_write_b16 v59, v252 offset:14256
	v_mul_f32_e32 v62, v82, v32
	v_max_f32_e32 v62, 0, v62
	v_mul_f32_e32 v62, v62, v62
	v_cvt_pk_bf16_f32 v62, v62, v62
	ds_write_b16 v59, v62 offset:64
	v_mul_f32_e32 v63, v83, v33
	v_max_f32_e32 v63, 0, v63
	v_mul_f32_e32 v63, v63, v63
	v_cvt_pk_bf16_f32 v63, v63, v63
	ds_write_b16 v59, v63 offset:592
	v_mul_f32_e32 v64, v84, v34
	v_max_f32_e32 v64, 0, v64
	v_mul_f32_e32 v64, v64, v64
	v_cvt_pk_bf16_f32 v64, v64, v64
	ds_write_b16 v59, v64 offset:1120
	v_mul_f32_e32 v252, v85, v35
	v_max_f32_e32 v252, 0, v252
	v_mul_f32_e32 v252, v252, v252
	v_cvt_pk_bf16_f32 v252, v252, v252
	ds_write_b16 v59, v252 offset:1648
	v_mul_f32_e32 v62, v86, v36
	v_max_f32_e32 v62, 0, v62
	v_mul_f32_e32 v62, v62, v62
	v_cvt_pk_bf16_f32 v62, v62, v62
	ds_write_b16 v59, v62 offset:4288
	v_mul_f32_e32 v63, v87, v37
	v_max_f32_e32 v63, 0, v63
	v_mul_f32_e32 v63, v63, v63
	v_cvt_pk_bf16_f32 v63, v63, v63
	ds_write_b16 v59, v63 offset:4816
	v_mul_f32_e32 v64, v88, v38
	v_max_f32_e32 v64, 0, v64
	v_mul_f32_e32 v64, v64, v64
	v_cvt_pk_bf16_f32 v64, v64, v64
	ds_write_b16 v59, v64 offset:5344
	v_mul_f32_e32 v252, v89, v39
	v_max_f32_e32 v252, 0, v252
	v_mul_f32_e32 v252, v252, v252
	v_cvt_pk_bf16_f32 v252, v252, v252
	ds_write_b16 v59, v252 offset:5872
	v_mul_f32_e32 v62, v90, v40
	v_max_f32_e32 v62, 0, v62
	v_mul_f32_e32 v62, v62, v62
	v_cvt_pk_bf16_f32 v62, v62, v62
	ds_write_b16 v59, v62 offset:8512
	v_mul_f32_e32 v63, v91, v41
	v_max_f32_e32 v63, 0, v63
	v_mul_f32_e32 v63, v63, v63
	v_cvt_pk_bf16_f32 v63, v63, v63
	ds_write_b16 v59, v63 offset:9040
	v_mul_f32_e32 v64, v92, v42
	v_max_f32_e32 v64, 0, v64
	v_mul_f32_e32 v64, v64, v64
	v_cvt_pk_bf16_f32 v64, v64, v64
	ds_write_b16 v59, v64 offset:9568
	v_mul_f32_e32 v252, v93, v43
	v_max_f32_e32 v252, 0, v252
	v_mul_f32_e32 v252, v252, v252
	v_cvt_pk_bf16_f32 v252, v252, v252
	ds_write_b16 v59, v252 offset:10096
	v_mul_f32_e32 v62, v94, v44
	v_max_f32_e32 v62, 0, v62
	v_mul_f32_e32 v62, v62, v62
	v_cvt_pk_bf16_f32 v62, v62, v62
	ds_write_b16 v59, v62 offset:12736
	v_mul_f32_e32 v63, v95, v45
	v_max_f32_e32 v63, 0, v63
	v_mul_f32_e32 v63, v63, v63
	v_cvt_pk_bf16_f32 v63, v63, v63
	ds_write_b16 v59, v63 offset:13264
	v_mul_f32_e32 v64, v96, v46
	v_max_f32_e32 v64, 0, v64
	v_mul_f32_e32 v64, v64, v64
	v_cvt_pk_bf16_f32 v64, v64, v64
	ds_write_b16 v59, v64 offset:13792
	v_mul_f32_e32 v252, v97, v47
	v_max_f32_e32 v252, 0, v252
	v_mul_f32_e32 v252, v252, v252
	v_cvt_pk_bf16_f32 v252, v252, v252
	ds_write_b16 v59, v252 offset:14320
	v_mul_f32_e32 v62, v98, v32
	v_max_f32_e32 v62, 0, v62
	v_mul_f32_e32 v62, v62, v62
	v_cvt_pk_bf16_f32 v62, v62, v62
	ds_write_b16 v59, v62 offset:128
	v_mul_f32_e32 v63, v99, v33
	v_max_f32_e32 v63, 0, v63
	v_mul_f32_e32 v63, v63, v63
	v_cvt_pk_bf16_f32 v63, v63, v63
	ds_write_b16 v59, v63 offset:656
	v_mul_f32_e32 v64, v100, v34
	v_max_f32_e32 v64, 0, v64
	v_mul_f32_e32 v64, v64, v64
	v_cvt_pk_bf16_f32 v64, v64, v64
	ds_write_b16 v59, v64 offset:1184
	v_mul_f32_e32 v252, v101, v35
	v_max_f32_e32 v252, 0, v252
	v_mul_f32_e32 v252, v252, v252
	v_cvt_pk_bf16_f32 v252, v252, v252
	ds_write_b16 v59, v252 offset:1712
; DI u16 f2bf(float x) { return (u16)(pack2(x, 0.f) & 0xffffu); }
; DI int opaque_tid() { int t = threadIdx.x; asm volatile("" : "+v"(t)); return t; }
; DI int crow(int i, int h) { return (i & 3) + 8 * (i >> 2) + 4 * h; }
; template <class F>
; DI void epi_bf16_tile(const f32x16 (&acc)[2][2], int m0, int n0, u16* dst0, long ld, char* smem, F f) {
;   const int tid = opaque_tid(), lane = tid & 63, w = tid >> 6, wm = w >> 1, wn = w & 1, h = lane >> 5;
;   u16* T = (u16*)smem;
; #pragma unroll
;   for (int mt = 0; mt < 2; mt++)
; #pragma unroll
;     for (int nt = 0; nt < 2; nt++)
; #pragma unroll
;       for (int i = 0; i < 16; i++) {
;         const int ml = wm * 64 + mt * 32 + crow(i, h), nl = wn * 64 + nt * 32 + (lane & 31);
;         T[ml * 136 + nl] = f2bf(f(m0 + ml, n0 + nl, acc[mt][nt][i]));
;       }
;   __syncthreads();
; DI void ffn_up_phase(const Params& p, const u16* xb, int ldx, const u16* wupT, u16* hid, char* smem) {
;     ...
;              [=](const f32x16 (&acc)[2][2], int m0, int n0) {
;                epi_bf16_tile(acc, m0, n0, hid + (long)m0 * 4096 + n0, 4096, smem, [=](int m, int n, float v) {
;                  const float a = fmaxf(v * rs[m], 0.f);
;                  return a * a;
;                });
	v_mul_f32_e32 v62, v102, v36
	v_max_f32_e32 v62, 0, v62
	v_mul_f32_e32 v62, v62, v62
	v_cvt_pk_bf16_f32 v62, v62, v62
	ds_write_b16 v59, v62 offset:4352
	v_mul_f32_e32 v63, v103, v37
	v_max_f32_e32 v63, 0, v63
	v_mul_f32_e32 v63, v63, v63
	v_cvt_pk_bf16_f32 v63, v63, v63
	ds_write_b16 v59, v63 offset:4880
	v_mul_f32_e32 v64, v104, v38
	v_max_f32_e32 v64, 0, v64
	v_mul_f32_e32 v64, v64, v64
	v_cvt_pk_bf16_f32 v64, v64, v64
	ds_write_b16 v59, v64 offset:5408
	v_mul_f32_e32 v252, v105, v39
	v_max_f32_e32 v252, 0, v252
	v_mul_f32_e32 v252, v252, v252
	v_cvt_pk_bf16_f32 v252, v252, v252
	ds_write_b16 v59, v252 offset:5936
	v_mul_f32_e32 v62, v106, v40
	v_max_f32_e32 v62, 0, v62
	v_mul_f32_e32 v62, v62, v62
	v_cvt_pk_bf16_f32 v62, v62, v62
	ds_write_b16 v59, v62 offset:8576
	v_mul_f32_e32 v63, v107, v41
	v_max_f32_e32 v63, 0, v63
	v_mul_f32_e32 v63, v63, v63
	v_cvt_pk_bf16_f32 v63, v63, v63
	ds_write_b16 v59, v63 offset:9104
	v_mul_f32_e32 v64, v108, v42
	v_max_f32_e32 v64, 0, v64
	v_mul_f32_e32 v64, v64, v64
	v_cvt_pk_bf16_f32 v64, v64, v64
	ds_write_b16 v59, v64 offset:9632
	v_mul_f32_e32 v252, v109, v43
	v_max_f32_e32 v252, 0, v252
	v_mul_f32_e32 v252, v252, v252
	v_cvt_pk_bf16_f32 v252, v252, v252
	ds_write_b16 v59, v252 offset:10160
	v_mul_f32_e32 v62, v110, v44
	v_max_f32_e32 v62, 0, v62
	v_mul_f32_e32 v62, v62, v62
	v_cvt_pk_bf16_f32 v62, v62, v62
	ds_write_b16 v59, v62 offset:12800
	v_mul_f32_e32 v63, v111, v45
	v_max_f32_e32 v63, 0, v63
	v_mul_f32_e32 v63, v63, v63
	v_cvt_pk_bf16_f32 v63, v63, v63
	ds_write_b16 v59, v63 offset:13328
	v_mul_f32_e32 v64, v112, v46
	v_max_f32_e32 v64, 0, v64
	v_mul_f32_e32 v64, v64, v64
	v_cvt_pk_bf16_f32 v64, v64, v64
	ds_write_b16 v59, v64 offset:13856
	v_mul_f32_e32 v252, v113, v47
	v_max_f32_e32 v252, 0, v252
	v_mul_f32_e32 v252, v252, v252
	v_cvt_pk_bf16_f32 v252, v252, v252
	ds_write_b16 v59, v252 offset:14384
	v_mul_f32_e32 v62, v114, v32
	v_max_f32_e32 v62, 0, v62
	v_mul_f32_e32 v62, v62, v62
	v_cvt_pk_bf16_f32 v62, v62, v62
	ds_write_b16 v59, v62 offset:192
	v_mul_f32_e32 v63, v115, v33
	v_max_f32_e32 v63, 0, v63
	v_mul_f32_e32 v63, v63, v63
	v_cvt_pk_bf16_f32 v63, v63, v63
	ds_write_b16 v59, v63 offset:720
	v_mul_f32_e32 v64, v116, v34
	v_max_f32_e32 v64, 0, v64
	v_mul_f32_e32 v64, v64, v64
	v_cvt_pk_bf16_f32 v64, v64, v64
	ds_write_b16 v59, v64 offset:1248
	v_mul_f32_e32 v252, v117, v35
	v_max_f32_e32 v252, 0, v252
	v_mul_f32_e32 v252, v252, v252
	v_cvt_pk_bf16_f32 v252, v252, v252
	ds_write_b16 v59, v252 offset:1776
	v_mul_f32_e32 v62, v118, v36
	v_max_f32_e32 v62, 0, v62
	v_mul_f32_e32 v62, v62, v62
	v_cvt_pk_bf16_f32 v62, v62, v62
	ds_write_b16 v59, v62 offset:4416
	v_mul_f32_e32 v63, v119, v37
	v_max_f32_e32 v63, 0, v63
	v_mul_f32_e32 v63, v63, v63
	v_cvt_pk_bf16_f32 v63, v63, v63
	ds_write_b16 v59, v63 offset:4944
	v_mul_f32_e32 v64, v120, v38
	v_max_f32_e32 v64, 0, v64
	v_mul_f32_e32 v64, v64, v64
	v_cvt_pk_bf16_f32 v64, v64, v64
	ds_write_b16 v59, v64 offset:5472
	v_mul_f32_e32 v252, v121, v39
	v_max_f32_e32 v252, 0, v252
	v_mul_f32_e32 v252, v252, v252
	v_cvt_pk_bf16_f32 v252, v252, v252
	ds_write_b16 v59, v252 offset:6000
	v_mul_f32_e32 v62, v122, v40
	v_max_f32_e32 v62, 0, v62
	v_mul_f32_e32 v62, v62, v62
	v_cvt_pk_bf16_f32 v62, v62, v62
	ds_write_b16 v59, v62 offset:8640
	v_mul_f32_e32 v63, v123, v41
	v_max_f32_e32 v63, 0, v63
	v_mul_f32_e32 v63, v63, v63
	v_cvt_pk_bf16_f32 v63, v63, v63
	ds_write_b16 v59, v63 offset:9168
	v_mul_f32_e32 v64, v124, v42
	v_max_f32_e32 v64, 0, v64
	v_mul_f32_e32 v64, v64, v64
	v_cvt_pk_bf16_f32 v64, v64, v64
	ds_write_b16 v59, v64 offset:9696
	v_mul_f32_e32 v252, v125, v43
	v_max_f32_e32 v252, 0, v252
	v_mul_f32_e32 v252, v252, v252
	v_cvt_pk_bf16_f32 v252, v252, v252
	ds_write_b16 v59, v252 offset:10224
	v_mul_f32_e32 v62, v126, v44
	v_max_f32_e32 v62, 0, v62
	v_mul_f32_e32 v62, v62, v62
	v_cvt_pk_bf16_f32 v62, v62, v62
	ds_write_b16 v59, v62 offset:12864
	v_mul_f32_e32 v63, v127, v45
	v_max_f32_e32 v63, 0, v63
	v_mul_f32_e32 v63, v63, v63
	v_cvt_pk_bf16_f32 v63, v63, v63
	ds_write_b16 v59, v63 offset:13392
	v_mul_f32_e32 v64, v128, v46
	v_max_f32_e32 v64, 0, v64
	v_mul_f32_e32 v64, v64, v64
	v_cvt_pk_bf16_f32 v64, v64, v64
	ds_write_b16 v59, v64 offset:13920
	v_mul_f32_e32 v252, v129, v47
	v_max_f32_e32 v252, 0, v252
	v_mul_f32_e32 v252, v252, v252
	v_cvt_pk_bf16_f32 v252, v252, v252
	ds_write_b16 v59, v252 offset:14448
	v_mul_f32_e32 v62, v130, v48
	v_max_f32_e32 v62, 0, v62
	v_mul_f32_e32 v62, v62, v62
	v_cvt_pk_bf16_f32 v62, v62, v62
	ds_write_b16 v59, v62 offset:16896
	v_mul_f32_e32 v63, v131, v49
	v_max_f32_e32 v63, 0, v63
	v_mul_f32_e32 v63, v63, v63
	v_cvt_pk_bf16_f32 v63, v63, v63
	ds_write_b16 v59, v63 offset:17424
	v_mul_f32_e32 v64, v132, v50
	v_max_f32_e32 v64, 0, v64
	v_mul_f32_e32 v64, v64, v64
	v_cvt_pk_bf16_f32 v64, v64, v64
	ds_write_b16 v59, v64 offset:17952
	v_mul_f32_e32 v252, v133, v51
	v_max_f32_e32 v252, 0, v252
	v_mul_f32_e32 v252, v252, v252
	v_cvt_pk_bf16_f32 v252, v252, v252
	ds_write_b16 v59, v252 offset:18480
	v_mul_f32_e32 v62, v134, v52
	v_max_f32_e32 v62, 0, v62
	v_mul_f32_e32 v62, v62, v62
	v_cvt_pk_bf16_f32 v62, v62, v62
	ds_write_b16 v59, v62 offset:21120
	v_mul_f32_e32 v63, v135, v53
	v_max_f32_e32 v63, 0, v63
	v_mul_f32_e32 v63, v63, v63
	v_cvt_pk_bf16_f32 v63, v63, v63
	ds_write_b16 v59, v63 offset:21648
	v_mul_f32_e32 v64, v136, v54
	v_max_f32_e32 v64, 0, v64
	v_mul_f32_e32 v64, v64, v64
	v_cvt_pk_bf16_f32 v64, v64, v64
	ds_write_b16 v59, v64 offset:22176
	v_mul_f32_e32 v252, v137, v55
	v_max_f32_e32 v252, 0, v252
	v_mul_f32_e32 v252, v252, v252
	v_cvt_pk_bf16_f32 v252, v252, v252
	ds_write_b16 v59, v252 offset:22704
; DI u16 f2bf(float x) { return (u16)(pack2(x, 0.f) & 0xffffu); }
; DI int opaque_tid() { int t = threadIdx.x; asm volatile("" : "+v"(t)); return t; }
; DI int crow(int i, int h) { return (i & 3) + 8 * (i >> 2) + 4 * h; }
; template <class F>
; DI void epi_bf16_tile(const f32x16 (&acc)[2][2], int m0, int n0, u16* dst0, long ld, char* smem, F f) {
;   const int tid = opaque_tid(), lane = tid & 63, w = tid >> 6, wm = w >> 1, wn = w & 1, h = lane >> 5;
;   u16* T = (u16*)smem;
; #pragma unroll
;   for (int mt = 0; mt < 2; mt++)
; #pragma unroll
;     for (int nt = 0; nt < 2; nt++)
; #pragma unroll
;       for (int i = 0; i < 16; i++) {
;         const int ml = wm * 64 + mt * 32 + crow(i, h), nl = wn * 64 + nt * 32 + (lane & 31);
;         T[ml * 136 + nl] = f2bf(f(m0 + ml, n0 + nl, acc[mt][nt][i]));
;       }
;   __syncthreads();
; DI void ffn_up_phase(const Params& p, const u16* xb, int ldx, const u16* wupT, u16* hid, char* smem) {
;     ...
;              [=](const f32x16 (&acc)[2][2], int m0, int n0) {
;                epi_bf16_tile(acc, m0, n0, hid + (long)m0 * 4096 + n0, 4096, smem, [=](int m, int n, float v) {
;                  const float a = fmaxf(v * rs[m], 0.f);
;                  return a * a;
;                });
	v_mul_f32_e32 v62, v138, v214
	v_max_f32_e32 v62, 0, v62
	v_mul_f32_e32 v62, v62, v62
	v_cvt_pk_bf16_f32 v62, v62, v62
	ds_write_b16 v59, v62 offset:25344
	v_mul_f32_e32 v63, v139, v215
	v_max_f32_e32 v63, 0, v63
	v_mul_f32_e32 v63, v63, v63
	v_cvt_pk_bf16_f32 v63, v63, v63
	ds_write_b16 v59, v63 offset:25872
	v_mul_f32_e32 v64, v140, v216
	v_max_f32_e32 v64, 0, v64
	v_mul_f32_e32 v64, v64, v64
	v_cvt_pk_bf16_f32 v64, v64, v64
	ds_write_b16 v59, v64 offset:26400
	v_mul_f32_e32 v252, v141, v217
	v_max_f32_e32 v252, 0, v252
	v_mul_f32_e32 v252, v252, v252
	v_cvt_pk_bf16_f32 v252, v252, v252
	ds_write_b16 v59, v252 offset:26928
	v_mul_f32_e32 v62, v142, v218
	v_max_f32_e32 v62, 0, v62
	v_mul_f32_e32 v62, v62, v62
	v_cvt_pk_bf16_f32 v62, v62, v62
	ds_write_b16 v59, v62 offset:29568
	v_mul_f32_e32 v63, v143, v219
	v_max_f32_e32 v63, 0, v63
	v_mul_f32_e32 v63, v63, v63
	v_cvt_pk_bf16_f32 v63, v63, v63
	ds_write_b16 v59, v63 offset:30096
	v_mul_f32_e32 v64, v144, v220
	v_max_f32_e32 v64, 0, v64
	v_mul_f32_e32 v64, v64, v64
	v_cvt_pk_bf16_f32 v64, v64, v64
	ds_write_b16 v59, v64 offset:30624
	v_mul_f32_e32 v252, v145, v221
	v_max_f32_e32 v252, 0, v252
	v_mul_f32_e32 v252, v252, v252
	v_cvt_pk_bf16_f32 v252, v252, v252
	ds_write_b16 v59, v252 offset:31152
	v_mul_f32_e32 v62, v146, v48
	v_max_f32_e32 v62, 0, v62
	v_mul_f32_e32 v62, v62, v62
	v_cvt_pk_bf16_f32 v62, v62, v62
	ds_write_b16 v59, v62 offset:16960
	v_mul_f32_e32 v63, v147, v49
	v_max_f32_e32 v63, 0, v63
	v_mul_f32_e32 v63, v63, v63
	v_cvt_pk_bf16_f32 v63, v63, v63
	ds_write_b16 v59, v63 offset:17488
	v_mul_f32_e32 v64, v148, v50
	v_max_f32_e32 v64, 0, v64
	v_mul_f32_e32 v64, v64, v64
	v_cvt_pk_bf16_f32 v64, v64, v64
	ds_write_b16 v59, v64 offset:18016
	v_mul_f32_e32 v252, v149, v51
	v_max_f32_e32 v252, 0, v252
	v_mul_f32_e32 v252, v252, v252
	v_cvt_pk_bf16_f32 v252, v252, v252
	ds_write_b16 v59, v252 offset:18544
	v_mul_f32_e32 v62, v150, v52
	v_max_f32_e32 v62, 0, v62
	v_mul_f32_e32 v62, v62, v62
	v_cvt_pk_bf16_f32 v62, v62, v62
	ds_write_b16 v59, v62 offset:21184
	v_mul_f32_e32 v63, v151, v53
	v_max_f32_e32 v63, 0, v63
	v_mul_f32_e32 v63, v63, v63
	v_cvt_pk_bf16_f32 v63, v63, v63
	ds_write_b16 v59, v63 offset:21712
	v_mul_f32_e32 v64, v152, v54
	v_max_f32_e32 v64, 0, v64
	v_mul_f32_e32 v64, v64, v64
	v_cvt_pk_bf16_f32 v64, v64, v64
	ds_write_b16 v59, v64 offset:22240
	v_mul_f32_e32 v252, v153, v55
	v_max_f32_e32 v252, 0, v252
	v_mul_f32_e32 v252, v252, v252
	v_cvt_pk_bf16_f32 v252, v252, v252
	ds_write_b16 v59, v252 offset:22768
	v_mul_f32_e32 v62, v154, v214
	v_max_f32_e32 v62, 0, v62
	v_mul_f32_e32 v62, v62, v62
	v_cvt_pk_bf16_f32 v62, v62, v62
	ds_write_b16 v59, v62 offset:25408
	v_mul_f32_e32 v63, v155, v215
	v_max_f32_e32 v63, 0, v63
	v_mul_f32_e32 v63, v63, v63
	v_cvt_pk_bf16_f32 v63, v63, v63
	ds_write_b16 v59, v63 offset:25936
	v_mul_f32_e32 v64, v156, v216
	v_max_f32_e32 v64, 0, v64
	v_mul_f32_e32 v64, v64, v64
	v_cvt_pk_bf16_f32 v64, v64, v64
	ds_write_b16 v59, v64 offset:26464
	v_mul_f32_e32 v252, v157, v217
	v_max_f32_e32 v252, 0, v252
	v_mul_f32_e32 v252, v252, v252
	v_cvt_pk_bf16_f32 v252, v252, v252
	ds_write_b16 v59, v252 offset:26992
	v_mul_f32_e32 v62, v158, v218
	v_max_f32_e32 v62, 0, v62
	v_mul_f32_e32 v62, v62, v62
	v_cvt_pk_bf16_f32 v62, v62, v62
	ds_write_b16 v59, v62 offset:29632
	v_mul_f32_e32 v63, v159, v219
	v_max_f32_e32 v63, 0, v63
	v_mul_f32_e32 v63, v63, v63
	v_cvt_pk_bf16_f32 v63, v63, v63
	ds_write_b16 v59, v63 offset:30160
	v_mul_f32_e32 v64, v160, v220
	v_max_f32_e32 v64, 0, v64
	v_mul_f32_e32 v64, v64, v64
	v_cvt_pk_bf16_f32 v64, v64, v64
	ds_write_b16 v59, v64 offset:30688
	v_mul_f32_e32 v252, v161, v221
	v_max_f32_e32 v252, 0, v252
	v_mul_f32_e32 v252, v252, v252
	v_cvt_pk_bf16_f32 v252, v252, v252
	ds_write_b16 v59, v252 offset:31216
	v_mul_f32_e32 v62, v162, v48
	v_max_f32_e32 v62, 0, v62
	v_mul_f32_e32 v62, v62, v62
	v_cvt_pk_bf16_f32 v62, v62, v62
	ds_write_b16 v59, v62 offset:17024
	v_mul_f32_e32 v63, v163, v49
	v_max_f32_e32 v63, 0, v63
	v_mul_f32_e32 v63, v63, v63
	v_cvt_pk_bf16_f32 v63, v63, v63
	ds_write_b16 v59, v63 offset:17552
	v_mul_f32_e32 v64, v164, v50
	v_max_f32_e32 v64, 0, v64
	v_mul_f32_e32 v64, v64, v64
	v_cvt_pk_bf16_f32 v64, v64, v64
	ds_write_b16 v59, v64 offset:18080
	v_mul_f32_e32 v252, v165, v51
	v_max_f32_e32 v252, 0, v252
	v_mul_f32_e32 v252, v252, v252
	v_cvt_pk_bf16_f32 v252, v252, v252
	ds_write_b16 v59, v252 offset:18608
	v_mul_f32_e32 v62, v166, v52
	v_max_f32_e32 v62, 0, v62
	v_mul_f32_e32 v62, v62, v62
	v_cvt_pk_bf16_f32 v62, v62, v62
	ds_write_b16 v59, v62 offset:21248
	v_mul_f32_e32 v63, v167, v53
	v_max_f32_e32 v63, 0, v63
	v_mul_f32_e32 v63, v63, v63
	v_cvt_pk_bf16_f32 v63, v63, v63
	ds_write_b16 v59, v63 offset:21776
	v_mul_f32_e32 v64, v168, v54
	v_max_f32_e32 v64, 0, v64
	v_mul_f32_e32 v64, v64, v64
	v_cvt_pk_bf16_f32 v64, v64, v64
	ds_write_b16 v59, v64 offset:22304
	v_mul_f32_e32 v252, v169, v55
	v_max_f32_e32 v252, 0, v252
	v_mul_f32_e32 v252, v252, v252
	v_cvt_pk_bf16_f32 v252, v252, v252
	ds_write_b16 v59, v252 offset:22832
	v_mul_f32_e32 v62, v170, v214
	v_max_f32_e32 v62, 0, v62
	v_mul_f32_e32 v62, v62, v62
	v_cvt_pk_bf16_f32 v62, v62, v62
	ds_write_b16 v59, v62 offset:25472
	v_mul_f32_e32 v63, v171, v215
	v_max_f32_e32 v63, 0, v63
	v_mul_f32_e32 v63, v63, v63
	v_cvt_pk_bf16_f32 v63, v63, v63
	ds_write_b16 v59, v63 offset:26000
	v_mul_f32_e32 v64, v172, v216
	v_max_f32_e32 v64, 0, v64
	v_mul_f32_e32 v64, v64, v64
	v_cvt_pk_bf16_f32 v64, v64, v64
	ds_write_b16 v59, v64 offset:26528
	v_mul_f32_e32 v252, v173, v217
	v_max_f32_e32 v252, 0, v252
	v_mul_f32_e32 v252, v252, v252
	v_cvt_pk_bf16_f32 v252, v252, v252
; template <class F>
; DI void epi_bf16_tile(const f32x16 (&acc)[2][2], int m0, int n0, u16* dst0, long ld, char* smem, F f) {
;     ...
;   __syncthreads();
; #pragma unroll
;   for (int j = 0; j < 8; j++) {
;     const int idx = tid + 256 * j, row = idx >> 4, ch = idx & 15;
;     *(uint4*)(dst0 + (long)row * ld + ch * 8) = *(const uint4*)(T + row * 136 + ch * 8);
;   }
;   __syncthreads();
; template <class AL, class BL, class EP>
; DI void gemm_phase(int MT, int NTL, int K, AL al, BL bl, EP ep, char* smem) {
;   for (int t = blockIdx.x; t < MT * NTL; t += gridDim.x) {
;     const int tm = t % MT, tn = t / MT;
;     f32x16 acc[2][2];
;     gemm_core(al, bl, tm * 128, tn * 128, K, smem, acc);
;     ep(acc, tm * 128, tn * 128);
;   }
; }
	ds_write_b16 v59, v252 offset:27056
	v_mul_f32_e32 v62, v174, v218
	v_max_f32_e32 v62, 0, v62
	v_mul_f32_e32 v62, v62, v62
	v_cvt_pk_bf16_f32 v62, v62, v62
	ds_write_b16 v59, v62 offset:29696
	v_mul_f32_e32 v63, v175, v219
	v_max_f32_e32 v63, 0, v63
	v_mul_f32_e32 v63, v63, v63
	v_cvt_pk_bf16_f32 v63, v63, v63
	ds_write_b16 v59, v63 offset:30224
	v_mul_f32_e32 v64, v176, v220
	v_max_f32_e32 v64, 0, v64
	v_mul_f32_e32 v64, v64, v64
	v_cvt_pk_bf16_f32 v64, v64, v64
	ds_write_b16 v59, v64 offset:30752
	v_mul_f32_e32 v252, v177, v221
	v_max_f32_e32 v252, 0, v252
	v_mul_f32_e32 v252, v252, v252
	v_cvt_pk_bf16_f32 v252, v252, v252
	ds_write_b16 v59, v252 offset:31280
	v_mul_f32_e32 v62, v178, v48
	v_max_f32_e32 v62, 0, v62
	v_mul_f32_e32 v62, v62, v62
	v_cvt_pk_bf16_f32 v62, v62, v62
	ds_write_b16 v59, v62 offset:17088
	v_mul_f32_e32 v63, v179, v49
	v_max_f32_e32 v63, 0, v63
	v_mul_f32_e32 v63, v63, v63
	v_cvt_pk_bf16_f32 v63, v63, v63
	ds_write_b16 v59, v63 offset:17616
	v_mul_f32_e32 v64, v180, v50
	v_max_f32_e32 v64, 0, v64
	v_mul_f32_e32 v64, v64, v64
	v_cvt_pk_bf16_f32 v64, v64, v64
	ds_write_b16 v59, v64 offset:18144
	v_mul_f32_e32 v252, v181, v51
	v_max_f32_e32 v252, 0, v252
	v_mul_f32_e32 v252, v252, v252
	v_cvt_pk_bf16_f32 v252, v252, v252
	ds_write_b16 v59, v252 offset:18672
	v_mul_f32_e32 v62, v182, v52
	v_max_f32_e32 v62, 0, v62
	v_mul_f32_e32 v62, v62, v62
	v_cvt_pk_bf16_f32 v62, v62, v62
	ds_write_b16 v59, v62 offset:21312
	v_mul_f32_e32 v63, v183, v53
	v_max_f32_e32 v63, 0, v63
	v_mul_f32_e32 v63, v63, v63
	v_cvt_pk_bf16_f32 v63, v63, v63
	ds_write_b16 v59, v63 offset:21840
	v_mul_f32_e32 v64, v184, v54
	v_max_f32_e32 v64, 0, v64
	v_mul_f32_e32 v64, v64, v64
	v_cvt_pk_bf16_f32 v64, v64, v64
	ds_write_b16 v59, v64 offset:22368
	v_mul_f32_e32 v252, v185, v55
	v_max_f32_e32 v252, 0, v252
	v_mul_f32_e32 v252, v252, v252
	v_cvt_pk_bf16_f32 v252, v252, v252
	ds_write_b16 v59, v252 offset:22896
	v_mul_f32_e32 v62, v186, v214
	v_max_f32_e32 v62, 0, v62
	v_mul_f32_e32 v62, v62, v62
	v_cvt_pk_bf16_f32 v62, v62, v62
	ds_write_b16 v59, v62 offset:25536
	v_mul_f32_e32 v63, v187, v215
	v_max_f32_e32 v63, 0, v63
	v_mul_f32_e32 v63, v63, v63
	v_cvt_pk_bf16_f32 v63, v63, v63
	ds_write_b16 v59, v63 offset:26064
	v_mul_f32_e32 v64, v188, v216
	v_max_f32_e32 v64, 0, v64
	v_mul_f32_e32 v64, v64, v64
	v_cvt_pk_bf16_f32 v64, v64, v64
	ds_write_b16 v59, v64 offset:26592
	v_mul_f32_e32 v252, v189, v217
	v_max_f32_e32 v252, 0, v252
	v_mul_f32_e32 v252, v252, v252
	v_cvt_pk_bf16_f32 v252, v252, v252
	ds_write_b16 v59, v252 offset:27120
	v_mul_f32_e32 v62, v190, v218
	v_max_f32_e32 v62, 0, v62
	v_mul_f32_e32 v62, v62, v62
	v_cvt_pk_bf16_f32 v62, v62, v62
	ds_write_b16 v59, v62 offset:29760
	v_mul_f32_e32 v63, v191, v219
	v_max_f32_e32 v63, 0, v63
	v_mul_f32_e32 v63, v63, v63
	v_cvt_pk_bf16_f32 v63, v63, v63
	ds_write_b16 v59, v63 offset:30288
	v_mul_f32_e32 v64, v192, v220
	v_max_f32_e32 v64, 0, v64
	v_mul_f32_e32 v64, v64, v64
	v_cvt_pk_bf16_f32 v64, v64, v64
	ds_write_b16 v59, v64 offset:30816
	v_mul_f32_e32 v252, v193, v221
	v_max_f32_e32 v252, 0, v252
	v_mul_f32_e32 v252, v252, v252
	v_cvt_pk_bf16_f32 v252, v252, v252
	ds_write_b16 v59, v252 offset:31344
	s_waitcnt lgkmcnt(0)
	s_barrier
	ds_read_b128 v[0:3], v60 offset:0
	ds_read_b128 v[4:7], v60 offset:4224
	ds_read_b128 v[8:11], v60 offset:8448
	ds_read_b128 v[12:15], v60 offset:12672
	ds_read_b128 v[16:19], v60 offset:16896
	ds_read_b128 v[20:23], v60 offset:21120
	ds_read_b128 v[24:27], v60 offset:25344
	ds_read_b128 v[28:31], v60 offset:29568
	s_waitcnt lgkmcnt(7)
	global_store_dwordx4 v227, v[0:3], s[20:21]
	s_add_u32 s20, s20, 65536
	s_addc_u32 s21, s21, 0
	ds_read_b128 v[0:3], v60 offset:33792
	s_waitcnt lgkmcnt(7)
	global_store_dwordx4 v227, v[4:7], s[20:21]
	s_add_u32 s20, s20, 65536
	s_addc_u32 s21, s21, 0
	ds_read_b128 v[4:7], v60 offset:38016
	s_waitcnt lgkmcnt(7)
	global_store_dwordx4 v227, v[8:11], s[20:21]
	s_add_u32 s20, s20, 65536
	s_addc_u32 s21, s21, 0
	ds_read_b128 v[8:11], v60 offset:42240
	s_waitcnt lgkmcnt(7)
	global_store_dwordx4 v227, v[12:15], s[20:21]
	s_add_u32 s20, s20, 65536
	s_addc_u32 s21, s21, 0
	ds_read_b128 v[12:15], v60 offset:46464
	s_waitcnt lgkmcnt(7)
	global_store_dwordx4 v227, v[16:19], s[20:21]
	s_add_u32 s20, s20, 65536
	s_addc_u32 s21, s21, 0
	ds_read_b128 v[16:19], v60 offset:50688
	s_waitcnt lgkmcnt(7)
	global_store_dwordx4 v227, v[20:23], s[20:21]
	s_add_u32 s20, s20, 65536
	s_addc_u32 s21, s21, 0
	ds_read_b128 v[20:23], v60 offset:54912
	s_waitcnt lgkmcnt(7)
	global_store_dwordx4 v227, v[24:27], s[20:21]
	s_add_u32 s20, s20, 65536
	s_addc_u32 s21, s21, 0
	ds_read_b128 v[24:27], v60 offset:59136
	s_waitcnt lgkmcnt(7)
	global_store_dwordx4 v227, v[28:31], s[20:21]
	s_add_u32 s20, s20, 65536
	s_addc_u32 s21, s21, 0
	ds_read_b128 v[28:31], v60 offset:63360
	s_waitcnt lgkmcnt(7)
	global_store_dwordx4 v227, v[0:3], s[20:21]
	s_add_u32 s20, s20, 65536
	s_addc_u32 s21, s21, 0
	s_waitcnt lgkmcnt(6)
	global_store_dwordx4 v227, v[4:7], s[20:21]
	s_add_u32 s20, s20, 65536
	s_addc_u32 s21, s21, 0
	s_waitcnt lgkmcnt(5)
	global_store_dwordx4 v227, v[8:11], s[20:21]
	s_add_u32 s20, s20, 65536
	s_addc_u32 s21, s21, 0
	s_waitcnt lgkmcnt(4)
	global_store_dwordx4 v227, v[12:15], s[20:21]
	s_add_u32 s20, s20, 65536
	s_addc_u32 s21, s21, 0
	s_waitcnt lgkmcnt(3)
	global_store_dwordx4 v227, v[16:19], s[20:21]
	s_add_u32 s20, s20, 65536
	s_addc_u32 s21, s21, 0
	s_waitcnt lgkmcnt(2)
	global_store_dwordx4 v227, v[20:23], s[20:21]
	s_add_u32 s20, s20, 65536
	s_addc_u32 s21, s21, 0
	s_waitcnt lgkmcnt(1)
	global_store_dwordx4 v227, v[24:27], s[20:21]
	s_add_u32 s20, s20, 65536
	s_addc_u32 s21, s21, 0
	s_waitcnt lgkmcnt(0)
	global_store_dwordx4 v227, v[28:31], s[20:21]
	s_barrier
	v_bfe_u32 v62, v202, 5, 1
	v_and_b32_e32 v63, 31, v202
	v_lshrrev_b32_e32 v64, 7, v202
	v_bfe_u32 v252, v202, 6, 1
	s_add_u32 s98, s98, s50
	s_cmpk_lt_u32 s98, 0x800
	s_cbranch_scc1 .Lfu0_tile
	s_cmpk_lt_u32 s78, 0xe0
	s_cbranch_scc0 .Lfu0_s2
	s_cmpk_ge_u32 s78, 0x70
	s_cselect_b32 s0, 1, 0
	s_mul_i32 s1, s0, 0x70
	s_sub_u32 s1, s78, s1
	s_add_u32 s1, s1, 32
	s_add_u32 s0, s0, 28
	s_branch .Lfu0_s3
; #define G_LOAD(S, kt_) do { G_LD1(S##a0, S##b0, 0, kt_); G_LD1(S##a1, S##b1, 1, kt_); G_LD1(S##a2, S##b2, 2, kt_); G_LD1(S##a3, S##b3, 3, kt_); } while (0)
; #define G_STORE(S, buf_) do { G_ST1(S##a0, S##b0, 0, buf_); G_ST1(S##a1, S##b1, 1, buf_); G_ST1(S##a2, S##b2, 2, buf_); G_ST1(S##a3, S##b3, 3, buf_); } while (0)
; template <class AL, class BL>
; DI void gemm_core(AL al, BL bl, int m0, int n0, int K, char* smem, f32x16 (&acc)[2][2]) {
;     ...
;   G_LOAD(x, 0);
;   G_STORE(x, 0);
;   G_LOAD(x, 1);
;   G_LOAD(y, (nk > 2) ? 2 : 1);
;   __syncthreads();
;   for (int kt = 0; kt < nk; kt += 2) {
;     G_TILE(0, x, true, (kt + 3 < nk), kt + 3);
; template <class AL, class BL, class EP>
; DI void gemm_phase(int MT, int NTL, int K, AL al, BL bl, EP ep, char* smem) {
;   for (int t = blockIdx.x; t < MT * NTL; t += gridDim.x) {
;     const int tm = t % MT, tn = t / MT;
;     f32x16 acc[2][2];
;     gemm_core(al, bl, tm * 128, tn * 128, K, smem, acc);
;     ep(acc, tm * 128, tn * 128);
;   }
; }
.Lfu0_s2:
	s_sub_u32 s1, s78, 0xe0
	s_cmpk_ge_u32 s1, 0x90
	s_cselect_b32 s0, 1, 0
	s_mul_i32 s2, s0, 0x90
	s_sub_u32 s1, s1, s2
	s_add_u32 s0, s0, 30
.Lfu0_s3:
	s_mul_i32 s0, s0, 0x90
	s_add_u32 s33, s0, s1
	s_lshl_b32 s24, s33, 7
	s_add_u32 s24, s24, 48
.LBB0_978:
	s_mul_hi_i32 s0, s33, 0x38e38e39
	s_lshr_b32 s1, s0, 31
	s_ashr_i32 s0, s0, 5
	s_add_i32 s1, s0, s1
	v_mov_b32_e32 v32, v202
	s_lshl_b32 s0, s1, 7
	s_mul_i32 s34, s1, 0x4800
	v_ashrrev_i32_e32 v33, 3, v32
	v_add_u32_e32 v4, s0, v33
	v_ashrrev_i32_e32 v5, 31, v4
	v_lshlrev_b32_e32 v2, 4, v32
	v_lshlrev_b64 v[4:5], 11, v[4:5]
	v_and_b32_e32 v64, 0x70, v2
	v_lshl_add_u64 v[4:5], s[8:9], 0, v[4:5]
	v_lshl_add_u64 v[78:79], v[4:5], 0, v[64:65]
	v_subrev_u32_e32 v0, s34, v33
	v_add_co_u32_e32 v12, vcc, s26, v78
	v_add_u32_e32 v24, s24, v0
	s_nop 0
	v_addc_co_u32_e32 v13, vcc, 0, v79, vcc
	v_subrev_u32_e32 v0, 48, v24
	v_add_co_u32_e32 v20, vcc, s27, v78
	v_ashrrev_i32_e32 v1, 31, v0
	global_load_dwordx4 v[4:7], v[78:79], off
	v_add_u32_e32 v8, -16, v24
	v_addc_co_u32_e32 v21, vcc, 0, v79, vcc
	v_lshlrev_b64 v[0:1], 12, v[0:1]
	v_ashrrev_i32_e32 v9, 31, v8
	global_load_dwordx4 v[12:15], v[12:13], off
	v_add_u32_e32 v16, 16, v24
	v_add_u32_e32 v28, 48, v24
	v_add_co_u32_e32 v24, vcc, s28, v78
	v_lshl_add_u64 v[0:1], s[68:69], 0, v[0:1]
	v_lshlrev_b64 v[8:9], 12, v[8:9]
	v_ashrrev_i32_e32 v17, 31, v16
	global_load_dwordx4 v[20:23], v[20:21], off
	v_addc_co_u32_e32 v25, vcc, 0, v79, vcc
	v_lshl_add_u64 v[76:77], v[0:1], 0, v[64:65]
	v_lshl_add_u64 v[8:9], s[68:69], 0, v[8:9]
	v_lshlrev_b64 v[16:17], 12, v[16:17]
	v_ashrrev_i32_e32 v29, 31, v28
	global_load_dwordx4 v[24:27], v[24:25], off
	v_lshl_add_u64 v[74:75], v[8:9], 0, v[64:65]
	global_load_dwordx4 v[0:3], v[76:77], off offset:2048
	global_load_dwordx4 v[8:11], v[74:75], off offset:2048
	v_lshl_add_u64 v[16:17], s[68:69], 0, v[16:17]
	v_lshlrev_b64 v[28:29], 12, v[28:29]
	v_lshl_add_u64 v[70:71], v[16:17], 0, v[64:65]
	v_lshl_add_u64 v[28:29], s[68:69], 0, v[28:29]
	global_load_dwordx4 v[16:19], v[70:71], off offset:2048
	v_lshl_add_u64 v[72:73], v[28:29], 0, v[64:65]
	global_load_dwordx4 v[28:31], v[72:73], off offset:2048
	v_lshrrev_b32_e32 v34, 1, v32
	v_and_b32_e32 v35, 31, v32
	v_mad_u64_u32 v[68:69], s[2:3], v33, s29, v[64:65]
	v_lshl_add_u64 v[84:85], v[78:79], 0, s[12:13]
	v_lshl_add_u64 v[82:83], v[78:79], 0, s[16:17]
	v_lshl_add_u64 v[80:81], v[78:79], 0, s[18:19]
	global_load_dwordx4 v[86:89], v[78:79], off offset:128
	global_load_dwordx4 v[90:93], v[78:79], off offset:256
	global_load_dwordx4 v[94:97], v[84:85], off offset:128
	global_load_dwordx4 v[98:101], v[84:85], off offset:256
	global_load_dwordx4 v[102:105], v[82:83], off offset:128
	global_load_dwordx4 v[106:109], v[82:83], off offset:256
	global_load_dwordx4 v[110:113], v[80:81], off offset:128
	global_load_dwordx4 v[114:117], v[80:81], off offset:256
	global_load_dwordx4 v[118:121], v[76:77], off offset:2176
	global_load_dwordx4 v[122:125], v[74:75], off offset:2176
	global_load_dwordx4 v[126:129], v[70:71], off offset:2176
	global_load_dwordx4 v[130:133], v[72:73], off offset:2176
	global_load_dwordx4 v[134:137], v[76:77], off offset:2304
	global_load_dwordx4 v[138:141], v[74:75], off offset:2304
	global_load_dwordx4 v[142:145], v[70:71], off offset:2304
	global_load_dwordx4 v[146:149], v[72:73], off offset:2304
	s_mulk_i32 s1, 0xb800
	s_add_i32 s1, s24, s1
	s_sub_i32 s20, s1, 48
	s_waitcnt vmcnt(23)
	ds_write_b128 v68, v[4:7] offset:36864
	s_waitcnt vmcnt(22)
	ds_write_b128 v68, v[12:15] offset:41472
	s_waitcnt vmcnt(21)
	ds_write_b128 v68, v[20:23] offset:46080
	s_waitcnt vmcnt(20)
	ds_write_b128 v68, v[24:27] offset:50688
	s_waitcnt vmcnt(19)
	ds_write_b128 v68, v[0:3]
	s_waitcnt vmcnt(18)
	ds_write_b128 v68, v[8:11] offset:4608
	s_waitcnt vmcnt(17)
	ds_write_b128 v68, v[16:19] offset:9216
	s_waitcnt vmcnt(16)
	ds_write_b128 v68, v[28:31] offset:13824
	v_and_or_b32 v0, v34, s30, v35
	v_and_b32_e32 v4, 16, v34
	v_mad_u64_u32 v[66:67], s[2:3], v0, s29, v[4:5]
	s_waitcnt lgkmcnt(0)
	s_barrier
	ds_read_b128 v[0:3], v66
	v_and_b32_e32 v5, 0x5f, v32
	v_mul_u32_u24_e32 v5, 0x48, v5
	v_lshl_add_u32 v64, v5, 1, v4
	ds_read_b128 v[4:7], v64 offset:36864
	ds_read_b128 v[150:153], v66 offset:32
	ds_read_b128 v[154:157], v64 offset:36896
	ds_read_b128 v[8:11], v64 offset:41472
	ds_read_b128 v[158:161], v64 offset:41504
	s_waitcnt lgkmcnt(4)
	v_mfma_f32_32x32x16_bf16 v[48:63], v[0:3], v[4:7], 0
	v_add_u32_e32 v67, 0x9000, v68
	s_waitcnt lgkmcnt(1)
	v_mfma_f32_32x32x16_bf16 v[32:47], v[0:3], v[8:11], 0
	ds_read_b128 v[0:3], v66 offset:4608
	ds_read_b128 v[162:165], v66 offset:4640
	global_load_dwordx4 v[166:169], v[76:77], off offset:2432
	global_load_dwordx4 v[170:173], v[78:79], off offset:384
	s_waitcnt vmcnt(9)
	ds_write_b128 v68, v[118:121] offset:18432
	ds_write_b128 v68, v[86:89] offset:55296
	s_waitcnt lgkmcnt(3)
	v_mfma_f32_32x32x16_bf16 v[16:31], v[0:3], v[4:7], 0
	v_mfma_f32_32x32x16_bf16 v[0:15], v[0:3], v[8:11], 0
	global_load_dwordx4 v[86:89], v[74:75], off offset:2432
	global_load_dwordx4 v[118:121], v[84:85], off offset:384
	v_mfma_f32_32x32x16_bf16 v[48:63], v[150:153], v[154:157], v[48:63]
	v_mfma_f32_32x32x16_bf16 v[32:47], v[150:153], v[158:161], v[32:47]
	s_waitcnt lgkmcnt(2)
	v_mfma_f32_32x32x16_bf16 v[16:31], v[162:165], v[154:157], v[16:31]
	ds_read_b128 v[150:153], v66 offset:64
	ds_read_b128 v[154:157], v66 offset:4672
	ds_read_b128 v[174:177], v64 offset:36928
	ds_read_b128 v[178:181], v64 offset:41536
	s_waitcnt vmcnt(10)
	ds_write_b128 v68, v[122:125] offset:23040
	ds_write_b128 v68, v[94:97] offset:59904
	v_mfma_f32_32x32x16_bf16 v[0:15], v[162:165], v[158:161], v[0:15]
	global_load_dwordx4 v[94:97], v[70:71], off offset:2432
	global_load_dwordx4 v[122:125], v[82:83], off offset:384
	s_waitcnt lgkmcnt(3)
	v_mfma_f32_32x32x16_bf16 v[48:63], v[150:153], v[174:177], v[48:63]
	s_waitcnt lgkmcnt(2)
	v_mfma_f32_32x32x16_bf16 v[32:47], v[150:153], v[178:181], v[32:47]
	v_mfma_f32_32x32x16_bf16 v[16:31], v[154:157], v[174:177], v[16:31]
	ds_read_b128 v[150:153], v66 offset:96
	ds_read_b128 v[158:161], v66 offset:4704
	ds_read_b128 v[162:165], v64 offset:36960
	ds_read_b128 v[174:177], v64 offset:41568
	s_waitcnt vmcnt(11)
	ds_write_b128 v68, v[126:129] offset:27648
	ds_write_b128 v68, v[102:105] offset:64512
	v_mfma_f32_32x32x16_bf16 v[0:15], v[154:157], v[178:181], v[0:15]
	global_load_dwordx4 v[102:105], v[72:73], off offset:2432
	global_load_dwordx4 v[126:129], v[80:81], off offset:384
	s_waitcnt lgkmcnt(3)
	v_mfma_f32_32x32x16_bf16 v[48:63], v[150:153], v[162:165], v[48:63]
	s_waitcnt vmcnt(12)
	ds_write_b128 v68, v[130:133] offset:32256
	ds_write_b128 v67, v[110:113] offset:32256
	s_waitcnt lgkmcnt(4)
	v_mfma_f32_32x32x16_bf16 v[32:47], v[150:153], v[174:177], v[32:47]
	v_mfma_f32_32x32x16_bf16 v[16:31], v[158:161], v[162:165], v[16:31]
	v_mfma_f32_32x32x16_bf16 v[0:15], v[158:161], v[174:177], v[0:15]
	s_waitcnt lgkmcnt(0)
	s_barrier
; #define G_LOAD(S, kt_) do { G_LD1(S##a0, S##b0, 0, kt_); G_LD1(S##a1, S##b1, 1, kt_); G_LD1(S##a2, S##b2, 2, kt_); G_LD1(S##a3, S##b3, 3, kt_); } while (0)
; #define G_STORE(S, buf_) do { G_ST1(S##a0, S##b0, 0, buf_); G_ST1(S##a1, S##b1, 1, buf_); G_ST1(S##a2, S##b2, 2, buf_); G_ST1(S##a3, S##b3, 3, buf_); } while (0)
; template <class AL, class BL>
; DI void gemm_core(AL al, BL bl, int m0, int n0, int K, char* smem, f32x16 (&acc)[2][2]) {
;     ...
;   G_LOAD(x, 0);
;   G_STORE(x, 0);
;   G_LOAD(x, 1);
;   G_LOAD(y, (nk > 2) ? 2 : 1);
;   __syncthreads();
;   for (int kt = 0; kt < nk; kt += 2) {
;     G_TILE(0, x, true, (kt + 3 < nk), kt + 3);
;     __syncthreads();
;     G_TILE(1, y, (kt + 2 < nk), (kt + 4 < nk), kt + 4);
	ds_read_b128 v[110:113], v66 offset:18432
	ds_read_b128 v[130:133], v64 offset:55296
	ds_read_b128 v[150:153], v66 offset:18464
	ds_read_b128 v[154:157], v64 offset:55328
	ds_read_b128 v[158:161], v64 offset:59904
	ds_read_b128 v[162:165], v64 offset:59936
	s_waitcnt lgkmcnt(4)
	v_mfma_f32_32x32x16_bf16 v[48:63], v[110:113], v[130:133], v[48:63]
	s_waitcnt lgkmcnt(1)
	v_mfma_f32_32x32x16_bf16 v[32:47], v[110:113], v[158:161], v[32:47]
	ds_read_b128 v[110:113], v66 offset:23040
	ds_read_b128 v[174:177], v66 offset:23072
	s_waitcnt lgkmcnt(1)
	v_mfma_f32_32x32x16_bf16 v[16:31], v[110:113], v[130:133], v[16:31]
	global_load_dwordx4 v[130:133], v[76:77], off offset:2560
	global_load_dwordx4 v[178:181], v[78:79], off offset:512
	s_waitcnt vmcnt(13)
	ds_write_b128 v68, v[134:137]
	ds_write_b128 v68, v[90:93] offset:36864
	v_mfma_f32_32x32x16_bf16 v[0:15], v[110:113], v[158:161], v[0:15]
	global_load_dwordx4 v[90:93], v[74:75], off offset:2560
	global_load_dwordx4 v[110:113], v[84:85], off offset:512
	v_mfma_f32_32x32x16_bf16 v[48:63], v[150:153], v[154:157], v[48:63]
	v_mfma_f32_32x32x16_bf16 v[32:47], v[150:153], v[162:165], v[32:47]
	s_waitcnt lgkmcnt(2)
	v_mfma_f32_32x32x16_bf16 v[16:31], v[174:177], v[154:157], v[16:31]
	ds_read_b128 v[134:137], v66 offset:18496
	ds_read_b128 v[150:153], v66 offset:23104
	ds_read_b128 v[154:157], v64 offset:55360
	ds_read_b128 v[158:161], v64 offset:59968
	s_waitcnt vmcnt(14)
	ds_write_b128 v68, v[138:141] offset:4608
	ds_write_b128 v68, v[98:101] offset:41472
	v_mfma_f32_32x32x16_bf16 v[0:15], v[174:177], v[162:165], v[0:15]
	s_waitcnt lgkmcnt(3)
	v_mfma_f32_32x32x16_bf16 v[48:63], v[134:137], v[154:157], v[48:63]
	s_waitcnt lgkmcnt(2)
	v_mfma_f32_32x32x16_bf16 v[32:47], v[134:137], v[158:161], v[32:47]
	global_load_dwordx4 v[98:101], v[70:71], off offset:2560
	global_load_dwordx4 v[134:137], v[82:83], off offset:512
	v_mfma_f32_32x32x16_bf16 v[16:31], v[150:153], v[154:157], v[16:31]
	ds_read_b128 v[138:141], v66 offset:18528
	ds_read_b128 v[154:157], v66 offset:23136
	ds_read_b128 v[162:165], v64 offset:55392
	ds_read_b128 v[174:177], v64 offset:60000
	s_waitcnt vmcnt(15)
	ds_write_b128 v68, v[142:145] offset:9216
	ds_write_b128 v68, v[106:109] offset:46080
	v_mfma_f32_32x32x16_bf16 v[0:15], v[150:153], v[158:161], v[0:15]
	s_waitcnt lgkmcnt(3)
	v_mfma_f32_32x32x16_bf16 v[48:63], v[138:141], v[162:165], v[48:63]
	s_waitcnt lgkmcnt(2)
	v_mfma_f32_32x32x16_bf16 v[32:47], v[138:141], v[174:177], v[32:47]
	global_load_dwordx4 v[106:109], v[72:73], off offset:2560
	global_load_dwordx4 v[138:141], v[80:81], off offset:512
	s_waitcnt vmcnt(16)
	ds_write_b128 v68, v[146:149] offset:13824
	ds_write_b128 v68, v[114:117] offset:50688
	v_mfma_f32_32x32x16_bf16 v[16:31], v[154:157], v[162:165], v[16:31]
	v_mfma_f32_32x32x16_bf16 v[0:15], v[154:157], v[174:177], v[0:15]
	s_waitcnt lgkmcnt(0)
	s_barrier
	ds_read_b128 v[114:117], v66
	ds_read_b128 v[142:145], v64 offset:36864
	ds_read_b128 v[146:149], v66 offset:32
	ds_read_b128 v[150:153], v64 offset:36896
	ds_read_b128 v[154:157], v64 offset:41472
	ds_read_b128 v[158:161], v64 offset:41504
	s_waitcnt lgkmcnt(4)
	v_mfma_f32_32x32x16_bf16 v[48:63], v[114:117], v[142:145], v[48:63]
	s_waitcnt lgkmcnt(1)
	v_mfma_f32_32x32x16_bf16 v[32:47], v[114:117], v[154:157], v[32:47]
	ds_read_b128 v[114:117], v66 offset:4608
	ds_read_b128 v[162:165], v66 offset:4640
	s_waitcnt lgkmcnt(1)
	v_mfma_f32_32x32x16_bf16 v[16:31], v[114:117], v[142:145], v[16:31]
	global_load_dwordx4 v[142:145], v[76:77], off offset:2688
	global_load_dwordx4 v[174:177], v[78:79], off offset:640
	s_waitcnt vmcnt(17)
	ds_write_b128 v68, v[166:169] offset:18432
	s_waitcnt vmcnt(16)
	ds_write_b128 v68, v[170:173] offset:55296
	v_mfma_f32_32x32x16_bf16 v[0:15], v[114:117], v[154:157], v[0:15]
	v_mfma_f32_32x32x16_bf16 v[48:63], v[146:149], v[150:153], v[48:63]
	v_mfma_f32_32x32x16_bf16 v[32:47], v[146:149], v[158:161], v[32:47]
	global_load_dwordx4 v[114:117], v[74:75], off offset:2688
	global_load_dwordx4 v[146:149], v[84:85], off offset:640
	s_waitcnt lgkmcnt(2)
	v_mfma_f32_32x32x16_bf16 v[16:31], v[162:165], v[150:153], v[16:31]
	ds_read_b128 v[150:153], v66 offset:64
	ds_read_b128 v[154:157], v66 offset:4672
	ds_read_b128 v[166:169], v64 offset:36928
	ds_read_b128 v[170:173], v64 offset:41536
	s_waitcnt vmcnt(17)
	ds_write_b128 v68, v[86:89] offset:23040
	s_waitcnt vmcnt(16)
	ds_write_b128 v68, v[118:121] offset:59904
	v_mfma_f32_32x32x16_bf16 v[0:15], v[162:165], v[158:161], v[0:15]
	global_load_dwordx4 v[86:89], v[70:71], off offset:2688
	global_load_dwordx4 v[118:121], v[82:83], off offset:640
	s_waitcnt lgkmcnt(3)
	v_mfma_f32_32x32x16_bf16 v[48:63], v[150:153], v[166:169], v[48:63]
	s_waitcnt lgkmcnt(2)
	v_mfma_f32_32x32x16_bf16 v[32:47], v[150:153], v[170:173], v[32:47]
	v_mfma_f32_32x32x16_bf16 v[16:31], v[154:157], v[166:169], v[16:31]
	ds_read_b128 v[150:153], v66 offset:96
	ds_read_b128 v[158:161], v66 offset:4704
	ds_read_b128 v[162:165], v64 offset:36960
	ds_read_b128 v[166:169], v64 offset:41568
	s_waitcnt vmcnt(17)
	ds_write_b128 v68, v[94:97] offset:27648
	s_waitcnt vmcnt(16)
	ds_write_b128 v68, v[122:125] offset:64512
	v_mfma_f32_32x32x16_bf16 v[0:15], v[154:157], v[170:173], v[0:15]
	global_load_dwordx4 v[94:97], v[72:73], off offset:2688
	global_load_dwordx4 v[122:125], v[80:81], off offset:640
	s_waitcnt lgkmcnt(3)
	v_mfma_f32_32x32x16_bf16 v[48:63], v[150:153], v[162:165], v[48:63]
	s_waitcnt vmcnt(17)
	ds_write_b128 v68, v[102:105] offset:32256
	s_waitcnt vmcnt(16)
	ds_write_b128 v67, v[126:129] offset:32256
	s_waitcnt lgkmcnt(4)
	v_mfma_f32_32x32x16_bf16 v[32:47], v[150:153], v[166:169], v[32:47]
	v_mfma_f32_32x32x16_bf16 v[16:31], v[158:161], v[162:165], v[16:31]
	v_mfma_f32_32x32x16_bf16 v[0:15], v[158:161], v[166:169], v[0:15]
	s_waitcnt lgkmcnt(0)
	s_barrier
; #define G_LOAD(S, kt_) do { G_LD1(S##a0, S##b0, 0, kt_); G_LD1(S##a1, S##b1, 1, kt_); G_LD1(S##a2, S##b2, 2, kt_); G_LD1(S##a3, S##b3, 3, kt_); } while (0)
; #define G_STORE(S, buf_) do { G_ST1(S##a0, S##b0, 0, buf_); G_ST1(S##a1, S##b1, 1, buf_); G_ST1(S##a2, S##b2, 2, buf_); G_ST1(S##a3, S##b3, 3, buf_); } while (0)
; template <class AL, class BL>
; DI void gemm_core(AL al, BL bl, int m0, int n0, int K, char* smem, f32x16 (&acc)[2][2]) {
;     ...
;   G_LOAD(x, 0);
;   G_STORE(x, 0);
;   G_LOAD(x, 1);
;   G_LOAD(y, (nk > 2) ? 2 : 1);
;   __syncthreads();
;   for (int kt = 0; kt < nk; kt += 2) {
;     G_TILE(0, x, true, (kt + 3 < nk), kt + 3);
;     __syncthreads();
;     G_TILE(1, y, (kt + 2 < nk), (kt + 4 < nk), kt + 4);
	ds_read_b128 v[102:105], v66 offset:18432
	ds_read_b128 v[126:129], v64 offset:55296
	ds_read_b128 v[150:153], v66 offset:18464
	ds_read_b128 v[154:157], v64 offset:55328
	ds_read_b128 v[158:161], v64 offset:59904
	ds_read_b128 v[162:165], v64 offset:59936
	s_waitcnt lgkmcnt(4)
	v_mfma_f32_32x32x16_bf16 v[48:63], v[102:105], v[126:129], v[48:63]
	s_waitcnt lgkmcnt(1)
	v_mfma_f32_32x32x16_bf16 v[32:47], v[102:105], v[158:161], v[32:47]
	ds_read_b128 v[102:105], v66 offset:23040
	ds_read_b128 v[166:169], v66 offset:23072
	s_waitcnt lgkmcnt(1)
	v_mfma_f32_32x32x16_bf16 v[16:31], v[102:105], v[126:129], v[16:31]
	global_load_dwordx4 v[126:129], v[76:77], off offset:2816
	global_load_dwordx4 v[170:173], v[78:79], off offset:768
	s_waitcnt vmcnt(17)
	ds_write_b128 v68, v[130:133]
	s_waitcnt vmcnt(16)
	ds_write_b128 v68, v[178:181] offset:36864
	v_mfma_f32_32x32x16_bf16 v[0:15], v[102:105], v[158:161], v[0:15]
	global_load_dwordx4 v[102:105], v[74:75], off offset:2816
	global_load_dwordx4 v[130:133], v[84:85], off offset:768
	v_mfma_f32_32x32x16_bf16 v[48:63], v[150:153], v[154:157], v[48:63]
	v_mfma_f32_32x32x16_bf16 v[32:47], v[150:153], v[162:165], v[32:47]
	s_waitcnt lgkmcnt(2)
	v_mfma_f32_32x32x16_bf16 v[16:31], v[166:169], v[154:157], v[16:31]
	ds_read_b128 v[150:153], v66 offset:18496
	ds_read_b128 v[154:157], v66 offset:23104
	ds_read_b128 v[158:161], v64 offset:55360
	ds_read_b128 v[178:181], v64 offset:59968
	s_waitcnt vmcnt(17)
	ds_write_b128 v68, v[90:93] offset:4608
	s_waitcnt vmcnt(16)
	ds_write_b128 v68, v[110:113] offset:41472
	v_mfma_f32_32x32x16_bf16 v[0:15], v[166:169], v[162:165], v[0:15]
	global_load_dwordx4 v[90:93], v[70:71], off offset:2816
	global_load_dwordx4 v[110:113], v[82:83], off offset:768
	s_waitcnt lgkmcnt(3)
	v_mfma_f32_32x32x16_bf16 v[48:63], v[150:153], v[158:161], v[48:63]
	s_waitcnt lgkmcnt(2)
	v_mfma_f32_32x32x16_bf16 v[32:47], v[150:153], v[178:181], v[32:47]
	v_mfma_f32_32x32x16_bf16 v[16:31], v[154:157], v[158:161], v[16:31]
	ds_read_b128 v[150:153], v66 offset:18528
	ds_read_b128 v[158:161], v66 offset:23136
	ds_read_b128 v[162:165], v64 offset:55392
	ds_read_b128 v[166:169], v64 offset:60000
	s_waitcnt vmcnt(17)
	ds_write_b128 v68, v[98:101] offset:9216
	s_waitcnt vmcnt(16)
	ds_write_b128 v68, v[134:137] offset:46080
	v_mfma_f32_32x32x16_bf16 v[0:15], v[154:157], v[178:181], v[0:15]
	global_load_dwordx4 v[98:101], v[72:73], off offset:2816
	global_load_dwordx4 v[134:137], v[80:81], off offset:768
	s_waitcnt lgkmcnt(3)
	v_mfma_f32_32x32x16_bf16 v[48:63], v[150:153], v[162:165], v[48:63]
	s_waitcnt vmcnt(17)
	ds_write_b128 v68, v[106:109] offset:13824
	s_waitcnt vmcnt(16)
	ds_write_b128 v68, v[138:141] offset:50688
	s_waitcnt lgkmcnt(4)
	v_mfma_f32_32x32x16_bf16 v[32:47], v[150:153], v[166:169], v[32:47]
	v_mfma_f32_32x32x16_bf16 v[16:31], v[158:161], v[162:165], v[16:31]
	v_mfma_f32_32x32x16_bf16 v[0:15], v[158:161], v[166:169], v[0:15]
	s_waitcnt lgkmcnt(0)
	s_barrier
	ds_read_b128 v[106:109], v66
	ds_read_b128 v[138:141], v64 offset:36864
	ds_read_b128 v[150:153], v66 offset:32
	ds_read_b128 v[154:157], v64 offset:36896
	ds_read_b128 v[158:161], v64 offset:41472
	ds_read_b128 v[162:165], v64 offset:41504
	s_waitcnt lgkmcnt(4)
	v_mfma_f32_32x32x16_bf16 v[48:63], v[106:109], v[138:141], v[48:63]
	s_waitcnt lgkmcnt(1)
	v_mfma_f32_32x32x16_bf16 v[32:47], v[106:109], v[158:161], v[32:47]
	ds_read_b128 v[106:109], v66 offset:4608
	ds_read_b128 v[166:169], v66 offset:4640
	s_waitcnt lgkmcnt(1)
	v_mfma_f32_32x32x16_bf16 v[16:31], v[106:109], v[138:141], v[16:31]
	global_load_dwordx4 v[138:141], v[76:77], off offset:2944
	global_load_dwordx4 v[178:181], v[78:79], off offset:896
	s_waitcnt vmcnt(17)
	ds_write_b128 v68, v[142:145] offset:18432
	s_waitcnt vmcnt(16)
	ds_write_b128 v68, v[174:177] offset:55296
	v_mfma_f32_32x32x16_bf16 v[0:15], v[106:109], v[158:161], v[0:15]
	global_load_dwordx4 v[106:109], v[74:75], off offset:2944
	global_load_dwordx4 v[142:145], v[84:85], off offset:896
	v_mfma_f32_32x32x16_bf16 v[48:63], v[150:153], v[154:157], v[48:63]
	v_mfma_f32_32x32x16_bf16 v[32:47], v[150:153], v[162:165], v[32:47]
	s_waitcnt lgkmcnt(2)
	v_mfma_f32_32x32x16_bf16 v[16:31], v[166:169], v[154:157], v[16:31]
	ds_read_b128 v[150:153], v66 offset:64
	ds_read_b128 v[154:157], v66 offset:4672
	ds_read_b128 v[158:161], v64 offset:36928
	ds_read_b128 v[174:177], v64 offset:41536
	s_waitcnt vmcnt(17)
	ds_write_b128 v68, v[114:117] offset:23040
	s_waitcnt vmcnt(16)
	ds_write_b128 v68, v[146:149] offset:59904
	v_mfma_f32_32x32x16_bf16 v[0:15], v[166:169], v[162:165], v[0:15]
	global_load_dwordx4 v[114:117], v[70:71], off offset:2944
	global_load_dwordx4 v[146:149], v[82:83], off offset:896
	s_waitcnt lgkmcnt(3)
	v_mfma_f32_32x32x16_bf16 v[48:63], v[150:153], v[158:161], v[48:63]
	s_waitcnt lgkmcnt(2)
	v_mfma_f32_32x32x16_bf16 v[32:47], v[150:153], v[174:177], v[32:47]
	v_mfma_f32_32x32x16_bf16 v[16:31], v[154:157], v[158:161], v[16:31]
	ds_read_b128 v[150:153], v66 offset:96
	ds_read_b128 v[158:161], v66 offset:4704
	ds_read_b128 v[162:165], v64 offset:36960
	ds_read_b128 v[166:169], v64 offset:41568
	s_waitcnt vmcnt(17)
	ds_write_b128 v68, v[86:89] offset:27648
	s_waitcnt vmcnt(16)
	ds_write_b128 v68, v[118:121] offset:64512
	v_mfma_f32_32x32x16_bf16 v[0:15], v[154:157], v[174:177], v[0:15]
	global_load_dwordx4 v[86:89], v[72:73], off offset:2944
	global_load_dwordx4 v[118:121], v[80:81], off offset:896
	s_waitcnt lgkmcnt(3)
	v_mfma_f32_32x32x16_bf16 v[48:63], v[150:153], v[162:165], v[48:63]
	s_waitcnt vmcnt(17)
	ds_write_b128 v68, v[94:97] offset:32256
	s_waitcnt vmcnt(16)
	ds_write_b128 v67, v[122:125] offset:32256
	s_waitcnt lgkmcnt(4)
	v_mfma_f32_32x32x16_bf16 v[32:47], v[150:153], v[166:169], v[32:47]
	v_mfma_f32_32x32x16_bf16 v[16:31], v[158:161], v[162:165], v[16:31]
	v_mfma_f32_32x32x16_bf16 v[0:15], v[158:161], v[166:169], v[0:15]
	s_waitcnt lgkmcnt(0)
	s_barrier
; #define G_LOAD(S, kt_) do { G_LD1(S##a0, S##b0, 0, kt_); G_LD1(S##a1, S##b1, 1, kt_); G_LD1(S##a2, S##b2, 2, kt_); G_LD1(S##a3, S##b3, 3, kt_); } while (0)
; #define G_STORE(S, buf_) do { G_ST1(S##a0, S##b0, 0, buf_); G_ST1(S##a1, S##b1, 1, buf_); G_ST1(S##a2, S##b2, 2, buf_); G_ST1(S##a3, S##b3, 3, buf_); } while (0)
; template <class AL, class BL>
; DI void gemm_core(AL al, BL bl, int m0, int n0, int K, char* smem, f32x16 (&acc)[2][2]) {
;     ...
;   G_LOAD(x, 0);
;   G_STORE(x, 0);
;   G_LOAD(x, 1);
;   G_LOAD(y, (nk > 2) ? 2 : 1);
;   __syncthreads();
;   for (int kt = 0; kt < nk; kt += 2) {
;     G_TILE(0, x, true, (kt + 3 < nk), kt + 3);
;     __syncthreads();
;     G_TILE(1, y, (kt + 2 < nk), (kt + 4 < nk), kt + 4);
	ds_read_b128 v[94:97], v66 offset:18432
	ds_read_b128 v[122:125], v64 offset:55296
	ds_read_b128 v[150:153], v66 offset:18464
	ds_read_b128 v[154:157], v64 offset:55328
	ds_read_b128 v[158:161], v64 offset:59904
	ds_read_b128 v[162:165], v64 offset:59936
	s_waitcnt lgkmcnt(4)
	v_mfma_f32_32x32x16_bf16 v[48:63], v[94:97], v[122:125], v[48:63]
	s_waitcnt lgkmcnt(1)
	v_mfma_f32_32x32x16_bf16 v[32:47], v[94:97], v[158:161], v[32:47]
	ds_read_b128 v[94:97], v66 offset:23040
	ds_read_b128 v[166:169], v66 offset:23072
	s_waitcnt lgkmcnt(1)
	v_mfma_f32_32x32x16_bf16 v[16:31], v[94:97], v[122:125], v[16:31]
	global_load_dwordx4 v[122:125], v[76:77], off offset:3072
	global_load_dwordx4 v[174:177], v[78:79], off offset:1024
	s_waitcnt vmcnt(17)
	ds_write_b128 v68, v[126:129]
	s_waitcnt vmcnt(16)
	ds_write_b128 v68, v[170:173] offset:36864
	v_mfma_f32_32x32x16_bf16 v[0:15], v[94:97], v[158:161], v[0:15]
	global_load_dwordx4 v[94:97], v[74:75], off offset:3072
	global_load_dwordx4 v[126:129], v[84:85], off offset:1024
	v_mfma_f32_32x32x16_bf16 v[48:63], v[150:153], v[154:157], v[48:63]
	v_mfma_f32_32x32x16_bf16 v[32:47], v[150:153], v[162:165], v[32:47]
	s_waitcnt lgkmcnt(2)
	v_mfma_f32_32x32x16_bf16 v[16:31], v[166:169], v[154:157], v[16:31]
	ds_read_b128 v[150:153], v66 offset:18496
	ds_read_b128 v[154:157], v66 offset:23104
	ds_read_b128 v[158:161], v64 offset:55360
	ds_read_b128 v[170:173], v64 offset:59968
	s_waitcnt vmcnt(17)
	ds_write_b128 v68, v[102:105] offset:4608
	s_waitcnt vmcnt(16)
	ds_write_b128 v68, v[130:133] offset:41472
	v_mfma_f32_32x32x16_bf16 v[0:15], v[166:169], v[162:165], v[0:15]
	global_load_dwordx4 v[102:105], v[70:71], off offset:3072
	global_load_dwordx4 v[130:133], v[82:83], off offset:1024
	s_waitcnt lgkmcnt(3)
	v_mfma_f32_32x32x16_bf16 v[48:63], v[150:153], v[158:161], v[48:63]
	s_waitcnt lgkmcnt(2)
	v_mfma_f32_32x32x16_bf16 v[32:47], v[150:153], v[170:173], v[32:47]
	v_mfma_f32_32x32x16_bf16 v[16:31], v[154:157], v[158:161], v[16:31]
	ds_read_b128 v[150:153], v66 offset:18528
	ds_read_b128 v[158:161], v66 offset:23136
	ds_read_b128 v[162:165], v64 offset:55392
	ds_read_b128 v[166:169], v64 offset:60000
	s_waitcnt vmcnt(17)
	ds_write_b128 v68, v[90:93] offset:9216
	s_waitcnt vmcnt(16)
	ds_write_b128 v68, v[110:113] offset:46080
	v_mfma_f32_32x32x16_bf16 v[0:15], v[154:157], v[170:173], v[0:15]
	global_load_dwordx4 v[90:93], v[72:73], off offset:3072
	global_load_dwordx4 v[110:113], v[80:81], off offset:1024
	s_waitcnt lgkmcnt(3)
	v_mfma_f32_32x32x16_bf16 v[48:63], v[150:153], v[162:165], v[48:63]
	s_waitcnt vmcnt(17)
	ds_write_b128 v68, v[98:101] offset:13824
	s_waitcnt vmcnt(16)
	ds_write_b128 v68, v[134:137] offset:50688
	s_waitcnt lgkmcnt(4)
	v_mfma_f32_32x32x16_bf16 v[32:47], v[150:153], v[166:169], v[32:47]
	v_mfma_f32_32x32x16_bf16 v[16:31], v[158:161], v[162:165], v[16:31]
	v_mfma_f32_32x32x16_bf16 v[0:15], v[158:161], v[166:169], v[0:15]
	s_waitcnt lgkmcnt(0)
	s_barrier
	ds_read_b128 v[98:101], v66
	ds_read_b128 v[134:137], v64 offset:36864
	ds_read_b128 v[150:153], v66 offset:32
	ds_read_b128 v[154:157], v64 offset:36896
	ds_read_b128 v[158:161], v64 offset:41472
	ds_read_b128 v[162:165], v64 offset:41504
	s_waitcnt lgkmcnt(4)
	v_mfma_f32_32x32x16_bf16 v[48:63], v[98:101], v[134:137], v[48:63]
	s_waitcnt lgkmcnt(1)
	v_mfma_f32_32x32x16_bf16 v[32:47], v[98:101], v[158:161], v[32:47]
	ds_read_b128 v[98:101], v66 offset:4608
	ds_read_b128 v[166:169], v66 offset:4640
	s_waitcnt lgkmcnt(1)
	v_mfma_f32_32x32x16_bf16 v[16:31], v[98:101], v[134:137], v[16:31]
	global_load_dwordx4 v[134:137], v[76:77], off offset:3200
	global_load_dwordx4 v[170:173], v[78:79], off offset:1152
	s_waitcnt vmcnt(17)
	ds_write_b128 v68, v[138:141] offset:18432
	s_waitcnt vmcnt(16)
	ds_write_b128 v68, v[178:181] offset:55296
	v_mfma_f32_32x32x16_bf16 v[0:15], v[98:101], v[158:161], v[0:15]
	global_load_dwordx4 v[98:101], v[74:75], off offset:3200
	global_load_dwordx4 v[138:141], v[84:85], off offset:1152
	v_mfma_f32_32x32x16_bf16 v[48:63], v[150:153], v[154:157], v[48:63]
	v_mfma_f32_32x32x16_bf16 v[32:47], v[150:153], v[162:165], v[32:47]
	s_waitcnt lgkmcnt(2)
	v_mfma_f32_32x32x16_bf16 v[16:31], v[166:169], v[154:157], v[16:31]
	ds_read_b128 v[150:153], v66 offset:64
	ds_read_b128 v[154:157], v66 offset:4672
	ds_read_b128 v[158:161], v64 offset:36928
	ds_read_b128 v[178:181], v64 offset:41536
	s_waitcnt vmcnt(17)
	ds_write_b128 v68, v[106:109] offset:23040
	s_waitcnt vmcnt(16)
	ds_write_b128 v68, v[142:145] offset:59904
	v_mfma_f32_32x32x16_bf16 v[0:15], v[166:169], v[162:165], v[0:15]
	global_load_dwordx4 v[106:109], v[70:71], off offset:3200
	global_load_dwordx4 v[142:145], v[82:83], off offset:1152
	s_waitcnt lgkmcnt(3)
	v_mfma_f32_32x32x16_bf16 v[48:63], v[150:153], v[158:161], v[48:63]
	s_waitcnt lgkmcnt(2)
	v_mfma_f32_32x32x16_bf16 v[32:47], v[150:153], v[178:181], v[32:47]
	v_mfma_f32_32x32x16_bf16 v[16:31], v[154:157], v[158:161], v[16:31]
	ds_read_b128 v[150:153], v66 offset:96
	ds_read_b128 v[158:161], v66 offset:4704
	ds_read_b128 v[162:165], v64 offset:36960
	ds_read_b128 v[166:169], v64 offset:41568
	s_waitcnt vmcnt(17)
	ds_write_b128 v68, v[114:117] offset:27648
	s_waitcnt vmcnt(16)
	ds_write_b128 v68, v[146:149] offset:64512
	v_mfma_f32_32x32x16_bf16 v[0:15], v[154:157], v[178:181], v[0:15]
	global_load_dwordx4 v[114:117], v[72:73], off offset:3200
	global_load_dwordx4 v[146:149], v[80:81], off offset:1152
	s_waitcnt lgkmcnt(3)
	v_mfma_f32_32x32x16_bf16 v[48:63], v[150:153], v[162:165], v[48:63]
	s_waitcnt vmcnt(17)
	ds_write_b128 v68, v[86:89] offset:32256
	s_waitcnt vmcnt(16)
	ds_write_b128 v67, v[118:121] offset:32256
	s_waitcnt lgkmcnt(4)
	v_mfma_f32_32x32x16_bf16 v[32:47], v[150:153], v[166:169], v[32:47]
	v_mfma_f32_32x32x16_bf16 v[16:31], v[158:161], v[162:165], v[16:31]
	v_mfma_f32_32x32x16_bf16 v[0:15], v[158:161], v[166:169], v[0:15]
	s_waitcnt lgkmcnt(0)
	s_barrier
; #define G_LOAD(S, kt_) do { G_LD1(S##a0, S##b0, 0, kt_); G_LD1(S##a1, S##b1, 1, kt_); G_LD1(S##a2, S##b2, 2, kt_); G_LD1(S##a3, S##b3, 3, kt_); } while (0)
; #define G_STORE(S, buf_) do { G_ST1(S##a0, S##b0, 0, buf_); G_ST1(S##a1, S##b1, 1, buf_); G_ST1(S##a2, S##b2, 2, buf_); G_ST1(S##a3, S##b3, 3, buf_); } while (0)
; template <class AL, class BL>
; DI void gemm_core(AL al, BL bl, int m0, int n0, int K, char* smem, f32x16 (&acc)[2][2]) {
;     ...
;   G_LOAD(x, 0);
;   G_STORE(x, 0);
;   G_LOAD(x, 1);
;   G_LOAD(y, (nk > 2) ? 2 : 1);
;   __syncthreads();
;   for (int kt = 0; kt < nk; kt += 2) {
;     G_TILE(0, x, true, (kt + 3 < nk), kt + 3);
;     __syncthreads();
;     G_TILE(1, y, (kt + 2 < nk), (kt + 4 < nk), kt + 4);
	ds_read_b128 v[86:89], v66 offset:18432
	ds_read_b128 v[118:121], v64 offset:55296
	ds_read_b128 v[150:153], v66 offset:18464
	ds_read_b128 v[154:157], v64 offset:55328
	ds_read_b128 v[158:161], v64 offset:59904
	ds_read_b128 v[162:165], v64 offset:59936
	s_waitcnt lgkmcnt(4)
	v_mfma_f32_32x32x16_bf16 v[48:63], v[86:89], v[118:121], v[48:63]
	s_waitcnt lgkmcnt(1)
	v_mfma_f32_32x32x16_bf16 v[32:47], v[86:89], v[158:161], v[32:47]
	ds_read_b128 v[86:89], v66 offset:23040
	ds_read_b128 v[166:169], v66 offset:23072
	s_waitcnt lgkmcnt(1)
	v_mfma_f32_32x32x16_bf16 v[16:31], v[86:89], v[118:121], v[16:31]
	global_load_dwordx4 v[118:121], v[76:77], off offset:3328
	global_load_dwordx4 v[178:181], v[78:79], off offset:1280
	s_waitcnt vmcnt(17)
	ds_write_b128 v68, v[122:125]
	s_waitcnt vmcnt(16)
	ds_write_b128 v68, v[174:177] offset:36864
	v_mfma_f32_32x32x16_bf16 v[0:15], v[86:89], v[158:161], v[0:15]
	global_load_dwordx4 v[86:89], v[74:75], off offset:3328
	global_load_dwordx4 v[122:125], v[84:85], off offset:1280
	v_mfma_f32_32x32x16_bf16 v[48:63], v[150:153], v[154:157], v[48:63]
	v_mfma_f32_32x32x16_bf16 v[32:47], v[150:153], v[162:165], v[32:47]
	s_waitcnt lgkmcnt(2)
	v_mfma_f32_32x32x16_bf16 v[16:31], v[166:169], v[154:157], v[16:31]
	ds_read_b128 v[150:153], v66 offset:18496
	ds_read_b128 v[154:157], v66 offset:23104
	ds_read_b128 v[158:161], v64 offset:55360
	ds_read_b128 v[174:177], v64 offset:59968
	s_waitcnt vmcnt(17)
	ds_write_b128 v68, v[94:97] offset:4608
	s_waitcnt vmcnt(16)
	ds_write_b128 v68, v[126:129] offset:41472
	v_mfma_f32_32x32x16_bf16 v[0:15], v[166:169], v[162:165], v[0:15]
	global_load_dwordx4 v[94:97], v[70:71], off offset:3328
	global_load_dwordx4 v[126:129], v[82:83], off offset:1280
	s_waitcnt lgkmcnt(3)
	v_mfma_f32_32x32x16_bf16 v[48:63], v[150:153], v[158:161], v[48:63]
	s_waitcnt lgkmcnt(2)
	v_mfma_f32_32x32x16_bf16 v[32:47], v[150:153], v[174:177], v[32:47]
	v_mfma_f32_32x32x16_bf16 v[16:31], v[154:157], v[158:161], v[16:31]
	ds_read_b128 v[150:153], v66 offset:18528
	ds_read_b128 v[158:161], v66 offset:23136
	ds_read_b128 v[162:165], v64 offset:55392
	ds_read_b128 v[166:169], v64 offset:60000
	s_waitcnt vmcnt(17)
	ds_write_b128 v68, v[102:105] offset:9216
	s_waitcnt vmcnt(16)
	ds_write_b128 v68, v[130:133] offset:46080
	v_mfma_f32_32x32x16_bf16 v[0:15], v[154:157], v[174:177], v[0:15]
	global_load_dwordx4 v[102:105], v[72:73], off offset:3328
	global_load_dwordx4 v[130:133], v[80:81], off offset:1280
	s_waitcnt lgkmcnt(3)
	v_mfma_f32_32x32x16_bf16 v[48:63], v[150:153], v[162:165], v[48:63]
	s_waitcnt vmcnt(17)
	ds_write_b128 v68, v[90:93] offset:13824
	s_waitcnt vmcnt(16)
	ds_write_b128 v68, v[110:113] offset:50688
	s_waitcnt lgkmcnt(4)
	v_mfma_f32_32x32x16_bf16 v[32:47], v[150:153], v[166:169], v[32:47]
	v_mfma_f32_32x32x16_bf16 v[16:31], v[158:161], v[162:165], v[16:31]
	v_mfma_f32_32x32x16_bf16 v[0:15], v[158:161], v[166:169], v[0:15]
	s_waitcnt lgkmcnt(0)
	s_barrier
	ds_read_b128 v[90:93], v66
	ds_read_b128 v[110:113], v64 offset:36864
	ds_read_b128 v[150:153], v66 offset:32
	ds_read_b128 v[154:157], v64 offset:36896
	ds_read_b128 v[158:161], v64 offset:41472
	ds_read_b128 v[162:165], v64 offset:41504
	s_waitcnt lgkmcnt(4)
	v_mfma_f32_32x32x16_bf16 v[48:63], v[90:93], v[110:113], v[48:63]
	s_waitcnt lgkmcnt(1)
	v_mfma_f32_32x32x16_bf16 v[32:47], v[90:93], v[158:161], v[32:47]
	ds_read_b128 v[90:93], v66 offset:4608
	ds_read_b128 v[166:169], v66 offset:4640
	s_waitcnt lgkmcnt(1)
	v_mfma_f32_32x32x16_bf16 v[16:31], v[90:93], v[110:113], v[16:31]
	global_load_dwordx4 v[110:113], v[76:77], off offset:3456
	global_load_dwordx4 v[174:177], v[78:79], off offset:1408
	s_waitcnt vmcnt(17)
	ds_write_b128 v68, v[134:137] offset:18432
	s_waitcnt vmcnt(16)
	ds_write_b128 v68, v[170:173] offset:55296
	v_mfma_f32_32x32x16_bf16 v[0:15], v[90:93], v[158:161], v[0:15]
	global_load_dwordx4 v[90:93], v[74:75], off offset:3456
	global_load_dwordx4 v[134:137], v[84:85], off offset:1408
	v_mfma_f32_32x32x16_bf16 v[48:63], v[150:153], v[154:157], v[48:63]
	v_mfma_f32_32x32x16_bf16 v[32:47], v[150:153], v[162:165], v[32:47]
	s_waitcnt lgkmcnt(2)
	v_mfma_f32_32x32x16_bf16 v[16:31], v[166:169], v[154:157], v[16:31]
	ds_read_b128 v[150:153], v66 offset:64
	ds_read_b128 v[154:157], v66 offset:4672
	ds_read_b128 v[158:161], v64 offset:36928
	ds_read_b128 v[170:173], v64 offset:41536
	s_waitcnt vmcnt(17)
	ds_write_b128 v68, v[98:101] offset:23040
	s_waitcnt vmcnt(16)
	ds_write_b128 v68, v[138:141] offset:59904
	v_mfma_f32_32x32x16_bf16 v[0:15], v[166:169], v[162:165], v[0:15]
	global_load_dwordx4 v[98:101], v[70:71], off offset:3456
	global_load_dwordx4 v[138:141], v[82:83], off offset:1408
	s_waitcnt lgkmcnt(3)
	v_mfma_f32_32x32x16_bf16 v[48:63], v[150:153], v[158:161], v[48:63]
	s_waitcnt lgkmcnt(2)
	v_mfma_f32_32x32x16_bf16 v[32:47], v[150:153], v[170:173], v[32:47]
	v_mfma_f32_32x32x16_bf16 v[16:31], v[154:157], v[158:161], v[16:31]
	ds_read_b128 v[150:153], v66 offset:96
	ds_read_b128 v[158:161], v66 offset:4704
	ds_read_b128 v[162:165], v64 offset:36960
	ds_read_b128 v[166:169], v64 offset:41568
	s_waitcnt vmcnt(17)
	ds_write_b128 v68, v[106:109] offset:27648
	s_waitcnt vmcnt(16)
	ds_write_b128 v68, v[142:145] offset:64512
	v_mfma_f32_32x32x16_bf16 v[0:15], v[154:157], v[170:173], v[0:15]
	global_load_dwordx4 v[106:109], v[72:73], off offset:3456
	global_load_dwordx4 v[142:145], v[80:81], off offset:1408
	s_waitcnt lgkmcnt(3)
	v_mfma_f32_32x32x16_bf16 v[48:63], v[150:153], v[162:165], v[48:63]
	s_waitcnt vmcnt(17)
	ds_write_b128 v68, v[114:117] offset:32256
	s_waitcnt vmcnt(16)
	ds_write_b128 v67, v[146:149] offset:32256
	s_waitcnt lgkmcnt(4)
	v_mfma_f32_32x32x16_bf16 v[32:47], v[150:153], v[166:169], v[32:47]
	v_mfma_f32_32x32x16_bf16 v[16:31], v[158:161], v[162:165], v[16:31]
	v_mfma_f32_32x32x16_bf16 v[0:15], v[158:161], v[166:169], v[0:15]
	s_waitcnt lgkmcnt(0)
	s_barrier
; #define G_LOAD(S, kt_) do { G_LD1(S##a0, S##b0, 0, kt_); G_LD1(S##a1, S##b1, 1, kt_); G_LD1(S##a2, S##b2, 2, kt_); G_LD1(S##a3, S##b3, 3, kt_); } while (0)
; #define G_STORE(S, buf_) do { G_ST1(S##a0, S##b0, 0, buf_); G_ST1(S##a1, S##b1, 1, buf_); G_ST1(S##a2, S##b2, 2, buf_); G_ST1(S##a3, S##b3, 3, buf_); } while (0)
; template <class AL, class BL>
; DI void gemm_core(AL al, BL bl, int m0, int n0, int K, char* smem, f32x16 (&acc)[2][2]) {
;     ...
;   G_LOAD(x, 0);
;   G_STORE(x, 0);
;   G_LOAD(x, 1);
;   G_LOAD(y, (nk > 2) ? 2 : 1);
;   __syncthreads();
;   for (int kt = 0; kt < nk; kt += 2) {
;     G_TILE(0, x, true, (kt + 3 < nk), kt + 3);
;     __syncthreads();
;     G_TILE(1, y, (kt + 2 < nk), (kt + 4 < nk), kt + 4);
	ds_read_b128 v[114:117], v66 offset:18432
	ds_read_b128 v[146:149], v64 offset:55296
	ds_read_b128 v[150:153], v66 offset:18464
	ds_read_b128 v[154:157], v64 offset:55328
	ds_read_b128 v[158:161], v64 offset:59904
	ds_read_b128 v[162:165], v64 offset:59936
	s_waitcnt lgkmcnt(4)
	v_mfma_f32_32x32x16_bf16 v[48:63], v[114:117], v[146:149], v[48:63]
	s_waitcnt lgkmcnt(1)
	v_mfma_f32_32x32x16_bf16 v[32:47], v[114:117], v[158:161], v[32:47]
	ds_read_b128 v[114:117], v66 offset:23040
	ds_read_b128 v[166:169], v66 offset:23072
	s_waitcnt lgkmcnt(1)
	v_mfma_f32_32x32x16_bf16 v[16:31], v[114:117], v[146:149], v[16:31]
	global_load_dwordx4 v[146:149], v[76:77], off offset:3584
	global_load_dwordx4 v[170:173], v[78:79], off offset:1536
	s_waitcnt vmcnt(17)
	ds_write_b128 v68, v[118:121]
	s_waitcnt vmcnt(16)
	ds_write_b128 v68, v[178:181] offset:36864
	v_mfma_f32_32x32x16_bf16 v[0:15], v[114:117], v[158:161], v[0:15]
	global_load_dwordx4 v[114:117], v[74:75], off offset:3584
	global_load_dwordx4 v[118:121], v[84:85], off offset:1536
	v_mfma_f32_32x32x16_bf16 v[48:63], v[150:153], v[154:157], v[48:63]
	v_mfma_f32_32x32x16_bf16 v[32:47], v[150:153], v[162:165], v[32:47]
	s_waitcnt lgkmcnt(2)
	v_mfma_f32_32x32x16_bf16 v[16:31], v[166:169], v[154:157], v[16:31]
	ds_read_b128 v[150:153], v66 offset:18496
	ds_read_b128 v[154:157], v66 offset:23104
	ds_read_b128 v[158:161], v64 offset:55360
	ds_read_b128 v[178:181], v64 offset:59968
	s_waitcnt vmcnt(17)
	ds_write_b128 v68, v[86:89] offset:4608
	s_waitcnt vmcnt(16)
	ds_write_b128 v68, v[122:125] offset:41472
	v_mfma_f32_32x32x16_bf16 v[0:15], v[166:169], v[162:165], v[0:15]
	global_load_dwordx4 v[86:89], v[70:71], off offset:3584
	global_load_dwordx4 v[122:125], v[82:83], off offset:1536
	s_waitcnt lgkmcnt(3)
	v_mfma_f32_32x32x16_bf16 v[48:63], v[150:153], v[158:161], v[48:63]
	s_waitcnt lgkmcnt(2)
	v_mfma_f32_32x32x16_bf16 v[32:47], v[150:153], v[178:181], v[32:47]
	v_mfma_f32_32x32x16_bf16 v[16:31], v[154:157], v[158:161], v[16:31]
	ds_read_b128 v[150:153], v66 offset:18528
	ds_read_b128 v[158:161], v66 offset:23136
	ds_read_b128 v[162:165], v64 offset:55392
	ds_read_b128 v[166:169], v64 offset:60000
	s_waitcnt vmcnt(17)
	ds_write_b128 v68, v[94:97] offset:9216
	s_waitcnt vmcnt(16)
	ds_write_b128 v68, v[126:129] offset:46080
	v_mfma_f32_32x32x16_bf16 v[0:15], v[154:157], v[178:181], v[0:15]
	global_load_dwordx4 v[94:97], v[72:73], off offset:3584
	global_load_dwordx4 v[126:129], v[80:81], off offset:1536
	s_waitcnt lgkmcnt(3)
	v_mfma_f32_32x32x16_bf16 v[48:63], v[150:153], v[162:165], v[48:63]
	s_waitcnt vmcnt(17)
	ds_write_b128 v68, v[102:105] offset:13824
	s_waitcnt vmcnt(16)
	ds_write_b128 v68, v[130:133] offset:50688
	s_waitcnt lgkmcnt(4)
	v_mfma_f32_32x32x16_bf16 v[32:47], v[150:153], v[166:169], v[32:47]
	v_mfma_f32_32x32x16_bf16 v[16:31], v[158:161], v[162:165], v[16:31]
	v_mfma_f32_32x32x16_bf16 v[0:15], v[158:161], v[166:169], v[0:15]
	s_waitcnt lgkmcnt(0)
	s_barrier
	ds_read_b128 v[102:105], v66
	ds_read_b128 v[130:133], v64 offset:36864
	ds_read_b128 v[150:153], v66 offset:32
	ds_read_b128 v[154:157], v64 offset:36896
	ds_read_b128 v[158:161], v64 offset:41472
	ds_read_b128 v[162:165], v64 offset:41504
	s_waitcnt lgkmcnt(4)
	v_mfma_f32_32x32x16_bf16 v[48:63], v[102:105], v[130:133], v[48:63]
	s_waitcnt lgkmcnt(1)
	v_mfma_f32_32x32x16_bf16 v[32:47], v[102:105], v[158:161], v[32:47]
	ds_read_b128 v[102:105], v66 offset:4608
	ds_read_b128 v[166:169], v66 offset:4640
	s_waitcnt lgkmcnt(1)
	v_mfma_f32_32x32x16_bf16 v[16:31], v[102:105], v[130:133], v[16:31]
	global_load_dwordx4 v[130:133], v[76:77], off offset:3712
	global_load_dwordx4 v[178:181], v[78:79], off offset:1664
	s_waitcnt vmcnt(17)
	ds_write_b128 v68, v[110:113] offset:18432
	s_waitcnt vmcnt(16)
	ds_write_b128 v68, v[174:177] offset:55296
	v_mfma_f32_32x32x16_bf16 v[0:15], v[102:105], v[158:161], v[0:15]
	global_load_dwordx4 v[102:105], v[74:75], off offset:3712
	global_load_dwordx4 v[110:113], v[84:85], off offset:1664
	v_mfma_f32_32x32x16_bf16 v[48:63], v[150:153], v[154:157], v[48:63]
	v_mfma_f32_32x32x16_bf16 v[32:47], v[150:153], v[162:165], v[32:47]
	s_waitcnt lgkmcnt(2)
	v_mfma_f32_32x32x16_bf16 v[16:31], v[166:169], v[154:157], v[16:31]
	ds_read_b128 v[150:153], v66 offset:64
	ds_read_b128 v[154:157], v66 offset:4672
	ds_read_b128 v[158:161], v64 offset:36928
	ds_read_b128 v[174:177], v64 offset:41536
	s_waitcnt vmcnt(17)
	ds_write_b128 v68, v[90:93] offset:23040
	s_waitcnt vmcnt(16)
	ds_write_b128 v68, v[134:137] offset:59904
	v_mfma_f32_32x32x16_bf16 v[0:15], v[166:169], v[162:165], v[0:15]
	global_load_dwordx4 v[90:93], v[70:71], off offset:3712
	global_load_dwordx4 v[134:137], v[82:83], off offset:1664
	s_waitcnt lgkmcnt(3)
	v_mfma_f32_32x32x16_bf16 v[48:63], v[150:153], v[158:161], v[48:63]
	s_waitcnt lgkmcnt(2)
	v_mfma_f32_32x32x16_bf16 v[32:47], v[150:153], v[174:177], v[32:47]
	v_mfma_f32_32x32x16_bf16 v[16:31], v[154:157], v[158:161], v[16:31]
	ds_read_b128 v[150:153], v66 offset:96
	ds_read_b128 v[158:161], v66 offset:4704
	ds_read_b128 v[162:165], v64 offset:36960
	ds_read_b128 v[166:169], v64 offset:41568
	s_waitcnt vmcnt(17)
	ds_write_b128 v68, v[98:101] offset:27648
	s_waitcnt vmcnt(16)
	ds_write_b128 v68, v[138:141] offset:64512
	v_mfma_f32_32x32x16_bf16 v[0:15], v[154:157], v[174:177], v[0:15]
	global_load_dwordx4 v[98:101], v[72:73], off offset:3712
	global_load_dwordx4 v[138:141], v[80:81], off offset:1664
	s_waitcnt lgkmcnt(3)
	v_mfma_f32_32x32x16_bf16 v[48:63], v[150:153], v[162:165], v[48:63]
	s_waitcnt vmcnt(17)
	ds_write_b128 v68, v[106:109] offset:32256
	s_waitcnt vmcnt(16)
	ds_write_b128 v67, v[142:145] offset:32256
	s_waitcnt lgkmcnt(4)
	v_mfma_f32_32x32x16_bf16 v[32:47], v[150:153], v[166:169], v[32:47]
	v_mfma_f32_32x32x16_bf16 v[16:31], v[158:161], v[162:165], v[16:31]
	v_mfma_f32_32x32x16_bf16 v[0:15], v[158:161], v[166:169], v[0:15]
	s_waitcnt lgkmcnt(0)
	s_barrier
; #define G_LOAD(S, kt_) do { G_LD1(S##a0, S##b0, 0, kt_); G_LD1(S##a1, S##b1, 1, kt_); G_LD1(S##a2, S##b2, 2, kt_); G_LD1(S##a3, S##b3, 3, kt_); } while (0)
; #define G_STORE(S, buf_) do { G_ST1(S##a0, S##b0, 0, buf_); G_ST1(S##a1, S##b1, 1, buf_); G_ST1(S##a2, S##b2, 2, buf_); G_ST1(S##a3, S##b3, 3, buf_); } while (0)
; template <class AL, class BL>
; DI void gemm_core(AL al, BL bl, int m0, int n0, int K, char* smem, f32x16 (&acc)[2][2]) {
;     ...
;   G_LOAD(x, 0);
;   G_STORE(x, 0);
;   G_LOAD(x, 1);
;   G_LOAD(y, (nk > 2) ? 2 : 1);
;   __syncthreads();
;   for (int kt = 0; kt < nk; kt += 2) {
;     G_TILE(0, x, true, (kt + 3 < nk), kt + 3);
;     __syncthreads();
;     G_TILE(1, y, (kt + 2 < nk), (kt + 4 < nk), kt + 4);
	ds_read_b128 v[106:109], v66 offset:18432
	ds_read_b128 v[142:145], v64 offset:55296
	ds_read_b128 v[150:153], v66 offset:18464
	ds_read_b128 v[154:157], v64 offset:55328
	ds_read_b128 v[158:161], v64 offset:59904
	ds_read_b128 v[162:165], v64 offset:59936
	s_waitcnt lgkmcnt(4)
	v_mfma_f32_32x32x16_bf16 v[48:63], v[106:109], v[142:145], v[48:63]
	s_waitcnt lgkmcnt(1)
	v_mfma_f32_32x32x16_bf16 v[32:47], v[106:109], v[158:161], v[32:47]
	ds_read_b128 v[106:109], v66 offset:23040
	ds_read_b128 v[166:169], v66 offset:23072
	s_waitcnt lgkmcnt(1)
	v_mfma_f32_32x32x16_bf16 v[16:31], v[106:109], v[142:145], v[16:31]
	global_load_dwordx4 v[142:145], v[76:77], off offset:3840
	global_load_dwordx4 v[174:177], v[78:79], off offset:1792
	s_waitcnt vmcnt(17)
	ds_write_b128 v68, v[146:149]
	s_waitcnt vmcnt(16)
	ds_write_b128 v68, v[170:173] offset:36864
	v_mfma_f32_32x32x16_bf16 v[0:15], v[106:109], v[158:161], v[0:15]
	global_load_dwordx4 v[106:109], v[74:75], off offset:3840
	global_load_dwordx4 v[146:149], v[84:85], off offset:1792
	v_mfma_f32_32x32x16_bf16 v[48:63], v[150:153], v[154:157], v[48:63]
	v_mfma_f32_32x32x16_bf16 v[32:47], v[150:153], v[162:165], v[32:47]
	s_waitcnt lgkmcnt(2)
	v_mfma_f32_32x32x16_bf16 v[16:31], v[166:169], v[154:157], v[16:31]
	ds_read_b128 v[150:153], v66 offset:18496
	ds_read_b128 v[154:157], v66 offset:23104
	ds_read_b128 v[158:161], v64 offset:55360
	ds_read_b128 v[170:173], v64 offset:59968
	s_waitcnt vmcnt(17)
	ds_write_b128 v68, v[114:117] offset:4608
	s_waitcnt vmcnt(16)
	ds_write_b128 v68, v[118:121] offset:41472
	v_mfma_f32_32x32x16_bf16 v[0:15], v[166:169], v[162:165], v[0:15]
	global_load_dwordx4 v[114:117], v[70:71], off offset:3840
	global_load_dwordx4 v[118:121], v[82:83], off offset:1792
	s_waitcnt lgkmcnt(3)
	v_mfma_f32_32x32x16_bf16 v[48:63], v[150:153], v[158:161], v[48:63]
	s_waitcnt lgkmcnt(2)
	v_mfma_f32_32x32x16_bf16 v[32:47], v[150:153], v[170:173], v[32:47]
	v_mfma_f32_32x32x16_bf16 v[16:31], v[154:157], v[158:161], v[16:31]
	ds_read_b128 v[150:153], v66 offset:18528
	ds_read_b128 v[158:161], v66 offset:23136
	ds_read_b128 v[162:165], v64 offset:55392
	ds_read_b128 v[166:169], v64 offset:60000
	s_waitcnt vmcnt(17)
	ds_write_b128 v68, v[86:89] offset:9216
	s_waitcnt vmcnt(16)
	ds_write_b128 v68, v[122:125] offset:46080
	v_mfma_f32_32x32x16_bf16 v[0:15], v[154:157], v[170:173], v[0:15]
	global_load_dwordx4 v[86:89], v[72:73], off offset:3840
	global_load_dwordx4 v[122:125], v[80:81], off offset:1792
	s_waitcnt lgkmcnt(3)
	v_mfma_f32_32x32x16_bf16 v[48:63], v[150:153], v[162:165], v[48:63]
	s_waitcnt vmcnt(17)
	ds_write_b128 v68, v[94:97] offset:13824
	s_waitcnt vmcnt(16)
	ds_write_b128 v68, v[126:129] offset:50688
	s_waitcnt lgkmcnt(4)
	v_mfma_f32_32x32x16_bf16 v[32:47], v[150:153], v[166:169], v[32:47]
	v_mfma_f32_32x32x16_bf16 v[16:31], v[158:161], v[162:165], v[16:31]
	v_mfma_f32_32x32x16_bf16 v[0:15], v[158:161], v[166:169], v[0:15]
	s_waitcnt lgkmcnt(0)
	s_barrier
	ds_read_b128 v[94:97], v66
	ds_read_b128 v[126:129], v64 offset:36864
	ds_read_b128 v[150:153], v66 offset:32
	ds_read_b128 v[154:157], v64 offset:36896
	ds_read_b128 v[158:161], v64 offset:41472
	ds_read_b128 v[162:165], v64 offset:41504
	s_waitcnt lgkmcnt(4)
	v_mfma_f32_32x32x16_bf16 v[48:63], v[94:97], v[126:129], v[48:63]
	s_waitcnt lgkmcnt(1)
	v_mfma_f32_32x32x16_bf16 v[32:47], v[94:97], v[158:161], v[32:47]
	ds_read_b128 v[94:97], v66 offset:4608
	ds_read_b128 v[166:169], v66 offset:4640
	s_waitcnt lgkmcnt(1)
	v_mfma_f32_32x32x16_bf16 v[16:31], v[94:97], v[126:129], v[16:31]
	global_load_dwordx4 v[126:129], v[76:77], off offset:3968
	s_nop 0
	global_load_dwordx4 v[76:79], v[78:79], off offset:1920
	s_waitcnt vmcnt(17)
	ds_write_b128 v68, v[130:133] offset:18432
	s_waitcnt vmcnt(16)
	ds_write_b128 v68, v[178:181] offset:55296
	v_mfma_f32_32x32x16_bf16 v[0:15], v[94:97], v[158:161], v[0:15]
	global_load_dwordx4 v[94:97], v[74:75], off offset:3968
	global_load_dwordx4 v[130:133], v[84:85], off offset:1920
	v_mfma_f32_32x32x16_bf16 v[48:63], v[150:153], v[154:157], v[48:63]
	v_mfma_f32_32x32x16_bf16 v[32:47], v[150:153], v[162:165], v[32:47]
	s_waitcnt lgkmcnt(2)
	v_mfma_f32_32x32x16_bf16 v[16:31], v[166:169], v[154:157], v[16:31]
	ds_read_b128 v[150:153], v66 offset:64
	ds_read_b128 v[154:157], v66 offset:4672
	ds_read_b128 v[158:161], v64 offset:36928
	ds_read_b128 v[170:173], v64 offset:41536
	s_waitcnt vmcnt(17)
	ds_write_b128 v68, v[102:105] offset:23040
	s_waitcnt vmcnt(16)
	ds_write_b128 v68, v[110:113] offset:59904
	v_mfma_f32_32x32x16_bf16 v[0:15], v[166:169], v[162:165], v[0:15]
	global_load_dwordx4 v[102:105], v[70:71], off offset:3968
	s_nop 0
	global_load_dwordx4 v[82:85], v[82:83], off offset:1920
	s_waitcnt lgkmcnt(3)
	v_mfma_f32_32x32x16_bf16 v[48:63], v[150:153], v[158:161], v[48:63]
	s_waitcnt lgkmcnt(2)
	v_mfma_f32_32x32x16_bf16 v[32:47], v[150:153], v[170:173], v[32:47]
	v_mfma_f32_32x32x16_bf16 v[16:31], v[154:157], v[158:161], v[16:31]
	ds_read_b128 v[110:113], v66 offset:96
	ds_read_b128 v[150:153], v66 offset:4704
	ds_read_b128 v[158:161], v64 offset:36960
	ds_read_b128 v[162:165], v64 offset:41568
	s_waitcnt vmcnt(17)
	ds_write_b128 v68, v[90:93] offset:27648
	s_waitcnt vmcnt(16)
	ds_write_b128 v68, v[134:137] offset:64512
	v_mfma_f32_32x32x16_bf16 v[0:15], v[154:157], v[170:173], v[0:15]
	global_load_dwordx4 v[70:73], v[72:73], off offset:3968
	s_nop 0
	global_load_dwordx4 v[90:93], v[80:81], off offset:1920
	s_waitcnt lgkmcnt(3)
	v_mfma_f32_32x32x16_bf16 v[48:63], v[110:113], v[158:161], v[48:63]
	s_waitcnt vmcnt(17)
	ds_write_b128 v68, v[98:101] offset:32256
	s_waitcnt vmcnt(16)
	ds_write_b128 v67, v[138:141] offset:32256
	s_waitcnt lgkmcnt(4)
	v_mfma_f32_32x32x16_bf16 v[32:47], v[110:113], v[162:165], v[32:47]
	v_mfma_f32_32x32x16_bf16 v[16:31], v[150:153], v[158:161], v[16:31]
	v_mfma_f32_32x32x16_bf16 v[0:15], v[150:153], v[162:165], v[0:15]
	s_waitcnt lgkmcnt(0)
	s_barrier
; #define G_LOAD(S, kt_) do { G_LD1(S##a0, S##b0, 0, kt_); G_LD1(S##a1, S##b1, 1, kt_); G_LD1(S##a2, S##b2, 2, kt_); G_LD1(S##a3, S##b3, 3, kt_); } while (0)
; #define G_STORE(S, buf_) do { G_ST1(S##a0, S##b0, 0, buf_); G_ST1(S##a1, S##b1, 1, buf_); G_ST1(S##a2, S##b2, 2, buf_); G_ST1(S##a3, S##b3, 3, buf_); } while (0)
; template <class AL, class BL>
; DI void gemm_core(AL al, BL bl, int m0, int n0, int K, char* smem, f32x16 (&acc)[2][2]) {
;     ...
;   G_LOAD(x, 0);
;   G_STORE(x, 0);
;   G_LOAD(x, 1);
;   G_LOAD(y, (nk > 2) ? 2 : 1);
;   __syncthreads();
;   for (int kt = 0; kt < nk; kt += 2) {
;     G_TILE(0, x, true, (kt + 3 < nk), kt + 3);
;     __syncthreads();
;     G_TILE(1, y, (kt + 2 < nk), (kt + 4 < nk), kt + 4);
	ds_read_b128 v[98:101], v66 offset:18432
	ds_read_b128 v[110:113], v64 offset:55296
	ds_read_b128 v[134:137], v66 offset:18464
	ds_read_b128 v[138:141], v64 offset:55328
	ds_read_b128 v[150:153], v64 offset:59904
	ds_read_b128 v[154:157], v64 offset:59936
	s_waitcnt lgkmcnt(4)
	v_mfma_f32_32x32x16_bf16 v[48:63], v[98:101], v[110:113], v[48:63]
	s_waitcnt lgkmcnt(1)
	v_mfma_f32_32x32x16_bf16 v[32:47], v[98:101], v[150:153], v[32:47]
	ds_read_b128 v[98:101], v66 offset:23040
	ds_read_b128 v[158:161], v66 offset:23072
	s_waitcnt vmcnt(15)
	ds_write_b128 v68, v[142:145]
	s_waitcnt vmcnt(14)
	ds_write_b128 v68, v[174:177] offset:36864
	s_waitcnt lgkmcnt(3)
	v_mfma_f32_32x32x16_bf16 v[16:31], v[98:101], v[110:113], v[16:31]
	v_mfma_f32_32x32x16_bf16 v[0:15], v[98:101], v[150:153], v[0:15]
	v_mfma_f32_32x32x16_bf16 v[48:63], v[134:137], v[138:141], v[48:63]
	v_mfma_f32_32x32x16_bf16 v[32:47], v[134:137], v[154:157], v[32:47]
	s_waitcnt lgkmcnt(2)
	v_mfma_f32_32x32x16_bf16 v[16:31], v[158:161], v[138:141], v[16:31]
	ds_read_b128 v[98:101], v66 offset:18496
	ds_read_b128 v[110:113], v66 offset:23104
	ds_read_b128 v[134:137], v64 offset:55360
	ds_read_b128 v[138:141], v64 offset:59968
	s_waitcnt vmcnt(13)
	ds_write_b128 v68, v[106:109] offset:4608
	s_waitcnt vmcnt(12)
	ds_write_b128 v68, v[146:149] offset:41472
	v_mfma_f32_32x32x16_bf16 v[0:15], v[158:161], v[154:157], v[0:15]
	s_waitcnt lgkmcnt(3)
	v_mfma_f32_32x32x16_bf16 v[48:63], v[98:101], v[134:137], v[48:63]
	s_waitcnt lgkmcnt(2)
	v_mfma_f32_32x32x16_bf16 v[32:47], v[98:101], v[138:141], v[32:47]
	v_mfma_f32_32x32x16_bf16 v[16:31], v[110:113], v[134:137], v[16:31]
	ds_read_b128 v[98:101], v66 offset:18528
	ds_read_b128 v[106:109], v66 offset:23136
	ds_read_b128 v[134:137], v64 offset:55392
	ds_read_b128 v[142:145], v64 offset:60000
	s_waitcnt vmcnt(11)
	ds_write_b128 v68, v[114:117] offset:9216
	s_waitcnt vmcnt(10)
	ds_write_b128 v68, v[118:121] offset:46080
	v_mfma_f32_32x32x16_bf16 v[0:15], v[110:113], v[138:141], v[0:15]
	s_waitcnt lgkmcnt(3)
	v_mfma_f32_32x32x16_bf16 v[48:63], v[98:101], v[134:137], v[48:63]
	s_waitcnt vmcnt(9)
	ds_write_b128 v68, v[86:89] offset:13824
	s_waitcnt vmcnt(8)
	ds_write_b128 v68, v[122:125] offset:50688
	s_waitcnt lgkmcnt(4)
	v_mfma_f32_32x32x16_bf16 v[32:47], v[98:101], v[142:145], v[32:47]
	v_mfma_f32_32x32x16_bf16 v[16:31], v[106:109], v[134:137], v[16:31]
	v_mfma_f32_32x32x16_bf16 v[0:15], v[106:109], v[142:145], v[0:15]
	s_waitcnt lgkmcnt(0)
	s_barrier
	ds_read_b128 v[86:89], v66
	ds_read_b128 v[98:101], v64 offset:36864
	ds_read_b128 v[106:109], v66 offset:32
	ds_read_b128 v[110:113], v64 offset:36896
	ds_read_b128 v[114:117], v64 offset:41472
	ds_read_b128 v[118:121], v64 offset:41504
	s_waitcnt lgkmcnt(4)
	v_mfma_f32_32x32x16_bf16 v[48:63], v[86:89], v[98:101], v[48:63]
	s_waitcnt lgkmcnt(1)
	v_mfma_f32_32x32x16_bf16 v[32:47], v[86:89], v[114:117], v[32:47]
	ds_read_b128 v[86:89], v66 offset:4608
	ds_read_b128 v[122:125], v66 offset:4640
	s_waitcnt vmcnt(7)
	ds_write_b128 v68, v[126:129] offset:18432
	s_waitcnt vmcnt(6)
	ds_write_b128 v68, v[76:79] offset:55296
	s_waitcnt lgkmcnt(3)
	v_mfma_f32_32x32x16_bf16 v[16:31], v[86:89], v[98:101], v[16:31]
	v_mfma_f32_32x32x16_bf16 v[0:15], v[86:89], v[114:117], v[0:15]
	ds_read_b128 v[74:77], v66 offset:64
	ds_read_b128 v[78:81], v66 offset:4672
	ds_read_b128 v[86:89], v64 offset:36928
	ds_read_b128 v[98:101], v64 offset:41536
	v_mfma_f32_32x32x16_bf16 v[48:63], v[106:109], v[110:113], v[48:63]
	s_waitcnt vmcnt(5)
	ds_write_b128 v68, v[94:97] offset:23040
	s_waitcnt vmcnt(4)
	ds_write_b128 v68, v[130:133] offset:59904
	v_mfma_f32_32x32x16_bf16 v[32:47], v[106:109], v[118:121], v[32:47]
	s_waitcnt lgkmcnt(8)
	v_mfma_f32_32x32x16_bf16 v[16:31], v[122:125], v[110:113], v[16:31]
	v_mfma_f32_32x32x16_bf16 v[0:15], v[122:125], v[118:121], v[0:15]
	s_waitcnt lgkmcnt(3)
	v_mfma_f32_32x32x16_bf16 v[48:63], v[74:77], v[86:89], v[48:63]
	s_waitcnt lgkmcnt(2)
	v_mfma_f32_32x32x16_bf16 v[32:47], v[74:77], v[98:101], v[32:47]
	v_mfma_f32_32x32x16_bf16 v[16:31], v[78:81], v[86:89], v[16:31]
	ds_read_b128 v[74:77], v66 offset:96
	ds_read_b128 v[86:89], v66 offset:4704
	ds_read_b128 v[94:97], v64 offset:36960
	ds_read_b128 v[106:109], v64 offset:41568
	s_waitcnt vmcnt(3)
	ds_write_b128 v68, v[102:105] offset:27648
	s_waitcnt vmcnt(2)
	ds_write_b128 v68, v[82:85] offset:64512
	v_mfma_f32_32x32x16_bf16 v[0:15], v[78:81], v[98:101], v[0:15]
	s_waitcnt lgkmcnt(3)
	v_mfma_f32_32x32x16_bf16 v[48:63], v[74:77], v[94:97], v[48:63]
	s_waitcnt vmcnt(1)
	ds_write_b128 v68, v[70:73] offset:32256
	s_waitcnt vmcnt(0)
	ds_write_b128 v67, v[90:93] offset:32256
	s_waitcnt lgkmcnt(4)
	v_mfma_f32_32x32x16_bf16 v[32:47], v[74:77], v[106:109], v[32:47]
	v_mfma_f32_32x32x16_bf16 v[16:31], v[86:89], v[94:97], v[16:31]
	v_mfma_f32_32x32x16_bf16 v[0:15], v[86:89], v[106:109], v[0:15]
	s_waitcnt lgkmcnt(0)
	s_barrier
; DI u16 f2bf(float x) { return (u16)(pack2(x, 0.f) & 0xffffu); }
; DI int opaque_tid() { int t = threadIdx.x; asm volatile("" : "+v"(t)); return t; }
; DI int crow(int i, int h) { return (i & 3) + 8 * (i >> 2) + 4 * h; }
; template <class AL, class BL>
; DI void gemm_core(AL al, BL bl, int m0, int n0, int K, char* smem, f32x16 (&acc)[2][2]) {
;     ...
;   for (int kt = 0; kt < nk; kt += 2) {
;     G_TILE(0, x, true, (kt + 3 < nk), kt + 3);
;     __syncthreads();
;     G_TILE(1, y, (kt + 2 < nk), (kt + 4 < nk), kt + 4);
;     __syncthreads();
;   }
; template <class F>
; DI void epi_bf16_tile(const f32x16 (&acc)[2][2], int m0, int n0, u16* dst0, long ld, char* smem, F f) {
;   const int tid = opaque_tid(), lane = tid & 63, w = tid >> 6, wm = w >> 1, wn = w & 1, h = lane >> 5;
;   u16* T = (u16*)smem;
; #pragma unroll
;   for (int mt = 0; mt < 2; mt++)
; #pragma unroll
;     for (int nt = 0; nt < 2; nt++)
; #pragma unroll
;       for (int i = 0; i < 16; i++) {
;         const int ml = wm * 64 + mt * 32 + crow(i, h), nl = wn * 64 + nt * 32 + (lane & 31);
;         T[ml * 136 + nl] = f2bf(f(m0 + ml, n0 + nl, acc[mt][nt][i]));
;       }
	ds_read_b128 v[68:71], v66 offset:18432
	ds_read_b128 v[72:75], v64 offset:55296
	ds_read_b128 v[76:79], v66 offset:18464
	ds_read_b128 v[80:83], v64 offset:55328
	ds_read_b128 v[84:87], v64 offset:59904
	ds_read_b128 v[88:91], v64 offset:59936
	s_waitcnt lgkmcnt(4)
	v_mfma_f32_32x32x16_bf16 v[48:63], v[68:71], v[72:75], v[48:63]
	s_waitcnt lgkmcnt(1)
	v_mfma_f32_32x32x16_bf16 v[32:47], v[68:71], v[84:87], v[32:47]
	ds_read_b128 v[68:71], v66 offset:23040
	ds_read_b128 v[92:95], v66 offset:23072
	s_waitcnt lgkmcnt(1)
	v_mfma_f32_32x32x16_bf16 v[16:31], v[68:71], v[72:75], v[16:31]
	v_mfma_f32_32x32x16_bf16 v[0:15], v[68:71], v[84:87], v[0:15]
	v_mfma_f32_32x32x16_bf16 v[48:63], v[76:79], v[80:83], v[48:63]
	v_mfma_f32_32x32x16_bf16 v[32:47], v[76:79], v[88:91], v[32:47]
	s_waitcnt lgkmcnt(0)
	v_mfma_f32_32x32x16_bf16 v[16:31], v[92:95], v[80:83], v[16:31]
	ds_read_b128 v[68:71], v66 offset:18496
	ds_read_b128 v[72:75], v66 offset:23104
	ds_read_b128 v[76:79], v64 offset:55360
	ds_read_b128 v[80:83], v64 offset:59968
	v_mfma_f32_32x32x16_bf16 v[0:15], v[92:95], v[88:91], v[0:15]
	s_waitcnt lgkmcnt(1)
	v_mfma_f32_32x32x16_bf16 v[48:63], v[68:71], v[76:79], v[48:63]
	s_waitcnt lgkmcnt(0)
	v_mfma_f32_32x32x16_bf16 v[32:47], v[68:71], v[80:83], v[32:47]
	v_mfma_f32_32x32x16_bf16 v[16:31], v[72:75], v[76:79], v[16:31]
	ds_read_b128 v[68:71], v66 offset:18528
	ds_read_b128 v[76:79], v66 offset:23136
	ds_read_b128 v[84:87], v64 offset:55392
	ds_read_b128 v[88:91], v64 offset:60000
	v_mfma_f32_32x32x16_bf16 v[0:15], v[72:75], v[80:83], v[0:15]
	s_waitcnt lgkmcnt(1)
	v_mfma_f32_32x32x16_bf16 v[48:63], v[68:71], v[84:87], v[48:63]
	s_waitcnt lgkmcnt(0)
	v_mfma_f32_32x32x16_bf16 v[32:47], v[68:71], v[88:91], v[32:47]
	v_mfma_f32_32x32x16_bf16 v[16:31], v[76:79], v[84:87], v[16:31]
	v_mfma_f32_32x32x16_bf16 v[0:15], v[76:79], v[88:91], v[0:15]
	v_mov_b32_e32 v64, v202
	s_barrier
	s_ashr_i32 s21, s20, 31
	s_lshl_b64 s[2:3], s[20:21], 13
	v_ashrrev_i32_e32 v66, 1, v64
	v_lshrrev_b32_e32 v67, 3, v64
	v_lshlrev_b32_e32 v69, 4, v64
	v_lshlrev_b32_e32 v68, 1, v64
	v_ashrrev_i32_e32 v70, 4, v64
	v_add_u32_e32 v72, 0x100, v64
	v_add_u32_e32 v73, 0x200, v64
	v_add_u32_e32 v74, 0x300, v64
	v_add_u32_e32 v75, 0x400, v64
	v_add_u32_e32 v76, 0x500, v64
	v_add_u32_e32 v77, 0x600, v64
	v_add_u32_e32 v78, 0x700, v64
	v_and_b32_e32 v98, 0xffffffc0, v66
	v_and_b32_e32 v99, 4, v67
	v_and_b32_e32 v64, 0xf0, v69
	s_add_u32 s2, s22, s2
	v_or_b32_e32 v82, v99, v98
	v_mad_u64_u32 v[66:67], s[20:21], v70, s31, v[64:65]
	s_addc_u32 s35, s23, s3
	s_ashr_i32 s1, s0, 31
	v_subrev_u32_e32 v67, s34, v82
	s_lshl_b64 s[0:1], s[0:1], 1
	v_add_u32_e32 v162, s24, v67
	v_and_b32_e32 v114, 0xbe, v68
	v_ashrrev_i32_e32 v71, 31, v70
	v_ashrrev_i32_e32 v84, 4, v72
	v_ashrrev_i32_e32 v86, 4, v73
	v_ashrrev_i32_e32 v88, 4, v74
	v_ashrrev_i32_e32 v90, 4, v75
	v_ashrrev_i32_e32 v92, 4, v76
	v_ashrrev_i32_e32 v94, 4, v77
	v_ashrrev_i32_e32 v96, 4, v78
	v_or_b32_e32 v115, 27, v99
	s_add_u32 s0, s2, s0
	v_subrev_u32_e32 v166, 48, v162
	v_subrev_u32_e32 v168, 40, v162
	v_subrev_u32_e32 v170, 32, v162
	v_subrev_u32_e32 v172, 24, v162
	v_add_u32_e32 v174, -16, v162
	v_add_u32_e32 v176, -8, v162
	v_add_u32_e32 v178, 8, v162
	v_or_b32_e32 v100, 1, v99
	v_or_b32_e32 v101, 2, v99
	v_or_b32_e32 v102, 3, v99
	v_or_b32_e32 v103, 8, v99
	v_or_b32_e32 v104, 9, v99
	v_or_b32_e32 v105, 10, v99
	v_or_b32_e32 v106, 11, v99
	v_or_b32_e32 v107, 16, v99
	v_or_b32_e32 v108, 17, v99
	v_or_b32_e32 v109, 18, v99
	v_or_b32_e32 v110, 19, v99
	v_or_b32_e32 v111, 24, v99
	v_or_b32_e32 v112, 25, v99
	v_or_b32_e32 v113, 26, v99
	v_or_b32_e32 v118, 32, v98
	v_lshlrev_b64 v[116:117], 13, v[70:71]
	v_mad_u64_u32 v[68:69], s[20:21], v84, s31, v[64:65]
	v_ashrrev_i32_e32 v85, 31, v84
	v_mad_u64_u32 v[70:71], s[20:21], v86, s31, v[64:65]
	v_ashrrev_i32_e32 v87, 31, v86
	v_mad_u64_u32 v[72:73], s[20:21], v88, s31, v[64:65]
	v_ashrrev_i32_e32 v89, 31, v88
	v_mad_u64_u32 v[74:75], s[20:21], v90, s31, v[64:65]
	v_ashrrev_i32_e32 v91, 31, v90
	v_mad_u64_u32 v[76:77], s[20:21], v92, s31, v[64:65]
	v_ashrrev_i32_e32 v93, 31, v92
	v_mad_u64_u32 v[78:79], s[20:21], v94, s31, v[64:65]
	v_ashrrev_i32_e32 v95, 31, v94
	v_mad_u64_u32 v[80:81], s[20:21], v96, s31, v[64:65]
	v_ashrrev_i32_e32 v97, 31, v96
	v_mad_u64_u32 v[82:83], s[2:3], v82, s31, v[114:115]
	s_addc_u32 s1, s35, s1
	v_ashrrev_i32_e32 v163, 31, v162
	v_ashrrev_i32_e32 v167, 31, v166
	v_ashrrev_i32_e32 v169, 31, v168
	v_ashrrev_i32_e32 v171, 31, v170
	v_ashrrev_i32_e32 v173, 31, v172
	v_ashrrev_i32_e32 v175, 31, v174
	v_ashrrev_i32_e32 v177, 31, v176
	v_ashrrev_i32_e32 v179, 31, v178
	v_or_b32_e32 v69, v100, v98
	v_or_b32_e32 v71, v101, v98
	v_or_b32_e32 v73, v102, v98
	v_or_b32_e32 v75, v103, v98
	v_or_b32_e32 v77, v104, v98
	v_or_b32_e32 v79, v105, v98
	v_or_b32_e32 v81, v106, v98
	v_or_b32_e32 v83, v107, v98
	v_or_b32_e32 v148, v108, v98
	v_or_b32_e32 v150, v109, v98
	v_or_b32_e32 v152, v110, v98
	v_or_b32_e32 v154, v111, v98
	v_or_b32_e32 v156, v112, v98
	v_or_b32_e32 v158, v113, v98
	v_or_b32_e32 v98, v115, v98
	v_or_b32_e32 v99, v118, v99
	v_or_b32_e32 v100, v100, v118
	v_or_b32_e32 v101, v101, v118
	v_or_b32_e32 v102, v102, v118
	v_or_b32_e32 v103, v103, v118
	v_or_b32_e32 v104, v104, v118
	v_or_b32_e32 v105, v105, v118
	v_or_b32_e32 v106, v106, v118
	v_or_b32_e32 v107, v107, v118
	v_or_b32_e32 v108, v108, v118
	v_or_b32_e32 v109, v109, v118
	v_or_b32_e32 v110, v110, v118
	v_or_b32_e32 v111, v111, v118
	v_or_b32_e32 v112, v112, v118
	v_or_b32_e32 v113, v113, v118
	v_or_b32_e32 v115, v115, v118
	v_lshlrev_b64 v[118:119], 13, v[84:85]
	v_lshlrev_b64 v[120:121], 13, v[86:87]
; DI u16 f2bf(float x) { return (u16)(pack2(x, 0.f) & 0xffffu); }
; DI int crow(int i, int h) { return (i & 3) + 8 * (i >> 2) + 4 * h; }
; template <class F>
; DI void epi_bf16_tile(const f32x16 (&acc)[2][2], int m0, int n0, u16* dst0, long ld, char* smem, F f) {
;     ...
;       for (int i = 0; i < 16; i++) {
;         const int ml = wm * 64 + mt * 32 + crow(i, h), nl = wn * 64 + nt * 32 + (lane & 31);
;         T[ml * 136 + nl] = f2bf(f(m0 + ml, n0 + nl, acc[mt][nt][i]));
; DI void ffn_up_phase(const Params& p, const u16* xb, int ldx, const u16* wupT, u16* hid, char* smem) {
;     ...
;              [=](const f32x16 (&acc)[2][2], int m0, int n0) {
;                epi_bf16_tile(acc, m0, n0, hid + (long)m0 * 4096 + n0, 4096, smem, [=](int m, int n, float v) {
;                  const float a = fmaxf(v * rs[m], 0.f);
;                  return a * a;
;                });
	v_lshlrev_b64 v[122:123], 13, v[88:89]
	v_lshlrev_b64 v[124:125], 13, v[90:91]
	v_lshlrev_b64 v[126:127], 13, v[92:93]
	v_lshlrev_b64 v[128:129], 13, v[94:95]
	v_lshlrev_b64 v[130:131], 13, v[96:97]
	v_lshl_add_u64 v[164:165], s[0:1], 0, v[64:65]
	v_lshl_add_u64 v[162:163], v[162:163], 2, s[14:15]
	v_lshl_add_u64 v[166:167], v[166:167], 2, s[14:15]
	v_lshl_add_u64 v[180:181], v[168:169], 2, s[14:15]
	v_lshl_add_u64 v[182:183], v[170:171], 2, s[14:15]
	v_lshl_add_u64 v[184:185], v[172:173], 2, s[14:15]
	v_lshl_add_u64 v[186:187], v[174:175], 2, s[14:15]
	v_lshl_add_u64 v[188:189], v[176:177], 2, s[14:15]
	v_lshl_add_u64 v[190:191], v[178:179], 2, s[14:15]
	v_lshl_add_u64 v[116:117], v[164:165], 0, v[116:117]
	v_lshl_add_u64 v[118:119], v[164:165], 0, v[118:119]
	v_lshl_add_u64 v[120:121], v[164:165], 0, v[120:121]
	v_lshl_add_u64 v[122:123], v[164:165], 0, v[122:123]
	v_lshl_add_u64 v[124:125], v[164:165], 0, v[124:125]
	v_lshl_add_u64 v[126:127], v[164:165], 0, v[126:127]
	v_lshl_add_u64 v[128:129], v[164:165], 0, v[128:129]
	v_lshl_add_u64 v[130:131], v[164:165], 0, v[130:131]
	global_load_dwordx4 v[162:165], v[162:163], off
	s_nop 0
	global_load_dwordx4 v[166:169], v[166:167], off
	s_nop 0
	global_load_dwordx4 v[170:173], v[180:181], off
	global_load_dwordx4 v[174:177], v[182:183], off
	s_nop 0
	global_load_dwordx4 v[178:181], v[184:185], off
	s_nop 0
	global_load_dwordx4 v[182:185], v[186:187], off
	s_nop 0
	global_load_dwordx4 v[186:189], v[188:189], off
	s_nop 0
	global_load_dwordx4 v[190:193], v[190:191], off
	v_mad_u64_u32 v[132:133], s[2:3], v69, s31, v[114:115]
	v_mad_u64_u32 v[134:135], s[2:3], v71, s31, v[114:115]
	v_mad_u64_u32 v[136:137], s[2:3], v73, s31, v[114:115]
	v_mad_u64_u32 v[138:139], s[2:3], v75, s31, v[114:115]
	v_mad_u64_u32 v[140:141], s[2:3], v77, s31, v[114:115]
	v_mad_u64_u32 v[142:143], s[2:3], v79, s31, v[114:115]
	v_mad_u64_u32 v[144:145], s[2:3], v81, s31, v[114:115]
	v_mad_u64_u32 v[146:147], s[2:3], v83, s31, v[114:115]
	v_mad_u64_u32 v[148:149], s[2:3], v148, s31, v[114:115]
	v_mad_u64_u32 v[150:151], s[2:3], v150, s31, v[114:115]
	v_mad_u64_u32 v[152:153], s[2:3], v152, s31, v[114:115]
	v_mad_u64_u32 v[154:155], s[2:3], v154, s31, v[114:115]
	v_mad_u64_u32 v[156:157], s[2:3], v156, s31, v[114:115]
	v_mad_u64_u32 v[158:159], s[2:3], v158, s31, v[114:115]
	v_mad_u64_u32 v[160:161], s[2:3], v98, s31, v[114:115]
	v_mad_u64_u32 v[84:85], s[2:3], v99, s31, v[114:115]
	v_mad_u64_u32 v[86:87], s[2:3], v100, s31, v[114:115]
	v_mad_u64_u32 v[88:89], s[2:3], v101, s31, v[114:115]
	v_mad_u64_u32 v[90:91], s[2:3], v102, s31, v[114:115]
	v_mad_u64_u32 v[92:93], s[2:3], v103, s31, v[114:115]
	v_mad_u64_u32 v[94:95], s[2:3], v104, s31, v[114:115]
	v_mad_u64_u32 v[96:97], s[2:3], v105, s31, v[114:115]
	v_mad_u64_u32 v[98:99], s[2:3], v106, s31, v[114:115]
	v_mad_u64_u32 v[100:101], s[2:3], v107, s31, v[114:115]
	v_mad_u64_u32 v[102:103], s[2:3], v108, s31, v[114:115]
	v_mad_u64_u32 v[104:105], s[2:3], v109, s31, v[114:115]
	v_mad_u64_u32 v[106:107], s[2:3], v110, s31, v[114:115]
	v_mad_u64_u32 v[108:109], s[2:3], v111, s31, v[114:115]
	v_mad_u64_u32 v[110:111], s[2:3], v112, s31, v[114:115]
	v_mad_u64_u32 v[112:113], s[2:3], v113, s31, v[114:115]
	v_mad_u64_u32 v[114:115], s[2:3], v115, s31, v[114:115]
	s_add_i32 s33, s33, s50
	s_add_i32 s24, s24, s25
	s_cmpk_lt_i32 s33, 0x1200
	s_waitcnt vmcnt(6)
	v_mul_f32_e32 v48, v48, v166
	v_mul_f32_e32 v49, v49, v167
	v_mul_f32_e32 v50, v50, v168
	v_mul_f32_e32 v51, v51, v169
	s_waitcnt vmcnt(2)
	v_mul_f32_e32 v16, v16, v182
	v_mul_f32_e32 v24, v24, v162
	v_mul_f32_e32 v25, v25, v163
	v_mul_f32_e32 v26, v26, v164
	v_mul_f32_e32 v27, v27, v165
	v_mul_f32_e32 v8, v8, v162
	v_mul_f32_e32 v9, v9, v163
	v_mul_f32_e32 v10, v10, v164
	v_mul_f32_e32 v11, v11, v165
	v_mul_f32_e32 v17, v17, v183
	v_mul_f32_e32 v18, v18, v184
	v_mul_f32_e32 v19, v19, v185
	s_waitcnt vmcnt(1)
	v_mul_f32_e32 v20, v20, v186
	v_mul_f32_e32 v21, v21, v187
	v_mul_f32_e32 v22, v22, v188
	v_mul_f32_e32 v23, v23, v189
	s_waitcnt vmcnt(0)
	v_mul_f32_e32 v28, v28, v190
	v_mul_f32_e32 v29, v29, v191
	v_mul_f32_e32 v30, v30, v192
	v_mul_f32_e32 v31, v31, v193
	v_mul_f32_e32 v0, v0, v182
	v_mul_f32_e32 v1, v1, v183
	v_mul_f32_e32 v2, v2, v184
	v_mul_f32_e32 v3, v3, v185
	v_mul_f32_e32 v4, v4, v186
	v_mul_f32_e32 v5, v5, v187
	v_mul_f32_e32 v6, v6, v188
	v_mul_f32_e32 v7, v7, v189
	v_mul_f32_e32 v12, v12, v190
	v_mul_f32_e32 v13, v13, v191
	v_mul_f32_e32 v14, v14, v192
	v_mul_f32_e32 v15, v15, v193
	v_mul_f32_e32 v52, v52, v170
	v_mul_f32_e32 v53, v53, v171
	v_mul_f32_e32 v54, v54, v172
	v_mul_f32_e32 v55, v55, v173
	v_mul_f32_e32 v56, v56, v174
	v_mul_f32_e32 v57, v57, v175
	v_mul_f32_e32 v58, v58, v176
	v_mul_f32_e32 v59, v59, v177
	v_mul_f32_e32 v60, v60, v178
	v_mul_f32_e32 v61, v61, v179
	v_mul_f32_e32 v62, v62, v180
	v_mul_f32_e32 v63, v63, v181
	v_mul_f32_e32 v32, v32, v166
	v_mul_f32_e32 v33, v33, v167
	v_mul_f32_e32 v34, v34, v168
	v_mul_f32_e32 v35, v35, v169
	v_mul_f32_e32 v36, v36, v170
	v_mul_f32_e32 v37, v37, v171
	v_mul_f32_e32 v38, v38, v172
	v_mul_f32_e32 v39, v39, v173
	v_mul_f32_e32 v40, v40, v174
	v_mul_f32_e32 v41, v41, v175
	v_mul_f32_e32 v42, v42, v176
	v_mul_f32_e32 v43, v43, v177
	v_mul_f32_e32 v44, v44, v178
	v_mul_f32_e32 v45, v45, v179
	v_mul_f32_e32 v46, v46, v180
	v_mul_f32_e32 v47, v47, v181
	v_max_f32_e32 v24, 0, v24
	v_max_f32_e32 v25, 0, v25
	v_max_f32_e32 v26, 0, v26
	v_max_f32_e32 v27, 0, v27
	v_max_f32_e32 v8, 0, v8
	v_max_f32_e32 v9, 0, v9
	v_max_f32_e32 v10, 0, v10
	v_max_f32_e32 v11, 0, v11
	v_max_f32_e32 v48, 0, v48
	v_max_f32_e32 v16, 0, v16
	v_max_f32_e32 v17, 0, v17
; DI u16 f2bf(float x) { return (u16)(pack2(x, 0.f) & 0xffffu); }
; DI int crow(int i, int h) { return (i & 3) + 8 * (i >> 2) + 4 * h; }
; template <class F>
; DI void epi_bf16_tile(const f32x16 (&acc)[2][2], int m0, int n0, u16* dst0, long ld, char* smem, F f) {
;     ...
;       for (int i = 0; i < 16; i++) {
;         const int ml = wm * 64 + mt * 32 + crow(i, h), nl = wn * 64 + nt * 32 + (lane & 31);
;         T[ml * 136 + nl] = f2bf(f(m0 + ml, n0 + nl, acc[mt][nt][i]));
; DI void ffn_up_phase(const Params& p, const u16* xb, int ldx, const u16* wupT, u16* hid, char* smem) {
;     ...
;                epi_bf16_tile(acc, m0, n0, hid + (long)m0 * 4096 + n0, 4096, smem, [=](int m, int n, float v) {
;                  const float a = fmaxf(v * rs[m], 0.f);
;                  return a * a;
;                });
	v_max_f32_e32 v18, 0, v18
	v_max_f32_e32 v19, 0, v19
	v_max_f32_e32 v20, 0, v20
	v_max_f32_e32 v21, 0, v21
	v_max_f32_e32 v22, 0, v22
	v_max_f32_e32 v23, 0, v23
	v_max_f32_e32 v28, 0, v28
	v_max_f32_e32 v29, 0, v29
	v_max_f32_e32 v30, 0, v30
	v_max_f32_e32 v31, 0, v31
	v_max_f32_e32 v0, 0, v0
	v_max_f32_e32 v1, 0, v1
	v_max_f32_e32 v2, 0, v2
	v_max_f32_e32 v3, 0, v3
	v_max_f32_e32 v4, 0, v4
	v_max_f32_e32 v5, 0, v5
	v_max_f32_e32 v6, 0, v6
	v_max_f32_e32 v7, 0, v7
	v_max_f32_e32 v12, 0, v12
	v_max_f32_e32 v13, 0, v13
	v_max_f32_e32 v14, 0, v14
	v_max_f32_e32 v15, 0, v15
	v_max_f32_e32 v49, 0, v49
	v_max_f32_e32 v50, 0, v50
	v_max_f32_e32 v51, 0, v51
	v_max_f32_e32 v52, 0, v52
	v_max_f32_e32 v53, 0, v53
	v_max_f32_e32 v54, 0, v54
	v_max_f32_e32 v55, 0, v55
	v_max_f32_e32 v56, 0, v56
	v_max_f32_e32 v57, 0, v57
	v_max_f32_e32 v58, 0, v58
	v_max_f32_e32 v59, 0, v59
	v_max_f32_e32 v60, 0, v60
	v_max_f32_e32 v61, 0, v61
	v_max_f32_e32 v62, 0, v62
	v_max_f32_e32 v63, 0, v63
	v_max_f32_e32 v32, 0, v32
	v_max_f32_e32 v33, 0, v33
	v_max_f32_e32 v34, 0, v34
	v_max_f32_e32 v35, 0, v35
	v_max_f32_e32 v36, 0, v36
	v_max_f32_e32 v37, 0, v37
	v_max_f32_e32 v38, 0, v38
	v_max_f32_e32 v39, 0, v39
	v_max_f32_e32 v40, 0, v40
	v_max_f32_e32 v41, 0, v41
	v_max_f32_e32 v42, 0, v42
	v_max_f32_e32 v43, 0, v43
	v_max_f32_e32 v44, 0, v44
	v_max_f32_e32 v45, 0, v45
	v_max_f32_e32 v46, 0, v46
	v_max_f32_e32 v47, 0, v47
	v_mul_f32_e32 v24, v24, v24
	v_mul_f32_e32 v25, v25, v25
	v_mul_f32_e32 v26, v26, v26
	v_mul_f32_e32 v27, v27, v27
	v_mul_f32_e32 v8, v8, v8
	v_mul_f32_e32 v9, v9, v9
	v_mul_f32_e32 v10, v10, v10
	v_mul_f32_e32 v11, v11, v11
	v_mul_f32_e32 v48, v48, v48
	v_mul_f32_e32 v16, v16, v16
	v_mul_f32_e32 v17, v17, v17
	v_mul_f32_e32 v18, v18, v18
	v_mul_f32_e32 v19, v19, v19
	v_mul_f32_e32 v20, v20, v20
	v_mul_f32_e32 v21, v21, v21
	v_mul_f32_e32 v22, v22, v22
	v_mul_f32_e32 v23, v23, v23
	v_mul_f32_e32 v28, v28, v28
	v_mul_f32_e32 v29, v29, v29
	v_mul_f32_e32 v30, v30, v30
	v_mul_f32_e32 v31, v31, v31
	v_mul_f32_e32 v0, v0, v0
	v_mul_f32_e32 v1, v1, v1
	v_mul_f32_e32 v2, v2, v2
	v_mul_f32_e32 v3, v3, v3
	v_mul_f32_e32 v4, v4, v4
	v_mul_f32_e32 v5, v5, v5
	v_mul_f32_e32 v6, v6, v6
	v_mul_f32_e32 v7, v7, v7
	v_mul_f32_e32 v12, v12, v12
	v_mul_f32_e32 v13, v13, v13
	v_mul_f32_e32 v14, v14, v14
	v_mul_f32_e32 v15, v15, v15
	v_mul_f32_e32 v49, v49, v49
	v_mul_f32_e32 v50, v50, v50
	v_mul_f32_e32 v51, v51, v51
	v_mul_f32_e32 v52, v52, v52
	v_mul_f32_e32 v53, v53, v53
	v_mul_f32_e32 v54, v54, v54
	v_mul_f32_e32 v55, v55, v55
	v_mul_f32_e32 v56, v56, v56
	v_mul_f32_e32 v57, v57, v57
	v_mul_f32_e32 v58, v58, v58
	v_mul_f32_e32 v59, v59, v59
	v_mul_f32_e32 v60, v60, v60
	v_mul_f32_e32 v61, v61, v61
	v_mul_f32_e32 v62, v62, v62
	v_mul_f32_e32 v63, v63, v63
	v_mul_f32_e32 v32, v32, v32
	v_mul_f32_e32 v33, v33, v33
	v_mul_f32_e32 v34, v34, v34
	v_mul_f32_e32 v35, v35, v35
	v_mul_f32_e32 v36, v36, v36
	v_mul_f32_e32 v37, v37, v37
	v_mul_f32_e32 v38, v38, v38
	v_mul_f32_e32 v39, v39, v39
	v_mul_f32_e32 v40, v40, v40
	v_mul_f32_e32 v41, v41, v41
	v_mul_f32_e32 v42, v42, v42
	v_mul_f32_e32 v43, v43, v43
	v_mul_f32_e32 v44, v44, v44
	v_mul_f32_e32 v45, v45, v45
	v_mul_f32_e32 v46, v46, v46
	v_mul_f32_e32 v47, v47, v47
	v_cvt_pk_bf16_f32 v24, v24, s0
	v_cvt_pk_bf16_f32 v25, v25, s0
	v_cvt_pk_bf16_f32 v26, v26, s0
	v_cvt_pk_bf16_f32 v27, v27, s0
	v_cvt_pk_bf16_f32 v8, v8, s0
	v_cvt_pk_bf16_f32 v9, v9, s0
	v_cvt_pk_bf16_f32 v10, v10, s0
	v_cvt_pk_bf16_f32 v11, v11, s0
	v_cvt_pk_bf16_f32 v48, v48, s0
	v_cvt_pk_bf16_f32 v16, v16, s0
	v_cvt_pk_bf16_f32 v17, v17, s0
	v_cvt_pk_bf16_f32 v18, v18, s0
	v_cvt_pk_bf16_f32 v19, v19, s0
	v_cvt_pk_bf16_f32 v20, v20, s0
	v_cvt_pk_bf16_f32 v21, v21, s0
	v_cvt_pk_bf16_f32 v22, v22, s0
	v_cvt_pk_bf16_f32 v23, v23, s0
	v_cvt_pk_bf16_f32 v28, v28, s0
	v_cvt_pk_bf16_f32 v29, v29, s0
	v_cvt_pk_bf16_f32 v30, v30, s0
	v_cvt_pk_bf16_f32 v31, v31, s0
	v_cvt_pk_bf16_f32 v0, v0, s0
	v_cvt_pk_bf16_f32 v1, v1, s0
; DI u16 f2bf(float x) { return (u16)(pack2(x, 0.f) & 0xffffu); }
; DI int crow(int i, int h) { return (i & 3) + 8 * (i >> 2) + 4 * h; }
; template <class F>
; DI void epi_bf16_tile(const f32x16 (&acc)[2][2], int m0, int n0, u16* dst0, long ld, char* smem, F f) {
;     ...
;       for (int i = 0; i < 16; i++) {
;         const int ml = wm * 64 + mt * 32 + crow(i, h), nl = wn * 64 + nt * 32 + (lane & 31);
;         T[ml * 136 + nl] = f2bf(f(m0 + ml, n0 + nl, acc[mt][nt][i]));
;       }
;   __syncthreads();
; #pragma unroll
;   for (int j = 0; j < 8; j++) {
;     const int idx = tid + 256 * j, row = idx >> 4, ch = idx & 15;
;     *(uint4*)(dst0 + (long)row * ld + ch * 8) = *(const uint4*)(T + row * 136 + ch * 8);
;   }
;   __syncthreads();
	v_cvt_pk_bf16_f32 v2, v2, s0
	v_cvt_pk_bf16_f32 v3, v3, s0
	v_cvt_pk_bf16_f32 v4, v4, s0
	v_cvt_pk_bf16_f32 v5, v5, s0
	v_cvt_pk_bf16_f32 v6, v6, s0
	v_cvt_pk_bf16_f32 v7, v7, s0
	v_cvt_pk_bf16_f32 v12, v12, s0
	v_cvt_pk_bf16_f32 v13, v13, s0
	v_cvt_pk_bf16_f32 v14, v14, s0
	v_cvt_pk_bf16_f32 v15, v15, s0
	v_cvt_pk_bf16_f32 v49, v49, s0
	v_cvt_pk_bf16_f32 v50, v50, s0
	v_cvt_pk_bf16_f32 v51, v51, s0
	v_cvt_pk_bf16_f32 v52, v52, s0
	v_cvt_pk_bf16_f32 v53, v53, s0
	v_cvt_pk_bf16_f32 v54, v54, s0
	v_cvt_pk_bf16_f32 v55, v55, s0
	v_cvt_pk_bf16_f32 v56, v56, s0
	v_cvt_pk_bf16_f32 v57, v57, s0
	v_cvt_pk_bf16_f32 v58, v58, s0
	v_cvt_pk_bf16_f32 v59, v59, s0
	v_cvt_pk_bf16_f32 v60, v60, s0
	v_cvt_pk_bf16_f32 v61, v61, s0
	v_cvt_pk_bf16_f32 v62, v62, s0
	v_cvt_pk_bf16_f32 v63, v63, s0
	v_cvt_pk_bf16_f32 v32, v32, s0
	v_cvt_pk_bf16_f32 v33, v33, s0
	v_cvt_pk_bf16_f32 v34, v34, s0
	v_cvt_pk_bf16_f32 v35, v35, s0
	v_cvt_pk_bf16_f32 v36, v36, s0
	v_cvt_pk_bf16_f32 v37, v37, s0
	v_cvt_pk_bf16_f32 v38, v38, s0
	v_cvt_pk_bf16_f32 v39, v39, s0
	v_cvt_pk_bf16_f32 v40, v40, s0
	v_cvt_pk_bf16_f32 v41, v41, s0
	v_cvt_pk_bf16_f32 v42, v42, s0
	v_cvt_pk_bf16_f32 v43, v43, s0
	v_cvt_pk_bf16_f32 v44, v44, s0
	v_cvt_pk_bf16_f32 v45, v45, s0
	v_cvt_pk_bf16_f32 v46, v46, s0
	v_cvt_pk_bf16_f32 v47, v47, s0
	ds_write_b16 v82, v48
	ds_write_b16 v132, v49
	ds_write_b16 v134, v50
	ds_write_b16 v136, v51
	ds_write_b16 v138, v52
	ds_write_b16 v140, v53
	ds_write_b16 v142, v54
	ds_write_b16 v144, v55
	ds_write_b16 v146, v56
	ds_write_b16 v148, v57
	ds_write_b16 v150, v58
	ds_write_b16 v152, v59
	ds_write_b16 v154, v60
	ds_write_b16 v156, v61
	ds_write_b16 v158, v62
	ds_write_b16 v160, v63
	ds_write_b16 v82, v32 offset:64
	ds_write_b16 v132, v33 offset:64
	ds_write_b16 v134, v34 offset:64
	ds_write_b16 v136, v35 offset:64
	ds_write_b16 v138, v36 offset:64
	ds_write_b16 v140, v37 offset:64
	ds_write_b16 v142, v38 offset:64
	ds_write_b16 v144, v39 offset:64
	ds_write_b16 v146, v40 offset:64
	ds_write_b16 v148, v41 offset:64
	ds_write_b16 v150, v42 offset:64
	ds_write_b16 v152, v43 offset:64
	ds_write_b16 v154, v44 offset:64
	ds_write_b16 v156, v45 offset:64
	ds_write_b16 v158, v46 offset:64
	ds_write_b16 v160, v47 offset:64
	ds_write_b16 v84, v16
	ds_write_b16 v86, v17
	ds_write_b16 v88, v18
	ds_write_b16 v90, v19
	ds_write_b16 v92, v20
	ds_write_b16 v94, v21
	ds_write_b16 v96, v22
	ds_write_b16 v98, v23
	ds_write_b16 v100, v24
	ds_write_b16 v102, v25
	ds_write_b16 v104, v26
	ds_write_b16 v106, v27
	ds_write_b16 v108, v28
	ds_write_b16 v110, v29
	ds_write_b16 v112, v30
	ds_write_b16 v114, v31
	ds_write_b16 v84, v0 offset:64
	ds_write_b16 v86, v1 offset:64
	ds_write_b16 v88, v2 offset:64
	ds_write_b16 v90, v3 offset:64
	ds_write_b16 v92, v4 offset:64
	ds_write_b16 v94, v5 offset:64
	ds_write_b16 v96, v6 offset:64
	ds_write_b16 v98, v7 offset:64
	ds_write_b16 v100, v8 offset:64
	ds_write_b16 v102, v9 offset:64
	ds_write_b16 v104, v10 offset:64
	ds_write_b16 v106, v11 offset:64
	ds_write_b16 v108, v12 offset:64
	ds_write_b16 v110, v13 offset:64
	ds_write_b16 v112, v14 offset:64
	ds_write_b16 v114, v15 offset:64
	s_waitcnt lgkmcnt(0)
	s_barrier
	ds_read_b128 v[0:3], v66
	ds_read_b128 v[4:7], v68
	ds_read_b128 v[8:11], v70
	ds_read_b128 v[12:15], v72
	ds_read_b128 v[16:19], v74
	ds_read_b128 v[20:23], v76
	ds_read_b128 v[24:27], v78
	ds_read_b128 v[28:31], v80
	s_waitcnt lgkmcnt(7)
	global_store_dwordx4 v[116:117], v[0:3], off
	s_waitcnt lgkmcnt(6)
	global_store_dwordx4 v[118:119], v[4:7], off
	s_waitcnt lgkmcnt(5)
	global_store_dwordx4 v[120:121], v[8:11], off
	s_waitcnt lgkmcnt(4)
	global_store_dwordx4 v[122:123], v[12:15], off
	s_waitcnt lgkmcnt(3)
	global_store_dwordx4 v[124:125], v[16:19], off
	s_waitcnt lgkmcnt(2)
	global_store_dwordx4 v[126:127], v[20:23], off
	s_waitcnt lgkmcnt(1)
	global_store_dwordx4 v[128:129], v[24:27], off
	s_waitcnt lgkmcnt(0)
	global_store_dwordx4 v[130:131], v[28:31], off
	s_barrier
	s_mov_b64 s[2:3], s[48:49]

; #define G_LOAD(S, kt_) do { G_LD1(S##a0, S##b0, 0, kt_); G_LD1(S##a1, S##b1, 1, kt_); G_LD1(S##a2, S##b2, 2, kt_); G_LD1(S##a3, S##b3, 3, kt_); } while (0)
; #define G_STORE(S, buf_) do { G_ST1(S##a0, S##b0, 0, buf_); G_ST1(S##a1, S##b1, 1, buf_); G_ST1(S##a2, S##b2, 2, buf_); G_ST1(S##a3, S##b3, 3, buf_); } while (0)
; template <class AL, class BL>
; DI void gemm_core(AL al, BL bl, int m0, int n0, int K, char* smem, f32x16 (&acc)[2][2]) {
;     ...
;   const int srow = tid >> 3, sch = tid & 7;
;     ...
;   G_LOAD(x, 0);
;   G_STORE(x, 0);
;   G_LOAD(x, 1);
;   G_LOAD(y, (nk > 2) ? 2 : 1);
;   __syncthreads();
;   for (int kt = 0; kt < nk; kt += 2) {
;     G_TILE(0, x, true, (kt + 3 < nk), kt + 3);
; template <class AL, class BL, class EP>
; DI void gemm_phase(int MT, int NTL, int K, AL al, BL bl, EP ep, char* smem) {
;   for (int t = blockIdx.x; t < MT * NTL; t += gridDim.x) {
;     const int tm = t % MT, tn = t / MT;
;     f32x16 acc[2][2];
;     gemm_core(al, bl, tm * 128, tn * 128, K, smem, acc);
;     ep(acc, tm * 128, tn * 128);
;   }
; }
.LBB0_1672:
	s_or_b64 exec, exec, s[0:1]
	s_andn2_b64 vcc, exec, s[58:59]
	s_waitcnt lgkmcnt(0)
	s_barrier
	s_cbranch_vccnz .LBB0_1676
	s_add_u32 s6, s70, 0x7000000
	s_addc_u32 s7, s71, 0
	s_add_u32 s20, s70, 0x8000000
	s_addc_u32 s21, s71, 0
	s_add_u32 s12, s70, 0x10000
	s_mov_b64 s[10:11], 0x10000
	s_addc_u32 s13, s71, 0
	s_add_i32 s22, s67, 48
	s_lshl_b32 s23, s50, 7
	v_mov_b32_e32 v65, 0
	s_mov_b32 s24, 0x10000
	s_mov_b64 s[14:15], 0x20000
	s_mov_b32 s25, 0x20000
	s_mov_b64 s[16:17], 0x30000
	s_mov_b32 s26, 0x30000
	s_movk_i32 s27, 0x90
	s_mov_b32 s28, 0xfffffc0
	s_movk_i32 s29, 0x110
	s_mov_b32 s30, s78
	v_bfe_u32 v62, v202, 5, 1
	v_and_b32_e32 v63, 31, v202
	v_lshrrev_b32_e32 v64, 7, v202
	v_bfe_u32 v252, v202, 6, 1
	v_lshlrev_b32_e32 v253, 2, v62
	v_lshl_add_u32 v253, v64, 6, v253
	v_mul_u32_u24_e32 v59, 528, v253
	v_lshl_add_u32 v253, v252, 7, v63
	v_lshl_add_u32 v59, v253, 1, v59
	v_lshrrev_b32_e32 v253, 5, v202
	v_mul_u32_u24_e32 v60, 528, v253
	v_lshl_add_u32 v60, v63, 4, v60
	s_mov_b32 s98, s78
.Lfu1_tile:
	s_cmpk_lt_u32 s98, 0x7e0
	s_cbranch_scc1 .Lfu1_main
	s_sub_u32 s31, s98, 0x7e0
	s_mov_b32 s33, 14
	s_branch .Lfu1_go
.Lfu1_main:
	s_mul_hi_u32 s0, s98, 0x38e38e39
	s_lshr_b32 s33, s0, 5
	s_mul_i32 s0, s33, 0x90
	s_sub_u32 s31, s98, s0
.Lfu1_go:
	s_lshl_b32 s0, s31, 7
	v_lshlrev_b32_e32 v253, 2, v62
	v_lshl_add_u32 v253, v64, 6, v253
	v_add_u32_e32 v253, s0, v253
	v_lshlrev_b32_e32 v61, 2, v253
	s_mul_i32 s1, s0, 8192
	s_mul_hi_u32 s2, s0, 8192
	s_add_u32 s18, s20, s1
	s_addc_u32 s19, s21, s2
	s_lshl_b32 s1, s33, 9
	s_add_u32 s18, s18, s1
	s_addc_u32 s19, s19, 0
	v_lshrrev_b32_e32 v253, 5, v202
	v_mul_u32_u24_e32 v227, 8192, v253
	v_lshl_add_u32 v227, v63, 4, v227
	v_lshrrev_b32_e32 v62, 2, v202
	v_and_b32_e32 v63, 3, v202
	v_lshlrev_b32_e32 v63, 4, v63
	v_mul_u32_u24_e32 v58, 80, v62
	v_add_u32_e32 v58, v58, v63
	s_lshl_b32 s0, s31, 7
	v_add_u32_e32 v64, s0, v62
	v_mov_b32_e32 v254, v63
	v_mov_b32_e32 v255, 0
	v_mov_b32_e32 v252, 4096
	v_mad_u64_u32 v[240:241], s[0:1], v64, v252, v[254:255]
	v_lshl_add_u64 v[240:241], v[240:241], 0, s[68:69]
	s_mov_b32 s0, 262144
	s_mov_b32 s1, 0
	v_lshl_add_u64 v[242:243], v[240:241], 0, s[0:1]
	s_lshl_b32 s0, s33, 8
	v_add_u32_e32 v64, s0, v62
	v_mov_b32_e32 v252, 2048
	v_mad_u64_u32 v[244:245], s[0:1], v64, v252, v[254:255]
	v_lshl_add_u64 v[244:245], v[244:245], 0, s[6:7]
	s_mov_b32 s0, 131072
	s_mov_b32 s1, 0
	v_lshl_add_u64 v[246:247], v[244:245], 0, s[0:1]
	v_lshl_add_u64 v[248:249], v[246:247], 0, s[0:1]
	v_lshl_add_u64 v[250:251], v[248:249], 0, s[0:1]
	v_and_b32_e32 v62, 31, v202
	v_bfe_u32 v63, v202, 5, 1
	v_lshrrev_b32_e32 v64, 7, v202
	v_bfe_u32 v252, v202, 6, 1
	v_lshl_add_u32 v253, v64, 6, v62
	v_mul_u32_u24_e32 v56, 80, v253
	v_lshl_add_u32 v56, v63, 4, v56
	v_lshl_add_u32 v253, v252, 7, v62
	v_mul_u32_u24_e32 v57, 80, v253
	v_lshl_add_u32 v57, v63, 4, v57
	v_add_u32_e32 v57, 10240, v57
	global_load_dwordx4 v[32:35], v[240:241], off offset:2048
	global_load_dwordx4 v[36:39], v[242:243], off offset:2048
	global_load_dwordx4 v[40:43], v[244:245], off offset:0
	global_load_dwordx4 v[44:47], v[246:247], off offset:0
	global_load_dwordx4 v[48:51], v[248:249], off offset:0
	global_load_dwordx4 v[52:55], v[250:251], off offset:0
	global_load_dwordx4 v[214:217], v[240:241], off offset:2112
	global_load_dwordx4 v[218:221], v[242:243], off offset:2112
	global_load_dwordx4 v[222:225], v[244:245], off offset:64
	global_load_dwordx4 v[228:231], v[246:247], off offset:64
	global_load_dwordx4 v[232:235], v[248:249], off offset:64
	global_load_dwordx4 v[236:239], v[250:251], off offset:64
	s_waitcnt vmcnt(6)
	ds_write_b128 v58, v[32:35] offset:0
	ds_write_b128 v58, v[36:39] offset:5120
	ds_write_b128 v58, v[40:43] offset:10240
	ds_write_b128 v58, v[44:47] offset:15360
	ds_write_b128 v58, v[48:51] offset:20480
	ds_write_b128 v58, v[52:55] offset:25600
	global_load_dwordx4 v[32:35], v[240:241], off offset:2176
	global_load_dwordx4 v[36:39], v[242:243], off offset:2176
	global_load_dwordx4 v[40:43], v[244:245], off offset:128
	global_load_dwordx4 v[44:47], v[246:247], off offset:128
	global_load_dwordx4 v[48:51], v[248:249], off offset:128
	global_load_dwordx4 v[52:55], v[250:251], off offset:128
	s_waitcnt lgkmcnt(0)
	s_barrier
	ds_read_b128 v[0:3], v56 offset:0
	ds_read_b128 v[4:7], v56 offset:2560
	ds_read_b128 v[8:11], v57 offset:0
	ds_read_b128 v[12:15], v57 offset:2560
	ds_read_b128 v[16:19], v57 offset:5120
	ds_read_b128 v[20:23], v57 offset:7680
	ds_read_b128 v[24:27], v56 offset:32
	ds_read_b128 v[28:31], v56 offset:2592
	s_waitcnt lgkmcnt(4)
	v_mfma_f32_32x32x16_bf16 v[66:81], v[0:3], v[8:11], 0
	v_mfma_f32_32x32x16_bf16 v[82:97], v[0:3], v[12:15], 0
	s_waitcnt vmcnt(6)
	ds_write_b128 v58, v[214:217] offset:30720
	ds_write_b128 v58, v[218:221] offset:35840
	s_waitcnt lgkmcnt(4)
	v_mfma_f32_32x32x16_bf16 v[98:113], v[0:3], v[16:19], 0
	v_mfma_f32_32x32x16_bf16 v[114:129], v[0:3], v[20:23], 0
	ds_read_b128 v[0:3], v57 offset:32
	ds_write_b128 v58, v[222:225] offset:40960
	ds_write_b128 v58, v[228:231] offset:46080
	v_mfma_f32_32x32x16_bf16 v[130:145], v[4:7], v[8:11], 0
	v_mfma_f32_32x32x16_bf16 v[146:161], v[4:7], v[12:15], 0
	ds_write_b128 v58, v[232:235] offset:51200
	ds_write_b128 v58, v[236:239] offset:56320
	v_mfma_f32_32x32x16_bf16 v[162:177], v[4:7], v[16:19], 0
	v_mfma_f32_32x32x16_bf16 v[178:193], v[4:7], v[20:23], 0
	ds_read_b128 v[4:7], v57 offset:2592
	ds_read_b128 v[8:11], v57 offset:5152
	ds_read_b128 v[12:15], v57 offset:7712
	s_waitcnt lgkmcnt(2)
	v_mfma_f32_32x32x16_bf16 v[66:81], v[24:27], v[0:3], v[66:81]
	global_load_dwordx4 v[214:217], v[240:241], off offset:2240
	global_load_dwordx4 v[218:221], v[242:243], off offset:2240
	v_mfma_f32_32x32x16_bf16 v[82:97], v[24:27], v[4:7], v[82:97]
	s_waitcnt lgkmcnt(0)
	v_mfma_f32_32x32x16_bf16 v[98:113], v[24:27], v[8:11], v[98:113]
	global_load_dwordx4 v[222:225], v[244:245], off offset:192
	global_load_dwordx4 v[228:231], v[246:247], off offset:192
	v_mfma_f32_32x32x16_bf16 v[114:129], v[24:27], v[12:15], v[114:129]
	v_mfma_f32_32x32x16_bf16 v[130:145], v[28:31], v[0:3], v[130:145]
	global_load_dwordx4 v[232:235], v[248:249], off offset:192
	global_load_dwordx4 v[236:239], v[250:251], off offset:192
	v_mfma_f32_32x32x16_bf16 v[146:161], v[28:31], v[4:7], v[146:161]
	v_mfma_f32_32x32x16_bf16 v[162:177], v[28:31], v[8:11], v[162:177]
	v_mfma_f32_32x32x16_bf16 v[178:193], v[28:31], v[12:15], v[178:193]
	s_waitcnt lgkmcnt(0)
	s_barrier
; #define G_LOAD(S, kt_) do { G_LD1(S##a0, S##b0, 0, kt_); G_LD1(S##a1, S##b1, 1, kt_); G_LD1(S##a2, S##b2, 2, kt_); G_LD1(S##a3, S##b3, 3, kt_); } while (0)
; #define G_STORE(S, buf_) do { G_ST1(S##a0, S##b0, 0, buf_); G_ST1(S##a1, S##b1, 1, buf_); G_ST1(S##a2, S##b2, 2, buf_); G_ST1(S##a3, S##b3, 3, buf_); } while (0)
; template <class AL, class BL>
; DI void gemm_core(AL al, BL bl, int m0, int n0, int K, char* smem, f32x16 (&acc)[2][2]) {
;     ...
;   G_LOAD(x, 0);
;   G_STORE(x, 0);
;   G_LOAD(x, 1);
;   G_LOAD(y, (nk > 2) ? 2 : 1);
;   __syncthreads();
;   for (int kt = 0; kt < nk; kt += 2) {
;     G_TILE(0, x, true, (kt + 3 < nk), kt + 3);
;     __syncthreads();
;     G_TILE(1, y, (kt + 2 < nk), (kt + 4 < nk), kt + 4);
;     __syncthreads();
	ds_read_b128 v[0:3], v56 offset:30720
	ds_read_b128 v[4:7], v56 offset:33280
	ds_read_b128 v[8:11], v57 offset:30720
	ds_read_b128 v[12:15], v57 offset:33280
	ds_read_b128 v[16:19], v57 offset:35840
	ds_read_b128 v[20:23], v57 offset:38400
	ds_read_b128 v[24:27], v56 offset:30752
	ds_read_b128 v[28:31], v56 offset:33312
	s_waitcnt lgkmcnt(4)
	v_mfma_f32_32x32x16_bf16 v[66:81], v[0:3], v[8:11], v[66:81]
	v_mfma_f32_32x32x16_bf16 v[82:97], v[0:3], v[12:15], v[82:97]
	s_waitcnt vmcnt(6)
	ds_write_b128 v58, v[32:35] offset:0
	ds_write_b128 v58, v[36:39] offset:5120
	s_waitcnt lgkmcnt(4)
	v_mfma_f32_32x32x16_bf16 v[98:113], v[0:3], v[16:19], v[98:113]
	v_mfma_f32_32x32x16_bf16 v[114:129], v[0:3], v[20:23], v[114:129]
	ds_read_b128 v[0:3], v57 offset:30752
	ds_write_b128 v58, v[40:43] offset:10240
	ds_write_b128 v58, v[44:47] offset:15360
	v_mfma_f32_32x32x16_bf16 v[130:145], v[4:7], v[8:11], v[130:145]
	v_mfma_f32_32x32x16_bf16 v[146:161], v[4:7], v[12:15], v[146:161]
	ds_write_b128 v58, v[48:51] offset:20480
	ds_write_b128 v58, v[52:55] offset:25600
	v_mfma_f32_32x32x16_bf16 v[162:177], v[4:7], v[16:19], v[162:177]
	v_mfma_f32_32x32x16_bf16 v[178:193], v[4:7], v[20:23], v[178:193]
	ds_read_b128 v[4:7], v57 offset:33312
	ds_read_b128 v[8:11], v57 offset:35872
	ds_read_b128 v[12:15], v57 offset:38432
	s_waitcnt lgkmcnt(2)
	v_mfma_f32_32x32x16_bf16 v[66:81], v[24:27], v[0:3], v[66:81]
	global_load_dwordx4 v[32:35], v[240:241], off offset:2304
	global_load_dwordx4 v[36:39], v[242:243], off offset:2304
	v_mfma_f32_32x32x16_bf16 v[82:97], v[24:27], v[4:7], v[82:97]
	s_waitcnt lgkmcnt(0)
	v_mfma_f32_32x32x16_bf16 v[98:113], v[24:27], v[8:11], v[98:113]
	global_load_dwordx4 v[40:43], v[244:245], off offset:256
	global_load_dwordx4 v[44:47], v[246:247], off offset:256
	v_mfma_f32_32x32x16_bf16 v[114:129], v[24:27], v[12:15], v[114:129]
	v_mfma_f32_32x32x16_bf16 v[130:145], v[28:31], v[0:3], v[130:145]
	global_load_dwordx4 v[48:51], v[248:249], off offset:256
	global_load_dwordx4 v[52:55], v[250:251], off offset:256
	v_mfma_f32_32x32x16_bf16 v[146:161], v[28:31], v[4:7], v[146:161]
	v_mfma_f32_32x32x16_bf16 v[162:177], v[28:31], v[8:11], v[162:177]
	v_mfma_f32_32x32x16_bf16 v[178:193], v[28:31], v[12:15], v[178:193]
	s_waitcnt lgkmcnt(0)
	s_barrier
	ds_read_b128 v[0:3], v56 offset:0
	ds_read_b128 v[4:7], v56 offset:2560
	ds_read_b128 v[8:11], v57 offset:0
	ds_read_b128 v[12:15], v57 offset:2560
	ds_read_b128 v[16:19], v57 offset:5120
	ds_read_b128 v[20:23], v57 offset:7680
	ds_read_b128 v[24:27], v56 offset:32
	ds_read_b128 v[28:31], v56 offset:2592
	s_waitcnt lgkmcnt(4)
	v_mfma_f32_32x32x16_bf16 v[66:81], v[0:3], v[8:11], v[66:81]
	v_mfma_f32_32x32x16_bf16 v[82:97], v[0:3], v[12:15], v[82:97]
	s_waitcnt vmcnt(6)
	ds_write_b128 v58, v[214:217] offset:30720
	ds_write_b128 v58, v[218:221] offset:35840
	s_waitcnt lgkmcnt(4)
	v_mfma_f32_32x32x16_bf16 v[98:113], v[0:3], v[16:19], v[98:113]
	v_mfma_f32_32x32x16_bf16 v[114:129], v[0:3], v[20:23], v[114:129]
	ds_read_b128 v[0:3], v57 offset:32
	ds_write_b128 v58, v[222:225] offset:40960
	ds_write_b128 v58, v[228:231] offset:46080
	v_mfma_f32_32x32x16_bf16 v[130:145], v[4:7], v[8:11], v[130:145]
	v_mfma_f32_32x32x16_bf16 v[146:161], v[4:7], v[12:15], v[146:161]
	ds_write_b128 v58, v[232:235] offset:51200
	ds_write_b128 v58, v[236:239] offset:56320
	v_mfma_f32_32x32x16_bf16 v[162:177], v[4:7], v[16:19], v[162:177]
	v_mfma_f32_32x32x16_bf16 v[178:193], v[4:7], v[20:23], v[178:193]
	ds_read_b128 v[4:7], v57 offset:2592
	ds_read_b128 v[8:11], v57 offset:5152
	ds_read_b128 v[12:15], v57 offset:7712
	s_waitcnt lgkmcnt(2)
	v_mfma_f32_32x32x16_bf16 v[66:81], v[24:27], v[0:3], v[66:81]
	global_load_dwordx4 v[214:217], v[240:241], off offset:2368
	global_load_dwordx4 v[218:221], v[242:243], off offset:2368
	v_mfma_f32_32x32x16_bf16 v[82:97], v[24:27], v[4:7], v[82:97]
	s_waitcnt lgkmcnt(0)
	v_mfma_f32_32x32x16_bf16 v[98:113], v[24:27], v[8:11], v[98:113]
	global_load_dwordx4 v[222:225], v[244:245], off offset:320
	global_load_dwordx4 v[228:231], v[246:247], off offset:320
	v_mfma_f32_32x32x16_bf16 v[114:129], v[24:27], v[12:15], v[114:129]
	v_mfma_f32_32x32x16_bf16 v[130:145], v[28:31], v[0:3], v[130:145]
	global_load_dwordx4 v[232:235], v[248:249], off offset:320
	global_load_dwordx4 v[236:239], v[250:251], off offset:320
	v_mfma_f32_32x32x16_bf16 v[146:161], v[28:31], v[4:7], v[146:161]
	v_mfma_f32_32x32x16_bf16 v[162:177], v[28:31], v[8:11], v[162:177]
	v_mfma_f32_32x32x16_bf16 v[178:193], v[28:31], v[12:15], v[178:193]
	s_waitcnt lgkmcnt(0)
	s_barrier
; #define G_LOAD(S, kt_) do { G_LD1(S##a0, S##b0, 0, kt_); G_LD1(S##a1, S##b1, 1, kt_); G_LD1(S##a2, S##b2, 2, kt_); G_LD1(S##a3, S##b3, 3, kt_); } while (0)
; #define G_STORE(S, buf_) do { G_ST1(S##a0, S##b0, 0, buf_); G_ST1(S##a1, S##b1, 1, buf_); G_ST1(S##a2, S##b2, 2, buf_); G_ST1(S##a3, S##b3, 3, buf_); } while (0)
; template <class AL, class BL>
; DI void gemm_core(AL al, BL bl, int m0, int n0, int K, char* smem, f32x16 (&acc)[2][2]) {
;     ...
;   G_LOAD(x, 0);
;   G_STORE(x, 0);
;   G_LOAD(x, 1);
;   G_LOAD(y, (nk > 2) ? 2 : 1);
;   __syncthreads();
;   for (int kt = 0; kt < nk; kt += 2) {
;     G_TILE(0, x, true, (kt + 3 < nk), kt + 3);
;     __syncthreads();
;     G_TILE(1, y, (kt + 2 < nk), (kt + 4 < nk), kt + 4);
;     __syncthreads();
	ds_read_b128 v[0:3], v56 offset:30720
	ds_read_b128 v[4:7], v56 offset:33280
	ds_read_b128 v[8:11], v57 offset:30720
	ds_read_b128 v[12:15], v57 offset:33280
	ds_read_b128 v[16:19], v57 offset:35840
	ds_read_b128 v[20:23], v57 offset:38400
	ds_read_b128 v[24:27], v56 offset:30752
	ds_read_b128 v[28:31], v56 offset:33312
	s_waitcnt lgkmcnt(4)
	v_mfma_f32_32x32x16_bf16 v[66:81], v[0:3], v[8:11], v[66:81]
	v_mfma_f32_32x32x16_bf16 v[82:97], v[0:3], v[12:15], v[82:97]
	s_waitcnt vmcnt(6)
	ds_write_b128 v58, v[32:35] offset:0
	ds_write_b128 v58, v[36:39] offset:5120
	s_waitcnt lgkmcnt(4)
	v_mfma_f32_32x32x16_bf16 v[98:113], v[0:3], v[16:19], v[98:113]
	v_mfma_f32_32x32x16_bf16 v[114:129], v[0:3], v[20:23], v[114:129]
	ds_read_b128 v[0:3], v57 offset:30752
	ds_write_b128 v58, v[40:43] offset:10240
	ds_write_b128 v58, v[44:47] offset:15360
	v_mfma_f32_32x32x16_bf16 v[130:145], v[4:7], v[8:11], v[130:145]
	v_mfma_f32_32x32x16_bf16 v[146:161], v[4:7], v[12:15], v[146:161]
	ds_write_b128 v58, v[48:51] offset:20480
	ds_write_b128 v58, v[52:55] offset:25600
	v_mfma_f32_32x32x16_bf16 v[162:177], v[4:7], v[16:19], v[162:177]
	v_mfma_f32_32x32x16_bf16 v[178:193], v[4:7], v[20:23], v[178:193]
	ds_read_b128 v[4:7], v57 offset:33312
	ds_read_b128 v[8:11], v57 offset:35872
	ds_read_b128 v[12:15], v57 offset:38432
	s_waitcnt lgkmcnt(2)
	v_mfma_f32_32x32x16_bf16 v[66:81], v[24:27], v[0:3], v[66:81]
	global_load_dwordx4 v[32:35], v[240:241], off offset:2432
	global_load_dwordx4 v[36:39], v[242:243], off offset:2432
	v_mfma_f32_32x32x16_bf16 v[82:97], v[24:27], v[4:7], v[82:97]
	s_waitcnt lgkmcnt(0)
	v_mfma_f32_32x32x16_bf16 v[98:113], v[24:27], v[8:11], v[98:113]
	global_load_dwordx4 v[40:43], v[244:245], off offset:384
	global_load_dwordx4 v[44:47], v[246:247], off offset:384
	v_mfma_f32_32x32x16_bf16 v[114:129], v[24:27], v[12:15], v[114:129]
	v_mfma_f32_32x32x16_bf16 v[130:145], v[28:31], v[0:3], v[130:145]
	global_load_dwordx4 v[48:51], v[248:249], off offset:384
	global_load_dwordx4 v[52:55], v[250:251], off offset:384
	v_mfma_f32_32x32x16_bf16 v[146:161], v[28:31], v[4:7], v[146:161]
	v_mfma_f32_32x32x16_bf16 v[162:177], v[28:31], v[8:11], v[162:177]
	v_mfma_f32_32x32x16_bf16 v[178:193], v[28:31], v[12:15], v[178:193]
	s_waitcnt lgkmcnt(0)
	s_barrier
	ds_read_b128 v[0:3], v56 offset:0
	ds_read_b128 v[4:7], v56 offset:2560
	ds_read_b128 v[8:11], v57 offset:0
	ds_read_b128 v[12:15], v57 offset:2560
	ds_read_b128 v[16:19], v57 offset:5120
	ds_read_b128 v[20:23], v57 offset:7680
	ds_read_b128 v[24:27], v56 offset:32
	ds_read_b128 v[28:31], v56 offset:2592
	s_waitcnt lgkmcnt(4)
	v_mfma_f32_32x32x16_bf16 v[66:81], v[0:3], v[8:11], v[66:81]
	v_mfma_f32_32x32x16_bf16 v[82:97], v[0:3], v[12:15], v[82:97]
	s_waitcnt vmcnt(6)
	ds_write_b128 v58, v[214:217] offset:30720
	ds_write_b128 v58, v[218:221] offset:35840
	s_waitcnt lgkmcnt(4)
	v_mfma_f32_32x32x16_bf16 v[98:113], v[0:3], v[16:19], v[98:113]
	v_mfma_f32_32x32x16_bf16 v[114:129], v[0:3], v[20:23], v[114:129]
	ds_read_b128 v[0:3], v57 offset:32
	ds_write_b128 v58, v[222:225] offset:40960
	ds_write_b128 v58, v[228:231] offset:46080
	v_mfma_f32_32x32x16_bf16 v[130:145], v[4:7], v[8:11], v[130:145]
	v_mfma_f32_32x32x16_bf16 v[146:161], v[4:7], v[12:15], v[146:161]
	ds_write_b128 v58, v[232:235] offset:51200
	ds_write_b128 v58, v[236:239] offset:56320
	v_mfma_f32_32x32x16_bf16 v[162:177], v[4:7], v[16:19], v[162:177]
	v_mfma_f32_32x32x16_bf16 v[178:193], v[4:7], v[20:23], v[178:193]
	ds_read_b128 v[4:7], v57 offset:2592
	ds_read_b128 v[8:11], v57 offset:5152
	ds_read_b128 v[12:15], v57 offset:7712
	s_waitcnt lgkmcnt(2)
	v_mfma_f32_32x32x16_bf16 v[66:81], v[24:27], v[0:3], v[66:81]
	global_load_dwordx4 v[214:217], v[240:241], off offset:2496
	global_load_dwordx4 v[218:221], v[242:243], off offset:2496
	v_mfma_f32_32x32x16_bf16 v[82:97], v[24:27], v[4:7], v[82:97]
	s_waitcnt lgkmcnt(0)
	v_mfma_f32_32x32x16_bf16 v[98:113], v[24:27], v[8:11], v[98:113]
	global_load_dwordx4 v[222:225], v[244:245], off offset:448
	global_load_dwordx4 v[228:231], v[246:247], off offset:448
	v_mfma_f32_32x32x16_bf16 v[114:129], v[24:27], v[12:15], v[114:129]
	v_mfma_f32_32x32x16_bf16 v[130:145], v[28:31], v[0:3], v[130:145]
	global_load_dwordx4 v[232:235], v[248:249], off offset:448
	global_load_dwordx4 v[236:239], v[250:251], off offset:448
	v_mfma_f32_32x32x16_bf16 v[146:161], v[28:31], v[4:7], v[146:161]
	v_mfma_f32_32x32x16_bf16 v[162:177], v[28:31], v[8:11], v[162:177]
	v_mfma_f32_32x32x16_bf16 v[178:193], v[28:31], v[12:15], v[178:193]
	s_waitcnt lgkmcnt(0)
	s_barrier
; #define G_LOAD(S, kt_) do { G_LD1(S##a0, S##b0, 0, kt_); G_LD1(S##a1, S##b1, 1, kt_); G_LD1(S##a2, S##b2, 2, kt_); G_LD1(S##a3, S##b3, 3, kt_); } while (0)
; #define G_STORE(S, buf_) do { G_ST1(S##a0, S##b0, 0, buf_); G_ST1(S##a1, S##b1, 1, buf_); G_ST1(S##a2, S##b2, 2, buf_); G_ST1(S##a3, S##b3, 3, buf_); } while (0)
; template <class AL, class BL>
; DI void gemm_core(AL al, BL bl, int m0, int n0, int K, char* smem, f32x16 (&acc)[2][2]) {
;     ...
;   G_LOAD(x, 0);
;   G_STORE(x, 0);
;   G_LOAD(x, 1);
;   G_LOAD(y, (nk > 2) ? 2 : 1);
;   __syncthreads();
;   for (int kt = 0; kt < nk; kt += 2) {
;     G_TILE(0, x, true, (kt + 3 < nk), kt + 3);
;     __syncthreads();
;     G_TILE(1, y, (kt + 2 < nk), (kt + 4 < nk), kt + 4);
;     __syncthreads();
	ds_read_b128 v[0:3], v56 offset:30720
	ds_read_b128 v[4:7], v56 offset:33280
	ds_read_b128 v[8:11], v57 offset:30720
	ds_read_b128 v[12:15], v57 offset:33280
	ds_read_b128 v[16:19], v57 offset:35840
	ds_read_b128 v[20:23], v57 offset:38400
	ds_read_b128 v[24:27], v56 offset:30752
	ds_read_b128 v[28:31], v56 offset:33312
	s_waitcnt lgkmcnt(4)
	v_mfma_f32_32x32x16_bf16 v[66:81], v[0:3], v[8:11], v[66:81]
	v_mfma_f32_32x32x16_bf16 v[82:97], v[0:3], v[12:15], v[82:97]
	s_waitcnt vmcnt(6)
	ds_write_b128 v58, v[32:35] offset:0
	ds_write_b128 v58, v[36:39] offset:5120
	s_waitcnt lgkmcnt(4)
	v_mfma_f32_32x32x16_bf16 v[98:113], v[0:3], v[16:19], v[98:113]
	v_mfma_f32_32x32x16_bf16 v[114:129], v[0:3], v[20:23], v[114:129]
	ds_read_b128 v[0:3], v57 offset:30752
	ds_write_b128 v58, v[40:43] offset:10240
	ds_write_b128 v58, v[44:47] offset:15360
	v_mfma_f32_32x32x16_bf16 v[130:145], v[4:7], v[8:11], v[130:145]
	v_mfma_f32_32x32x16_bf16 v[146:161], v[4:7], v[12:15], v[146:161]
	ds_write_b128 v58, v[48:51] offset:20480
	ds_write_b128 v58, v[52:55] offset:25600
	v_mfma_f32_32x32x16_bf16 v[162:177], v[4:7], v[16:19], v[162:177]
	v_mfma_f32_32x32x16_bf16 v[178:193], v[4:7], v[20:23], v[178:193]
	ds_read_b128 v[4:7], v57 offset:33312
	ds_read_b128 v[8:11], v57 offset:35872
	ds_read_b128 v[12:15], v57 offset:38432
	s_waitcnt lgkmcnt(2)
	v_mfma_f32_32x32x16_bf16 v[66:81], v[24:27], v[0:3], v[66:81]
	global_load_dwordx4 v[32:35], v[240:241], off offset:2560
	global_load_dwordx4 v[36:39], v[242:243], off offset:2560
	v_mfma_f32_32x32x16_bf16 v[82:97], v[24:27], v[4:7], v[82:97]
	s_waitcnt lgkmcnt(0)
	v_mfma_f32_32x32x16_bf16 v[98:113], v[24:27], v[8:11], v[98:113]
	global_load_dwordx4 v[40:43], v[244:245], off offset:512
	global_load_dwordx4 v[44:47], v[246:247], off offset:512
	v_mfma_f32_32x32x16_bf16 v[114:129], v[24:27], v[12:15], v[114:129]
	v_mfma_f32_32x32x16_bf16 v[130:145], v[28:31], v[0:3], v[130:145]
	global_load_dwordx4 v[48:51], v[248:249], off offset:512
	global_load_dwordx4 v[52:55], v[250:251], off offset:512
	v_mfma_f32_32x32x16_bf16 v[146:161], v[28:31], v[4:7], v[146:161]
	v_mfma_f32_32x32x16_bf16 v[162:177], v[28:31], v[8:11], v[162:177]
	v_mfma_f32_32x32x16_bf16 v[178:193], v[28:31], v[12:15], v[178:193]
	s_waitcnt lgkmcnt(0)
	s_barrier
	ds_read_b128 v[0:3], v56 offset:0
	ds_read_b128 v[4:7], v56 offset:2560
	ds_read_b128 v[8:11], v57 offset:0
	ds_read_b128 v[12:15], v57 offset:2560
	ds_read_b128 v[16:19], v57 offset:5120
	ds_read_b128 v[20:23], v57 offset:7680
	ds_read_b128 v[24:27], v56 offset:32
	ds_read_b128 v[28:31], v56 offset:2592
	s_waitcnt lgkmcnt(4)
	v_mfma_f32_32x32x16_bf16 v[66:81], v[0:3], v[8:11], v[66:81]
	v_mfma_f32_32x32x16_bf16 v[82:97], v[0:3], v[12:15], v[82:97]
	s_waitcnt vmcnt(6)
	ds_write_b128 v58, v[214:217] offset:30720
	ds_write_b128 v58, v[218:221] offset:35840
	s_waitcnt lgkmcnt(4)
	v_mfma_f32_32x32x16_bf16 v[98:113], v[0:3], v[16:19], v[98:113]
	v_mfma_f32_32x32x16_bf16 v[114:129], v[0:3], v[20:23], v[114:129]
	ds_read_b128 v[0:3], v57 offset:32
	ds_write_b128 v58, v[222:225] offset:40960
	ds_write_b128 v58, v[228:231] offset:46080
	v_mfma_f32_32x32x16_bf16 v[130:145], v[4:7], v[8:11], v[130:145]
	v_mfma_f32_32x32x16_bf16 v[146:161], v[4:7], v[12:15], v[146:161]
	ds_write_b128 v58, v[232:235] offset:51200
	ds_write_b128 v58, v[236:239] offset:56320
	v_mfma_f32_32x32x16_bf16 v[162:177], v[4:7], v[16:19], v[162:177]
	v_mfma_f32_32x32x16_bf16 v[178:193], v[4:7], v[20:23], v[178:193]
	ds_read_b128 v[4:7], v57 offset:2592
	ds_read_b128 v[8:11], v57 offset:5152
	ds_read_b128 v[12:15], v57 offset:7712
	s_waitcnt lgkmcnt(2)
	v_mfma_f32_32x32x16_bf16 v[66:81], v[24:27], v[0:3], v[66:81]
	global_load_dwordx4 v[214:217], v[240:241], off offset:2624
	global_load_dwordx4 v[218:221], v[242:243], off offset:2624
	v_mfma_f32_32x32x16_bf16 v[82:97], v[24:27], v[4:7], v[82:97]
	s_waitcnt lgkmcnt(0)
	v_mfma_f32_32x32x16_bf16 v[98:113], v[24:27], v[8:11], v[98:113]
	global_load_dwordx4 v[222:225], v[244:245], off offset:576
	global_load_dwordx4 v[228:231], v[246:247], off offset:576
	v_mfma_f32_32x32x16_bf16 v[114:129], v[24:27], v[12:15], v[114:129]
	v_mfma_f32_32x32x16_bf16 v[130:145], v[28:31], v[0:3], v[130:145]
	global_load_dwordx4 v[232:235], v[248:249], off offset:576
	global_load_dwordx4 v[236:239], v[250:251], off offset:576
	v_mfma_f32_32x32x16_bf16 v[146:161], v[28:31], v[4:7], v[146:161]
	v_mfma_f32_32x32x16_bf16 v[162:177], v[28:31], v[8:11], v[162:177]
	v_mfma_f32_32x32x16_bf16 v[178:193], v[28:31], v[12:15], v[178:193]
	s_waitcnt lgkmcnt(0)
	s_barrier
; #define G_LOAD(S, kt_) do { G_LD1(S##a0, S##b0, 0, kt_); G_LD1(S##a1, S##b1, 1, kt_); G_LD1(S##a2, S##b2, 2, kt_); G_LD1(S##a3, S##b3, 3, kt_); } while (0)
; #define G_STORE(S, buf_) do { G_ST1(S##a0, S##b0, 0, buf_); G_ST1(S##a1, S##b1, 1, buf_); G_ST1(S##a2, S##b2, 2, buf_); G_ST1(S##a3, S##b3, 3, buf_); } while (0)
; template <class AL, class BL>
; DI void gemm_core(AL al, BL bl, int m0, int n0, int K, char* smem, f32x16 (&acc)[2][2]) {
;     ...
;   G_LOAD(x, 0);
;   G_STORE(x, 0);
;   G_LOAD(x, 1);
;   G_LOAD(y, (nk > 2) ? 2 : 1);
;   __syncthreads();
;   for (int kt = 0; kt < nk; kt += 2) {
;     G_TILE(0, x, true, (kt + 3 < nk), kt + 3);
;     __syncthreads();
;     G_TILE(1, y, (kt + 2 < nk), (kt + 4 < nk), kt + 4);
;     __syncthreads();
	ds_read_b128 v[0:3], v56 offset:30720
	ds_read_b128 v[4:7], v56 offset:33280
	ds_read_b128 v[8:11], v57 offset:30720
	ds_read_b128 v[12:15], v57 offset:33280
	ds_read_b128 v[16:19], v57 offset:35840
	ds_read_b128 v[20:23], v57 offset:38400
	ds_read_b128 v[24:27], v56 offset:30752
	ds_read_b128 v[28:31], v56 offset:33312
	s_waitcnt lgkmcnt(4)
	v_mfma_f32_32x32x16_bf16 v[66:81], v[0:3], v[8:11], v[66:81]
	v_mfma_f32_32x32x16_bf16 v[82:97], v[0:3], v[12:15], v[82:97]
	s_waitcnt vmcnt(6)
	ds_write_b128 v58, v[32:35] offset:0
	ds_write_b128 v58, v[36:39] offset:5120
	s_waitcnt lgkmcnt(4)
	v_mfma_f32_32x32x16_bf16 v[98:113], v[0:3], v[16:19], v[98:113]
	v_mfma_f32_32x32x16_bf16 v[114:129], v[0:3], v[20:23], v[114:129]
	ds_read_b128 v[0:3], v57 offset:30752
	ds_write_b128 v58, v[40:43] offset:10240
	ds_write_b128 v58, v[44:47] offset:15360
	v_mfma_f32_32x32x16_bf16 v[130:145], v[4:7], v[8:11], v[130:145]
	v_mfma_f32_32x32x16_bf16 v[146:161], v[4:7], v[12:15], v[146:161]
	ds_write_b128 v58, v[48:51] offset:20480
	ds_write_b128 v58, v[52:55] offset:25600
	v_mfma_f32_32x32x16_bf16 v[162:177], v[4:7], v[16:19], v[162:177]
	v_mfma_f32_32x32x16_bf16 v[178:193], v[4:7], v[20:23], v[178:193]
	ds_read_b128 v[4:7], v57 offset:33312
	ds_read_b128 v[8:11], v57 offset:35872
	ds_read_b128 v[12:15], v57 offset:38432
	s_waitcnt lgkmcnt(2)
	v_mfma_f32_32x32x16_bf16 v[66:81], v[24:27], v[0:3], v[66:81]
	global_load_dwordx4 v[32:35], v[240:241], off offset:2688
	global_load_dwordx4 v[36:39], v[242:243], off offset:2688
	v_mfma_f32_32x32x16_bf16 v[82:97], v[24:27], v[4:7], v[82:97]
	s_waitcnt lgkmcnt(0)
	v_mfma_f32_32x32x16_bf16 v[98:113], v[24:27], v[8:11], v[98:113]
	global_load_dwordx4 v[40:43], v[244:245], off offset:640
	global_load_dwordx4 v[44:47], v[246:247], off offset:640
	v_mfma_f32_32x32x16_bf16 v[114:129], v[24:27], v[12:15], v[114:129]
	v_mfma_f32_32x32x16_bf16 v[130:145], v[28:31], v[0:3], v[130:145]
	global_load_dwordx4 v[48:51], v[248:249], off offset:640
	global_load_dwordx4 v[52:55], v[250:251], off offset:640
	v_mfma_f32_32x32x16_bf16 v[146:161], v[28:31], v[4:7], v[146:161]
	v_mfma_f32_32x32x16_bf16 v[162:177], v[28:31], v[8:11], v[162:177]
	v_mfma_f32_32x32x16_bf16 v[178:193], v[28:31], v[12:15], v[178:193]
	s_waitcnt lgkmcnt(0)
	s_barrier
	ds_read_b128 v[0:3], v56 offset:0
	ds_read_b128 v[4:7], v56 offset:2560
	ds_read_b128 v[8:11], v57 offset:0
	ds_read_b128 v[12:15], v57 offset:2560
	ds_read_b128 v[16:19], v57 offset:5120
	ds_read_b128 v[20:23], v57 offset:7680
	ds_read_b128 v[24:27], v56 offset:32
	ds_read_b128 v[28:31], v56 offset:2592
	s_waitcnt lgkmcnt(4)
	v_mfma_f32_32x32x16_bf16 v[66:81], v[0:3], v[8:11], v[66:81]
	v_mfma_f32_32x32x16_bf16 v[82:97], v[0:3], v[12:15], v[82:97]
	s_waitcnt vmcnt(6)
	ds_write_b128 v58, v[214:217] offset:30720
	ds_write_b128 v58, v[218:221] offset:35840
	s_waitcnt lgkmcnt(4)
	v_mfma_f32_32x32x16_bf16 v[98:113], v[0:3], v[16:19], v[98:113]
	v_mfma_f32_32x32x16_bf16 v[114:129], v[0:3], v[20:23], v[114:129]
	ds_read_b128 v[0:3], v57 offset:32
	ds_write_b128 v58, v[222:225] offset:40960
	ds_write_b128 v58, v[228:231] offset:46080
	v_mfma_f32_32x32x16_bf16 v[130:145], v[4:7], v[8:11], v[130:145]
	v_mfma_f32_32x32x16_bf16 v[146:161], v[4:7], v[12:15], v[146:161]
	ds_write_b128 v58, v[232:235] offset:51200
	ds_write_b128 v58, v[236:239] offset:56320
	v_mfma_f32_32x32x16_bf16 v[162:177], v[4:7], v[16:19], v[162:177]
	v_mfma_f32_32x32x16_bf16 v[178:193], v[4:7], v[20:23], v[178:193]
	ds_read_b128 v[4:7], v57 offset:2592
	ds_read_b128 v[8:11], v57 offset:5152
	ds_read_b128 v[12:15], v57 offset:7712
	s_waitcnt lgkmcnt(2)
	v_mfma_f32_32x32x16_bf16 v[66:81], v[24:27], v[0:3], v[66:81]
	global_load_dwordx4 v[214:217], v[240:241], off offset:2752
	global_load_dwordx4 v[218:221], v[242:243], off offset:2752
	v_mfma_f32_32x32x16_bf16 v[82:97], v[24:27], v[4:7], v[82:97]
	s_waitcnt lgkmcnt(0)
	v_mfma_f32_32x32x16_bf16 v[98:113], v[24:27], v[8:11], v[98:113]
	global_load_dwordx4 v[222:225], v[244:245], off offset:704
	global_load_dwordx4 v[228:231], v[246:247], off offset:704
	v_mfma_f32_32x32x16_bf16 v[114:129], v[24:27], v[12:15], v[114:129]
	v_mfma_f32_32x32x16_bf16 v[130:145], v[28:31], v[0:3], v[130:145]
	global_load_dwordx4 v[232:235], v[248:249], off offset:704
	global_load_dwordx4 v[236:239], v[250:251], off offset:704
	v_mfma_f32_32x32x16_bf16 v[146:161], v[28:31], v[4:7], v[146:161]
	v_mfma_f32_32x32x16_bf16 v[162:177], v[28:31], v[8:11], v[162:177]
	v_mfma_f32_32x32x16_bf16 v[178:193], v[28:31], v[12:15], v[178:193]
	s_waitcnt lgkmcnt(0)
	s_barrier
; #define G_LOAD(S, kt_) do { G_LD1(S##a0, S##b0, 0, kt_); G_LD1(S##a1, S##b1, 1, kt_); G_LD1(S##a2, S##b2, 2, kt_); G_LD1(S##a3, S##b3, 3, kt_); } while (0)
; #define G_STORE(S, buf_) do { G_ST1(S##a0, S##b0, 0, buf_); G_ST1(S##a1, S##b1, 1, buf_); G_ST1(S##a2, S##b2, 2, buf_); G_ST1(S##a3, S##b3, 3, buf_); } while (0)
; template <class AL, class BL>
; DI void gemm_core(AL al, BL bl, int m0, int n0, int K, char* smem, f32x16 (&acc)[2][2]) {
;     ...
;   G_LOAD(x, 0);
;   G_STORE(x, 0);
;   G_LOAD(x, 1);
;   G_LOAD(y, (nk > 2) ? 2 : 1);
;   __syncthreads();
;   for (int kt = 0; kt < nk; kt += 2) {
;     G_TILE(0, x, true, (kt + 3 < nk), kt + 3);
;     __syncthreads();
;     G_TILE(1, y, (kt + 2 < nk), (kt + 4 < nk), kt + 4);
;     __syncthreads();
	ds_read_b128 v[0:3], v56 offset:30720
	ds_read_b128 v[4:7], v56 offset:33280
	ds_read_b128 v[8:11], v57 offset:30720
	ds_read_b128 v[12:15], v57 offset:33280
	ds_read_b128 v[16:19], v57 offset:35840
	ds_read_b128 v[20:23], v57 offset:38400
	ds_read_b128 v[24:27], v56 offset:30752
	ds_read_b128 v[28:31], v56 offset:33312
	s_waitcnt lgkmcnt(4)
	v_mfma_f32_32x32x16_bf16 v[66:81], v[0:3], v[8:11], v[66:81]
	v_mfma_f32_32x32x16_bf16 v[82:97], v[0:3], v[12:15], v[82:97]
	s_waitcnt vmcnt(6)
	ds_write_b128 v58, v[32:35] offset:0
	ds_write_b128 v58, v[36:39] offset:5120
	s_waitcnt lgkmcnt(4)
	v_mfma_f32_32x32x16_bf16 v[98:113], v[0:3], v[16:19], v[98:113]
	v_mfma_f32_32x32x16_bf16 v[114:129], v[0:3], v[20:23], v[114:129]
	ds_read_b128 v[0:3], v57 offset:30752
	ds_write_b128 v58, v[40:43] offset:10240
	ds_write_b128 v58, v[44:47] offset:15360
	v_mfma_f32_32x32x16_bf16 v[130:145], v[4:7], v[8:11], v[130:145]
	v_mfma_f32_32x32x16_bf16 v[146:161], v[4:7], v[12:15], v[146:161]
	ds_write_b128 v58, v[48:51] offset:20480
	ds_write_b128 v58, v[52:55] offset:25600
	v_mfma_f32_32x32x16_bf16 v[162:177], v[4:7], v[16:19], v[162:177]
	v_mfma_f32_32x32x16_bf16 v[178:193], v[4:7], v[20:23], v[178:193]
	ds_read_b128 v[4:7], v57 offset:33312
	ds_read_b128 v[8:11], v57 offset:35872
	ds_read_b128 v[12:15], v57 offset:38432
	s_waitcnt lgkmcnt(2)
	v_mfma_f32_32x32x16_bf16 v[66:81], v[24:27], v[0:3], v[66:81]
	global_load_dwordx4 v[32:35], v[240:241], off offset:2816
	global_load_dwordx4 v[36:39], v[242:243], off offset:2816
	v_mfma_f32_32x32x16_bf16 v[82:97], v[24:27], v[4:7], v[82:97]
	s_waitcnt lgkmcnt(0)
	v_mfma_f32_32x32x16_bf16 v[98:113], v[24:27], v[8:11], v[98:113]
	global_load_dwordx4 v[40:43], v[244:245], off offset:768
	global_load_dwordx4 v[44:47], v[246:247], off offset:768
	v_mfma_f32_32x32x16_bf16 v[114:129], v[24:27], v[12:15], v[114:129]
	v_mfma_f32_32x32x16_bf16 v[130:145], v[28:31], v[0:3], v[130:145]
	global_load_dwordx4 v[48:51], v[248:249], off offset:768
	global_load_dwordx4 v[52:55], v[250:251], off offset:768
	v_mfma_f32_32x32x16_bf16 v[146:161], v[28:31], v[4:7], v[146:161]
	v_mfma_f32_32x32x16_bf16 v[162:177], v[28:31], v[8:11], v[162:177]
	v_mfma_f32_32x32x16_bf16 v[178:193], v[28:31], v[12:15], v[178:193]
	s_waitcnt lgkmcnt(0)
	s_barrier
	ds_read_b128 v[0:3], v56 offset:0
	ds_read_b128 v[4:7], v56 offset:2560
	ds_read_b128 v[8:11], v57 offset:0
	ds_read_b128 v[12:15], v57 offset:2560
	ds_read_b128 v[16:19], v57 offset:5120
	ds_read_b128 v[20:23], v57 offset:7680
	ds_read_b128 v[24:27], v56 offset:32
	ds_read_b128 v[28:31], v56 offset:2592
	s_waitcnt lgkmcnt(4)
	v_mfma_f32_32x32x16_bf16 v[66:81], v[0:3], v[8:11], v[66:81]
	v_mfma_f32_32x32x16_bf16 v[82:97], v[0:3], v[12:15], v[82:97]
	s_waitcnt vmcnt(6)
	ds_write_b128 v58, v[214:217] offset:30720
	ds_write_b128 v58, v[218:221] offset:35840
	s_waitcnt lgkmcnt(4)
	v_mfma_f32_32x32x16_bf16 v[98:113], v[0:3], v[16:19], v[98:113]
	v_mfma_f32_32x32x16_bf16 v[114:129], v[0:3], v[20:23], v[114:129]
	ds_read_b128 v[0:3], v57 offset:32
	ds_write_b128 v58, v[222:225] offset:40960
	ds_write_b128 v58, v[228:231] offset:46080
	v_mfma_f32_32x32x16_bf16 v[130:145], v[4:7], v[8:11], v[130:145]
	v_mfma_f32_32x32x16_bf16 v[146:161], v[4:7], v[12:15], v[146:161]
	ds_write_b128 v58, v[232:235] offset:51200
	ds_write_b128 v58, v[236:239] offset:56320
	v_mfma_f32_32x32x16_bf16 v[162:177], v[4:7], v[16:19], v[162:177]
	v_mfma_f32_32x32x16_bf16 v[178:193], v[4:7], v[20:23], v[178:193]
	ds_read_b128 v[4:7], v57 offset:2592
	ds_read_b128 v[8:11], v57 offset:5152
	ds_read_b128 v[12:15], v57 offset:7712
	s_waitcnt lgkmcnt(2)
	v_mfma_f32_32x32x16_bf16 v[66:81], v[24:27], v[0:3], v[66:81]
	global_load_dwordx4 v[214:217], v[240:241], off offset:2880
	global_load_dwordx4 v[218:221], v[242:243], off offset:2880
	v_mfma_f32_32x32x16_bf16 v[82:97], v[24:27], v[4:7], v[82:97]
	s_waitcnt lgkmcnt(0)
	v_mfma_f32_32x32x16_bf16 v[98:113], v[24:27], v[8:11], v[98:113]
	global_load_dwordx4 v[222:225], v[244:245], off offset:832
	global_load_dwordx4 v[228:231], v[246:247], off offset:832
	v_mfma_f32_32x32x16_bf16 v[114:129], v[24:27], v[12:15], v[114:129]
	v_mfma_f32_32x32x16_bf16 v[130:145], v[28:31], v[0:3], v[130:145]
	global_load_dwordx4 v[232:235], v[248:249], off offset:832
	global_load_dwordx4 v[236:239], v[250:251], off offset:832
	v_mfma_f32_32x32x16_bf16 v[146:161], v[28:31], v[4:7], v[146:161]
	v_mfma_f32_32x32x16_bf16 v[162:177], v[28:31], v[8:11], v[162:177]
	v_mfma_f32_32x32x16_bf16 v[178:193], v[28:31], v[12:15], v[178:193]
	s_waitcnt lgkmcnt(0)
	s_barrier
; #define G_LOAD(S, kt_) do { G_LD1(S##a0, S##b0, 0, kt_); G_LD1(S##a1, S##b1, 1, kt_); G_LD1(S##a2, S##b2, 2, kt_); G_LD1(S##a3, S##b3, 3, kt_); } while (0)
; #define G_STORE(S, buf_) do { G_ST1(S##a0, S##b0, 0, buf_); G_ST1(S##a1, S##b1, 1, buf_); G_ST1(S##a2, S##b2, 2, buf_); G_ST1(S##a3, S##b3, 3, buf_); } while (0)
; template <class AL, class BL>
; DI void gemm_core(AL al, BL bl, int m0, int n0, int K, char* smem, f32x16 (&acc)[2][2]) {
;     ...
;   G_LOAD(x, 0);
;   G_STORE(x, 0);
;   G_LOAD(x, 1);
;   G_LOAD(y, (nk > 2) ? 2 : 1);
;   __syncthreads();
;   for (int kt = 0; kt < nk; kt += 2) {
;     G_TILE(0, x, true, (kt + 3 < nk), kt + 3);
;     __syncthreads();
;     G_TILE(1, y, (kt + 2 < nk), (kt + 4 < nk), kt + 4);
;     __syncthreads();
	ds_read_b128 v[0:3], v56 offset:30720
	ds_read_b128 v[4:7], v56 offset:33280
	ds_read_b128 v[8:11], v57 offset:30720
	ds_read_b128 v[12:15], v57 offset:33280
	ds_read_b128 v[16:19], v57 offset:35840
	ds_read_b128 v[20:23], v57 offset:38400
	ds_read_b128 v[24:27], v56 offset:30752
	ds_read_b128 v[28:31], v56 offset:33312
	s_waitcnt lgkmcnt(4)
	v_mfma_f32_32x32x16_bf16 v[66:81], v[0:3], v[8:11], v[66:81]
	v_mfma_f32_32x32x16_bf16 v[82:97], v[0:3], v[12:15], v[82:97]
	s_waitcnt vmcnt(6)
	ds_write_b128 v58, v[32:35] offset:0
	ds_write_b128 v58, v[36:39] offset:5120
	s_waitcnt lgkmcnt(4)
	v_mfma_f32_32x32x16_bf16 v[98:113], v[0:3], v[16:19], v[98:113]
	v_mfma_f32_32x32x16_bf16 v[114:129], v[0:3], v[20:23], v[114:129]
	ds_read_b128 v[0:3], v57 offset:30752
	ds_write_b128 v58, v[40:43] offset:10240
	ds_write_b128 v58, v[44:47] offset:15360
	v_mfma_f32_32x32x16_bf16 v[130:145], v[4:7], v[8:11], v[130:145]
	v_mfma_f32_32x32x16_bf16 v[146:161], v[4:7], v[12:15], v[146:161]
	ds_write_b128 v58, v[48:51] offset:20480
	ds_write_b128 v58, v[52:55] offset:25600
	v_mfma_f32_32x32x16_bf16 v[162:177], v[4:7], v[16:19], v[162:177]
	v_mfma_f32_32x32x16_bf16 v[178:193], v[4:7], v[20:23], v[178:193]
	ds_read_b128 v[4:7], v57 offset:33312
	ds_read_b128 v[8:11], v57 offset:35872
	ds_read_b128 v[12:15], v57 offset:38432
	s_waitcnt lgkmcnt(2)
	v_mfma_f32_32x32x16_bf16 v[66:81], v[24:27], v[0:3], v[66:81]
	global_load_dwordx4 v[32:35], v[240:241], off offset:2944
	global_load_dwordx4 v[36:39], v[242:243], off offset:2944
	v_mfma_f32_32x32x16_bf16 v[82:97], v[24:27], v[4:7], v[82:97]
	s_waitcnt lgkmcnt(0)
	v_mfma_f32_32x32x16_bf16 v[98:113], v[24:27], v[8:11], v[98:113]
	global_load_dwordx4 v[40:43], v[244:245], off offset:896
	global_load_dwordx4 v[44:47], v[246:247], off offset:896
	v_mfma_f32_32x32x16_bf16 v[114:129], v[24:27], v[12:15], v[114:129]
	v_mfma_f32_32x32x16_bf16 v[130:145], v[28:31], v[0:3], v[130:145]
	global_load_dwordx4 v[48:51], v[248:249], off offset:896
	global_load_dwordx4 v[52:55], v[250:251], off offset:896
	v_mfma_f32_32x32x16_bf16 v[146:161], v[28:31], v[4:7], v[146:161]
	v_mfma_f32_32x32x16_bf16 v[162:177], v[28:31], v[8:11], v[162:177]
	v_mfma_f32_32x32x16_bf16 v[178:193], v[28:31], v[12:15], v[178:193]
	s_waitcnt lgkmcnt(0)
	s_barrier
	ds_read_b128 v[0:3], v56 offset:0
	ds_read_b128 v[4:7], v56 offset:2560
	ds_read_b128 v[8:11], v57 offset:0
	ds_read_b128 v[12:15], v57 offset:2560
	ds_read_b128 v[16:19], v57 offset:5120
	ds_read_b128 v[20:23], v57 offset:7680
	ds_read_b128 v[24:27], v56 offset:32
	ds_read_b128 v[28:31], v56 offset:2592
	s_waitcnt lgkmcnt(4)
	v_mfma_f32_32x32x16_bf16 v[66:81], v[0:3], v[8:11], v[66:81]
	v_mfma_f32_32x32x16_bf16 v[82:97], v[0:3], v[12:15], v[82:97]
	s_waitcnt vmcnt(6)
	ds_write_b128 v58, v[214:217] offset:30720
	ds_write_b128 v58, v[218:221] offset:35840
	s_waitcnt lgkmcnt(4)
	v_mfma_f32_32x32x16_bf16 v[98:113], v[0:3], v[16:19], v[98:113]
	v_mfma_f32_32x32x16_bf16 v[114:129], v[0:3], v[20:23], v[114:129]
	ds_read_b128 v[0:3], v57 offset:32
	ds_write_b128 v58, v[222:225] offset:40960
	ds_write_b128 v58, v[228:231] offset:46080
	v_mfma_f32_32x32x16_bf16 v[130:145], v[4:7], v[8:11], v[130:145]
	v_mfma_f32_32x32x16_bf16 v[146:161], v[4:7], v[12:15], v[146:161]
	ds_write_b128 v58, v[232:235] offset:51200
	ds_write_b128 v58, v[236:239] offset:56320
	v_mfma_f32_32x32x16_bf16 v[162:177], v[4:7], v[16:19], v[162:177]
	v_mfma_f32_32x32x16_bf16 v[178:193], v[4:7], v[20:23], v[178:193]
	ds_read_b128 v[4:7], v57 offset:2592
	ds_read_b128 v[8:11], v57 offset:5152
	ds_read_b128 v[12:15], v57 offset:7712
	s_waitcnt lgkmcnt(2)
	v_mfma_f32_32x32x16_bf16 v[66:81], v[24:27], v[0:3], v[66:81]
	global_load_dwordx4 v[214:217], v[240:241], off offset:3008
	global_load_dwordx4 v[218:221], v[242:243], off offset:3008
	v_mfma_f32_32x32x16_bf16 v[82:97], v[24:27], v[4:7], v[82:97]
	s_waitcnt lgkmcnt(0)
	v_mfma_f32_32x32x16_bf16 v[98:113], v[24:27], v[8:11], v[98:113]
	global_load_dwordx4 v[222:225], v[244:245], off offset:960
	global_load_dwordx4 v[228:231], v[246:247], off offset:960
	v_mfma_f32_32x32x16_bf16 v[114:129], v[24:27], v[12:15], v[114:129]
	v_mfma_f32_32x32x16_bf16 v[130:145], v[28:31], v[0:3], v[130:145]
	global_load_dwordx4 v[232:235], v[248:249], off offset:960
	global_load_dwordx4 v[236:239], v[250:251], off offset:960
	v_mfma_f32_32x32x16_bf16 v[146:161], v[28:31], v[4:7], v[146:161]
	v_mfma_f32_32x32x16_bf16 v[162:177], v[28:31], v[8:11], v[162:177]
	v_mfma_f32_32x32x16_bf16 v[178:193], v[28:31], v[12:15], v[178:193]
	s_waitcnt lgkmcnt(0)
	s_barrier
; #define G_LOAD(S, kt_) do { G_LD1(S##a0, S##b0, 0, kt_); G_LD1(S##a1, S##b1, 1, kt_); G_LD1(S##a2, S##b2, 2, kt_); G_LD1(S##a3, S##b3, 3, kt_); } while (0)
; #define G_STORE(S, buf_) do { G_ST1(S##a0, S##b0, 0, buf_); G_ST1(S##a1, S##b1, 1, buf_); G_ST1(S##a2, S##b2, 2, buf_); G_ST1(S##a3, S##b3, 3, buf_); } while (0)
; template <class AL, class BL>
; DI void gemm_core(AL al, BL bl, int m0, int n0, int K, char* smem, f32x16 (&acc)[2][2]) {
;     ...
;   G_LOAD(x, 0);
;   G_STORE(x, 0);
;   G_LOAD(x, 1);
;   G_LOAD(y, (nk > 2) ? 2 : 1);
;   __syncthreads();
;   for (int kt = 0; kt < nk; kt += 2) {
;     G_TILE(0, x, true, (kt + 3 < nk), kt + 3);
;     __syncthreads();
;     G_TILE(1, y, (kt + 2 < nk), (kt + 4 < nk), kt + 4);
;     __syncthreads();
	ds_read_b128 v[0:3], v56 offset:30720
	ds_read_b128 v[4:7], v56 offset:33280
	ds_read_b128 v[8:11], v57 offset:30720
	ds_read_b128 v[12:15], v57 offset:33280
	ds_read_b128 v[16:19], v57 offset:35840
	ds_read_b128 v[20:23], v57 offset:38400
	ds_read_b128 v[24:27], v56 offset:30752
	ds_read_b128 v[28:31], v56 offset:33312
	s_waitcnt lgkmcnt(4)
	v_mfma_f32_32x32x16_bf16 v[66:81], v[0:3], v[8:11], v[66:81]
	v_mfma_f32_32x32x16_bf16 v[82:97], v[0:3], v[12:15], v[82:97]
	s_waitcnt vmcnt(6)
	ds_write_b128 v58, v[32:35] offset:0
	ds_write_b128 v58, v[36:39] offset:5120
	s_waitcnt lgkmcnt(4)
	v_mfma_f32_32x32x16_bf16 v[98:113], v[0:3], v[16:19], v[98:113]
	v_mfma_f32_32x32x16_bf16 v[114:129], v[0:3], v[20:23], v[114:129]
	ds_read_b128 v[0:3], v57 offset:30752
	ds_write_b128 v58, v[40:43] offset:10240
	ds_write_b128 v58, v[44:47] offset:15360
	v_mfma_f32_32x32x16_bf16 v[130:145], v[4:7], v[8:11], v[130:145]
	v_mfma_f32_32x32x16_bf16 v[146:161], v[4:7], v[12:15], v[146:161]
	ds_write_b128 v58, v[48:51] offset:20480
	ds_write_b128 v58, v[52:55] offset:25600
	v_mfma_f32_32x32x16_bf16 v[162:177], v[4:7], v[16:19], v[162:177]
	v_mfma_f32_32x32x16_bf16 v[178:193], v[4:7], v[20:23], v[178:193]
	ds_read_b128 v[4:7], v57 offset:33312
	ds_read_b128 v[8:11], v57 offset:35872
	ds_read_b128 v[12:15], v57 offset:38432
	s_waitcnt lgkmcnt(2)
	v_mfma_f32_32x32x16_bf16 v[66:81], v[24:27], v[0:3], v[66:81]
	global_load_dwordx4 v[32:35], v[240:241], off offset:3072
	global_load_dwordx4 v[36:39], v[242:243], off offset:3072
	v_mfma_f32_32x32x16_bf16 v[82:97], v[24:27], v[4:7], v[82:97]
	s_waitcnt lgkmcnt(0)
	v_mfma_f32_32x32x16_bf16 v[98:113], v[24:27], v[8:11], v[98:113]
	global_load_dwordx4 v[40:43], v[244:245], off offset:1024
	global_load_dwordx4 v[44:47], v[246:247], off offset:1024
	v_mfma_f32_32x32x16_bf16 v[114:129], v[24:27], v[12:15], v[114:129]
	v_mfma_f32_32x32x16_bf16 v[130:145], v[28:31], v[0:3], v[130:145]
	global_load_dwordx4 v[48:51], v[248:249], off offset:1024
	global_load_dwordx4 v[52:55], v[250:251], off offset:1024
	v_mfma_f32_32x32x16_bf16 v[146:161], v[28:31], v[4:7], v[146:161]
	v_mfma_f32_32x32x16_bf16 v[162:177], v[28:31], v[8:11], v[162:177]
	v_mfma_f32_32x32x16_bf16 v[178:193], v[28:31], v[12:15], v[178:193]
	s_waitcnt lgkmcnt(0)
	s_barrier
	ds_read_b128 v[0:3], v56 offset:0
	ds_read_b128 v[4:7], v56 offset:2560
	ds_read_b128 v[8:11], v57 offset:0
	ds_read_b128 v[12:15], v57 offset:2560
	ds_read_b128 v[16:19], v57 offset:5120
	ds_read_b128 v[20:23], v57 offset:7680
	ds_read_b128 v[24:27], v56 offset:32
	ds_read_b128 v[28:31], v56 offset:2592
	s_waitcnt lgkmcnt(4)
	v_mfma_f32_32x32x16_bf16 v[66:81], v[0:3], v[8:11], v[66:81]
	v_mfma_f32_32x32x16_bf16 v[82:97], v[0:3], v[12:15], v[82:97]
	s_waitcnt vmcnt(6)
	ds_write_b128 v58, v[214:217] offset:30720
	ds_write_b128 v58, v[218:221] offset:35840
	s_waitcnt lgkmcnt(4)
	v_mfma_f32_32x32x16_bf16 v[98:113], v[0:3], v[16:19], v[98:113]
	v_mfma_f32_32x32x16_bf16 v[114:129], v[0:3], v[20:23], v[114:129]
	ds_read_b128 v[0:3], v57 offset:32
	ds_write_b128 v58, v[222:225] offset:40960
	ds_write_b128 v58, v[228:231] offset:46080
	v_mfma_f32_32x32x16_bf16 v[130:145], v[4:7], v[8:11], v[130:145]
	v_mfma_f32_32x32x16_bf16 v[146:161], v[4:7], v[12:15], v[146:161]
	ds_write_b128 v58, v[232:235] offset:51200
	ds_write_b128 v58, v[236:239] offset:56320
	v_mfma_f32_32x32x16_bf16 v[162:177], v[4:7], v[16:19], v[162:177]
	v_mfma_f32_32x32x16_bf16 v[178:193], v[4:7], v[20:23], v[178:193]
	ds_read_b128 v[4:7], v57 offset:2592
	ds_read_b128 v[8:11], v57 offset:5152
	ds_read_b128 v[12:15], v57 offset:7712
	s_waitcnt lgkmcnt(2)
	v_mfma_f32_32x32x16_bf16 v[66:81], v[24:27], v[0:3], v[66:81]
	global_load_dwordx4 v[214:217], v[240:241], off offset:3136
	global_load_dwordx4 v[218:221], v[242:243], off offset:3136
	v_mfma_f32_32x32x16_bf16 v[82:97], v[24:27], v[4:7], v[82:97]
	s_waitcnt lgkmcnt(0)
	v_mfma_f32_32x32x16_bf16 v[98:113], v[24:27], v[8:11], v[98:113]
	global_load_dwordx4 v[222:225], v[244:245], off offset:1088
	global_load_dwordx4 v[228:231], v[246:247], off offset:1088
	v_mfma_f32_32x32x16_bf16 v[114:129], v[24:27], v[12:15], v[114:129]
	v_mfma_f32_32x32x16_bf16 v[130:145], v[28:31], v[0:3], v[130:145]
	global_load_dwordx4 v[232:235], v[248:249], off offset:1088
	global_load_dwordx4 v[236:239], v[250:251], off offset:1088
	v_mfma_f32_32x32x16_bf16 v[146:161], v[28:31], v[4:7], v[146:161]
	v_mfma_f32_32x32x16_bf16 v[162:177], v[28:31], v[8:11], v[162:177]
	v_mfma_f32_32x32x16_bf16 v[178:193], v[28:31], v[12:15], v[178:193]
	s_waitcnt lgkmcnt(0)
	s_barrier
; #define G_LOAD(S, kt_) do { G_LD1(S##a0, S##b0, 0, kt_); G_LD1(S##a1, S##b1, 1, kt_); G_LD1(S##a2, S##b2, 2, kt_); G_LD1(S##a3, S##b3, 3, kt_); } while (0)
; #define G_STORE(S, buf_) do { G_ST1(S##a0, S##b0, 0, buf_); G_ST1(S##a1, S##b1, 1, buf_); G_ST1(S##a2, S##b2, 2, buf_); G_ST1(S##a3, S##b3, 3, buf_); } while (0)
; template <class AL, class BL>
; DI void gemm_core(AL al, BL bl, int m0, int n0, int K, char* smem, f32x16 (&acc)[2][2]) {
;     ...
;   G_LOAD(x, 0);
;   G_STORE(x, 0);
;   G_LOAD(x, 1);
;   G_LOAD(y, (nk > 2) ? 2 : 1);
;   __syncthreads();
;   for (int kt = 0; kt < nk; kt += 2) {
;     G_TILE(0, x, true, (kt + 3 < nk), kt + 3);
;     __syncthreads();
;     G_TILE(1, y, (kt + 2 < nk), (kt + 4 < nk), kt + 4);
;     __syncthreads();
	ds_read_b128 v[0:3], v56 offset:30720
	ds_read_b128 v[4:7], v56 offset:33280
	ds_read_b128 v[8:11], v57 offset:30720
	ds_read_b128 v[12:15], v57 offset:33280
	ds_read_b128 v[16:19], v57 offset:35840
	ds_read_b128 v[20:23], v57 offset:38400
	ds_read_b128 v[24:27], v56 offset:30752
	ds_read_b128 v[28:31], v56 offset:33312
	s_waitcnt lgkmcnt(4)
	v_mfma_f32_32x32x16_bf16 v[66:81], v[0:3], v[8:11], v[66:81]
	v_mfma_f32_32x32x16_bf16 v[82:97], v[0:3], v[12:15], v[82:97]
	s_waitcnt vmcnt(6)
	ds_write_b128 v58, v[32:35] offset:0
	ds_write_b128 v58, v[36:39] offset:5120
	s_waitcnt lgkmcnt(4)
	v_mfma_f32_32x32x16_bf16 v[98:113], v[0:3], v[16:19], v[98:113]
	v_mfma_f32_32x32x16_bf16 v[114:129], v[0:3], v[20:23], v[114:129]
	ds_read_b128 v[0:3], v57 offset:30752
	ds_write_b128 v58, v[40:43] offset:10240
	ds_write_b128 v58, v[44:47] offset:15360
	v_mfma_f32_32x32x16_bf16 v[130:145], v[4:7], v[8:11], v[130:145]
	v_mfma_f32_32x32x16_bf16 v[146:161], v[4:7], v[12:15], v[146:161]
	ds_write_b128 v58, v[48:51] offset:20480
	ds_write_b128 v58, v[52:55] offset:25600
	v_mfma_f32_32x32x16_bf16 v[162:177], v[4:7], v[16:19], v[162:177]
	v_mfma_f32_32x32x16_bf16 v[178:193], v[4:7], v[20:23], v[178:193]
	ds_read_b128 v[4:7], v57 offset:33312
	ds_read_b128 v[8:11], v57 offset:35872
	ds_read_b128 v[12:15], v57 offset:38432
	s_waitcnt lgkmcnt(2)
	v_mfma_f32_32x32x16_bf16 v[66:81], v[24:27], v[0:3], v[66:81]
	global_load_dwordx4 v[32:35], v[240:241], off offset:3200
	global_load_dwordx4 v[36:39], v[242:243], off offset:3200
	v_mfma_f32_32x32x16_bf16 v[82:97], v[24:27], v[4:7], v[82:97]
	s_waitcnt lgkmcnt(0)
	v_mfma_f32_32x32x16_bf16 v[98:113], v[24:27], v[8:11], v[98:113]
	global_load_dwordx4 v[40:43], v[244:245], off offset:1152
	global_load_dwordx4 v[44:47], v[246:247], off offset:1152
	v_mfma_f32_32x32x16_bf16 v[114:129], v[24:27], v[12:15], v[114:129]
	v_mfma_f32_32x32x16_bf16 v[130:145], v[28:31], v[0:3], v[130:145]
	global_load_dwordx4 v[48:51], v[248:249], off offset:1152
	global_load_dwordx4 v[52:55], v[250:251], off offset:1152
	v_mfma_f32_32x32x16_bf16 v[146:161], v[28:31], v[4:7], v[146:161]
	v_mfma_f32_32x32x16_bf16 v[162:177], v[28:31], v[8:11], v[162:177]
	v_mfma_f32_32x32x16_bf16 v[178:193], v[28:31], v[12:15], v[178:193]
	s_waitcnt lgkmcnt(0)
	s_barrier
	ds_read_b128 v[0:3], v56 offset:0
	ds_read_b128 v[4:7], v56 offset:2560
	ds_read_b128 v[8:11], v57 offset:0
	ds_read_b128 v[12:15], v57 offset:2560
	ds_read_b128 v[16:19], v57 offset:5120
	ds_read_b128 v[20:23], v57 offset:7680
	ds_read_b128 v[24:27], v56 offset:32
	ds_read_b128 v[28:31], v56 offset:2592
	s_waitcnt lgkmcnt(4)
	v_mfma_f32_32x32x16_bf16 v[66:81], v[0:3], v[8:11], v[66:81]
	v_mfma_f32_32x32x16_bf16 v[82:97], v[0:3], v[12:15], v[82:97]
	s_waitcnt vmcnt(6)
	ds_write_b128 v58, v[214:217] offset:30720
	ds_write_b128 v58, v[218:221] offset:35840
	s_waitcnt lgkmcnt(4)
	v_mfma_f32_32x32x16_bf16 v[98:113], v[0:3], v[16:19], v[98:113]
	v_mfma_f32_32x32x16_bf16 v[114:129], v[0:3], v[20:23], v[114:129]
	ds_read_b128 v[0:3], v57 offset:32
	ds_write_b128 v58, v[222:225] offset:40960
	ds_write_b128 v58, v[228:231] offset:46080
	v_mfma_f32_32x32x16_bf16 v[130:145], v[4:7], v[8:11], v[130:145]
	v_mfma_f32_32x32x16_bf16 v[146:161], v[4:7], v[12:15], v[146:161]
	ds_write_b128 v58, v[232:235] offset:51200
	ds_write_b128 v58, v[236:239] offset:56320
	v_mfma_f32_32x32x16_bf16 v[162:177], v[4:7], v[16:19], v[162:177]
	v_mfma_f32_32x32x16_bf16 v[178:193], v[4:7], v[20:23], v[178:193]
	ds_read_b128 v[4:7], v57 offset:2592
	ds_read_b128 v[8:11], v57 offset:5152
	ds_read_b128 v[12:15], v57 offset:7712
	s_waitcnt lgkmcnt(2)
	v_mfma_f32_32x32x16_bf16 v[66:81], v[24:27], v[0:3], v[66:81]
	global_load_dwordx4 v[214:217], v[240:241], off offset:3264
	global_load_dwordx4 v[218:221], v[242:243], off offset:3264
	v_mfma_f32_32x32x16_bf16 v[82:97], v[24:27], v[4:7], v[82:97]
	s_waitcnt lgkmcnt(0)
	v_mfma_f32_32x32x16_bf16 v[98:113], v[24:27], v[8:11], v[98:113]
	global_load_dwordx4 v[222:225], v[244:245], off offset:1216
	global_load_dwordx4 v[228:231], v[246:247], off offset:1216
	v_mfma_f32_32x32x16_bf16 v[114:129], v[24:27], v[12:15], v[114:129]
	v_mfma_f32_32x32x16_bf16 v[130:145], v[28:31], v[0:3], v[130:145]
	global_load_dwordx4 v[232:235], v[248:249], off offset:1216
	global_load_dwordx4 v[236:239], v[250:251], off offset:1216
	v_mfma_f32_32x32x16_bf16 v[146:161], v[28:31], v[4:7], v[146:161]
	v_mfma_f32_32x32x16_bf16 v[162:177], v[28:31], v[8:11], v[162:177]
	v_mfma_f32_32x32x16_bf16 v[178:193], v[28:31], v[12:15], v[178:193]
	s_waitcnt lgkmcnt(0)
	s_barrier
; #define G_LOAD(S, kt_) do { G_LD1(S##a0, S##b0, 0, kt_); G_LD1(S##a1, S##b1, 1, kt_); G_LD1(S##a2, S##b2, 2, kt_); G_LD1(S##a3, S##b3, 3, kt_); } while (0)
; #define G_STORE(S, buf_) do { G_ST1(S##a0, S##b0, 0, buf_); G_ST1(S##a1, S##b1, 1, buf_); G_ST1(S##a2, S##b2, 2, buf_); G_ST1(S##a3, S##b3, 3, buf_); } while (0)
; template <class AL, class BL>
; DI void gemm_core(AL al, BL bl, int m0, int n0, int K, char* smem, f32x16 (&acc)[2][2]) {
;     ...
;   G_LOAD(x, 0);
;   G_STORE(x, 0);
;   G_LOAD(x, 1);
;   G_LOAD(y, (nk > 2) ? 2 : 1);
;   __syncthreads();
;   for (int kt = 0; kt < nk; kt += 2) {
;     G_TILE(0, x, true, (kt + 3 < nk), kt + 3);
;     __syncthreads();
;     G_TILE(1, y, (kt + 2 < nk), (kt + 4 < nk), kt + 4);
;     __syncthreads();
	ds_read_b128 v[0:3], v56 offset:30720
	ds_read_b128 v[4:7], v56 offset:33280
	ds_read_b128 v[8:11], v57 offset:30720
	ds_read_b128 v[12:15], v57 offset:33280
	ds_read_b128 v[16:19], v57 offset:35840
	ds_read_b128 v[20:23], v57 offset:38400
	ds_read_b128 v[24:27], v56 offset:30752
	ds_read_b128 v[28:31], v56 offset:33312
	s_waitcnt lgkmcnt(4)
	v_mfma_f32_32x32x16_bf16 v[66:81], v[0:3], v[8:11], v[66:81]
	v_mfma_f32_32x32x16_bf16 v[82:97], v[0:3], v[12:15], v[82:97]
	s_waitcnt vmcnt(6)
	ds_write_b128 v58, v[32:35] offset:0
	ds_write_b128 v58, v[36:39] offset:5120
	s_waitcnt lgkmcnt(4)
	v_mfma_f32_32x32x16_bf16 v[98:113], v[0:3], v[16:19], v[98:113]
	v_mfma_f32_32x32x16_bf16 v[114:129], v[0:3], v[20:23], v[114:129]
	ds_read_b128 v[0:3], v57 offset:30752
	ds_write_b128 v58, v[40:43] offset:10240
	ds_write_b128 v58, v[44:47] offset:15360
	v_mfma_f32_32x32x16_bf16 v[130:145], v[4:7], v[8:11], v[130:145]
	v_mfma_f32_32x32x16_bf16 v[146:161], v[4:7], v[12:15], v[146:161]
	ds_write_b128 v58, v[48:51] offset:20480
	ds_write_b128 v58, v[52:55] offset:25600
	v_mfma_f32_32x32x16_bf16 v[162:177], v[4:7], v[16:19], v[162:177]
	v_mfma_f32_32x32x16_bf16 v[178:193], v[4:7], v[20:23], v[178:193]
	ds_read_b128 v[4:7], v57 offset:33312
	ds_read_b128 v[8:11], v57 offset:35872
	ds_read_b128 v[12:15], v57 offset:38432
	s_waitcnt lgkmcnt(2)
	v_mfma_f32_32x32x16_bf16 v[66:81], v[24:27], v[0:3], v[66:81]
	global_load_dwordx4 v[32:35], v[240:241], off offset:3328
	global_load_dwordx4 v[36:39], v[242:243], off offset:3328
	v_mfma_f32_32x32x16_bf16 v[82:97], v[24:27], v[4:7], v[82:97]
	s_waitcnt lgkmcnt(0)
	v_mfma_f32_32x32x16_bf16 v[98:113], v[24:27], v[8:11], v[98:113]
	global_load_dwordx4 v[40:43], v[244:245], off offset:1280
	global_load_dwordx4 v[44:47], v[246:247], off offset:1280
	v_mfma_f32_32x32x16_bf16 v[114:129], v[24:27], v[12:15], v[114:129]
	v_mfma_f32_32x32x16_bf16 v[130:145], v[28:31], v[0:3], v[130:145]
	global_load_dwordx4 v[48:51], v[248:249], off offset:1280
	global_load_dwordx4 v[52:55], v[250:251], off offset:1280
	v_mfma_f32_32x32x16_bf16 v[146:161], v[28:31], v[4:7], v[146:161]
	v_mfma_f32_32x32x16_bf16 v[162:177], v[28:31], v[8:11], v[162:177]
	v_mfma_f32_32x32x16_bf16 v[178:193], v[28:31], v[12:15], v[178:193]
	s_waitcnt lgkmcnt(0)
	s_barrier
	ds_read_b128 v[0:3], v56 offset:0
	ds_read_b128 v[4:7], v56 offset:2560
	ds_read_b128 v[8:11], v57 offset:0
	ds_read_b128 v[12:15], v57 offset:2560
	ds_read_b128 v[16:19], v57 offset:5120
	ds_read_b128 v[20:23], v57 offset:7680
	ds_read_b128 v[24:27], v56 offset:32
	ds_read_b128 v[28:31], v56 offset:2592
	s_waitcnt lgkmcnt(4)
	v_mfma_f32_32x32x16_bf16 v[66:81], v[0:3], v[8:11], v[66:81]
	v_mfma_f32_32x32x16_bf16 v[82:97], v[0:3], v[12:15], v[82:97]
	s_waitcnt vmcnt(6)
	ds_write_b128 v58, v[214:217] offset:30720
	ds_write_b128 v58, v[218:221] offset:35840
	s_waitcnt lgkmcnt(4)
	v_mfma_f32_32x32x16_bf16 v[98:113], v[0:3], v[16:19], v[98:113]
	v_mfma_f32_32x32x16_bf16 v[114:129], v[0:3], v[20:23], v[114:129]
	ds_read_b128 v[0:3], v57 offset:32
	ds_write_b128 v58, v[222:225] offset:40960
	ds_write_b128 v58, v[228:231] offset:46080
	v_mfma_f32_32x32x16_bf16 v[130:145], v[4:7], v[8:11], v[130:145]
	v_mfma_f32_32x32x16_bf16 v[146:161], v[4:7], v[12:15], v[146:161]
	ds_write_b128 v58, v[232:235] offset:51200
	ds_write_b128 v58, v[236:239] offset:56320
	v_mfma_f32_32x32x16_bf16 v[162:177], v[4:7], v[16:19], v[162:177]
	v_mfma_f32_32x32x16_bf16 v[178:193], v[4:7], v[20:23], v[178:193]
	ds_read_b128 v[4:7], v57 offset:2592
	ds_read_b128 v[8:11], v57 offset:5152
	ds_read_b128 v[12:15], v57 offset:7712
	s_waitcnt lgkmcnt(2)
	v_mfma_f32_32x32x16_bf16 v[66:81], v[24:27], v[0:3], v[66:81]
	global_load_dwordx4 v[214:217], v[240:241], off offset:3392
	global_load_dwordx4 v[218:221], v[242:243], off offset:3392
	v_mfma_f32_32x32x16_bf16 v[82:97], v[24:27], v[4:7], v[82:97]
	s_waitcnt lgkmcnt(0)
	v_mfma_f32_32x32x16_bf16 v[98:113], v[24:27], v[8:11], v[98:113]
	global_load_dwordx4 v[222:225], v[244:245], off offset:1344
	global_load_dwordx4 v[228:231], v[246:247], off offset:1344
	v_mfma_f32_32x32x16_bf16 v[114:129], v[24:27], v[12:15], v[114:129]
	v_mfma_f32_32x32x16_bf16 v[130:145], v[28:31], v[0:3], v[130:145]
	global_load_dwordx4 v[232:235], v[248:249], off offset:1344
	global_load_dwordx4 v[236:239], v[250:251], off offset:1344
	v_mfma_f32_32x32x16_bf16 v[146:161], v[28:31], v[4:7], v[146:161]
	v_mfma_f32_32x32x16_bf16 v[162:177], v[28:31], v[8:11], v[162:177]
	v_mfma_f32_32x32x16_bf16 v[178:193], v[28:31], v[12:15], v[178:193]
	s_waitcnt lgkmcnt(0)
	s_barrier
; #define G_LOAD(S, kt_) do { G_LD1(S##a0, S##b0, 0, kt_); G_LD1(S##a1, S##b1, 1, kt_); G_LD1(S##a2, S##b2, 2, kt_); G_LD1(S##a3, S##b3, 3, kt_); } while (0)
; #define G_STORE(S, buf_) do { G_ST1(S##a0, S##b0, 0, buf_); G_ST1(S##a1, S##b1, 1, buf_); G_ST1(S##a2, S##b2, 2, buf_); G_ST1(S##a3, S##b3, 3, buf_); } while (0)
; template <class AL, class BL>
; DI void gemm_core(AL al, BL bl, int m0, int n0, int K, char* smem, f32x16 (&acc)[2][2]) {
;     ...
;   G_LOAD(x, 0);
;   G_STORE(x, 0);
;   G_LOAD(x, 1);
;   G_LOAD(y, (nk > 2) ? 2 : 1);
;   __syncthreads();
;   for (int kt = 0; kt < nk; kt += 2) {
;     G_TILE(0, x, true, (kt + 3 < nk), kt + 3);
;     __syncthreads();
;     G_TILE(1, y, (kt + 2 < nk), (kt + 4 < nk), kt + 4);
;     __syncthreads();
	ds_read_b128 v[0:3], v56 offset:30720
	ds_read_b128 v[4:7], v56 offset:33280
	ds_read_b128 v[8:11], v57 offset:30720
	ds_read_b128 v[12:15], v57 offset:33280
	ds_read_b128 v[16:19], v57 offset:35840
	ds_read_b128 v[20:23], v57 offset:38400
	ds_read_b128 v[24:27], v56 offset:30752
	ds_read_b128 v[28:31], v56 offset:33312
	s_waitcnt lgkmcnt(4)
	v_mfma_f32_32x32x16_bf16 v[66:81], v[0:3], v[8:11], v[66:81]
	v_mfma_f32_32x32x16_bf16 v[82:97], v[0:3], v[12:15], v[82:97]
	s_waitcnt vmcnt(6)
	ds_write_b128 v58, v[32:35] offset:0
	ds_write_b128 v58, v[36:39] offset:5120
	s_waitcnt lgkmcnt(4)
	v_mfma_f32_32x32x16_bf16 v[98:113], v[0:3], v[16:19], v[98:113]
	v_mfma_f32_32x32x16_bf16 v[114:129], v[0:3], v[20:23], v[114:129]
	ds_read_b128 v[0:3], v57 offset:30752
	ds_write_b128 v58, v[40:43] offset:10240
	ds_write_b128 v58, v[44:47] offset:15360
	v_mfma_f32_32x32x16_bf16 v[130:145], v[4:7], v[8:11], v[130:145]
	v_mfma_f32_32x32x16_bf16 v[146:161], v[4:7], v[12:15], v[146:161]
	ds_write_b128 v58, v[48:51] offset:20480
	ds_write_b128 v58, v[52:55] offset:25600
	v_mfma_f32_32x32x16_bf16 v[162:177], v[4:7], v[16:19], v[162:177]
	v_mfma_f32_32x32x16_bf16 v[178:193], v[4:7], v[20:23], v[178:193]
	ds_read_b128 v[4:7], v57 offset:33312
	ds_read_b128 v[8:11], v57 offset:35872
	ds_read_b128 v[12:15], v57 offset:38432
	s_waitcnt lgkmcnt(2)
	v_mfma_f32_32x32x16_bf16 v[66:81], v[24:27], v[0:3], v[66:81]
	global_load_dwordx4 v[32:35], v[240:241], off offset:3456
	global_load_dwordx4 v[36:39], v[242:243], off offset:3456
	v_mfma_f32_32x32x16_bf16 v[82:97], v[24:27], v[4:7], v[82:97]
	s_waitcnt lgkmcnt(0)
	v_mfma_f32_32x32x16_bf16 v[98:113], v[24:27], v[8:11], v[98:113]
	global_load_dwordx4 v[40:43], v[244:245], off offset:1408
	global_load_dwordx4 v[44:47], v[246:247], off offset:1408
	v_mfma_f32_32x32x16_bf16 v[114:129], v[24:27], v[12:15], v[114:129]
	v_mfma_f32_32x32x16_bf16 v[130:145], v[28:31], v[0:3], v[130:145]
	global_load_dwordx4 v[48:51], v[248:249], off offset:1408
	global_load_dwordx4 v[52:55], v[250:251], off offset:1408
	v_mfma_f32_32x32x16_bf16 v[146:161], v[28:31], v[4:7], v[146:161]
	v_mfma_f32_32x32x16_bf16 v[162:177], v[28:31], v[8:11], v[162:177]
	v_mfma_f32_32x32x16_bf16 v[178:193], v[28:31], v[12:15], v[178:193]
	s_waitcnt lgkmcnt(0)
	s_barrier
	ds_read_b128 v[0:3], v56 offset:0
	ds_read_b128 v[4:7], v56 offset:2560
	ds_read_b128 v[8:11], v57 offset:0
	ds_read_b128 v[12:15], v57 offset:2560
	ds_read_b128 v[16:19], v57 offset:5120
	ds_read_b128 v[20:23], v57 offset:7680
	ds_read_b128 v[24:27], v56 offset:32
	ds_read_b128 v[28:31], v56 offset:2592
	s_waitcnt lgkmcnt(4)
	v_mfma_f32_32x32x16_bf16 v[66:81], v[0:3], v[8:11], v[66:81]
	v_mfma_f32_32x32x16_bf16 v[82:97], v[0:3], v[12:15], v[82:97]
	s_waitcnt vmcnt(6)
	ds_write_b128 v58, v[214:217] offset:30720
	ds_write_b128 v58, v[218:221] offset:35840
	s_waitcnt lgkmcnt(4)
	v_mfma_f32_32x32x16_bf16 v[98:113], v[0:3], v[16:19], v[98:113]
	v_mfma_f32_32x32x16_bf16 v[114:129], v[0:3], v[20:23], v[114:129]
	ds_read_b128 v[0:3], v57 offset:32
	ds_write_b128 v58, v[222:225] offset:40960
	ds_write_b128 v58, v[228:231] offset:46080
	v_mfma_f32_32x32x16_bf16 v[130:145], v[4:7], v[8:11], v[130:145]
	v_mfma_f32_32x32x16_bf16 v[146:161], v[4:7], v[12:15], v[146:161]
	ds_write_b128 v58, v[232:235] offset:51200
	ds_write_b128 v58, v[236:239] offset:56320
	v_mfma_f32_32x32x16_bf16 v[162:177], v[4:7], v[16:19], v[162:177]
	v_mfma_f32_32x32x16_bf16 v[178:193], v[4:7], v[20:23], v[178:193]
	ds_read_b128 v[4:7], v57 offset:2592
	ds_read_b128 v[8:11], v57 offset:5152
	ds_read_b128 v[12:15], v57 offset:7712
	s_waitcnt lgkmcnt(2)
	v_mfma_f32_32x32x16_bf16 v[66:81], v[24:27], v[0:3], v[66:81]
	global_load_dwordx4 v[214:217], v[240:241], off offset:3520
	global_load_dwordx4 v[218:221], v[242:243], off offset:3520
	v_mfma_f32_32x32x16_bf16 v[82:97], v[24:27], v[4:7], v[82:97]
	s_waitcnt lgkmcnt(0)
	v_mfma_f32_32x32x16_bf16 v[98:113], v[24:27], v[8:11], v[98:113]
	global_load_dwordx4 v[222:225], v[244:245], off offset:1472
	global_load_dwordx4 v[228:231], v[246:247], off offset:1472
	v_mfma_f32_32x32x16_bf16 v[114:129], v[24:27], v[12:15], v[114:129]
	v_mfma_f32_32x32x16_bf16 v[130:145], v[28:31], v[0:3], v[130:145]
	global_load_dwordx4 v[232:235], v[248:249], off offset:1472
	global_load_dwordx4 v[236:239], v[250:251], off offset:1472
	v_mfma_f32_32x32x16_bf16 v[146:161], v[28:31], v[4:7], v[146:161]
	v_mfma_f32_32x32x16_bf16 v[162:177], v[28:31], v[8:11], v[162:177]
	v_mfma_f32_32x32x16_bf16 v[178:193], v[28:31], v[12:15], v[178:193]
	s_waitcnt lgkmcnt(0)
	s_barrier
; #define G_LOAD(S, kt_) do { G_LD1(S##a0, S##b0, 0, kt_); G_LD1(S##a1, S##b1, 1, kt_); G_LD1(S##a2, S##b2, 2, kt_); G_LD1(S##a3, S##b3, 3, kt_); } while (0)
; #define G_STORE(S, buf_) do { G_ST1(S##a0, S##b0, 0, buf_); G_ST1(S##a1, S##b1, 1, buf_); G_ST1(S##a2, S##b2, 2, buf_); G_ST1(S##a3, S##b3, 3, buf_); } while (0)
; template <class AL, class BL>
; DI void gemm_core(AL al, BL bl, int m0, int n0, int K, char* smem, f32x16 (&acc)[2][2]) {
;     ...
;   G_LOAD(x, 0);
;   G_STORE(x, 0);
;   G_LOAD(x, 1);
;   G_LOAD(y, (nk > 2) ? 2 : 1);
;   __syncthreads();
;   for (int kt = 0; kt < nk; kt += 2) {
;     G_TILE(0, x, true, (kt + 3 < nk), kt + 3);
;     __syncthreads();
;     G_TILE(1, y, (kt + 2 < nk), (kt + 4 < nk), kt + 4);
;     __syncthreads();
	ds_read_b128 v[0:3], v56 offset:30720
	ds_read_b128 v[4:7], v56 offset:33280
	ds_read_b128 v[8:11], v57 offset:30720
	ds_read_b128 v[12:15], v57 offset:33280
	ds_read_b128 v[16:19], v57 offset:35840
	ds_read_b128 v[20:23], v57 offset:38400
	ds_read_b128 v[24:27], v56 offset:30752
	ds_read_b128 v[28:31], v56 offset:33312
	s_waitcnt lgkmcnt(4)
	v_mfma_f32_32x32x16_bf16 v[66:81], v[0:3], v[8:11], v[66:81]
	v_mfma_f32_32x32x16_bf16 v[82:97], v[0:3], v[12:15], v[82:97]
	s_waitcnt vmcnt(6)
	ds_write_b128 v58, v[32:35] offset:0
	ds_write_b128 v58, v[36:39] offset:5120
	s_waitcnt lgkmcnt(4)
	v_mfma_f32_32x32x16_bf16 v[98:113], v[0:3], v[16:19], v[98:113]
	v_mfma_f32_32x32x16_bf16 v[114:129], v[0:3], v[20:23], v[114:129]
	ds_read_b128 v[0:3], v57 offset:30752
	ds_write_b128 v58, v[40:43] offset:10240
	ds_write_b128 v58, v[44:47] offset:15360
	v_mfma_f32_32x32x16_bf16 v[130:145], v[4:7], v[8:11], v[130:145]
	v_mfma_f32_32x32x16_bf16 v[146:161], v[4:7], v[12:15], v[146:161]
	ds_write_b128 v58, v[48:51] offset:20480
	ds_write_b128 v58, v[52:55] offset:25600
	v_mfma_f32_32x32x16_bf16 v[162:177], v[4:7], v[16:19], v[162:177]
	v_mfma_f32_32x32x16_bf16 v[178:193], v[4:7], v[20:23], v[178:193]
	ds_read_b128 v[4:7], v57 offset:33312
	ds_read_b128 v[8:11], v57 offset:35872
	ds_read_b128 v[12:15], v57 offset:38432
	s_waitcnt lgkmcnt(2)
	v_mfma_f32_32x32x16_bf16 v[66:81], v[24:27], v[0:3], v[66:81]
	global_load_dwordx4 v[32:35], v[240:241], off offset:3584
	global_load_dwordx4 v[36:39], v[242:243], off offset:3584
	v_mfma_f32_32x32x16_bf16 v[82:97], v[24:27], v[4:7], v[82:97]
	s_waitcnt lgkmcnt(0)
	v_mfma_f32_32x32x16_bf16 v[98:113], v[24:27], v[8:11], v[98:113]
	global_load_dwordx4 v[40:43], v[244:245], off offset:1536
	global_load_dwordx4 v[44:47], v[246:247], off offset:1536
	v_mfma_f32_32x32x16_bf16 v[114:129], v[24:27], v[12:15], v[114:129]
	v_mfma_f32_32x32x16_bf16 v[130:145], v[28:31], v[0:3], v[130:145]
	global_load_dwordx4 v[48:51], v[248:249], off offset:1536
	global_load_dwordx4 v[52:55], v[250:251], off offset:1536
	v_mfma_f32_32x32x16_bf16 v[146:161], v[28:31], v[4:7], v[146:161]
	v_mfma_f32_32x32x16_bf16 v[162:177], v[28:31], v[8:11], v[162:177]
	v_mfma_f32_32x32x16_bf16 v[178:193], v[28:31], v[12:15], v[178:193]
	s_waitcnt lgkmcnt(0)
	s_barrier
	ds_read_b128 v[0:3], v56 offset:0
	ds_read_b128 v[4:7], v56 offset:2560
	ds_read_b128 v[8:11], v57 offset:0
	ds_read_b128 v[12:15], v57 offset:2560
	ds_read_b128 v[16:19], v57 offset:5120
	ds_read_b128 v[20:23], v57 offset:7680
	ds_read_b128 v[24:27], v56 offset:32
	ds_read_b128 v[28:31], v56 offset:2592
	s_waitcnt lgkmcnt(4)
	v_mfma_f32_32x32x16_bf16 v[66:81], v[0:3], v[8:11], v[66:81]
	v_mfma_f32_32x32x16_bf16 v[82:97], v[0:3], v[12:15], v[82:97]
	s_waitcnt vmcnt(6)
	ds_write_b128 v58, v[214:217] offset:30720
	ds_write_b128 v58, v[218:221] offset:35840
	s_waitcnt lgkmcnt(4)
	v_mfma_f32_32x32x16_bf16 v[98:113], v[0:3], v[16:19], v[98:113]
	v_mfma_f32_32x32x16_bf16 v[114:129], v[0:3], v[20:23], v[114:129]
	ds_read_b128 v[0:3], v57 offset:32
	ds_write_b128 v58, v[222:225] offset:40960
	ds_write_b128 v58, v[228:231] offset:46080
	v_mfma_f32_32x32x16_bf16 v[130:145], v[4:7], v[8:11], v[130:145]
	v_mfma_f32_32x32x16_bf16 v[146:161], v[4:7], v[12:15], v[146:161]
	ds_write_b128 v58, v[232:235] offset:51200
	ds_write_b128 v58, v[236:239] offset:56320
	v_mfma_f32_32x32x16_bf16 v[162:177], v[4:7], v[16:19], v[162:177]
	v_mfma_f32_32x32x16_bf16 v[178:193], v[4:7], v[20:23], v[178:193]
	ds_read_b128 v[4:7], v57 offset:2592
	ds_read_b128 v[8:11], v57 offset:5152
	ds_read_b128 v[12:15], v57 offset:7712
	s_waitcnt lgkmcnt(2)
	v_mfma_f32_32x32x16_bf16 v[66:81], v[24:27], v[0:3], v[66:81]
	global_load_dwordx4 v[214:217], v[240:241], off offset:3648
	global_load_dwordx4 v[218:221], v[242:243], off offset:3648
	v_mfma_f32_32x32x16_bf16 v[82:97], v[24:27], v[4:7], v[82:97]
	s_waitcnt lgkmcnt(0)
	v_mfma_f32_32x32x16_bf16 v[98:113], v[24:27], v[8:11], v[98:113]
	global_load_dwordx4 v[222:225], v[244:245], off offset:1600
	global_load_dwordx4 v[228:231], v[246:247], off offset:1600
	v_mfma_f32_32x32x16_bf16 v[114:129], v[24:27], v[12:15], v[114:129]
	v_mfma_f32_32x32x16_bf16 v[130:145], v[28:31], v[0:3], v[130:145]
	global_load_dwordx4 v[232:235], v[248:249], off offset:1600
	global_load_dwordx4 v[236:239], v[250:251], off offset:1600
	v_mfma_f32_32x32x16_bf16 v[146:161], v[28:31], v[4:7], v[146:161]
	v_mfma_f32_32x32x16_bf16 v[162:177], v[28:31], v[8:11], v[162:177]
	v_mfma_f32_32x32x16_bf16 v[178:193], v[28:31], v[12:15], v[178:193]
	s_waitcnt lgkmcnt(0)
	s_barrier
; template <class AL, class BL>
; DI void gemm_core(AL al, BL bl, int m0, int n0, int K, char* smem, f32x16 (&acc)[2][2]) {
;     ...
;   for (int kt = 0; kt < nk; kt += 2) {
;     G_TILE(0, x, true, (kt + 3 < nk), kt + 3);
;     __syncthreads();
;     G_TILE(1, y, (kt + 2 < nk), (kt + 4 < nk), kt + 4);
;     __syncthreads();
;   }
	ds_read_b128 v[0:3], v56 offset:30720
	ds_read_b128 v[4:7], v56 offset:33280
	ds_read_b128 v[8:11], v57 offset:30720
	ds_read_b128 v[12:15], v57 offset:33280
	ds_read_b128 v[16:19], v57 offset:35840
	ds_read_b128 v[20:23], v57 offset:38400
	ds_read_b128 v[24:27], v56 offset:30752
	ds_read_b128 v[28:31], v56 offset:33312
	s_waitcnt lgkmcnt(4)
	v_mfma_f32_32x32x16_bf16 v[66:81], v[0:3], v[8:11], v[66:81]
	v_mfma_f32_32x32x16_bf16 v[82:97], v[0:3], v[12:15], v[82:97]
	s_waitcnt vmcnt(6)
	ds_write_b128 v58, v[32:35] offset:0
	ds_write_b128 v58, v[36:39] offset:5120
	s_waitcnt lgkmcnt(4)
	v_mfma_f32_32x32x16_bf16 v[98:113], v[0:3], v[16:19], v[98:113]
	v_mfma_f32_32x32x16_bf16 v[114:129], v[0:3], v[20:23], v[114:129]
	ds_read_b128 v[0:3], v57 offset:30752
	ds_write_b128 v58, v[40:43] offset:10240
	ds_write_b128 v58, v[44:47] offset:15360
	v_mfma_f32_32x32x16_bf16 v[130:145], v[4:7], v[8:11], v[130:145]
	v_mfma_f32_32x32x16_bf16 v[146:161], v[4:7], v[12:15], v[146:161]
	ds_write_b128 v58, v[48:51] offset:20480
	ds_write_b128 v58, v[52:55] offset:25600
	v_mfma_f32_32x32x16_bf16 v[162:177], v[4:7], v[16:19], v[162:177]
	v_mfma_f32_32x32x16_bf16 v[178:193], v[4:7], v[20:23], v[178:193]
	ds_read_b128 v[4:7], v57 offset:33312
	ds_read_b128 v[8:11], v57 offset:35872
	ds_read_b128 v[12:15], v57 offset:38432
	s_waitcnt lgkmcnt(2)
	v_mfma_f32_32x32x16_bf16 v[66:81], v[24:27], v[0:3], v[66:81]
	global_load_dwordx4 v[32:35], v[240:241], off offset:3712
	global_load_dwordx4 v[36:39], v[242:243], off offset:3712
	v_mfma_f32_32x32x16_bf16 v[82:97], v[24:27], v[4:7], v[82:97]
	s_waitcnt lgkmcnt(0)
	v_mfma_f32_32x32x16_bf16 v[98:113], v[24:27], v[8:11], v[98:113]
	global_load_dwordx4 v[40:43], v[244:245], off offset:1664
	global_load_dwordx4 v[44:47], v[246:247], off offset:1664
	v_mfma_f32_32x32x16_bf16 v[114:129], v[24:27], v[12:15], v[114:129]
	v_mfma_f32_32x32x16_bf16 v[130:145], v[28:31], v[0:3], v[130:145]
	global_load_dwordx4 v[48:51], v[248:249], off offset:1664
	global_load_dwordx4 v[52:55], v[250:251], off offset:1664
	v_mfma_f32_32x32x16_bf16 v[146:161], v[28:31], v[4:7], v[146:161]
	v_mfma_f32_32x32x16_bf16 v[162:177], v[28:31], v[8:11], v[162:177]
	v_mfma_f32_32x32x16_bf16 v[178:193], v[28:31], v[12:15], v[178:193]
	s_waitcnt lgkmcnt(0)
	s_barrier
	ds_read_b128 v[0:3], v56 offset:0
	ds_read_b128 v[4:7], v56 offset:2560
	ds_read_b128 v[8:11], v57 offset:0
	ds_read_b128 v[12:15], v57 offset:2560
	ds_read_b128 v[16:19], v57 offset:5120
	ds_read_b128 v[20:23], v57 offset:7680
	ds_read_b128 v[24:27], v56 offset:32
	ds_read_b128 v[28:31], v56 offset:2592
	s_waitcnt lgkmcnt(4)
	v_mfma_f32_32x32x16_bf16 v[66:81], v[0:3], v[8:11], v[66:81]
	v_mfma_f32_32x32x16_bf16 v[82:97], v[0:3], v[12:15], v[82:97]
	s_waitcnt vmcnt(6)
	ds_write_b128 v58, v[214:217] offset:30720
	ds_write_b128 v58, v[218:221] offset:35840
	s_waitcnt lgkmcnt(4)
	v_mfma_f32_32x32x16_bf16 v[98:113], v[0:3], v[16:19], v[98:113]
	v_mfma_f32_32x32x16_bf16 v[114:129], v[0:3], v[20:23], v[114:129]
	ds_read_b128 v[0:3], v57 offset:32
	ds_write_b128 v58, v[222:225] offset:40960
	ds_write_b128 v58, v[228:231] offset:46080
	v_mfma_f32_32x32x16_bf16 v[130:145], v[4:7], v[8:11], v[130:145]
	v_mfma_f32_32x32x16_bf16 v[146:161], v[4:7], v[12:15], v[146:161]
	ds_write_b128 v58, v[232:235] offset:51200
	ds_write_b128 v58, v[236:239] offset:56320
	v_mfma_f32_32x32x16_bf16 v[162:177], v[4:7], v[16:19], v[162:177]
	v_mfma_f32_32x32x16_bf16 v[178:193], v[4:7], v[20:23], v[178:193]
	ds_read_b128 v[4:7], v57 offset:2592
	ds_read_b128 v[8:11], v57 offset:5152
	ds_read_b128 v[12:15], v57 offset:7712
	s_waitcnt lgkmcnt(2)
	v_mfma_f32_32x32x16_bf16 v[66:81], v[24:27], v[0:3], v[66:81]
	global_load_dwordx4 v[214:217], v[240:241], off offset:3776
	global_load_dwordx4 v[218:221], v[242:243], off offset:3776
	v_mfma_f32_32x32x16_bf16 v[82:97], v[24:27], v[4:7], v[82:97]
	s_waitcnt lgkmcnt(0)
	v_mfma_f32_32x32x16_bf16 v[98:113], v[24:27], v[8:11], v[98:113]
	global_load_dwordx4 v[222:225], v[244:245], off offset:1728
	global_load_dwordx4 v[228:231], v[246:247], off offset:1728
	v_mfma_f32_32x32x16_bf16 v[114:129], v[24:27], v[12:15], v[114:129]
	v_mfma_f32_32x32x16_bf16 v[130:145], v[28:31], v[0:3], v[130:145]
	global_load_dwordx4 v[232:235], v[248:249], off offset:1728
	global_load_dwordx4 v[236:239], v[250:251], off offset:1728
	v_mfma_f32_32x32x16_bf16 v[146:161], v[28:31], v[4:7], v[146:161]
	v_mfma_f32_32x32x16_bf16 v[162:177], v[28:31], v[8:11], v[162:177]
	v_mfma_f32_32x32x16_bf16 v[178:193], v[28:31], v[12:15], v[178:193]
	s_waitcnt lgkmcnt(0)
	s_barrier
; template <class AL, class BL>
; DI void gemm_core(AL al, BL bl, int m0, int n0, int K, char* smem, f32x16 (&acc)[2][2]) {
;     ...
;   for (int kt = 0; kt < nk; kt += 2) {
;     G_TILE(0, x, true, (kt + 3 < nk), kt + 3);
;     __syncthreads();
;     G_TILE(1, y, (kt + 2 < nk), (kt + 4 < nk), kt + 4);
;     __syncthreads();
;   }
	ds_read_b128 v[0:3], v56 offset:30720
	ds_read_b128 v[4:7], v56 offset:33280
	ds_read_b128 v[8:11], v57 offset:30720
	ds_read_b128 v[12:15], v57 offset:33280
	ds_read_b128 v[16:19], v57 offset:35840
	ds_read_b128 v[20:23], v57 offset:38400
	ds_read_b128 v[24:27], v56 offset:30752
	ds_read_b128 v[28:31], v56 offset:33312
	s_waitcnt lgkmcnt(4)
	v_mfma_f32_32x32x16_bf16 v[66:81], v[0:3], v[8:11], v[66:81]
	v_mfma_f32_32x32x16_bf16 v[82:97], v[0:3], v[12:15], v[82:97]
	s_waitcnt vmcnt(6)
	ds_write_b128 v58, v[32:35] offset:0
	ds_write_b128 v58, v[36:39] offset:5120
	s_waitcnt lgkmcnt(4)
	v_mfma_f32_32x32x16_bf16 v[98:113], v[0:3], v[16:19], v[98:113]
	v_mfma_f32_32x32x16_bf16 v[114:129], v[0:3], v[20:23], v[114:129]
	ds_read_b128 v[0:3], v57 offset:30752
	ds_write_b128 v58, v[40:43] offset:10240
	ds_write_b128 v58, v[44:47] offset:15360
	v_mfma_f32_32x32x16_bf16 v[130:145], v[4:7], v[8:11], v[130:145]
	v_mfma_f32_32x32x16_bf16 v[146:161], v[4:7], v[12:15], v[146:161]
	ds_write_b128 v58, v[48:51] offset:20480
	ds_write_b128 v58, v[52:55] offset:25600
	v_mfma_f32_32x32x16_bf16 v[162:177], v[4:7], v[16:19], v[162:177]
	v_mfma_f32_32x32x16_bf16 v[178:193], v[4:7], v[20:23], v[178:193]
	ds_read_b128 v[4:7], v57 offset:33312
	ds_read_b128 v[8:11], v57 offset:35872
	ds_read_b128 v[12:15], v57 offset:38432
	s_waitcnt lgkmcnt(2)
	v_mfma_f32_32x32x16_bf16 v[66:81], v[24:27], v[0:3], v[66:81]
	global_load_dwordx4 v[32:35], v[240:241], off offset:3840
	global_load_dwordx4 v[36:39], v[242:243], off offset:3840
	v_mfma_f32_32x32x16_bf16 v[82:97], v[24:27], v[4:7], v[82:97]
	s_waitcnt lgkmcnt(0)
	v_mfma_f32_32x32x16_bf16 v[98:113], v[24:27], v[8:11], v[98:113]
	global_load_dwordx4 v[40:43], v[244:245], off offset:1792
	global_load_dwordx4 v[44:47], v[246:247], off offset:1792
	v_mfma_f32_32x32x16_bf16 v[114:129], v[24:27], v[12:15], v[114:129]
	v_mfma_f32_32x32x16_bf16 v[130:145], v[28:31], v[0:3], v[130:145]
	global_load_dwordx4 v[48:51], v[248:249], off offset:1792
	global_load_dwordx4 v[52:55], v[250:251], off offset:1792
	v_mfma_f32_32x32x16_bf16 v[146:161], v[28:31], v[4:7], v[146:161]
	v_mfma_f32_32x32x16_bf16 v[162:177], v[28:31], v[8:11], v[162:177]
	v_mfma_f32_32x32x16_bf16 v[178:193], v[28:31], v[12:15], v[178:193]
	s_waitcnt lgkmcnt(0)
	s_barrier
	ds_read_b128 v[0:3], v56 offset:0
	ds_read_b128 v[4:7], v56 offset:2560
	ds_read_b128 v[8:11], v57 offset:0
	ds_read_b128 v[12:15], v57 offset:2560
	ds_read_b128 v[16:19], v57 offset:5120
	ds_read_b128 v[20:23], v57 offset:7680
	ds_read_b128 v[24:27], v56 offset:32
	ds_read_b128 v[28:31], v56 offset:2592
	s_waitcnt lgkmcnt(4)
	v_mfma_f32_32x32x16_bf16 v[66:81], v[0:3], v[8:11], v[66:81]
	v_mfma_f32_32x32x16_bf16 v[82:97], v[0:3], v[12:15], v[82:97]
	s_waitcnt vmcnt(6)
	ds_write_b128 v58, v[214:217] offset:30720
	ds_write_b128 v58, v[218:221] offset:35840
	s_waitcnt lgkmcnt(4)
	v_mfma_f32_32x32x16_bf16 v[98:113], v[0:3], v[16:19], v[98:113]
	v_mfma_f32_32x32x16_bf16 v[114:129], v[0:3], v[20:23], v[114:129]
	ds_read_b128 v[0:3], v57 offset:32
	ds_write_b128 v58, v[222:225] offset:40960
	ds_write_b128 v58, v[228:231] offset:46080
	v_mfma_f32_32x32x16_bf16 v[130:145], v[4:7], v[8:11], v[130:145]
	v_mfma_f32_32x32x16_bf16 v[146:161], v[4:7], v[12:15], v[146:161]
	ds_write_b128 v58, v[232:235] offset:51200
	ds_write_b128 v58, v[236:239] offset:56320
	v_mfma_f32_32x32x16_bf16 v[162:177], v[4:7], v[16:19], v[162:177]
	v_mfma_f32_32x32x16_bf16 v[178:193], v[4:7], v[20:23], v[178:193]
	ds_read_b128 v[4:7], v57 offset:2592
	ds_read_b128 v[8:11], v57 offset:5152
	ds_read_b128 v[12:15], v57 offset:7712
	s_waitcnt lgkmcnt(2)
	v_mfma_f32_32x32x16_bf16 v[66:81], v[24:27], v[0:3], v[66:81]
	global_load_dwordx4 v[214:217], v[240:241], off offset:3904
	global_load_dwordx4 v[218:221], v[242:243], off offset:3904
	v_mfma_f32_32x32x16_bf16 v[82:97], v[24:27], v[4:7], v[82:97]
	s_waitcnt lgkmcnt(0)
	v_mfma_f32_32x32x16_bf16 v[98:113], v[24:27], v[8:11], v[98:113]
	global_load_dwordx4 v[222:225], v[244:245], off offset:1856
	global_load_dwordx4 v[228:231], v[246:247], off offset:1856
	v_mfma_f32_32x32x16_bf16 v[114:129], v[24:27], v[12:15], v[114:129]
	v_mfma_f32_32x32x16_bf16 v[130:145], v[28:31], v[0:3], v[130:145]
	global_load_dwordx4 v[232:235], v[248:249], off offset:1856
	global_load_dwordx4 v[236:239], v[250:251], off offset:1856
	v_mfma_f32_32x32x16_bf16 v[146:161], v[28:31], v[4:7], v[146:161]
	v_mfma_f32_32x32x16_bf16 v[162:177], v[28:31], v[8:11], v[162:177]
	v_mfma_f32_32x32x16_bf16 v[178:193], v[28:31], v[12:15], v[178:193]
	s_waitcnt lgkmcnt(0)
	s_barrier
; template <class AL, class BL>
; DI void gemm_core(AL al, BL bl, int m0, int n0, int K, char* smem, f32x16 (&acc)[2][2]) {
;     ...
;   for (int kt = 0; kt < nk; kt += 2) {
;     G_TILE(0, x, true, (kt + 3 < nk), kt + 3);
;     __syncthreads();
;     G_TILE(1, y, (kt + 2 < nk), (kt + 4 < nk), kt + 4);
;     __syncthreads();
;   }
	ds_read_b128 v[0:3], v56 offset:30720
	ds_read_b128 v[4:7], v56 offset:33280
	ds_read_b128 v[8:11], v57 offset:30720
	ds_read_b128 v[12:15], v57 offset:33280
	ds_read_b128 v[16:19], v57 offset:35840
	ds_read_b128 v[20:23], v57 offset:38400
	ds_read_b128 v[24:27], v56 offset:30752
	ds_read_b128 v[28:31], v56 offset:33312
	s_waitcnt lgkmcnt(4)
	v_mfma_f32_32x32x16_bf16 v[66:81], v[0:3], v[8:11], v[66:81]
	v_mfma_f32_32x32x16_bf16 v[82:97], v[0:3], v[12:15], v[82:97]
	s_waitcnt vmcnt(6)
	ds_write_b128 v58, v[32:35] offset:0
	ds_write_b128 v58, v[36:39] offset:5120
	s_waitcnt lgkmcnt(4)
	v_mfma_f32_32x32x16_bf16 v[98:113], v[0:3], v[16:19], v[98:113]
	v_mfma_f32_32x32x16_bf16 v[114:129], v[0:3], v[20:23], v[114:129]
	ds_read_b128 v[0:3], v57 offset:30752
	ds_write_b128 v58, v[40:43] offset:10240
	ds_write_b128 v58, v[44:47] offset:15360
	v_mfma_f32_32x32x16_bf16 v[130:145], v[4:7], v[8:11], v[130:145]
	v_mfma_f32_32x32x16_bf16 v[146:161], v[4:7], v[12:15], v[146:161]
	ds_write_b128 v58, v[48:51] offset:20480
	ds_write_b128 v58, v[52:55] offset:25600
	v_mfma_f32_32x32x16_bf16 v[162:177], v[4:7], v[16:19], v[162:177]
	v_mfma_f32_32x32x16_bf16 v[178:193], v[4:7], v[20:23], v[178:193]
	ds_read_b128 v[4:7], v57 offset:33312
	ds_read_b128 v[8:11], v57 offset:35872
	ds_read_b128 v[12:15], v57 offset:38432
	s_waitcnt lgkmcnt(2)
	v_mfma_f32_32x32x16_bf16 v[66:81], v[24:27], v[0:3], v[66:81]
	global_load_dwordx4 v[32:35], v[240:241], off offset:3968
	global_load_dwordx4 v[36:39], v[242:243], off offset:3968
	v_mfma_f32_32x32x16_bf16 v[82:97], v[24:27], v[4:7], v[82:97]
	s_waitcnt lgkmcnt(0)
	v_mfma_f32_32x32x16_bf16 v[98:113], v[24:27], v[8:11], v[98:113]
	global_load_dwordx4 v[40:43], v[244:245], off offset:1920
	global_load_dwordx4 v[44:47], v[246:247], off offset:1920
	v_mfma_f32_32x32x16_bf16 v[114:129], v[24:27], v[12:15], v[114:129]
	v_mfma_f32_32x32x16_bf16 v[130:145], v[28:31], v[0:3], v[130:145]
	global_load_dwordx4 v[48:51], v[248:249], off offset:1920
	global_load_dwordx4 v[52:55], v[250:251], off offset:1920
	v_mfma_f32_32x32x16_bf16 v[146:161], v[28:31], v[4:7], v[146:161]
	v_mfma_f32_32x32x16_bf16 v[162:177], v[28:31], v[8:11], v[162:177]
	v_mfma_f32_32x32x16_bf16 v[178:193], v[28:31], v[12:15], v[178:193]
	s_waitcnt lgkmcnt(0)
	s_barrier
	ds_read_b128 v[0:3], v56 offset:0
	ds_read_b128 v[4:7], v56 offset:2560
	ds_read_b128 v[8:11], v57 offset:0
	ds_read_b128 v[12:15], v57 offset:2560
	ds_read_b128 v[16:19], v57 offset:5120
	ds_read_b128 v[20:23], v57 offset:7680
	ds_read_b128 v[24:27], v56 offset:32
	ds_read_b128 v[28:31], v56 offset:2592
	s_waitcnt lgkmcnt(4)
	v_mfma_f32_32x32x16_bf16 v[66:81], v[0:3], v[8:11], v[66:81]
	v_mfma_f32_32x32x16_bf16 v[82:97], v[0:3], v[12:15], v[82:97]
	s_waitcnt vmcnt(6)
	ds_write_b128 v58, v[214:217] offset:30720
	ds_write_b128 v58, v[218:221] offset:35840
	s_waitcnt lgkmcnt(4)
	v_mfma_f32_32x32x16_bf16 v[98:113], v[0:3], v[16:19], v[98:113]
	v_mfma_f32_32x32x16_bf16 v[114:129], v[0:3], v[20:23], v[114:129]
	ds_read_b128 v[0:3], v57 offset:32
	ds_write_b128 v58, v[222:225] offset:40960
	ds_write_b128 v58, v[228:231] offset:46080
	v_mfma_f32_32x32x16_bf16 v[130:145], v[4:7], v[8:11], v[130:145]
	v_mfma_f32_32x32x16_bf16 v[146:161], v[4:7], v[12:15], v[146:161]
	ds_write_b128 v58, v[232:235] offset:51200
	ds_write_b128 v58, v[236:239] offset:56320
	v_mfma_f32_32x32x16_bf16 v[162:177], v[4:7], v[16:19], v[162:177]
	v_mfma_f32_32x32x16_bf16 v[178:193], v[4:7], v[20:23], v[178:193]
	ds_read_b128 v[4:7], v57 offset:2592
	ds_read_b128 v[8:11], v57 offset:5152
	ds_read_b128 v[12:15], v57 offset:7712
	s_waitcnt lgkmcnt(2)
	v_mfma_f32_32x32x16_bf16 v[66:81], v[24:27], v[0:3], v[66:81]
	global_load_dwordx4 v[214:217], v[240:241], off offset:4032
	global_load_dwordx4 v[218:221], v[242:243], off offset:4032
	v_mfma_f32_32x32x16_bf16 v[82:97], v[24:27], v[4:7], v[82:97]
	s_waitcnt lgkmcnt(0)
	v_mfma_f32_32x32x16_bf16 v[98:113], v[24:27], v[8:11], v[98:113]
	global_load_dwordx4 v[222:225], v[244:245], off offset:1984
	global_load_dwordx4 v[228:231], v[246:247], off offset:1984
	v_mfma_f32_32x32x16_bf16 v[114:129], v[24:27], v[12:15], v[114:129]
	v_mfma_f32_32x32x16_bf16 v[130:145], v[28:31], v[0:3], v[130:145]
	global_load_dwordx4 v[232:235], v[248:249], off offset:1984
	global_load_dwordx4 v[236:239], v[250:251], off offset:1984
	v_mfma_f32_32x32x16_bf16 v[146:161], v[28:31], v[4:7], v[146:161]
	v_mfma_f32_32x32x16_bf16 v[162:177], v[28:31], v[8:11], v[162:177]
	v_mfma_f32_32x32x16_bf16 v[178:193], v[28:31], v[12:15], v[178:193]
	s_waitcnt lgkmcnt(0)
	s_barrier
	ds_read_b128 v[0:3], v56 offset:30720
	ds_read_b128 v[4:7], v56 offset:33280
	ds_read_b128 v[8:11], v57 offset:30720
	ds_read_b128 v[12:15], v57 offset:33280
	ds_read_b128 v[16:19], v57 offset:35840
	ds_read_b128 v[20:23], v57 offset:38400
	ds_read_b128 v[24:27], v56 offset:30752
	ds_read_b128 v[28:31], v56 offset:33312
	s_waitcnt lgkmcnt(4)
	v_mfma_f32_32x32x16_bf16 v[66:81], v[0:3], v[8:11], v[66:81]
	v_mfma_f32_32x32x16_bf16 v[82:97], v[0:3], v[12:15], v[82:97]
	s_waitcnt vmcnt(6)
	ds_write_b128 v58, v[32:35] offset:0
	ds_write_b128 v58, v[36:39] offset:5120
	s_waitcnt lgkmcnt(4)
	v_mfma_f32_32x32x16_bf16 v[98:113], v[0:3], v[16:19], v[98:113]
	v_mfma_f32_32x32x16_bf16 v[114:129], v[0:3], v[20:23], v[114:129]
	ds_read_b128 v[0:3], v57 offset:30752
	ds_write_b128 v58, v[40:43] offset:10240
	ds_write_b128 v58, v[44:47] offset:15360
	v_mfma_f32_32x32x16_bf16 v[130:145], v[4:7], v[8:11], v[130:145]
	v_mfma_f32_32x32x16_bf16 v[146:161], v[4:7], v[12:15], v[146:161]
	ds_write_b128 v58, v[48:51] offset:20480
	ds_write_b128 v58, v[52:55] offset:25600
	v_mfma_f32_32x32x16_bf16 v[162:177], v[4:7], v[16:19], v[162:177]
	v_mfma_f32_32x32x16_bf16 v[178:193], v[4:7], v[20:23], v[178:193]
	ds_read_b128 v[4:7], v57 offset:33312
	ds_read_b128 v[8:11], v57 offset:35872
	ds_read_b128 v[12:15], v57 offset:38432
	s_waitcnt lgkmcnt(2)
	v_mfma_f32_32x32x16_bf16 v[66:81], v[24:27], v[0:3], v[66:81]
	v_mfma_f32_32x32x16_bf16 v[82:97], v[24:27], v[4:7], v[82:97]
	s_waitcnt lgkmcnt(0)
	v_mfma_f32_32x32x16_bf16 v[98:113], v[24:27], v[8:11], v[98:113]
	v_mfma_f32_32x32x16_bf16 v[114:129], v[24:27], v[12:15], v[114:129]
	v_mfma_f32_32x32x16_bf16 v[130:145], v[28:31], v[0:3], v[130:145]
	v_mfma_f32_32x32x16_bf16 v[146:161], v[28:31], v[4:7], v[146:161]
	v_mfma_f32_32x32x16_bf16 v[162:177], v[28:31], v[8:11], v[162:177]
	v_mfma_f32_32x32x16_bf16 v[178:193], v[28:31], v[12:15], v[178:193]
	s_waitcnt lgkmcnt(0)
	s_barrier
; template <class AL, class BL>
; DI void gemm_core(AL al, BL bl, int m0, int n0, int K, char* smem, f32x16 (&acc)[2][2]) {
;     ...
;   for (int kt = 0; kt < nk; kt += 2) {
;     G_TILE(0, x, true, (kt + 3 < nk), kt + 3);
;     __syncthreads();
;     G_TILE(1, y, (kt + 2 < nk), (kt + 4 < nk), kt + 4);
;     __syncthreads();
;   }
; DI void ffn_up_phase(const Params& p, const u16* xb, int ldx, const u16* wupT, u16* hid, char* smem) {
;     ...
;                epi_bf16_tile(acc, m0, n0, hid + (long)m0 * 4096 + n0, 4096, smem, [=](int m, int n, float v) {
;                  const float a = fmaxf(v * rs[m], 0.f);
;                  return a * a;
	ds_read_b128 v[0:3], v56 offset:0
	ds_read_b128 v[4:7], v56 offset:2560
	ds_read_b128 v[8:11], v57 offset:0
	ds_read_b128 v[12:15], v57 offset:2560
	ds_read_b128 v[16:19], v57 offset:5120
	ds_read_b128 v[20:23], v57 offset:7680
	ds_read_b128 v[24:27], v56 offset:32
	ds_read_b128 v[28:31], v56 offset:2592
	s_waitcnt lgkmcnt(4)
	v_mfma_f32_32x32x16_bf16 v[66:81], v[0:3], v[8:11], v[66:81]
	v_mfma_f32_32x32x16_bf16 v[82:97], v[0:3], v[12:15], v[82:97]
	s_waitcnt vmcnt(0)
	ds_write_b128 v58, v[214:217] offset:30720
	ds_write_b128 v58, v[218:221] offset:35840
	s_waitcnt lgkmcnt(4)
	v_mfma_f32_32x32x16_bf16 v[98:113], v[0:3], v[16:19], v[98:113]
	v_mfma_f32_32x32x16_bf16 v[114:129], v[0:3], v[20:23], v[114:129]
	ds_read_b128 v[0:3], v57 offset:32
	ds_write_b128 v58, v[222:225] offset:40960
	ds_write_b128 v58, v[228:231] offset:46080
	v_mfma_f32_32x32x16_bf16 v[130:145], v[4:7], v[8:11], v[130:145]
	v_mfma_f32_32x32x16_bf16 v[146:161], v[4:7], v[12:15], v[146:161]
	ds_write_b128 v58, v[232:235] offset:51200
	ds_write_b128 v58, v[236:239] offset:56320
	v_mfma_f32_32x32x16_bf16 v[162:177], v[4:7], v[16:19], v[162:177]
	v_mfma_f32_32x32x16_bf16 v[178:193], v[4:7], v[20:23], v[178:193]
	ds_read_b128 v[4:7], v57 offset:2592
	ds_read_b128 v[8:11], v57 offset:5152
	ds_read_b128 v[12:15], v57 offset:7712
	s_waitcnt lgkmcnt(2)
	v_mfma_f32_32x32x16_bf16 v[66:81], v[24:27], v[0:3], v[66:81]
	v_mfma_f32_32x32x16_bf16 v[82:97], v[24:27], v[4:7], v[82:97]
	s_waitcnt lgkmcnt(0)
	v_mfma_f32_32x32x16_bf16 v[98:113], v[24:27], v[8:11], v[98:113]
	v_mfma_f32_32x32x16_bf16 v[114:129], v[24:27], v[12:15], v[114:129]
	v_mfma_f32_32x32x16_bf16 v[130:145], v[28:31], v[0:3], v[130:145]
	v_mfma_f32_32x32x16_bf16 v[146:161], v[28:31], v[4:7], v[146:161]
	v_mfma_f32_32x32x16_bf16 v[162:177], v[28:31], v[8:11], v[162:177]
	v_mfma_f32_32x32x16_bf16 v[178:193], v[28:31], v[12:15], v[178:193]
	s_waitcnt lgkmcnt(0)
	s_barrier
	ds_read_b128 v[0:3], v56 offset:30720
	ds_read_b128 v[4:7], v56 offset:33280
	ds_read_b128 v[8:11], v57 offset:30720
	ds_read_b128 v[12:15], v57 offset:33280
	ds_read_b128 v[16:19], v57 offset:35840
	ds_read_b128 v[20:23], v57 offset:38400
	ds_read_b128 v[24:27], v56 offset:30752
	ds_read_b128 v[28:31], v56 offset:33312
	s_waitcnt lgkmcnt(4)
	v_mfma_f32_32x32x16_bf16 v[66:81], v[0:3], v[8:11], v[66:81]
	global_load_dword v32, v61, s[12:13] offset:0
	global_load_dword v33, v61, s[12:13] offset:4
	global_load_dword v34, v61, s[12:13] offset:8
	global_load_dword v35, v61, s[12:13] offset:12
	v_mfma_f32_32x32x16_bf16 v[82:97], v[0:3], v[12:15], v[82:97]
	s_waitcnt lgkmcnt(2)
	v_mfma_f32_32x32x16_bf16 v[98:113], v[0:3], v[16:19], v[98:113]
	global_load_dword v36, v61, s[12:13] offset:32
	global_load_dword v37, v61, s[12:13] offset:36
	global_load_dword v38, v61, s[12:13] offset:40
	global_load_dword v39, v61, s[12:13] offset:44
	v_mfma_f32_32x32x16_bf16 v[114:129], v[0:3], v[20:23], v[114:129]
	ds_read_b128 v[0:3], v57 offset:30752
	v_mfma_f32_32x32x16_bf16 v[130:145], v[4:7], v[8:11], v[130:145]
	global_load_dword v40, v61, s[12:13] offset:64
	global_load_dword v41, v61, s[12:13] offset:68
	global_load_dword v42, v61, s[12:13] offset:72
	global_load_dword v43, v61, s[12:13] offset:76
	v_mfma_f32_32x32x16_bf16 v[146:161], v[4:7], v[12:15], v[146:161]
	v_mfma_f32_32x32x16_bf16 v[162:177], v[4:7], v[16:19], v[162:177]
	global_load_dword v44, v61, s[12:13] offset:96
	global_load_dword v45, v61, s[12:13] offset:100
	global_load_dword v46, v61, s[12:13] offset:104
	global_load_dword v47, v61, s[12:13] offset:108
	v_mfma_f32_32x32x16_bf16 v[178:193], v[4:7], v[20:23], v[178:193]
	ds_read_b128 v[4:7], v57 offset:33312
	ds_read_b128 v[8:11], v57 offset:35872
	ds_read_b128 v[12:15], v57 offset:38432
	s_waitcnt lgkmcnt(2)
	v_mfma_f32_32x32x16_bf16 v[66:81], v[24:27], v[0:3], v[66:81]
	global_load_dword v48, v61, s[12:13] offset:128
	global_load_dword v49, v61, s[12:13] offset:132
	global_load_dword v50, v61, s[12:13] offset:136
	global_load_dword v51, v61, s[12:13] offset:140
	v_mfma_f32_32x32x16_bf16 v[82:97], v[24:27], v[4:7], v[82:97]
	s_waitcnt lgkmcnt(0)
	v_mfma_f32_32x32x16_bf16 v[98:113], v[24:27], v[8:11], v[98:113]
	global_load_dword v52, v61, s[12:13] offset:160
	global_load_dword v53, v61, s[12:13] offset:164
	global_load_dword v54, v61, s[12:13] offset:168
	global_load_dword v55, v61, s[12:13] offset:172
	v_mfma_f32_32x32x16_bf16 v[114:129], v[24:27], v[12:15], v[114:129]
	v_mfma_f32_32x32x16_bf16 v[130:145], v[28:31], v[0:3], v[130:145]
	global_load_dword v214, v61, s[12:13] offset:192
	global_load_dword v215, v61, s[12:13] offset:196
	global_load_dword v216, v61, s[12:13] offset:200
	global_load_dword v217, v61, s[12:13] offset:204
	v_mfma_f32_32x32x16_bf16 v[146:161], v[28:31], v[4:7], v[146:161]
	v_mfma_f32_32x32x16_bf16 v[162:177], v[28:31], v[8:11], v[162:177]
	global_load_dword v218, v61, s[12:13] offset:224
	global_load_dword v219, v61, s[12:13] offset:228
	global_load_dword v220, v61, s[12:13] offset:232
	global_load_dword v221, v61, s[12:13] offset:236
	v_mfma_f32_32x32x16_bf16 v[178:193], v[28:31], v[12:15], v[178:193]
	s_waitcnt lgkmcnt(0)
	s_barrier
; DI u16 f2bf(float x) { return (u16)(pack2(x, 0.f) & 0xffffu); }
; DI int crow(int i, int h) { return (i & 3) + 8 * (i >> 2) + 4 * h; }
; template <class F>
; DI void epi_bf16_tile(const f32x16 (&acc)[2][2], int m0, int n0, u16* dst0, long ld, char* smem, F f) {
;     ...
;       for (int i = 0; i < 16; i++) {
;         const int ml = wm * 64 + mt * 32 + crow(i, h), nl = wn * 64 + nt * 32 + (lane & 31);
;         T[ml * 136 + nl] = f2bf(f(m0 + ml, n0 + nl, acc[mt][nt][i]));
;       }
; DI void ffn_up_phase(const Params& p, const u16* xb, int ldx, const u16* wupT, u16* hid, char* smem) {
;     ...
;                epi_bf16_tile(acc, m0, n0, hid + (long)m0 * 4096 + n0, 4096, smem, [=](int m, int n, float v) {
;                  const float a = fmaxf(v * rs[m], 0.f);
;                  return a * a;
	s_nop 7
	s_nop 3
	s_waitcnt vmcnt(0)
	v_mul_f32_e32 v62, v66, v32
	v_max_f32_e32 v62, 0, v62
	v_mul_f32_e32 v62, v62, v62
	v_cvt_pk_bf16_f32 v62, v62, v62
	ds_write_b16 v59, v62 offset:0
	v_mul_f32_e32 v63, v67, v33
	v_max_f32_e32 v63, 0, v63
	v_mul_f32_e32 v63, v63, v63
	v_cvt_pk_bf16_f32 v63, v63, v63
	ds_write_b16 v59, v63 offset:528
	v_mul_f32_e32 v64, v68, v34
	v_max_f32_e32 v64, 0, v64
	v_mul_f32_e32 v64, v64, v64
	v_cvt_pk_bf16_f32 v64, v64, v64
	ds_write_b16 v59, v64 offset:1056
	v_mul_f32_e32 v252, v69, v35
	v_max_f32_e32 v252, 0, v252
	v_mul_f32_e32 v252, v252, v252
	v_cvt_pk_bf16_f32 v252, v252, v252
	ds_write_b16 v59, v252 offset:1584
	v_mul_f32_e32 v62, v70, v36
	v_max_f32_e32 v62, 0, v62
	v_mul_f32_e32 v62, v62, v62
	v_cvt_pk_bf16_f32 v62, v62, v62
	ds_write_b16 v59, v62 offset:4224
	v_mul_f32_e32 v63, v71, v37
	v_max_f32_e32 v63, 0, v63
	v_mul_f32_e32 v63, v63, v63
	v_cvt_pk_bf16_f32 v63, v63, v63
	ds_write_b16 v59, v63 offset:4752
	v_mul_f32_e32 v64, v72, v38
	v_max_f32_e32 v64, 0, v64
	v_mul_f32_e32 v64, v64, v64
	v_cvt_pk_bf16_f32 v64, v64, v64
	ds_write_b16 v59, v64 offset:5280
	v_mul_f32_e32 v252, v73, v39
	v_max_f32_e32 v252, 0, v252
	v_mul_f32_e32 v252, v252, v252
	v_cvt_pk_bf16_f32 v252, v252, v252
	ds_write_b16 v59, v252 offset:5808
	v_mul_f32_e32 v62, v74, v40
	v_max_f32_e32 v62, 0, v62
	v_mul_f32_e32 v62, v62, v62
	v_cvt_pk_bf16_f32 v62, v62, v62
	ds_write_b16 v59, v62 offset:8448
	v_mul_f32_e32 v63, v75, v41
	v_max_f32_e32 v63, 0, v63
	v_mul_f32_e32 v63, v63, v63
	v_cvt_pk_bf16_f32 v63, v63, v63
	ds_write_b16 v59, v63 offset:8976
	v_mul_f32_e32 v64, v76, v42
	v_max_f32_e32 v64, 0, v64
	v_mul_f32_e32 v64, v64, v64
	v_cvt_pk_bf16_f32 v64, v64, v64
	ds_write_b16 v59, v64 offset:9504
	v_mul_f32_e32 v252, v77, v43
	v_max_f32_e32 v252, 0, v252
	v_mul_f32_e32 v252, v252, v252
	v_cvt_pk_bf16_f32 v252, v252, v252
	ds_write_b16 v59, v252 offset:10032
	v_mul_f32_e32 v62, v78, v44
	v_max_f32_e32 v62, 0, v62
	v_mul_f32_e32 v62, v62, v62
	v_cvt_pk_bf16_f32 v62, v62, v62
	ds_write_b16 v59, v62 offset:12672
	v_mul_f32_e32 v63, v79, v45
	v_max_f32_e32 v63, 0, v63
	v_mul_f32_e32 v63, v63, v63
	v_cvt_pk_bf16_f32 v63, v63, v63
	ds_write_b16 v59, v63 offset:13200
	v_mul_f32_e32 v64, v80, v46
	v_max_f32_e32 v64, 0, v64
	v_mul_f32_e32 v64, v64, v64
	v_cvt_pk_bf16_f32 v64, v64, v64
	ds_write_b16 v59, v64 offset:13728
	v_mul_f32_e32 v252, v81, v47
	v_max_f32_e32 v252, 0, v252
	v_mul_f32_e32 v252, v252, v252
	v_cvt_pk_bf16_f32 v252, v252, v252
	ds_write_b16 v59, v252 offset:14256
	v_mul_f32_e32 v62, v82, v32
	v_max_f32_e32 v62, 0, v62
	v_mul_f32_e32 v62, v62, v62
	v_cvt_pk_bf16_f32 v62, v62, v62
	ds_write_b16 v59, v62 offset:64
	v_mul_f32_e32 v63, v83, v33
	v_max_f32_e32 v63, 0, v63
	v_mul_f32_e32 v63, v63, v63
	v_cvt_pk_bf16_f32 v63, v63, v63
	ds_write_b16 v59, v63 offset:592
	v_mul_f32_e32 v64, v84, v34
	v_max_f32_e32 v64, 0, v64
	v_mul_f32_e32 v64, v64, v64
	v_cvt_pk_bf16_f32 v64, v64, v64
	ds_write_b16 v59, v64 offset:1120
	v_mul_f32_e32 v252, v85, v35
	v_max_f32_e32 v252, 0, v252
	v_mul_f32_e32 v252, v252, v252
	v_cvt_pk_bf16_f32 v252, v252, v252
	ds_write_b16 v59, v252 offset:1648
	v_mul_f32_e32 v62, v86, v36
	v_max_f32_e32 v62, 0, v62
	v_mul_f32_e32 v62, v62, v62
	v_cvt_pk_bf16_f32 v62, v62, v62
	ds_write_b16 v59, v62 offset:4288
	v_mul_f32_e32 v63, v87, v37
	v_max_f32_e32 v63, 0, v63
	v_mul_f32_e32 v63, v63, v63
	v_cvt_pk_bf16_f32 v63, v63, v63
	ds_write_b16 v59, v63 offset:4816
	v_mul_f32_e32 v64, v88, v38
	v_max_f32_e32 v64, 0, v64
	v_mul_f32_e32 v64, v64, v64
	v_cvt_pk_bf16_f32 v64, v64, v64
	ds_write_b16 v59, v64 offset:5344
	v_mul_f32_e32 v252, v89, v39
	v_max_f32_e32 v252, 0, v252
	v_mul_f32_e32 v252, v252, v252
	v_cvt_pk_bf16_f32 v252, v252, v252
	ds_write_b16 v59, v252 offset:5872
	v_mul_f32_e32 v62, v90, v40
	v_max_f32_e32 v62, 0, v62
	v_mul_f32_e32 v62, v62, v62
	v_cvt_pk_bf16_f32 v62, v62, v62
	ds_write_b16 v59, v62 offset:8512
	v_mul_f32_e32 v63, v91, v41
	v_max_f32_e32 v63, 0, v63
	v_mul_f32_e32 v63, v63, v63
	v_cvt_pk_bf16_f32 v63, v63, v63
	ds_write_b16 v59, v63 offset:9040
	v_mul_f32_e32 v64, v92, v42
	v_max_f32_e32 v64, 0, v64
	v_mul_f32_e32 v64, v64, v64
	v_cvt_pk_bf16_f32 v64, v64, v64
	ds_write_b16 v59, v64 offset:9568
	v_mul_f32_e32 v252, v93, v43
	v_max_f32_e32 v252, 0, v252
	v_mul_f32_e32 v252, v252, v252
	v_cvt_pk_bf16_f32 v252, v252, v252
	ds_write_b16 v59, v252 offset:10096
	v_mul_f32_e32 v62, v94, v44
	v_max_f32_e32 v62, 0, v62
	v_mul_f32_e32 v62, v62, v62
	v_cvt_pk_bf16_f32 v62, v62, v62
	ds_write_b16 v59, v62 offset:12736
	v_mul_f32_e32 v63, v95, v45
	v_max_f32_e32 v63, 0, v63
	v_mul_f32_e32 v63, v63, v63
	v_cvt_pk_bf16_f32 v63, v63, v63
	ds_write_b16 v59, v63 offset:13264
	v_mul_f32_e32 v64, v96, v46
	v_max_f32_e32 v64, 0, v64
	v_mul_f32_e32 v64, v64, v64
	v_cvt_pk_bf16_f32 v64, v64, v64
	ds_write_b16 v59, v64 offset:13792
	v_mul_f32_e32 v252, v97, v47
	v_max_f32_e32 v252, 0, v252
	v_mul_f32_e32 v252, v252, v252
	v_cvt_pk_bf16_f32 v252, v252, v252
	ds_write_b16 v59, v252 offset:14320
	v_mul_f32_e32 v62, v98, v32
	v_max_f32_e32 v62, 0, v62
	v_mul_f32_e32 v62, v62, v62
	v_cvt_pk_bf16_f32 v62, v62, v62
	ds_write_b16 v59, v62 offset:128
	v_mul_f32_e32 v63, v99, v33
	v_max_f32_e32 v63, 0, v63
	v_mul_f32_e32 v63, v63, v63
	v_cvt_pk_bf16_f32 v63, v63, v63
	ds_write_b16 v59, v63 offset:656
	v_mul_f32_e32 v64, v100, v34
	v_max_f32_e32 v64, 0, v64
	v_mul_f32_e32 v64, v64, v64
	v_cvt_pk_bf16_f32 v64, v64, v64
	ds_write_b16 v59, v64 offset:1184
	v_mul_f32_e32 v252, v101, v35
	v_max_f32_e32 v252, 0, v252
	v_mul_f32_e32 v252, v252, v252
	v_cvt_pk_bf16_f32 v252, v252, v252
	ds_write_b16 v59, v252 offset:1712
; DI u16 f2bf(float x) { return (u16)(pack2(x, 0.f) & 0xffffu); }
; DI int crow(int i, int h) { return (i & 3) + 8 * (i >> 2) + 4 * h; }
; template <class F>
; DI void epi_bf16_tile(const f32x16 (&acc)[2][2], int m0, int n0, u16* dst0, long ld, char* smem, F f) {
;     ...
;       for (int i = 0; i < 16; i++) {
;         const int ml = wm * 64 + mt * 32 + crow(i, h), nl = wn * 64 + nt * 32 + (lane & 31);
;         T[ml * 136 + nl] = f2bf(f(m0 + ml, n0 + nl, acc[mt][nt][i]));
;       }
; DI void ffn_up_phase(const Params& p, const u16* xb, int ldx, const u16* wupT, u16* hid, char* smem) {
;     ...
;                epi_bf16_tile(acc, m0, n0, hid + (long)m0 * 4096 + n0, 4096, smem, [=](int m, int n, float v) {
;                  const float a = fmaxf(v * rs[m], 0.f);
;                  return a * a;
	v_mul_f32_e32 v62, v102, v36
	v_max_f32_e32 v62, 0, v62
	v_mul_f32_e32 v62, v62, v62
	v_cvt_pk_bf16_f32 v62, v62, v62
	ds_write_b16 v59, v62 offset:4352
	v_mul_f32_e32 v63, v103, v37
	v_max_f32_e32 v63, 0, v63
	v_mul_f32_e32 v63, v63, v63
	v_cvt_pk_bf16_f32 v63, v63, v63
	ds_write_b16 v59, v63 offset:4880
	v_mul_f32_e32 v64, v104, v38
	v_max_f32_e32 v64, 0, v64
	v_mul_f32_e32 v64, v64, v64
	v_cvt_pk_bf16_f32 v64, v64, v64
	ds_write_b16 v59, v64 offset:5408
	v_mul_f32_e32 v252, v105, v39
	v_max_f32_e32 v252, 0, v252
	v_mul_f32_e32 v252, v252, v252
	v_cvt_pk_bf16_f32 v252, v252, v252
	ds_write_b16 v59, v252 offset:5936
	v_mul_f32_e32 v62, v106, v40
	v_max_f32_e32 v62, 0, v62
	v_mul_f32_e32 v62, v62, v62
	v_cvt_pk_bf16_f32 v62, v62, v62
	ds_write_b16 v59, v62 offset:8576
	v_mul_f32_e32 v63, v107, v41
	v_max_f32_e32 v63, 0, v63
	v_mul_f32_e32 v63, v63, v63
	v_cvt_pk_bf16_f32 v63, v63, v63
	ds_write_b16 v59, v63 offset:9104
	v_mul_f32_e32 v64, v108, v42
	v_max_f32_e32 v64, 0, v64
	v_mul_f32_e32 v64, v64, v64
	v_cvt_pk_bf16_f32 v64, v64, v64
	ds_write_b16 v59, v64 offset:9632
	v_mul_f32_e32 v252, v109, v43
	v_max_f32_e32 v252, 0, v252
	v_mul_f32_e32 v252, v252, v252
	v_cvt_pk_bf16_f32 v252, v252, v252
	ds_write_b16 v59, v252 offset:10160
	v_mul_f32_e32 v62, v110, v44
	v_max_f32_e32 v62, 0, v62
	v_mul_f32_e32 v62, v62, v62
	v_cvt_pk_bf16_f32 v62, v62, v62
	ds_write_b16 v59, v62 offset:12800
	v_mul_f32_e32 v63, v111, v45
	v_max_f32_e32 v63, 0, v63
	v_mul_f32_e32 v63, v63, v63
	v_cvt_pk_bf16_f32 v63, v63, v63
	ds_write_b16 v59, v63 offset:13328
	v_mul_f32_e32 v64, v112, v46
	v_max_f32_e32 v64, 0, v64
	v_mul_f32_e32 v64, v64, v64
	v_cvt_pk_bf16_f32 v64, v64, v64
	ds_write_b16 v59, v64 offset:13856
	v_mul_f32_e32 v252, v113, v47
	v_max_f32_e32 v252, 0, v252
	v_mul_f32_e32 v252, v252, v252
	v_cvt_pk_bf16_f32 v252, v252, v252
	ds_write_b16 v59, v252 offset:14384
	v_mul_f32_e32 v62, v114, v32
	v_max_f32_e32 v62, 0, v62
	v_mul_f32_e32 v62, v62, v62
	v_cvt_pk_bf16_f32 v62, v62, v62
	ds_write_b16 v59, v62 offset:192
	v_mul_f32_e32 v63, v115, v33
	v_max_f32_e32 v63, 0, v63
	v_mul_f32_e32 v63, v63, v63
	v_cvt_pk_bf16_f32 v63, v63, v63
	ds_write_b16 v59, v63 offset:720
	v_mul_f32_e32 v64, v116, v34
	v_max_f32_e32 v64, 0, v64
	v_mul_f32_e32 v64, v64, v64
	v_cvt_pk_bf16_f32 v64, v64, v64
	ds_write_b16 v59, v64 offset:1248
	v_mul_f32_e32 v252, v117, v35
	v_max_f32_e32 v252, 0, v252
	v_mul_f32_e32 v252, v252, v252
	v_cvt_pk_bf16_f32 v252, v252, v252
	ds_write_b16 v59, v252 offset:1776
	v_mul_f32_e32 v62, v118, v36
	v_max_f32_e32 v62, 0, v62
	v_mul_f32_e32 v62, v62, v62
	v_cvt_pk_bf16_f32 v62, v62, v62
	ds_write_b16 v59, v62 offset:4416
	v_mul_f32_e32 v63, v119, v37
	v_max_f32_e32 v63, 0, v63
	v_mul_f32_e32 v63, v63, v63
	v_cvt_pk_bf16_f32 v63, v63, v63
	ds_write_b16 v59, v63 offset:4944
	v_mul_f32_e32 v64, v120, v38
	v_max_f32_e32 v64, 0, v64
	v_mul_f32_e32 v64, v64, v64
	v_cvt_pk_bf16_f32 v64, v64, v64
	ds_write_b16 v59, v64 offset:5472
	v_mul_f32_e32 v252, v121, v39
	v_max_f32_e32 v252, 0, v252
	v_mul_f32_e32 v252, v252, v252
	v_cvt_pk_bf16_f32 v252, v252, v252
	ds_write_b16 v59, v252 offset:6000
	v_mul_f32_e32 v62, v122, v40
	v_max_f32_e32 v62, 0, v62
	v_mul_f32_e32 v62, v62, v62
	v_cvt_pk_bf16_f32 v62, v62, v62
	ds_write_b16 v59, v62 offset:8640
	v_mul_f32_e32 v63, v123, v41
	v_max_f32_e32 v63, 0, v63
	v_mul_f32_e32 v63, v63, v63
	v_cvt_pk_bf16_f32 v63, v63, v63
	ds_write_b16 v59, v63 offset:9168
	v_mul_f32_e32 v64, v124, v42
	v_max_f32_e32 v64, 0, v64
	v_mul_f32_e32 v64, v64, v64
	v_cvt_pk_bf16_f32 v64, v64, v64
	ds_write_b16 v59, v64 offset:9696
	v_mul_f32_e32 v252, v125, v43
	v_max_f32_e32 v252, 0, v252
	v_mul_f32_e32 v252, v252, v252
	v_cvt_pk_bf16_f32 v252, v252, v252
	ds_write_b16 v59, v252 offset:10224
	v_mul_f32_e32 v62, v126, v44
	v_max_f32_e32 v62, 0, v62
	v_mul_f32_e32 v62, v62, v62
	v_cvt_pk_bf16_f32 v62, v62, v62
	ds_write_b16 v59, v62 offset:12864
	v_mul_f32_e32 v63, v127, v45
	v_max_f32_e32 v63, 0, v63
	v_mul_f32_e32 v63, v63, v63
	v_cvt_pk_bf16_f32 v63, v63, v63
	ds_write_b16 v59, v63 offset:13392
	v_mul_f32_e32 v64, v128, v46
	v_max_f32_e32 v64, 0, v64
	v_mul_f32_e32 v64, v64, v64
	v_cvt_pk_bf16_f32 v64, v64, v64
	ds_write_b16 v59, v64 offset:13920
	v_mul_f32_e32 v252, v129, v47
	v_max_f32_e32 v252, 0, v252
	v_mul_f32_e32 v252, v252, v252
	v_cvt_pk_bf16_f32 v252, v252, v252
	ds_write_b16 v59, v252 offset:14448
	v_mul_f32_e32 v62, v130, v48
	v_max_f32_e32 v62, 0, v62
	v_mul_f32_e32 v62, v62, v62
	v_cvt_pk_bf16_f32 v62, v62, v62
	ds_write_b16 v59, v62 offset:16896
	v_mul_f32_e32 v63, v131, v49
	v_max_f32_e32 v63, 0, v63
	v_mul_f32_e32 v63, v63, v63
	v_cvt_pk_bf16_f32 v63, v63, v63
	ds_write_b16 v59, v63 offset:17424
	v_mul_f32_e32 v64, v132, v50
	v_max_f32_e32 v64, 0, v64
	v_mul_f32_e32 v64, v64, v64
	v_cvt_pk_bf16_f32 v64, v64, v64
	ds_write_b16 v59, v64 offset:17952
	v_mul_f32_e32 v252, v133, v51
	v_max_f32_e32 v252, 0, v252
	v_mul_f32_e32 v252, v252, v252
	v_cvt_pk_bf16_f32 v252, v252, v252
	ds_write_b16 v59, v252 offset:18480
	v_mul_f32_e32 v62, v134, v52
	v_max_f32_e32 v62, 0, v62
	v_mul_f32_e32 v62, v62, v62
	v_cvt_pk_bf16_f32 v62, v62, v62
	ds_write_b16 v59, v62 offset:21120
	v_mul_f32_e32 v63, v135, v53
	v_max_f32_e32 v63, 0, v63
	v_mul_f32_e32 v63, v63, v63
	v_cvt_pk_bf16_f32 v63, v63, v63
	ds_write_b16 v59, v63 offset:21648
	v_mul_f32_e32 v64, v136, v54
	v_max_f32_e32 v64, 0, v64
	v_mul_f32_e32 v64, v64, v64
	v_cvt_pk_bf16_f32 v64, v64, v64
	ds_write_b16 v59, v64 offset:22176
	v_mul_f32_e32 v252, v137, v55
	v_max_f32_e32 v252, 0, v252
	v_mul_f32_e32 v252, v252, v252
	v_cvt_pk_bf16_f32 v252, v252, v252
	ds_write_b16 v59, v252 offset:22704
; DI u16 f2bf(float x) { return (u16)(pack2(x, 0.f) & 0xffffu); }
; DI int crow(int i, int h) { return (i & 3) + 8 * (i >> 2) + 4 * h; }
; template <class F>
; DI void epi_bf16_tile(const f32x16 (&acc)[2][2], int m0, int n0, u16* dst0, long ld, char* smem, F f) {
;     ...
;       for (int i = 0; i < 16; i++) {
;         const int ml = wm * 64 + mt * 32 + crow(i, h), nl = wn * 64 + nt * 32 + (lane & 31);
;         T[ml * 136 + nl] = f2bf(f(m0 + ml, n0 + nl, acc[mt][nt][i]));
;       }
; DI void ffn_up_phase(const Params& p, const u16* xb, int ldx, const u16* wupT, u16* hid, char* smem) {
;     ...
;                epi_bf16_tile(acc, m0, n0, hid + (long)m0 * 4096 + n0, 4096, smem, [=](int m, int n, float v) {
;                  const float a = fmaxf(v * rs[m], 0.f);
;                  return a * a;
	v_mul_f32_e32 v62, v138, v214
	v_max_f32_e32 v62, 0, v62
	v_mul_f32_e32 v62, v62, v62
	v_cvt_pk_bf16_f32 v62, v62, v62
	ds_write_b16 v59, v62 offset:25344
	v_mul_f32_e32 v63, v139, v215
	v_max_f32_e32 v63, 0, v63
	v_mul_f32_e32 v63, v63, v63
	v_cvt_pk_bf16_f32 v63, v63, v63
	ds_write_b16 v59, v63 offset:25872
	v_mul_f32_e32 v64, v140, v216
	v_max_f32_e32 v64, 0, v64
	v_mul_f32_e32 v64, v64, v64
	v_cvt_pk_bf16_f32 v64, v64, v64
	ds_write_b16 v59, v64 offset:26400
	v_mul_f32_e32 v252, v141, v217
	v_max_f32_e32 v252, 0, v252
	v_mul_f32_e32 v252, v252, v252
	v_cvt_pk_bf16_f32 v252, v252, v252
	ds_write_b16 v59, v252 offset:26928
	v_mul_f32_e32 v62, v142, v218
	v_max_f32_e32 v62, 0, v62
	v_mul_f32_e32 v62, v62, v62
	v_cvt_pk_bf16_f32 v62, v62, v62
	ds_write_b16 v59, v62 offset:29568
	v_mul_f32_e32 v63, v143, v219
	v_max_f32_e32 v63, 0, v63
	v_mul_f32_e32 v63, v63, v63
	v_cvt_pk_bf16_f32 v63, v63, v63
	ds_write_b16 v59, v63 offset:30096
	v_mul_f32_e32 v64, v144, v220
	v_max_f32_e32 v64, 0, v64
	v_mul_f32_e32 v64, v64, v64
	v_cvt_pk_bf16_f32 v64, v64, v64
	ds_write_b16 v59, v64 offset:30624
	v_mul_f32_e32 v252, v145, v221
	v_max_f32_e32 v252, 0, v252
	v_mul_f32_e32 v252, v252, v252
	v_cvt_pk_bf16_f32 v252, v252, v252
	ds_write_b16 v59, v252 offset:31152
	v_mul_f32_e32 v62, v146, v48
	v_max_f32_e32 v62, 0, v62
	v_mul_f32_e32 v62, v62, v62
	v_cvt_pk_bf16_f32 v62, v62, v62
	ds_write_b16 v59, v62 offset:16960
	v_mul_f32_e32 v63, v147, v49
	v_max_f32_e32 v63, 0, v63
	v_mul_f32_e32 v63, v63, v63
	v_cvt_pk_bf16_f32 v63, v63, v63
	ds_write_b16 v59, v63 offset:17488
	v_mul_f32_e32 v64, v148, v50
	v_max_f32_e32 v64, 0, v64
	v_mul_f32_e32 v64, v64, v64
	v_cvt_pk_bf16_f32 v64, v64, v64
	ds_write_b16 v59, v64 offset:18016
	v_mul_f32_e32 v252, v149, v51
	v_max_f32_e32 v252, 0, v252
	v_mul_f32_e32 v252, v252, v252
	v_cvt_pk_bf16_f32 v252, v252, v252
	ds_write_b16 v59, v252 offset:18544
	v_mul_f32_e32 v62, v150, v52
	v_max_f32_e32 v62, 0, v62
	v_mul_f32_e32 v62, v62, v62
	v_cvt_pk_bf16_f32 v62, v62, v62
	ds_write_b16 v59, v62 offset:21184
	v_mul_f32_e32 v63, v151, v53
	v_max_f32_e32 v63, 0, v63
	v_mul_f32_e32 v63, v63, v63
	v_cvt_pk_bf16_f32 v63, v63, v63
	ds_write_b16 v59, v63 offset:21712
	v_mul_f32_e32 v64, v152, v54
	v_max_f32_e32 v64, 0, v64
	v_mul_f32_e32 v64, v64, v64
	v_cvt_pk_bf16_f32 v64, v64, v64
	ds_write_b16 v59, v64 offset:22240
	v_mul_f32_e32 v252, v153, v55
	v_max_f32_e32 v252, 0, v252
	v_mul_f32_e32 v252, v252, v252
	v_cvt_pk_bf16_f32 v252, v252, v252
	ds_write_b16 v59, v252 offset:22768
	v_mul_f32_e32 v62, v154, v214
	v_max_f32_e32 v62, 0, v62
	v_mul_f32_e32 v62, v62, v62
	v_cvt_pk_bf16_f32 v62, v62, v62
	ds_write_b16 v59, v62 offset:25408
	v_mul_f32_e32 v63, v155, v215
	v_max_f32_e32 v63, 0, v63
	v_mul_f32_e32 v63, v63, v63
	v_cvt_pk_bf16_f32 v63, v63, v63
	ds_write_b16 v59, v63 offset:25936
	v_mul_f32_e32 v64, v156, v216
	v_max_f32_e32 v64, 0, v64
	v_mul_f32_e32 v64, v64, v64
	v_cvt_pk_bf16_f32 v64, v64, v64
	ds_write_b16 v59, v64 offset:26464
	v_mul_f32_e32 v252, v157, v217
	v_max_f32_e32 v252, 0, v252
	v_mul_f32_e32 v252, v252, v252
	v_cvt_pk_bf16_f32 v252, v252, v252
	ds_write_b16 v59, v252 offset:26992
	v_mul_f32_e32 v62, v158, v218
	v_max_f32_e32 v62, 0, v62
	v_mul_f32_e32 v62, v62, v62
	v_cvt_pk_bf16_f32 v62, v62, v62
	ds_write_b16 v59, v62 offset:29632
	v_mul_f32_e32 v63, v159, v219
	v_max_f32_e32 v63, 0, v63
	v_mul_f32_e32 v63, v63, v63
	v_cvt_pk_bf16_f32 v63, v63, v63
	ds_write_b16 v59, v63 offset:30160
	v_mul_f32_e32 v64, v160, v220
	v_max_f32_e32 v64, 0, v64
	v_mul_f32_e32 v64, v64, v64
	v_cvt_pk_bf16_f32 v64, v64, v64
	ds_write_b16 v59, v64 offset:30688
	v_mul_f32_e32 v252, v161, v221
	v_max_f32_e32 v252, 0, v252
	v_mul_f32_e32 v252, v252, v252
	v_cvt_pk_bf16_f32 v252, v252, v252
	ds_write_b16 v59, v252 offset:31216
	v_mul_f32_e32 v62, v162, v48
	v_max_f32_e32 v62, 0, v62
	v_mul_f32_e32 v62, v62, v62
	v_cvt_pk_bf16_f32 v62, v62, v62
	ds_write_b16 v59, v62 offset:17024
	v_mul_f32_e32 v63, v163, v49
	v_max_f32_e32 v63, 0, v63
	v_mul_f32_e32 v63, v63, v63
	v_cvt_pk_bf16_f32 v63, v63, v63
	ds_write_b16 v59, v63 offset:17552
	v_mul_f32_e32 v64, v164, v50
	v_max_f32_e32 v64, 0, v64
	v_mul_f32_e32 v64, v64, v64
	v_cvt_pk_bf16_f32 v64, v64, v64
	ds_write_b16 v59, v64 offset:18080
	v_mul_f32_e32 v252, v165, v51
	v_max_f32_e32 v252, 0, v252
	v_mul_f32_e32 v252, v252, v252
	v_cvt_pk_bf16_f32 v252, v252, v252
	ds_write_b16 v59, v252 offset:18608
	v_mul_f32_e32 v62, v166, v52
	v_max_f32_e32 v62, 0, v62
	v_mul_f32_e32 v62, v62, v62
	v_cvt_pk_bf16_f32 v62, v62, v62
	ds_write_b16 v59, v62 offset:21248
	v_mul_f32_e32 v63, v167, v53
	v_max_f32_e32 v63, 0, v63
	v_mul_f32_e32 v63, v63, v63
	v_cvt_pk_bf16_f32 v63, v63, v63
	ds_write_b16 v59, v63 offset:21776
	v_mul_f32_e32 v64, v168, v54
	v_max_f32_e32 v64, 0, v64
	v_mul_f32_e32 v64, v64, v64
	v_cvt_pk_bf16_f32 v64, v64, v64
	ds_write_b16 v59, v64 offset:22304
	v_mul_f32_e32 v252, v169, v55
	v_max_f32_e32 v252, 0, v252
	v_mul_f32_e32 v252, v252, v252
	v_cvt_pk_bf16_f32 v252, v252, v252
	ds_write_b16 v59, v252 offset:22832
	v_mul_f32_e32 v62, v170, v214
	v_max_f32_e32 v62, 0, v62
	v_mul_f32_e32 v62, v62, v62
	v_cvt_pk_bf16_f32 v62, v62, v62
	ds_write_b16 v59, v62 offset:25472
	v_mul_f32_e32 v63, v171, v215
	v_max_f32_e32 v63, 0, v63
	v_mul_f32_e32 v63, v63, v63
	v_cvt_pk_bf16_f32 v63, v63, v63
	ds_write_b16 v59, v63 offset:26000
	v_mul_f32_e32 v64, v172, v216
	v_max_f32_e32 v64, 0, v64
	v_mul_f32_e32 v64, v64, v64
	v_cvt_pk_bf16_f32 v64, v64, v64
	ds_write_b16 v59, v64 offset:26528
	v_mul_f32_e32 v252, v173, v217
	v_max_f32_e32 v252, 0, v252
	v_mul_f32_e32 v252, v252, v252
	v_cvt_pk_bf16_f32 v252, v252, v252
; DI u16 f2bf(float x) { return (u16)(pack2(x, 0.f) & 0xffffu); }
; DI int crow(int i, int h) { return (i & 3) + 8 * (i >> 2) + 4 * h; }
; template <class F>
; DI void epi_bf16_tile(const f32x16 (&acc)[2][2], int m0, int n0, u16* dst0, long ld, char* smem, F f) {
;     ...
;       for (int i = 0; i < 16; i++) {
;         const int ml = wm * 64 + mt * 32 + crow(i, h), nl = wn * 64 + nt * 32 + (lane & 31);
;         T[ml * 136 + nl] = f2bf(f(m0 + ml, n0 + nl, acc[mt][nt][i]));
;       }
;   __syncthreads();
; #pragma unroll
;   for (int j = 0; j < 8; j++) {
;     const int idx = tid + 256 * j, row = idx >> 4, ch = idx & 15;
;     *(uint4*)(dst0 + (long)row * ld + ch * 8) = *(const uint4*)(T + row * 136 + ch * 8);
;   }
;   __syncthreads();
; template <class AL, class BL, class EP>
; DI void gemm_phase(int MT, int NTL, int K, AL al, BL bl, EP ep, char* smem) {
;   for (int t = blockIdx.x; t < MT * NTL; t += gridDim.x) {
	ds_write_b16 v59, v252 offset:27056
	v_mul_f32_e32 v62, v174, v218
	v_max_f32_e32 v62, 0, v62
	v_mul_f32_e32 v62, v62, v62
	v_cvt_pk_bf16_f32 v62, v62, v62
	ds_write_b16 v59, v62 offset:29696
	v_mul_f32_e32 v63, v175, v219
	v_max_f32_e32 v63, 0, v63
	v_mul_f32_e32 v63, v63, v63
	v_cvt_pk_bf16_f32 v63, v63, v63
	ds_write_b16 v59, v63 offset:30224
	v_mul_f32_e32 v64, v176, v220
	v_max_f32_e32 v64, 0, v64
	v_mul_f32_e32 v64, v64, v64
	v_cvt_pk_bf16_f32 v64, v64, v64
	ds_write_b16 v59, v64 offset:30752
	v_mul_f32_e32 v252, v177, v221
	v_max_f32_e32 v252, 0, v252
	v_mul_f32_e32 v252, v252, v252
	v_cvt_pk_bf16_f32 v252, v252, v252
	ds_write_b16 v59, v252 offset:31280
	v_mul_f32_e32 v62, v178, v48
	v_max_f32_e32 v62, 0, v62
	v_mul_f32_e32 v62, v62, v62
	v_cvt_pk_bf16_f32 v62, v62, v62
	ds_write_b16 v59, v62 offset:17088
	v_mul_f32_e32 v63, v179, v49
	v_max_f32_e32 v63, 0, v63
	v_mul_f32_e32 v63, v63, v63
	v_cvt_pk_bf16_f32 v63, v63, v63
	ds_write_b16 v59, v63 offset:17616
	v_mul_f32_e32 v64, v180, v50
	v_max_f32_e32 v64, 0, v64
	v_mul_f32_e32 v64, v64, v64
	v_cvt_pk_bf16_f32 v64, v64, v64
	ds_write_b16 v59, v64 offset:18144
	v_mul_f32_e32 v252, v181, v51
	v_max_f32_e32 v252, 0, v252
	v_mul_f32_e32 v252, v252, v252
	v_cvt_pk_bf16_f32 v252, v252, v252
	ds_write_b16 v59, v252 offset:18672
	v_mul_f32_e32 v62, v182, v52
	v_max_f32_e32 v62, 0, v62
	v_mul_f32_e32 v62, v62, v62
	v_cvt_pk_bf16_f32 v62, v62, v62
	ds_write_b16 v59, v62 offset:21312
	v_mul_f32_e32 v63, v183, v53
	v_max_f32_e32 v63, 0, v63
	v_mul_f32_e32 v63, v63, v63
	v_cvt_pk_bf16_f32 v63, v63, v63
	ds_write_b16 v59, v63 offset:21840
	v_mul_f32_e32 v64, v184, v54
	v_max_f32_e32 v64, 0, v64
	v_mul_f32_e32 v64, v64, v64
	v_cvt_pk_bf16_f32 v64, v64, v64
	ds_write_b16 v59, v64 offset:22368
	v_mul_f32_e32 v252, v185, v55
	v_max_f32_e32 v252, 0, v252
	v_mul_f32_e32 v252, v252, v252
	v_cvt_pk_bf16_f32 v252, v252, v252
	ds_write_b16 v59, v252 offset:22896
	v_mul_f32_e32 v62, v186, v214
	v_max_f32_e32 v62, 0, v62
	v_mul_f32_e32 v62, v62, v62
	v_cvt_pk_bf16_f32 v62, v62, v62
	ds_write_b16 v59, v62 offset:25536
	v_mul_f32_e32 v63, v187, v215
	v_max_f32_e32 v63, 0, v63
	v_mul_f32_e32 v63, v63, v63
	v_cvt_pk_bf16_f32 v63, v63, v63
	ds_write_b16 v59, v63 offset:26064
	v_mul_f32_e32 v64, v188, v216
	v_max_f32_e32 v64, 0, v64
	v_mul_f32_e32 v64, v64, v64
	v_cvt_pk_bf16_f32 v64, v64, v64
	ds_write_b16 v59, v64 offset:26592
	v_mul_f32_e32 v252, v189, v217
	v_max_f32_e32 v252, 0, v252
	v_mul_f32_e32 v252, v252, v252
	v_cvt_pk_bf16_f32 v252, v252, v252
	ds_write_b16 v59, v252 offset:27120
	v_mul_f32_e32 v62, v190, v218
	v_max_f32_e32 v62, 0, v62
	v_mul_f32_e32 v62, v62, v62
	v_cvt_pk_bf16_f32 v62, v62, v62
	ds_write_b16 v59, v62 offset:29760
	v_mul_f32_e32 v63, v191, v219
	v_max_f32_e32 v63, 0, v63
	v_mul_f32_e32 v63, v63, v63
	v_cvt_pk_bf16_f32 v63, v63, v63
	ds_write_b16 v59, v63 offset:30288
	v_mul_f32_e32 v64, v192, v220
	v_max_f32_e32 v64, 0, v64
	v_mul_f32_e32 v64, v64, v64
	v_cvt_pk_bf16_f32 v64, v64, v64
	ds_write_b16 v59, v64 offset:30816
	v_mul_f32_e32 v252, v193, v221
	v_max_f32_e32 v252, 0, v252
	v_mul_f32_e32 v252, v252, v252
	v_cvt_pk_bf16_f32 v252, v252, v252
	ds_write_b16 v59, v252 offset:31344
	s_waitcnt lgkmcnt(0)
	s_barrier
	ds_read_b128 v[0:3], v60 offset:0
	ds_read_b128 v[4:7], v60 offset:4224
	ds_read_b128 v[8:11], v60 offset:8448
	ds_read_b128 v[12:15], v60 offset:12672
	ds_read_b128 v[16:19], v60 offset:16896
	ds_read_b128 v[20:23], v60 offset:21120
	ds_read_b128 v[24:27], v60 offset:25344
	ds_read_b128 v[28:31], v60 offset:29568
	s_waitcnt lgkmcnt(7)
	global_store_dwordx4 v227, v[0:3], s[18:19]
	s_add_u32 s18, s18, 65536
	s_addc_u32 s19, s19, 0
	ds_read_b128 v[0:3], v60 offset:33792
	s_waitcnt lgkmcnt(7)
	global_store_dwordx4 v227, v[4:7], s[18:19]
	s_add_u32 s18, s18, 65536
	s_addc_u32 s19, s19, 0
	ds_read_b128 v[4:7], v60 offset:38016
	s_waitcnt lgkmcnt(7)
	global_store_dwordx4 v227, v[8:11], s[18:19]
	s_add_u32 s18, s18, 65536
	s_addc_u32 s19, s19, 0
	ds_read_b128 v[8:11], v60 offset:42240
	s_waitcnt lgkmcnt(7)
	global_store_dwordx4 v227, v[12:15], s[18:19]
	s_add_u32 s18, s18, 65536
	s_addc_u32 s19, s19, 0
	ds_read_b128 v[12:15], v60 offset:46464
	s_waitcnt lgkmcnt(7)
	global_store_dwordx4 v227, v[16:19], s[18:19]
	s_add_u32 s18, s18, 65536
	s_addc_u32 s19, s19, 0
	ds_read_b128 v[16:19], v60 offset:50688
	s_waitcnt lgkmcnt(7)
	global_store_dwordx4 v227, v[20:23], s[18:19]
	s_add_u32 s18, s18, 65536
	s_addc_u32 s19, s19, 0
	ds_read_b128 v[20:23], v60 offset:54912
	s_waitcnt lgkmcnt(7)
	global_store_dwordx4 v227, v[24:27], s[18:19]
	s_add_u32 s18, s18, 65536
	s_addc_u32 s19, s19, 0
	ds_read_b128 v[24:27], v60 offset:59136
	s_waitcnt lgkmcnt(7)
	global_store_dwordx4 v227, v[28:31], s[18:19]
	s_add_u32 s18, s18, 65536
	s_addc_u32 s19, s19, 0
	ds_read_b128 v[28:31], v60 offset:63360
	s_waitcnt lgkmcnt(7)
	global_store_dwordx4 v227, v[0:3], s[18:19]
	s_add_u32 s18, s18, 65536
	s_addc_u32 s19, s19, 0
	s_waitcnt lgkmcnt(6)
	global_store_dwordx4 v227, v[4:7], s[18:19]
	s_add_u32 s18, s18, 65536
	s_addc_u32 s19, s19, 0
	s_waitcnt lgkmcnt(5)
	global_store_dwordx4 v227, v[8:11], s[18:19]
	s_add_u32 s18, s18, 65536
	s_addc_u32 s19, s19, 0
	s_waitcnt lgkmcnt(4)
	global_store_dwordx4 v227, v[12:15], s[18:19]
	s_add_u32 s18, s18, 65536
	s_addc_u32 s19, s19, 0
	s_waitcnt lgkmcnt(3)
	global_store_dwordx4 v227, v[16:19], s[18:19]
	s_add_u32 s18, s18, 65536
	s_addc_u32 s19, s19, 0
	s_waitcnt lgkmcnt(2)
	global_store_dwordx4 v227, v[20:23], s[18:19]
	s_add_u32 s18, s18, 65536
	s_addc_u32 s19, s19, 0
	s_waitcnt lgkmcnt(1)
	global_store_dwordx4 v227, v[24:27], s[18:19]
	s_add_u32 s18, s18, 65536
	s_addc_u32 s19, s19, 0
	s_waitcnt lgkmcnt(0)
	global_store_dwordx4 v227, v[28:31], s[18:19]
	s_barrier
	v_bfe_u32 v62, v202, 5, 1
	v_and_b32_e32 v63, 31, v202
	v_lshrrev_b32_e32 v64, 7, v202
	v_bfe_u32 v252, v202, 6, 1
	s_add_u32 s98, s98, s50
	s_cmpk_lt_u32 s98, 0x800
	s_cbranch_scc1 .Lfu1_tile
	s_cmpk_lt_u32 s78, 0xe0
	s_cbranch_scc0 .Lfu1_s2
	s_cmpk_ge_u32 s78, 0x70
	s_cselect_b32 s0, 1, 0
	s_mul_i32 s1, s0, 0x70
	s_sub_u32 s1, s78, s1
	s_add_u32 s1, s1, 32
	s_add_u32 s0, s0, 28
	s_branch .Lfu1_s3

; #define G_LOAD(S, kt_) do { G_LD1(S##a0, S##b0, 0, kt_); G_LD1(S##a1, S##b1, 1, kt_); G_LD1(S##a2, S##b2, 2, kt_); G_LD1(S##a3, S##b3, 3, kt_); } while (0)
; #define G_STORE(S, buf_) do { G_ST1(S##a0, S##b0, 0, buf_); G_ST1(S##a1, S##b1, 1, buf_); G_ST1(S##a2, S##b2, 2, buf_); G_ST1(S##a3, S##b3, 3, buf_); } while (0)
; template <class AL, class BL>
; DI void gemm_core(AL al, BL bl, int m0, int n0, int K, char* smem, f32x16 (&acc)[2][2]) {
;     ...
;   G_LOAD(x, 0);
;   G_STORE(x, 0);
;   G_LOAD(x, 1);
;   G_LOAD(y, (nk > 2) ? 2 : 1);
;   __syncthreads();
;   for (int kt = 0; kt < nk; kt += 2) {
;     G_TILE(0, x, true, (kt + 3 < nk), kt + 3);
;     __syncthreads();
;     G_TILE(1, y, (kt + 2 < nk), (kt + 4 < nk), kt + 4);
;     __syncthreads();
;   }
; template <class AL, class BL, class EP>
; DI void gemm_phase(int MT, int NTL, int K, AL al, BL bl, EP ep, char* smem) {
;   for (int t = blockIdx.x; t < MT * NTL; t += gridDim.x) {
;     const int tm = t % MT, tn = t / MT;
;     f32x16 acc[2][2];
;     gemm_core(al, bl, tm * 128, tn * 128, K, smem, acc);
.Lfu1_s3:
	s_mul_i32 s0, s0, 0x90
	s_add_u32 s30, s0, s1
	s_lshl_b32 s22, s30, 7
	s_add_u32 s22, s22, 48
.LBB0_1674:
	s_mul_hi_i32 s0, s30, 0x38e38e39
	s_lshr_b32 s1, s0, 31
	s_ashr_i32 s0, s0, 5
	s_add_i32 s1, s0, s1
	v_mov_b32_e32 v32, v202
	s_lshl_b32 s0, s1, 7
	s_mul_i32 s31, s1, 0x4800
	v_ashrrev_i32_e32 v33, 3, v32
	v_add_u32_e32 v4, s0, v33
	v_ashrrev_i32_e32 v5, 31, v4
	v_lshlrev_b32_e32 v2, 4, v32
	v_lshlrev_b64 v[4:5], 11, v[4:5]
	v_and_b32_e32 v64, 0x70, v2
	v_lshl_add_u64 v[4:5], s[6:7], 0, v[4:5]
	v_lshl_add_u64 v[78:79], v[4:5], 0, v[64:65]
	v_subrev_u32_e32 v0, s31, v33
	v_add_co_u32_e32 v12, vcc, s24, v78
	v_add_u32_e32 v24, s22, v0
	s_nop 0
	v_addc_co_u32_e32 v13, vcc, 0, v79, vcc
	v_subrev_u32_e32 v0, 48, v24
	v_add_co_u32_e32 v20, vcc, s25, v78
	v_ashrrev_i32_e32 v1, 31, v0
	global_load_dwordx4 v[4:7], v[78:79], off
	v_add_u32_e32 v8, -16, v24
	v_addc_co_u32_e32 v21, vcc, 0, v79, vcc
	v_lshlrev_b64 v[0:1], 12, v[0:1]
	v_ashrrev_i32_e32 v9, 31, v8
	global_load_dwordx4 v[12:15], v[12:13], off
	v_add_u32_e32 v16, 16, v24
	v_add_u32_e32 v28, 48, v24
	v_add_co_u32_e32 v24, vcc, s26, v78
	v_lshl_add_u64 v[0:1], s[68:69], 0, v[0:1]
	v_lshlrev_b64 v[8:9], 12, v[8:9]
	v_ashrrev_i32_e32 v17, 31, v16
	global_load_dwordx4 v[20:23], v[20:21], off
	v_addc_co_u32_e32 v25, vcc, 0, v79, vcc
	v_lshl_add_u64 v[76:77], v[0:1], 0, v[64:65]
	v_lshl_add_u64 v[8:9], s[68:69], 0, v[8:9]
	v_lshlrev_b64 v[16:17], 12, v[16:17]
	v_ashrrev_i32_e32 v29, 31, v28
	global_load_dwordx4 v[24:27], v[24:25], off
	v_lshl_add_u64 v[74:75], v[8:9], 0, v[64:65]
	global_load_dwordx4 v[0:3], v[76:77], off offset:2048
	global_load_dwordx4 v[8:11], v[74:75], off offset:2048
	v_lshl_add_u64 v[16:17], s[68:69], 0, v[16:17]
	v_lshlrev_b64 v[28:29], 12, v[28:29]
	v_lshl_add_u64 v[70:71], v[16:17], 0, v[64:65]
	v_lshl_add_u64 v[28:29], s[68:69], 0, v[28:29]
	global_load_dwordx4 v[16:19], v[70:71], off offset:2048
	v_lshl_add_u64 v[72:73], v[28:29], 0, v[64:65]
	global_load_dwordx4 v[28:31], v[72:73], off offset:2048
	v_lshrrev_b32_e32 v34, 1, v32
	v_and_b32_e32 v35, 31, v32
	v_mad_u64_u32 v[68:69], s[2:3], v33, s27, v[64:65]
	v_lshl_add_u64 v[84:85], v[78:79], 0, s[10:11]
	v_lshl_add_u64 v[82:83], v[78:79], 0, s[14:15]
	v_lshl_add_u64 v[80:81], v[78:79], 0, s[16:17]
	global_load_dwordx4 v[86:89], v[78:79], off offset:128
	global_load_dwordx4 v[90:93], v[78:79], off offset:256
	global_load_dwordx4 v[94:97], v[84:85], off offset:128
	global_load_dwordx4 v[98:101], v[84:85], off offset:256
	global_load_dwordx4 v[102:105], v[82:83], off offset:128
	global_load_dwordx4 v[106:109], v[82:83], off offset:256
	global_load_dwordx4 v[110:113], v[80:81], off offset:128
	global_load_dwordx4 v[114:117], v[80:81], off offset:256
	global_load_dwordx4 v[118:121], v[76:77], off offset:2176
	global_load_dwordx4 v[122:125], v[74:75], off offset:2176
	global_load_dwordx4 v[126:129], v[70:71], off offset:2176
	global_load_dwordx4 v[130:133], v[72:73], off offset:2176
	global_load_dwordx4 v[134:137], v[76:77], off offset:2304
	global_load_dwordx4 v[138:141], v[74:75], off offset:2304
	global_load_dwordx4 v[142:145], v[70:71], off offset:2304
	global_load_dwordx4 v[146:149], v[72:73], off offset:2304
	s_mulk_i32 s1, 0xb800
	s_add_i32 s1, s22, s1
	s_sub_i32 s18, s1, 48
	s_waitcnt vmcnt(23)
	ds_write_b128 v68, v[4:7] offset:36864
	s_waitcnt vmcnt(22)
	ds_write_b128 v68, v[12:15] offset:41472
	s_waitcnt vmcnt(21)
	ds_write_b128 v68, v[20:23] offset:46080
	s_waitcnt vmcnt(20)
	ds_write_b128 v68, v[24:27] offset:50688
	s_waitcnt vmcnt(19)
	ds_write_b128 v68, v[0:3]
	s_waitcnt vmcnt(18)
	ds_write_b128 v68, v[8:11] offset:4608
	s_waitcnt vmcnt(17)
	ds_write_b128 v68, v[16:19] offset:9216
	s_waitcnt vmcnt(16)
	ds_write_b128 v68, v[28:31] offset:13824
	v_and_or_b32 v0, v34, s28, v35
	v_and_b32_e32 v4, 16, v34
	v_mad_u64_u32 v[66:67], s[2:3], v0, s27, v[4:5]
	s_waitcnt lgkmcnt(0)
	s_barrier
	ds_read_b128 v[0:3], v66
	v_and_b32_e32 v5, 0x5f, v32
	v_mul_u32_u24_e32 v5, 0x48, v5
	v_lshl_add_u32 v64, v5, 1, v4
	ds_read_b128 v[4:7], v64 offset:36864
	ds_read_b128 v[150:153], v66 offset:32
	ds_read_b128 v[154:157], v64 offset:36896
	ds_read_b128 v[8:11], v64 offset:41472
	ds_read_b128 v[158:161], v64 offset:41504
	s_waitcnt lgkmcnt(4)
	v_mfma_f32_32x32x16_bf16 v[48:63], v[0:3], v[4:7], 0
	v_add_u32_e32 v67, 0x9000, v68
	s_waitcnt lgkmcnt(1)
	v_mfma_f32_32x32x16_bf16 v[32:47], v[0:3], v[8:11], 0
	ds_read_b128 v[0:3], v66 offset:4608
	ds_read_b128 v[162:165], v66 offset:4640
	global_load_dwordx4 v[166:169], v[76:77], off offset:2432
	global_load_dwordx4 v[170:173], v[78:79], off offset:384
	s_waitcnt vmcnt(9)
	ds_write_b128 v68, v[118:121] offset:18432
	ds_write_b128 v68, v[86:89] offset:55296
	s_waitcnt lgkmcnt(3)
	v_mfma_f32_32x32x16_bf16 v[16:31], v[0:3], v[4:7], 0
	v_mfma_f32_32x32x16_bf16 v[0:15], v[0:3], v[8:11], 0
	global_load_dwordx4 v[86:89], v[74:75], off offset:2432
	global_load_dwordx4 v[118:121], v[84:85], off offset:384
	v_mfma_f32_32x32x16_bf16 v[48:63], v[150:153], v[154:157], v[48:63]
	v_mfma_f32_32x32x16_bf16 v[32:47], v[150:153], v[158:161], v[32:47]
	s_waitcnt lgkmcnt(2)
	v_mfma_f32_32x32x16_bf16 v[16:31], v[162:165], v[154:157], v[16:31]
	ds_read_b128 v[150:153], v66 offset:64
	ds_read_b128 v[154:157], v66 offset:4672
	ds_read_b128 v[174:177], v64 offset:36928
	ds_read_b128 v[178:181], v64 offset:41536
	s_waitcnt vmcnt(10)
	ds_write_b128 v68, v[122:125] offset:23040
	ds_write_b128 v68, v[94:97] offset:59904
	v_mfma_f32_32x32x16_bf16 v[0:15], v[162:165], v[158:161], v[0:15]
	global_load_dwordx4 v[94:97], v[70:71], off offset:2432
	global_load_dwordx4 v[122:125], v[82:83], off offset:384
	s_waitcnt lgkmcnt(3)
	v_mfma_f32_32x32x16_bf16 v[48:63], v[150:153], v[174:177], v[48:63]
	s_waitcnt lgkmcnt(2)
	v_mfma_f32_32x32x16_bf16 v[32:47], v[150:153], v[178:181], v[32:47]
	v_mfma_f32_32x32x16_bf16 v[16:31], v[154:157], v[174:177], v[16:31]
	ds_read_b128 v[150:153], v66 offset:96
	ds_read_b128 v[158:161], v66 offset:4704
	ds_read_b128 v[162:165], v64 offset:36960
	ds_read_b128 v[174:177], v64 offset:41568
	s_waitcnt vmcnt(11)
	ds_write_b128 v68, v[126:129] offset:27648
	ds_write_b128 v68, v[102:105] offset:64512
	v_mfma_f32_32x32x16_bf16 v[0:15], v[154:157], v[178:181], v[0:15]
	global_load_dwordx4 v[102:105], v[72:73], off offset:2432
	global_load_dwordx4 v[126:129], v[80:81], off offset:384
	s_waitcnt lgkmcnt(3)
	v_mfma_f32_32x32x16_bf16 v[48:63], v[150:153], v[162:165], v[48:63]
	s_waitcnt vmcnt(12)
	ds_write_b128 v68, v[130:133] offset:32256
	ds_write_b128 v67, v[110:113] offset:32256
	s_waitcnt lgkmcnt(4)
	v_mfma_f32_32x32x16_bf16 v[32:47], v[150:153], v[174:177], v[32:47]
	v_mfma_f32_32x32x16_bf16 v[16:31], v[158:161], v[162:165], v[16:31]
	v_mfma_f32_32x32x16_bf16 v[0:15], v[158:161], v[174:177], v[0:15]
	s_waitcnt lgkmcnt(0)
	s_barrier
; template <class AL, class BL>
; DI void gemm_core(AL al, BL bl, int m0, int n0, int K, char* smem, f32x16 (&acc)[2][2]) {
;     ...
;   for (int kt = 0; kt < nk; kt += 2) {
;     G_TILE(0, x, true, (kt + 3 < nk), kt + 3);
;     __syncthreads();
;     G_TILE(1, y, (kt + 2 < nk), (kt + 4 < nk), kt + 4);
;     __syncthreads();
;   }
	ds_read_b128 v[110:113], v66 offset:18432
	ds_read_b128 v[130:133], v64 offset:55296
	ds_read_b128 v[150:153], v66 offset:18464
	ds_read_b128 v[154:157], v64 offset:55328
	ds_read_b128 v[158:161], v64 offset:59904
	ds_read_b128 v[162:165], v64 offset:59936
	s_waitcnt lgkmcnt(4)
	v_mfma_f32_32x32x16_bf16 v[48:63], v[110:113], v[130:133], v[48:63]
	s_waitcnt lgkmcnt(1)
	v_mfma_f32_32x32x16_bf16 v[32:47], v[110:113], v[158:161], v[32:47]
	ds_read_b128 v[110:113], v66 offset:23040
	ds_read_b128 v[174:177], v66 offset:23072
	s_waitcnt lgkmcnt(1)
	v_mfma_f32_32x32x16_bf16 v[16:31], v[110:113], v[130:133], v[16:31]
	global_load_dwordx4 v[130:133], v[76:77], off offset:2560
	global_load_dwordx4 v[178:181], v[78:79], off offset:512
	s_waitcnt vmcnt(13)
	ds_write_b128 v68, v[134:137]
	ds_write_b128 v68, v[90:93] offset:36864
	v_mfma_f32_32x32x16_bf16 v[0:15], v[110:113], v[158:161], v[0:15]
	global_load_dwordx4 v[90:93], v[74:75], off offset:2560
	global_load_dwordx4 v[110:113], v[84:85], off offset:512
	v_mfma_f32_32x32x16_bf16 v[48:63], v[150:153], v[154:157], v[48:63]
	v_mfma_f32_32x32x16_bf16 v[32:47], v[150:153], v[162:165], v[32:47]
	s_waitcnt lgkmcnt(2)
	v_mfma_f32_32x32x16_bf16 v[16:31], v[174:177], v[154:157], v[16:31]
	ds_read_b128 v[134:137], v66 offset:18496
	ds_read_b128 v[150:153], v66 offset:23104
	ds_read_b128 v[154:157], v64 offset:55360
	ds_read_b128 v[158:161], v64 offset:59968
	s_waitcnt vmcnt(14)
	ds_write_b128 v68, v[138:141] offset:4608
	ds_write_b128 v68, v[98:101] offset:41472
	v_mfma_f32_32x32x16_bf16 v[0:15], v[174:177], v[162:165], v[0:15]
	s_waitcnt lgkmcnt(3)
	v_mfma_f32_32x32x16_bf16 v[48:63], v[134:137], v[154:157], v[48:63]
	s_waitcnt lgkmcnt(2)
	v_mfma_f32_32x32x16_bf16 v[32:47], v[134:137], v[158:161], v[32:47]
	global_load_dwordx4 v[98:101], v[70:71], off offset:2560
	global_load_dwordx4 v[134:137], v[82:83], off offset:512
	v_mfma_f32_32x32x16_bf16 v[16:31], v[150:153], v[154:157], v[16:31]
	ds_read_b128 v[138:141], v66 offset:18528
	ds_read_b128 v[154:157], v66 offset:23136
	ds_read_b128 v[162:165], v64 offset:55392
	ds_read_b128 v[174:177], v64 offset:60000
	s_waitcnt vmcnt(15)
	ds_write_b128 v68, v[142:145] offset:9216
	ds_write_b128 v68, v[106:109] offset:46080
	v_mfma_f32_32x32x16_bf16 v[0:15], v[150:153], v[158:161], v[0:15]
	s_waitcnt lgkmcnt(3)
	v_mfma_f32_32x32x16_bf16 v[48:63], v[138:141], v[162:165], v[48:63]
	s_waitcnt lgkmcnt(2)
	v_mfma_f32_32x32x16_bf16 v[32:47], v[138:141], v[174:177], v[32:47]
	global_load_dwordx4 v[106:109], v[72:73], off offset:2560
	global_load_dwordx4 v[138:141], v[80:81], off offset:512
	s_waitcnt vmcnt(16)
	ds_write_b128 v68, v[146:149] offset:13824
	ds_write_b128 v68, v[114:117] offset:50688
	v_mfma_f32_32x32x16_bf16 v[16:31], v[154:157], v[162:165], v[16:31]
	v_mfma_f32_32x32x16_bf16 v[0:15], v[154:157], v[174:177], v[0:15]
	s_waitcnt lgkmcnt(0)
	s_barrier
	ds_read_b128 v[114:117], v66
	ds_read_b128 v[142:145], v64 offset:36864
	ds_read_b128 v[146:149], v66 offset:32
	ds_read_b128 v[150:153], v64 offset:36896
	ds_read_b128 v[154:157], v64 offset:41472
	ds_read_b128 v[158:161], v64 offset:41504
	s_waitcnt lgkmcnt(4)
	v_mfma_f32_32x32x16_bf16 v[48:63], v[114:117], v[142:145], v[48:63]
	s_waitcnt lgkmcnt(1)
	v_mfma_f32_32x32x16_bf16 v[32:47], v[114:117], v[154:157], v[32:47]
	ds_read_b128 v[114:117], v66 offset:4608
	ds_read_b128 v[162:165], v66 offset:4640
	s_waitcnt lgkmcnt(1)
	v_mfma_f32_32x32x16_bf16 v[16:31], v[114:117], v[142:145], v[16:31]
	global_load_dwordx4 v[142:145], v[76:77], off offset:2688
	global_load_dwordx4 v[174:177], v[78:79], off offset:640
	s_waitcnt vmcnt(17)
	ds_write_b128 v68, v[166:169] offset:18432
	s_waitcnt vmcnt(16)
	ds_write_b128 v68, v[170:173] offset:55296
	v_mfma_f32_32x32x16_bf16 v[0:15], v[114:117], v[154:157], v[0:15]
	v_mfma_f32_32x32x16_bf16 v[48:63], v[146:149], v[150:153], v[48:63]
	v_mfma_f32_32x32x16_bf16 v[32:47], v[146:149], v[158:161], v[32:47]
	global_load_dwordx4 v[114:117], v[74:75], off offset:2688
	global_load_dwordx4 v[146:149], v[84:85], off offset:640
	s_waitcnt lgkmcnt(2)
	v_mfma_f32_32x32x16_bf16 v[16:31], v[162:165], v[150:153], v[16:31]
	ds_read_b128 v[150:153], v66 offset:64
	ds_read_b128 v[154:157], v66 offset:4672
	ds_read_b128 v[166:169], v64 offset:36928
	ds_read_b128 v[170:173], v64 offset:41536
	s_waitcnt vmcnt(17)
	ds_write_b128 v68, v[86:89] offset:23040
	s_waitcnt vmcnt(16)
	ds_write_b128 v68, v[118:121] offset:59904
	v_mfma_f32_32x32x16_bf16 v[0:15], v[162:165], v[158:161], v[0:15]
	global_load_dwordx4 v[86:89], v[70:71], off offset:2688
	global_load_dwordx4 v[118:121], v[82:83], off offset:640
	s_waitcnt lgkmcnt(3)
	v_mfma_f32_32x32x16_bf16 v[48:63], v[150:153], v[166:169], v[48:63]
	s_waitcnt lgkmcnt(2)
	v_mfma_f32_32x32x16_bf16 v[32:47], v[150:153], v[170:173], v[32:47]
	v_mfma_f32_32x32x16_bf16 v[16:31], v[154:157], v[166:169], v[16:31]
	ds_read_b128 v[150:153], v66 offset:96
	ds_read_b128 v[158:161], v66 offset:4704
	ds_read_b128 v[162:165], v64 offset:36960
	ds_read_b128 v[166:169], v64 offset:41568
	s_waitcnt vmcnt(17)
	ds_write_b128 v68, v[94:97] offset:27648
	s_waitcnt vmcnt(16)
	ds_write_b128 v68, v[122:125] offset:64512
	v_mfma_f32_32x32x16_bf16 v[0:15], v[154:157], v[170:173], v[0:15]
	global_load_dwordx4 v[94:97], v[72:73], off offset:2688
	global_load_dwordx4 v[122:125], v[80:81], off offset:640
	s_waitcnt lgkmcnt(3)
	v_mfma_f32_32x32x16_bf16 v[48:63], v[150:153], v[162:165], v[48:63]
	s_waitcnt vmcnt(17)
	ds_write_b128 v68, v[102:105] offset:32256
	s_waitcnt vmcnt(16)
	ds_write_b128 v67, v[126:129] offset:32256
	s_waitcnt lgkmcnt(4)
	v_mfma_f32_32x32x16_bf16 v[32:47], v[150:153], v[166:169], v[32:47]
	v_mfma_f32_32x32x16_bf16 v[16:31], v[158:161], v[162:165], v[16:31]
	v_mfma_f32_32x32x16_bf16 v[0:15], v[158:161], v[166:169], v[0:15]
	s_waitcnt lgkmcnt(0)
	s_barrier
; template <class AL, class BL>
; DI void gemm_core(AL al, BL bl, int m0, int n0, int K, char* smem, f32x16 (&acc)[2][2]) {
;     ...
;   for (int kt = 0; kt < nk; kt += 2) {
;     G_TILE(0, x, true, (kt + 3 < nk), kt + 3);
;     __syncthreads();
;     G_TILE(1, y, (kt + 2 < nk), (kt + 4 < nk), kt + 4);
;     __syncthreads();
;   }
	ds_read_b128 v[102:105], v66 offset:18432
	ds_read_b128 v[126:129], v64 offset:55296
	ds_read_b128 v[150:153], v66 offset:18464
	ds_read_b128 v[154:157], v64 offset:55328
	ds_read_b128 v[158:161], v64 offset:59904
	ds_read_b128 v[162:165], v64 offset:59936
	s_waitcnt lgkmcnt(4)
	v_mfma_f32_32x32x16_bf16 v[48:63], v[102:105], v[126:129], v[48:63]
	s_waitcnt lgkmcnt(1)
	v_mfma_f32_32x32x16_bf16 v[32:47], v[102:105], v[158:161], v[32:47]
	ds_read_b128 v[102:105], v66 offset:23040
	ds_read_b128 v[166:169], v66 offset:23072
	s_waitcnt lgkmcnt(1)
	v_mfma_f32_32x32x16_bf16 v[16:31], v[102:105], v[126:129], v[16:31]
	global_load_dwordx4 v[126:129], v[76:77], off offset:2816
	global_load_dwordx4 v[170:173], v[78:79], off offset:768
	s_waitcnt vmcnt(17)
	ds_write_b128 v68, v[130:133]
	s_waitcnt vmcnt(16)
	ds_write_b128 v68, v[178:181] offset:36864
	v_mfma_f32_32x32x16_bf16 v[0:15], v[102:105], v[158:161], v[0:15]
	global_load_dwordx4 v[102:105], v[74:75], off offset:2816
	global_load_dwordx4 v[130:133], v[84:85], off offset:768
	v_mfma_f32_32x32x16_bf16 v[48:63], v[150:153], v[154:157], v[48:63]
	v_mfma_f32_32x32x16_bf16 v[32:47], v[150:153], v[162:165], v[32:47]
	s_waitcnt lgkmcnt(2)
	v_mfma_f32_32x32x16_bf16 v[16:31], v[166:169], v[154:157], v[16:31]
	ds_read_b128 v[150:153], v66 offset:18496
	ds_read_b128 v[154:157], v66 offset:23104
	ds_read_b128 v[158:161], v64 offset:55360
	ds_read_b128 v[178:181], v64 offset:59968
	s_waitcnt vmcnt(17)
	ds_write_b128 v68, v[90:93] offset:4608
	s_waitcnt vmcnt(16)
	ds_write_b128 v68, v[110:113] offset:41472
	v_mfma_f32_32x32x16_bf16 v[0:15], v[166:169], v[162:165], v[0:15]
	global_load_dwordx4 v[90:93], v[70:71], off offset:2816
	global_load_dwordx4 v[110:113], v[82:83], off offset:768
	s_waitcnt lgkmcnt(3)
	v_mfma_f32_32x32x16_bf16 v[48:63], v[150:153], v[158:161], v[48:63]
	s_waitcnt lgkmcnt(2)
	v_mfma_f32_32x32x16_bf16 v[32:47], v[150:153], v[178:181], v[32:47]
	v_mfma_f32_32x32x16_bf16 v[16:31], v[154:157], v[158:161], v[16:31]
	ds_read_b128 v[150:153], v66 offset:18528
	ds_read_b128 v[158:161], v66 offset:23136
	ds_read_b128 v[162:165], v64 offset:55392
	ds_read_b128 v[166:169], v64 offset:60000
	s_waitcnt vmcnt(17)
	ds_write_b128 v68, v[98:101] offset:9216
	s_waitcnt vmcnt(16)
	ds_write_b128 v68, v[134:137] offset:46080
	v_mfma_f32_32x32x16_bf16 v[0:15], v[154:157], v[178:181], v[0:15]
	global_load_dwordx4 v[98:101], v[72:73], off offset:2816
	global_load_dwordx4 v[134:137], v[80:81], off offset:768
	s_waitcnt lgkmcnt(3)
	v_mfma_f32_32x32x16_bf16 v[48:63], v[150:153], v[162:165], v[48:63]
	s_waitcnt vmcnt(17)
	ds_write_b128 v68, v[106:109] offset:13824
	s_waitcnt vmcnt(16)
	ds_write_b128 v68, v[138:141] offset:50688
	s_waitcnt lgkmcnt(4)
	v_mfma_f32_32x32x16_bf16 v[32:47], v[150:153], v[166:169], v[32:47]
	v_mfma_f32_32x32x16_bf16 v[16:31], v[158:161], v[162:165], v[16:31]
	v_mfma_f32_32x32x16_bf16 v[0:15], v[158:161], v[166:169], v[0:15]
	s_waitcnt lgkmcnt(0)
	s_barrier
	ds_read_b128 v[106:109], v66
	ds_read_b128 v[138:141], v64 offset:36864
	ds_read_b128 v[150:153], v66 offset:32
	ds_read_b128 v[154:157], v64 offset:36896
	ds_read_b128 v[158:161], v64 offset:41472
	ds_read_b128 v[162:165], v64 offset:41504
	s_waitcnt lgkmcnt(4)
	v_mfma_f32_32x32x16_bf16 v[48:63], v[106:109], v[138:141], v[48:63]
	s_waitcnt lgkmcnt(1)
	v_mfma_f32_32x32x16_bf16 v[32:47], v[106:109], v[158:161], v[32:47]
	ds_read_b128 v[106:109], v66 offset:4608
	ds_read_b128 v[166:169], v66 offset:4640
	s_waitcnt lgkmcnt(1)
	v_mfma_f32_32x32x16_bf16 v[16:31], v[106:109], v[138:141], v[16:31]
	global_load_dwordx4 v[138:141], v[76:77], off offset:2944
	global_load_dwordx4 v[178:181], v[78:79], off offset:896
	s_waitcnt vmcnt(17)
	ds_write_b128 v68, v[142:145] offset:18432
	s_waitcnt vmcnt(16)
	ds_write_b128 v68, v[174:177] offset:55296
	v_mfma_f32_32x32x16_bf16 v[0:15], v[106:109], v[158:161], v[0:15]
	global_load_dwordx4 v[106:109], v[74:75], off offset:2944
	global_load_dwordx4 v[142:145], v[84:85], off offset:896
	v_mfma_f32_32x32x16_bf16 v[48:63], v[150:153], v[154:157], v[48:63]
	v_mfma_f32_32x32x16_bf16 v[32:47], v[150:153], v[162:165], v[32:47]
	s_waitcnt lgkmcnt(2)
	v_mfma_f32_32x32x16_bf16 v[16:31], v[166:169], v[154:157], v[16:31]
	ds_read_b128 v[150:153], v66 offset:64
	ds_read_b128 v[154:157], v66 offset:4672
	ds_read_b128 v[158:161], v64 offset:36928
	ds_read_b128 v[174:177], v64 offset:41536
	s_waitcnt vmcnt(17)
	ds_write_b128 v68, v[114:117] offset:23040
	s_waitcnt vmcnt(16)
	ds_write_b128 v68, v[146:149] offset:59904
	v_mfma_f32_32x32x16_bf16 v[0:15], v[166:169], v[162:165], v[0:15]
	global_load_dwordx4 v[114:117], v[70:71], off offset:2944
	global_load_dwordx4 v[146:149], v[82:83], off offset:896
	s_waitcnt lgkmcnt(3)
	v_mfma_f32_32x32x16_bf16 v[48:63], v[150:153], v[158:161], v[48:63]
	s_waitcnt lgkmcnt(2)
	v_mfma_f32_32x32x16_bf16 v[32:47], v[150:153], v[174:177], v[32:47]
	v_mfma_f32_32x32x16_bf16 v[16:31], v[154:157], v[158:161], v[16:31]
	ds_read_b128 v[150:153], v66 offset:96
	ds_read_b128 v[158:161], v66 offset:4704
	ds_read_b128 v[162:165], v64 offset:36960
	ds_read_b128 v[166:169], v64 offset:41568
	s_waitcnt vmcnt(17)
	ds_write_b128 v68, v[86:89] offset:27648
	s_waitcnt vmcnt(16)
	ds_write_b128 v68, v[118:121] offset:64512
	v_mfma_f32_32x32x16_bf16 v[0:15], v[154:157], v[174:177], v[0:15]
	global_load_dwordx4 v[86:89], v[72:73], off offset:2944
	global_load_dwordx4 v[118:121], v[80:81], off offset:896
	s_waitcnt lgkmcnt(3)
	v_mfma_f32_32x32x16_bf16 v[48:63], v[150:153], v[162:165], v[48:63]
	s_waitcnt vmcnt(17)
	ds_write_b128 v68, v[94:97] offset:32256
	s_waitcnt vmcnt(16)
	ds_write_b128 v67, v[122:125] offset:32256
	s_waitcnt lgkmcnt(4)
	v_mfma_f32_32x32x16_bf16 v[32:47], v[150:153], v[166:169], v[32:47]
	v_mfma_f32_32x32x16_bf16 v[16:31], v[158:161], v[162:165], v[16:31]
	v_mfma_f32_32x32x16_bf16 v[0:15], v[158:161], v[166:169], v[0:15]
	s_waitcnt lgkmcnt(0)
	s_barrier
; template <class AL, class BL>
; DI void gemm_core(AL al, BL bl, int m0, int n0, int K, char* smem, f32x16 (&acc)[2][2]) {
;     ...
;   for (int kt = 0; kt < nk; kt += 2) {
;     G_TILE(0, x, true, (kt + 3 < nk), kt + 3);
;     __syncthreads();
;     G_TILE(1, y, (kt + 2 < nk), (kt + 4 < nk), kt + 4);
;     __syncthreads();
;   }
	ds_read_b128 v[94:97], v66 offset:18432
	ds_read_b128 v[122:125], v64 offset:55296
	ds_read_b128 v[150:153], v66 offset:18464
	ds_read_b128 v[154:157], v64 offset:55328
	ds_read_b128 v[158:161], v64 offset:59904
	ds_read_b128 v[162:165], v64 offset:59936
	s_waitcnt lgkmcnt(4)
	v_mfma_f32_32x32x16_bf16 v[48:63], v[94:97], v[122:125], v[48:63]
	s_waitcnt lgkmcnt(1)
	v_mfma_f32_32x32x16_bf16 v[32:47], v[94:97], v[158:161], v[32:47]
	ds_read_b128 v[94:97], v66 offset:23040
	ds_read_b128 v[166:169], v66 offset:23072
	s_waitcnt lgkmcnt(1)
	v_mfma_f32_32x32x16_bf16 v[16:31], v[94:97], v[122:125], v[16:31]
	global_load_dwordx4 v[122:125], v[76:77], off offset:3072
	global_load_dwordx4 v[174:177], v[78:79], off offset:1024
	s_waitcnt vmcnt(17)
	ds_write_b128 v68, v[126:129]
	s_waitcnt vmcnt(16)
	ds_write_b128 v68, v[170:173] offset:36864
	v_mfma_f32_32x32x16_bf16 v[0:15], v[94:97], v[158:161], v[0:15]
	global_load_dwordx4 v[94:97], v[74:75], off offset:3072
	global_load_dwordx4 v[126:129], v[84:85], off offset:1024
	v_mfma_f32_32x32x16_bf16 v[48:63], v[150:153], v[154:157], v[48:63]
	v_mfma_f32_32x32x16_bf16 v[32:47], v[150:153], v[162:165], v[32:47]
	s_waitcnt lgkmcnt(2)
	v_mfma_f32_32x32x16_bf16 v[16:31], v[166:169], v[154:157], v[16:31]
	ds_read_b128 v[150:153], v66 offset:18496
	ds_read_b128 v[154:157], v66 offset:23104
	ds_read_b128 v[158:161], v64 offset:55360
	ds_read_b128 v[170:173], v64 offset:59968
	s_waitcnt vmcnt(17)
	ds_write_b128 v68, v[102:105] offset:4608
	s_waitcnt vmcnt(16)
	ds_write_b128 v68, v[130:133] offset:41472
	v_mfma_f32_32x32x16_bf16 v[0:15], v[166:169], v[162:165], v[0:15]
	global_load_dwordx4 v[102:105], v[70:71], off offset:3072
	global_load_dwordx4 v[130:133], v[82:83], off offset:1024
	s_waitcnt lgkmcnt(3)
	v_mfma_f32_32x32x16_bf16 v[48:63], v[150:153], v[158:161], v[48:63]
	s_waitcnt lgkmcnt(2)
	v_mfma_f32_32x32x16_bf16 v[32:47], v[150:153], v[170:173], v[32:47]
	v_mfma_f32_32x32x16_bf16 v[16:31], v[154:157], v[158:161], v[16:31]
	ds_read_b128 v[150:153], v66 offset:18528
	ds_read_b128 v[158:161], v66 offset:23136
	ds_read_b128 v[162:165], v64 offset:55392
	ds_read_b128 v[166:169], v64 offset:60000
	s_waitcnt vmcnt(17)
	ds_write_b128 v68, v[90:93] offset:9216
	s_waitcnt vmcnt(16)
	ds_write_b128 v68, v[110:113] offset:46080
	v_mfma_f32_32x32x16_bf16 v[0:15], v[154:157], v[170:173], v[0:15]
	global_load_dwordx4 v[90:93], v[72:73], off offset:3072
	global_load_dwordx4 v[110:113], v[80:81], off offset:1024
	s_waitcnt lgkmcnt(3)
	v_mfma_f32_32x32x16_bf16 v[48:63], v[150:153], v[162:165], v[48:63]
	s_waitcnt vmcnt(17)
	ds_write_b128 v68, v[98:101] offset:13824
	s_waitcnt vmcnt(16)
	ds_write_b128 v68, v[134:137] offset:50688
	s_waitcnt lgkmcnt(4)
	v_mfma_f32_32x32x16_bf16 v[32:47], v[150:153], v[166:169], v[32:47]
	v_mfma_f32_32x32x16_bf16 v[16:31], v[158:161], v[162:165], v[16:31]
	v_mfma_f32_32x32x16_bf16 v[0:15], v[158:161], v[166:169], v[0:15]
	s_waitcnt lgkmcnt(0)
	s_barrier
	ds_read_b128 v[98:101], v66
	ds_read_b128 v[134:137], v64 offset:36864
	ds_read_b128 v[150:153], v66 offset:32
	ds_read_b128 v[154:157], v64 offset:36896
	ds_read_b128 v[158:161], v64 offset:41472
	ds_read_b128 v[162:165], v64 offset:41504
	s_waitcnt lgkmcnt(4)
	v_mfma_f32_32x32x16_bf16 v[48:63], v[98:101], v[134:137], v[48:63]
	s_waitcnt lgkmcnt(1)
	v_mfma_f32_32x32x16_bf16 v[32:47], v[98:101], v[158:161], v[32:47]
	ds_read_b128 v[98:101], v66 offset:4608
	ds_read_b128 v[166:169], v66 offset:4640
	s_waitcnt lgkmcnt(1)
	v_mfma_f32_32x32x16_bf16 v[16:31], v[98:101], v[134:137], v[16:31]
	global_load_dwordx4 v[134:137], v[76:77], off offset:3200
	global_load_dwordx4 v[170:173], v[78:79], off offset:1152
	s_waitcnt vmcnt(17)
	ds_write_b128 v68, v[138:141] offset:18432
	s_waitcnt vmcnt(16)
	ds_write_b128 v68, v[178:181] offset:55296
	v_mfma_f32_32x32x16_bf16 v[0:15], v[98:101], v[158:161], v[0:15]
	global_load_dwordx4 v[98:101], v[74:75], off offset:3200
	global_load_dwordx4 v[138:141], v[84:85], off offset:1152
	v_mfma_f32_32x32x16_bf16 v[48:63], v[150:153], v[154:157], v[48:63]
	v_mfma_f32_32x32x16_bf16 v[32:47], v[150:153], v[162:165], v[32:47]
	s_waitcnt lgkmcnt(2)
	v_mfma_f32_32x32x16_bf16 v[16:31], v[166:169], v[154:157], v[16:31]
	ds_read_b128 v[150:153], v66 offset:64
	ds_read_b128 v[154:157], v66 offset:4672
	ds_read_b128 v[158:161], v64 offset:36928
	ds_read_b128 v[178:181], v64 offset:41536
	s_waitcnt vmcnt(17)
	ds_write_b128 v68, v[106:109] offset:23040
	s_waitcnt vmcnt(16)
	ds_write_b128 v68, v[142:145] offset:59904
	v_mfma_f32_32x32x16_bf16 v[0:15], v[166:169], v[162:165], v[0:15]
	global_load_dwordx4 v[106:109], v[70:71], off offset:3200
	global_load_dwordx4 v[142:145], v[82:83], off offset:1152
	s_waitcnt lgkmcnt(3)
	v_mfma_f32_32x32x16_bf16 v[48:63], v[150:153], v[158:161], v[48:63]
	s_waitcnt lgkmcnt(2)
	v_mfma_f32_32x32x16_bf16 v[32:47], v[150:153], v[178:181], v[32:47]
	v_mfma_f32_32x32x16_bf16 v[16:31], v[154:157], v[158:161], v[16:31]
	ds_read_b128 v[150:153], v66 offset:96
	ds_read_b128 v[158:161], v66 offset:4704
	ds_read_b128 v[162:165], v64 offset:36960
	ds_read_b128 v[166:169], v64 offset:41568
	s_waitcnt vmcnt(17)
	ds_write_b128 v68, v[114:117] offset:27648
	s_waitcnt vmcnt(16)
	ds_write_b128 v68, v[146:149] offset:64512
	v_mfma_f32_32x32x16_bf16 v[0:15], v[154:157], v[178:181], v[0:15]
	global_load_dwordx4 v[114:117], v[72:73], off offset:3200
	global_load_dwordx4 v[146:149], v[80:81], off offset:1152
	s_waitcnt lgkmcnt(3)
	v_mfma_f32_32x32x16_bf16 v[48:63], v[150:153], v[162:165], v[48:63]
	s_waitcnt vmcnt(17)
	ds_write_b128 v68, v[86:89] offset:32256
	s_waitcnt vmcnt(16)
	ds_write_b128 v67, v[118:121] offset:32256
	s_waitcnt lgkmcnt(4)
	v_mfma_f32_32x32x16_bf16 v[32:47], v[150:153], v[166:169], v[32:47]
	v_mfma_f32_32x32x16_bf16 v[16:31], v[158:161], v[162:165], v[16:31]
	v_mfma_f32_32x32x16_bf16 v[0:15], v[158:161], v[166:169], v[0:15]
	s_waitcnt lgkmcnt(0)
	s_barrier
; template <class AL, class BL>
; DI void gemm_core(AL al, BL bl, int m0, int n0, int K, char* smem, f32x16 (&acc)[2][2]) {
;     ...
;   for (int kt = 0; kt < nk; kt += 2) {
;     G_TILE(0, x, true, (kt + 3 < nk), kt + 3);
;     __syncthreads();
;     G_TILE(1, y, (kt + 2 < nk), (kt + 4 < nk), kt + 4);
;     __syncthreads();
;   }
	ds_read_b128 v[86:89], v66 offset:18432
	ds_read_b128 v[118:121], v64 offset:55296
	ds_read_b128 v[150:153], v66 offset:18464
	ds_read_b128 v[154:157], v64 offset:55328
	ds_read_b128 v[158:161], v64 offset:59904
	ds_read_b128 v[162:165], v64 offset:59936
	s_waitcnt lgkmcnt(4)
	v_mfma_f32_32x32x16_bf16 v[48:63], v[86:89], v[118:121], v[48:63]
	s_waitcnt lgkmcnt(1)
	v_mfma_f32_32x32x16_bf16 v[32:47], v[86:89], v[158:161], v[32:47]
	ds_read_b128 v[86:89], v66 offset:23040
	ds_read_b128 v[166:169], v66 offset:23072
	s_waitcnt lgkmcnt(1)
	v_mfma_f32_32x32x16_bf16 v[16:31], v[86:89], v[118:121], v[16:31]
	global_load_dwordx4 v[118:121], v[76:77], off offset:3328
	global_load_dwordx4 v[178:181], v[78:79], off offset:1280
	s_waitcnt vmcnt(17)
	ds_write_b128 v68, v[122:125]
	s_waitcnt vmcnt(16)
	ds_write_b128 v68, v[174:177] offset:36864
	v_mfma_f32_32x32x16_bf16 v[0:15], v[86:89], v[158:161], v[0:15]
	global_load_dwordx4 v[86:89], v[74:75], off offset:3328
	global_load_dwordx4 v[122:125], v[84:85], off offset:1280
	v_mfma_f32_32x32x16_bf16 v[48:63], v[150:153], v[154:157], v[48:63]
	v_mfma_f32_32x32x16_bf16 v[32:47], v[150:153], v[162:165], v[32:47]
	s_waitcnt lgkmcnt(2)
	v_mfma_f32_32x32x16_bf16 v[16:31], v[166:169], v[154:157], v[16:31]
	ds_read_b128 v[150:153], v66 offset:18496
	ds_read_b128 v[154:157], v66 offset:23104
	ds_read_b128 v[158:161], v64 offset:55360
	ds_read_b128 v[174:177], v64 offset:59968
	s_waitcnt vmcnt(17)
	ds_write_b128 v68, v[94:97] offset:4608
	s_waitcnt vmcnt(16)
	ds_write_b128 v68, v[126:129] offset:41472
	v_mfma_f32_32x32x16_bf16 v[0:15], v[166:169], v[162:165], v[0:15]
	global_load_dwordx4 v[94:97], v[70:71], off offset:3328
	global_load_dwordx4 v[126:129], v[82:83], off offset:1280
	s_waitcnt lgkmcnt(3)
	v_mfma_f32_32x32x16_bf16 v[48:63], v[150:153], v[158:161], v[48:63]
	s_waitcnt lgkmcnt(2)
	v_mfma_f32_32x32x16_bf16 v[32:47], v[150:153], v[174:177], v[32:47]
	v_mfma_f32_32x32x16_bf16 v[16:31], v[154:157], v[158:161], v[16:31]
	ds_read_b128 v[150:153], v66 offset:18528
	ds_read_b128 v[158:161], v66 offset:23136
	ds_read_b128 v[162:165], v64 offset:55392
	ds_read_b128 v[166:169], v64 offset:60000
	s_waitcnt vmcnt(17)
	ds_write_b128 v68, v[102:105] offset:9216
	s_waitcnt vmcnt(16)
	ds_write_b128 v68, v[130:133] offset:46080
	v_mfma_f32_32x32x16_bf16 v[0:15], v[154:157], v[174:177], v[0:15]
	global_load_dwordx4 v[102:105], v[72:73], off offset:3328
	global_load_dwordx4 v[130:133], v[80:81], off offset:1280
	s_waitcnt lgkmcnt(3)
	v_mfma_f32_32x32x16_bf16 v[48:63], v[150:153], v[162:165], v[48:63]
	s_waitcnt vmcnt(17)
	ds_write_b128 v68, v[90:93] offset:13824
	s_waitcnt vmcnt(16)
	ds_write_b128 v68, v[110:113] offset:50688
	s_waitcnt lgkmcnt(4)
	v_mfma_f32_32x32x16_bf16 v[32:47], v[150:153], v[166:169], v[32:47]
	v_mfma_f32_32x32x16_bf16 v[16:31], v[158:161], v[162:165], v[16:31]
	v_mfma_f32_32x32x16_bf16 v[0:15], v[158:161], v[166:169], v[0:15]
	s_waitcnt lgkmcnt(0)
	s_barrier
	ds_read_b128 v[90:93], v66
	ds_read_b128 v[110:113], v64 offset:36864
	ds_read_b128 v[150:153], v66 offset:32
	ds_read_b128 v[154:157], v64 offset:36896
	ds_read_b128 v[158:161], v64 offset:41472
	ds_read_b128 v[162:165], v64 offset:41504
	s_waitcnt lgkmcnt(4)
	v_mfma_f32_32x32x16_bf16 v[48:63], v[90:93], v[110:113], v[48:63]
	s_waitcnt lgkmcnt(1)
	v_mfma_f32_32x32x16_bf16 v[32:47], v[90:93], v[158:161], v[32:47]
	ds_read_b128 v[90:93], v66 offset:4608
	ds_read_b128 v[166:169], v66 offset:4640
	s_waitcnt lgkmcnt(1)
	v_mfma_f32_32x32x16_bf16 v[16:31], v[90:93], v[110:113], v[16:31]
	global_load_dwordx4 v[110:113], v[76:77], off offset:3456
	global_load_dwordx4 v[174:177], v[78:79], off offset:1408
	s_waitcnt vmcnt(17)
	ds_write_b128 v68, v[134:137] offset:18432
	s_waitcnt vmcnt(16)
	ds_write_b128 v68, v[170:173] offset:55296
	v_mfma_f32_32x32x16_bf16 v[0:15], v[90:93], v[158:161], v[0:15]
	global_load_dwordx4 v[90:93], v[74:75], off offset:3456
	global_load_dwordx4 v[134:137], v[84:85], off offset:1408
	v_mfma_f32_32x32x16_bf16 v[48:63], v[150:153], v[154:157], v[48:63]
	v_mfma_f32_32x32x16_bf16 v[32:47], v[150:153], v[162:165], v[32:47]
	s_waitcnt lgkmcnt(2)
	v_mfma_f32_32x32x16_bf16 v[16:31], v[166:169], v[154:157], v[16:31]
	ds_read_b128 v[150:153], v66 offset:64
	ds_read_b128 v[154:157], v66 offset:4672
	ds_read_b128 v[158:161], v64 offset:36928
	ds_read_b128 v[170:173], v64 offset:41536
	s_waitcnt vmcnt(17)
	ds_write_b128 v68, v[98:101] offset:23040
	s_waitcnt vmcnt(16)
	ds_write_b128 v68, v[138:141] offset:59904
	v_mfma_f32_32x32x16_bf16 v[0:15], v[166:169], v[162:165], v[0:15]
	global_load_dwordx4 v[98:101], v[70:71], off offset:3456
	global_load_dwordx4 v[138:141], v[82:83], off offset:1408
	s_waitcnt lgkmcnt(3)
	v_mfma_f32_32x32x16_bf16 v[48:63], v[150:153], v[158:161], v[48:63]
	s_waitcnt lgkmcnt(2)
	v_mfma_f32_32x32x16_bf16 v[32:47], v[150:153], v[170:173], v[32:47]
	v_mfma_f32_32x32x16_bf16 v[16:31], v[154:157], v[158:161], v[16:31]
	ds_read_b128 v[150:153], v66 offset:96
	ds_read_b128 v[158:161], v66 offset:4704
	ds_read_b128 v[162:165], v64 offset:36960
	ds_read_b128 v[166:169], v64 offset:41568
	s_waitcnt vmcnt(17)
	ds_write_b128 v68, v[106:109] offset:27648
	s_waitcnt vmcnt(16)
	ds_write_b128 v68, v[142:145] offset:64512
	v_mfma_f32_32x32x16_bf16 v[0:15], v[154:157], v[170:173], v[0:15]
	global_load_dwordx4 v[106:109], v[72:73], off offset:3456
	global_load_dwordx4 v[142:145], v[80:81], off offset:1408
	s_waitcnt lgkmcnt(3)
	v_mfma_f32_32x32x16_bf16 v[48:63], v[150:153], v[162:165], v[48:63]
	s_waitcnt vmcnt(17)
	ds_write_b128 v68, v[114:117] offset:32256
	s_waitcnt vmcnt(16)
	ds_write_b128 v67, v[146:149] offset:32256
	s_waitcnt lgkmcnt(4)
	v_mfma_f32_32x32x16_bf16 v[32:47], v[150:153], v[166:169], v[32:47]
	v_mfma_f32_32x32x16_bf16 v[16:31], v[158:161], v[162:165], v[16:31]
	v_mfma_f32_32x32x16_bf16 v[0:15], v[158:161], v[166:169], v[0:15]
	s_waitcnt lgkmcnt(0)
	s_barrier
; template <class AL, class BL>
; DI void gemm_core(AL al, BL bl, int m0, int n0, int K, char* smem, f32x16 (&acc)[2][2]) {
;     ...
;   for (int kt = 0; kt < nk; kt += 2) {
;     G_TILE(0, x, true, (kt + 3 < nk), kt + 3);
;     __syncthreads();
;     G_TILE(1, y, (kt + 2 < nk), (kt + 4 < nk), kt + 4);
;     __syncthreads();
;   }
	ds_read_b128 v[114:117], v66 offset:18432
	ds_read_b128 v[146:149], v64 offset:55296
	ds_read_b128 v[150:153], v66 offset:18464
	ds_read_b128 v[154:157], v64 offset:55328
	ds_read_b128 v[158:161], v64 offset:59904
	ds_read_b128 v[162:165], v64 offset:59936
	s_waitcnt lgkmcnt(4)
	v_mfma_f32_32x32x16_bf16 v[48:63], v[114:117], v[146:149], v[48:63]
	s_waitcnt lgkmcnt(1)
	v_mfma_f32_32x32x16_bf16 v[32:47], v[114:117], v[158:161], v[32:47]
	ds_read_b128 v[114:117], v66 offset:23040
	ds_read_b128 v[166:169], v66 offset:23072
	s_waitcnt lgkmcnt(1)
	v_mfma_f32_32x32x16_bf16 v[16:31], v[114:117], v[146:149], v[16:31]
	global_load_dwordx4 v[146:149], v[76:77], off offset:3584
	global_load_dwordx4 v[170:173], v[78:79], off offset:1536
	s_waitcnt vmcnt(17)
	ds_write_b128 v68, v[118:121]
	s_waitcnt vmcnt(16)
	ds_write_b128 v68, v[178:181] offset:36864
	v_mfma_f32_32x32x16_bf16 v[0:15], v[114:117], v[158:161], v[0:15]
	global_load_dwordx4 v[114:117], v[74:75], off offset:3584
	global_load_dwordx4 v[118:121], v[84:85], off offset:1536
	v_mfma_f32_32x32x16_bf16 v[48:63], v[150:153], v[154:157], v[48:63]
	v_mfma_f32_32x32x16_bf16 v[32:47], v[150:153], v[162:165], v[32:47]
	s_waitcnt lgkmcnt(2)
	v_mfma_f32_32x32x16_bf16 v[16:31], v[166:169], v[154:157], v[16:31]
	ds_read_b128 v[150:153], v66 offset:18496
	ds_read_b128 v[154:157], v66 offset:23104
	ds_read_b128 v[158:161], v64 offset:55360
	ds_read_b128 v[178:181], v64 offset:59968
	s_waitcnt vmcnt(17)
	ds_write_b128 v68, v[86:89] offset:4608
	s_waitcnt vmcnt(16)
	ds_write_b128 v68, v[122:125] offset:41472
	v_mfma_f32_32x32x16_bf16 v[0:15], v[166:169], v[162:165], v[0:15]
	global_load_dwordx4 v[86:89], v[70:71], off offset:3584
	global_load_dwordx4 v[122:125], v[82:83], off offset:1536
	s_waitcnt lgkmcnt(3)
	v_mfma_f32_32x32x16_bf16 v[48:63], v[150:153], v[158:161], v[48:63]
	s_waitcnt lgkmcnt(2)
	v_mfma_f32_32x32x16_bf16 v[32:47], v[150:153], v[178:181], v[32:47]
	v_mfma_f32_32x32x16_bf16 v[16:31], v[154:157], v[158:161], v[16:31]
	ds_read_b128 v[150:153], v66 offset:18528
	ds_read_b128 v[158:161], v66 offset:23136
	ds_read_b128 v[162:165], v64 offset:55392
	ds_read_b128 v[166:169], v64 offset:60000
	s_waitcnt vmcnt(17)
	ds_write_b128 v68, v[94:97] offset:9216
	s_waitcnt vmcnt(16)
	ds_write_b128 v68, v[126:129] offset:46080
	v_mfma_f32_32x32x16_bf16 v[0:15], v[154:157], v[178:181], v[0:15]
	global_load_dwordx4 v[94:97], v[72:73], off offset:3584
	global_load_dwordx4 v[126:129], v[80:81], off offset:1536
	s_waitcnt lgkmcnt(3)
	v_mfma_f32_32x32x16_bf16 v[48:63], v[150:153], v[162:165], v[48:63]
	s_waitcnt vmcnt(17)
	ds_write_b128 v68, v[102:105] offset:13824
	s_waitcnt vmcnt(16)
	ds_write_b128 v68, v[130:133] offset:50688
	s_waitcnt lgkmcnt(4)
	v_mfma_f32_32x32x16_bf16 v[32:47], v[150:153], v[166:169], v[32:47]
	v_mfma_f32_32x32x16_bf16 v[16:31], v[158:161], v[162:165], v[16:31]
	v_mfma_f32_32x32x16_bf16 v[0:15], v[158:161], v[166:169], v[0:15]
	s_waitcnt lgkmcnt(0)
	s_barrier
	ds_read_b128 v[102:105], v66
	ds_read_b128 v[130:133], v64 offset:36864
	ds_read_b128 v[150:153], v66 offset:32
	ds_read_b128 v[154:157], v64 offset:36896
	ds_read_b128 v[158:161], v64 offset:41472
	ds_read_b128 v[162:165], v64 offset:41504
	s_waitcnt lgkmcnt(4)
	v_mfma_f32_32x32x16_bf16 v[48:63], v[102:105], v[130:133], v[48:63]
	s_waitcnt lgkmcnt(1)
	v_mfma_f32_32x32x16_bf16 v[32:47], v[102:105], v[158:161], v[32:47]
	ds_read_b128 v[102:105], v66 offset:4608
	ds_read_b128 v[166:169], v66 offset:4640
	s_waitcnt lgkmcnt(1)
	v_mfma_f32_32x32x16_bf16 v[16:31], v[102:105], v[130:133], v[16:31]
	global_load_dwordx4 v[130:133], v[76:77], off offset:3712
	global_load_dwordx4 v[178:181], v[78:79], off offset:1664
	s_waitcnt vmcnt(17)
	ds_write_b128 v68, v[110:113] offset:18432
	s_waitcnt vmcnt(16)
	ds_write_b128 v68, v[174:177] offset:55296
	v_mfma_f32_32x32x16_bf16 v[0:15], v[102:105], v[158:161], v[0:15]
	global_load_dwordx4 v[102:105], v[74:75], off offset:3712
	global_load_dwordx4 v[110:113], v[84:85], off offset:1664
	v_mfma_f32_32x32x16_bf16 v[48:63], v[150:153], v[154:157], v[48:63]
	v_mfma_f32_32x32x16_bf16 v[32:47], v[150:153], v[162:165], v[32:47]
	s_waitcnt lgkmcnt(2)
	v_mfma_f32_32x32x16_bf16 v[16:31], v[166:169], v[154:157], v[16:31]
	ds_read_b128 v[150:153], v66 offset:64
	ds_read_b128 v[154:157], v66 offset:4672
	ds_read_b128 v[158:161], v64 offset:36928
	ds_read_b128 v[174:177], v64 offset:41536
	s_waitcnt vmcnt(17)
	ds_write_b128 v68, v[90:93] offset:23040
	s_waitcnt vmcnt(16)
	ds_write_b128 v68, v[134:137] offset:59904
	v_mfma_f32_32x32x16_bf16 v[0:15], v[166:169], v[162:165], v[0:15]
	global_load_dwordx4 v[90:93], v[70:71], off offset:3712
	global_load_dwordx4 v[134:137], v[82:83], off offset:1664
	s_waitcnt lgkmcnt(3)
	v_mfma_f32_32x32x16_bf16 v[48:63], v[150:153], v[158:161], v[48:63]
	s_waitcnt lgkmcnt(2)
	v_mfma_f32_32x32x16_bf16 v[32:47], v[150:153], v[174:177], v[32:47]
	v_mfma_f32_32x32x16_bf16 v[16:31], v[154:157], v[158:161], v[16:31]
	ds_read_b128 v[150:153], v66 offset:96
	ds_read_b128 v[158:161], v66 offset:4704
	ds_read_b128 v[162:165], v64 offset:36960
	ds_read_b128 v[166:169], v64 offset:41568
	s_waitcnt vmcnt(17)
	ds_write_b128 v68, v[98:101] offset:27648
	s_waitcnt vmcnt(16)
	ds_write_b128 v68, v[138:141] offset:64512
	v_mfma_f32_32x32x16_bf16 v[0:15], v[154:157], v[174:177], v[0:15]
	global_load_dwordx4 v[98:101], v[72:73], off offset:3712
	global_load_dwordx4 v[138:141], v[80:81], off offset:1664
	s_waitcnt lgkmcnt(3)
	v_mfma_f32_32x32x16_bf16 v[48:63], v[150:153], v[162:165], v[48:63]
	s_waitcnt vmcnt(17)
	ds_write_b128 v68, v[106:109] offset:32256
	s_waitcnt vmcnt(16)
	ds_write_b128 v67, v[142:145] offset:32256
	s_waitcnt lgkmcnt(4)
	v_mfma_f32_32x32x16_bf16 v[32:47], v[150:153], v[166:169], v[32:47]
	v_mfma_f32_32x32x16_bf16 v[16:31], v[158:161], v[162:165], v[16:31]
	v_mfma_f32_32x32x16_bf16 v[0:15], v[158:161], v[166:169], v[0:15]
	s_waitcnt lgkmcnt(0)
	s_barrier
; template <class AL, class BL>
; DI void gemm_core(AL al, BL bl, int m0, int n0, int K, char* smem, f32x16 (&acc)[2][2]) {
;     ...
;   for (int kt = 0; kt < nk; kt += 2) {
;     G_TILE(0, x, true, (kt + 3 < nk), kt + 3);
;     __syncthreads();
;     G_TILE(1, y, (kt + 2 < nk), (kt + 4 < nk), kt + 4);
;     __syncthreads();
;   }
	ds_read_b128 v[106:109], v66 offset:18432
	ds_read_b128 v[142:145], v64 offset:55296
	ds_read_b128 v[150:153], v66 offset:18464
	ds_read_b128 v[154:157], v64 offset:55328
	ds_read_b128 v[158:161], v64 offset:59904
	ds_read_b128 v[162:165], v64 offset:59936
	s_waitcnt lgkmcnt(4)
	v_mfma_f32_32x32x16_bf16 v[48:63], v[106:109], v[142:145], v[48:63]
	s_waitcnt lgkmcnt(1)
	v_mfma_f32_32x32x16_bf16 v[32:47], v[106:109], v[158:161], v[32:47]
	ds_read_b128 v[106:109], v66 offset:23040
	ds_read_b128 v[166:169], v66 offset:23072
	s_waitcnt lgkmcnt(1)
	v_mfma_f32_32x32x16_bf16 v[16:31], v[106:109], v[142:145], v[16:31]
	global_load_dwordx4 v[142:145], v[76:77], off offset:3840
	global_load_dwordx4 v[174:177], v[78:79], off offset:1792
	s_waitcnt vmcnt(17)
	ds_write_b128 v68, v[146:149]
	s_waitcnt vmcnt(16)
	ds_write_b128 v68, v[170:173] offset:36864
	v_mfma_f32_32x32x16_bf16 v[0:15], v[106:109], v[158:161], v[0:15]
	global_load_dwordx4 v[106:109], v[74:75], off offset:3840
	global_load_dwordx4 v[146:149], v[84:85], off offset:1792
	v_mfma_f32_32x32x16_bf16 v[48:63], v[150:153], v[154:157], v[48:63]
	v_mfma_f32_32x32x16_bf16 v[32:47], v[150:153], v[162:165], v[32:47]
	s_waitcnt lgkmcnt(2)
	v_mfma_f32_32x32x16_bf16 v[16:31], v[166:169], v[154:157], v[16:31]
	ds_read_b128 v[150:153], v66 offset:18496
	ds_read_b128 v[154:157], v66 offset:23104
	ds_read_b128 v[158:161], v64 offset:55360
	ds_read_b128 v[170:173], v64 offset:59968
	s_waitcnt vmcnt(17)
	ds_write_b128 v68, v[114:117] offset:4608
	s_waitcnt vmcnt(16)
	ds_write_b128 v68, v[118:121] offset:41472
	v_mfma_f32_32x32x16_bf16 v[0:15], v[166:169], v[162:165], v[0:15]
	global_load_dwordx4 v[114:117], v[70:71], off offset:3840
	global_load_dwordx4 v[118:121], v[82:83], off offset:1792
	s_waitcnt lgkmcnt(3)
	v_mfma_f32_32x32x16_bf16 v[48:63], v[150:153], v[158:161], v[48:63]
	s_waitcnt lgkmcnt(2)
	v_mfma_f32_32x32x16_bf16 v[32:47], v[150:153], v[170:173], v[32:47]
	v_mfma_f32_32x32x16_bf16 v[16:31], v[154:157], v[158:161], v[16:31]
	ds_read_b128 v[150:153], v66 offset:18528
	ds_read_b128 v[158:161], v66 offset:23136
	ds_read_b128 v[162:165], v64 offset:55392
	ds_read_b128 v[166:169], v64 offset:60000
	s_waitcnt vmcnt(17)
	ds_write_b128 v68, v[86:89] offset:9216
	s_waitcnt vmcnt(16)
	ds_write_b128 v68, v[122:125] offset:46080
	v_mfma_f32_32x32x16_bf16 v[0:15], v[154:157], v[170:173], v[0:15]
	global_load_dwordx4 v[86:89], v[72:73], off offset:3840
	global_load_dwordx4 v[122:125], v[80:81], off offset:1792
	s_waitcnt lgkmcnt(3)
	v_mfma_f32_32x32x16_bf16 v[48:63], v[150:153], v[162:165], v[48:63]
	s_waitcnt vmcnt(17)
	ds_write_b128 v68, v[94:97] offset:13824
	s_waitcnt vmcnt(16)
	ds_write_b128 v68, v[126:129] offset:50688
	s_waitcnt lgkmcnt(4)
	v_mfma_f32_32x32x16_bf16 v[32:47], v[150:153], v[166:169], v[32:47]
	v_mfma_f32_32x32x16_bf16 v[16:31], v[158:161], v[162:165], v[16:31]
	v_mfma_f32_32x32x16_bf16 v[0:15], v[158:161], v[166:169], v[0:15]
	s_waitcnt lgkmcnt(0)
	s_barrier
	ds_read_b128 v[94:97], v66
	ds_read_b128 v[126:129], v64 offset:36864
	ds_read_b128 v[150:153], v66 offset:32
	ds_read_b128 v[154:157], v64 offset:36896
	ds_read_b128 v[158:161], v64 offset:41472
	ds_read_b128 v[162:165], v64 offset:41504
	s_waitcnt lgkmcnt(4)
	v_mfma_f32_32x32x16_bf16 v[48:63], v[94:97], v[126:129], v[48:63]
	s_waitcnt lgkmcnt(1)
	v_mfma_f32_32x32x16_bf16 v[32:47], v[94:97], v[158:161], v[32:47]
	ds_read_b128 v[94:97], v66 offset:4608
	ds_read_b128 v[166:169], v66 offset:4640
	s_waitcnt lgkmcnt(1)
	v_mfma_f32_32x32x16_bf16 v[16:31], v[94:97], v[126:129], v[16:31]
	global_load_dwordx4 v[126:129], v[76:77], off offset:3968
	s_nop 0
	global_load_dwordx4 v[76:79], v[78:79], off offset:1920
	s_waitcnt vmcnt(17)
	ds_write_b128 v68, v[130:133] offset:18432
	s_waitcnt vmcnt(16)
	ds_write_b128 v68, v[178:181] offset:55296
	v_mfma_f32_32x32x16_bf16 v[0:15], v[94:97], v[158:161], v[0:15]
	global_load_dwordx4 v[94:97], v[74:75], off offset:3968
	global_load_dwordx4 v[130:133], v[84:85], off offset:1920
	v_mfma_f32_32x32x16_bf16 v[48:63], v[150:153], v[154:157], v[48:63]
	v_mfma_f32_32x32x16_bf16 v[32:47], v[150:153], v[162:165], v[32:47]
	s_waitcnt lgkmcnt(2)
	v_mfma_f32_32x32x16_bf16 v[16:31], v[166:169], v[154:157], v[16:31]
	ds_read_b128 v[150:153], v66 offset:64
	ds_read_b128 v[154:157], v66 offset:4672
	ds_read_b128 v[158:161], v64 offset:36928
	ds_read_b128 v[170:173], v64 offset:41536
	s_waitcnt vmcnt(17)
	ds_write_b128 v68, v[102:105] offset:23040
	s_waitcnt vmcnt(16)
	ds_write_b128 v68, v[110:113] offset:59904
	v_mfma_f32_32x32x16_bf16 v[0:15], v[166:169], v[162:165], v[0:15]
	global_load_dwordx4 v[102:105], v[70:71], off offset:3968
	s_nop 0
	global_load_dwordx4 v[82:85], v[82:83], off offset:1920
	s_waitcnt lgkmcnt(3)
	v_mfma_f32_32x32x16_bf16 v[48:63], v[150:153], v[158:161], v[48:63]
	s_waitcnt lgkmcnt(2)
	v_mfma_f32_32x32x16_bf16 v[32:47], v[150:153], v[170:173], v[32:47]
	v_mfma_f32_32x32x16_bf16 v[16:31], v[154:157], v[158:161], v[16:31]
	ds_read_b128 v[110:113], v66 offset:96
	ds_read_b128 v[150:153], v66 offset:4704
	ds_read_b128 v[158:161], v64 offset:36960
	ds_read_b128 v[162:165], v64 offset:41568
	s_waitcnt vmcnt(17)
	ds_write_b128 v68, v[90:93] offset:27648
	s_waitcnt vmcnt(16)
	ds_write_b128 v68, v[134:137] offset:64512
	v_mfma_f32_32x32x16_bf16 v[0:15], v[154:157], v[170:173], v[0:15]
	global_load_dwordx4 v[70:73], v[72:73], off offset:3968
	s_nop 0
	global_load_dwordx4 v[90:93], v[80:81], off offset:1920
	s_waitcnt lgkmcnt(3)
	v_mfma_f32_32x32x16_bf16 v[48:63], v[110:113], v[158:161], v[48:63]
	s_waitcnt vmcnt(17)
	ds_write_b128 v68, v[98:101] offset:32256
	s_waitcnt vmcnt(16)
	ds_write_b128 v67, v[138:141] offset:32256
	s_waitcnt lgkmcnt(4)
	v_mfma_f32_32x32x16_bf16 v[32:47], v[110:113], v[162:165], v[32:47]
	v_mfma_f32_32x32x16_bf16 v[16:31], v[150:153], v[158:161], v[16:31]
	v_mfma_f32_32x32x16_bf16 v[0:15], v[150:153], v[162:165], v[0:15]
	s_waitcnt lgkmcnt(0)
	s_barrier
; template <class AL, class BL>
; DI void gemm_core(AL al, BL bl, int m0, int n0, int K, char* smem, f32x16 (&acc)[2][2]) {
;     ...
;   for (int kt = 0; kt < nk; kt += 2) {
;     G_TILE(0, x, true, (kt + 3 < nk), kt + 3);
;     __syncthreads();
;     G_TILE(1, y, (kt + 2 < nk), (kt + 4 < nk), kt + 4);
;     __syncthreads();
;   }
	ds_read_b128 v[98:101], v66 offset:18432
	ds_read_b128 v[110:113], v64 offset:55296
	ds_read_b128 v[134:137], v66 offset:18464
	ds_read_b128 v[138:141], v64 offset:55328
	ds_read_b128 v[150:153], v64 offset:59904
	ds_read_b128 v[154:157], v64 offset:59936
	s_waitcnt lgkmcnt(4)
	v_mfma_f32_32x32x16_bf16 v[48:63], v[98:101], v[110:113], v[48:63]
	s_waitcnt lgkmcnt(1)
	v_mfma_f32_32x32x16_bf16 v[32:47], v[98:101], v[150:153], v[32:47]
	ds_read_b128 v[98:101], v66 offset:23040
	ds_read_b128 v[158:161], v66 offset:23072
	s_waitcnt vmcnt(15)
	ds_write_b128 v68, v[142:145]
	s_waitcnt vmcnt(14)
	ds_write_b128 v68, v[174:177] offset:36864
	s_waitcnt lgkmcnt(3)
	v_mfma_f32_32x32x16_bf16 v[16:31], v[98:101], v[110:113], v[16:31]
	v_mfma_f32_32x32x16_bf16 v[0:15], v[98:101], v[150:153], v[0:15]
	v_mfma_f32_32x32x16_bf16 v[48:63], v[134:137], v[138:141], v[48:63]
	v_mfma_f32_32x32x16_bf16 v[32:47], v[134:137], v[154:157], v[32:47]
	s_waitcnt lgkmcnt(2)
	v_mfma_f32_32x32x16_bf16 v[16:31], v[158:161], v[138:141], v[16:31]
	ds_read_b128 v[98:101], v66 offset:18496
	ds_read_b128 v[110:113], v66 offset:23104
	ds_read_b128 v[134:137], v64 offset:55360
	ds_read_b128 v[138:141], v64 offset:59968
	s_waitcnt vmcnt(13)
	ds_write_b128 v68, v[106:109] offset:4608
	s_waitcnt vmcnt(12)
	ds_write_b128 v68, v[146:149] offset:41472
	v_mfma_f32_32x32x16_bf16 v[0:15], v[158:161], v[154:157], v[0:15]
	s_waitcnt lgkmcnt(3)
	v_mfma_f32_32x32x16_bf16 v[48:63], v[98:101], v[134:137], v[48:63]
	s_waitcnt lgkmcnt(2)
	v_mfma_f32_32x32x16_bf16 v[32:47], v[98:101], v[138:141], v[32:47]
	v_mfma_f32_32x32x16_bf16 v[16:31], v[110:113], v[134:137], v[16:31]
	ds_read_b128 v[98:101], v66 offset:18528
	ds_read_b128 v[106:109], v66 offset:23136
	ds_read_b128 v[134:137], v64 offset:55392
	ds_read_b128 v[142:145], v64 offset:60000
	s_waitcnt vmcnt(11)
	ds_write_b128 v68, v[114:117] offset:9216
	s_waitcnt vmcnt(10)
	ds_write_b128 v68, v[118:121] offset:46080
	v_mfma_f32_32x32x16_bf16 v[0:15], v[110:113], v[138:141], v[0:15]
	s_waitcnt lgkmcnt(3)
	v_mfma_f32_32x32x16_bf16 v[48:63], v[98:101], v[134:137], v[48:63]
	s_waitcnt vmcnt(9)
	ds_write_b128 v68, v[86:89] offset:13824
	s_waitcnt vmcnt(8)
	ds_write_b128 v68, v[122:125] offset:50688
	s_waitcnt lgkmcnt(4)
	v_mfma_f32_32x32x16_bf16 v[32:47], v[98:101], v[142:145], v[32:47]
	v_mfma_f32_32x32x16_bf16 v[16:31], v[106:109], v[134:137], v[16:31]
	v_mfma_f32_32x32x16_bf16 v[0:15], v[106:109], v[142:145], v[0:15]
	s_waitcnt lgkmcnt(0)
	s_barrier
	ds_read_b128 v[86:89], v66
	ds_read_b128 v[98:101], v64 offset:36864
	ds_read_b128 v[106:109], v66 offset:32
	ds_read_b128 v[110:113], v64 offset:36896
	ds_read_b128 v[114:117], v64 offset:41472
	ds_read_b128 v[118:121], v64 offset:41504
	s_waitcnt lgkmcnt(4)
	v_mfma_f32_32x32x16_bf16 v[48:63], v[86:89], v[98:101], v[48:63]
	s_waitcnt lgkmcnt(1)
	v_mfma_f32_32x32x16_bf16 v[32:47], v[86:89], v[114:117], v[32:47]
	ds_read_b128 v[86:89], v66 offset:4608
	ds_read_b128 v[122:125], v66 offset:4640
	s_waitcnt vmcnt(7)
	ds_write_b128 v68, v[126:129] offset:18432
	s_waitcnt vmcnt(6)
	ds_write_b128 v68, v[76:79] offset:55296
	s_waitcnt lgkmcnt(3)
	v_mfma_f32_32x32x16_bf16 v[16:31], v[86:89], v[98:101], v[16:31]
	v_mfma_f32_32x32x16_bf16 v[0:15], v[86:89], v[114:117], v[0:15]
	ds_read_b128 v[74:77], v66 offset:64
	ds_read_b128 v[78:81], v66 offset:4672
	ds_read_b128 v[86:89], v64 offset:36928
	ds_read_b128 v[98:101], v64 offset:41536
	v_mfma_f32_32x32x16_bf16 v[48:63], v[106:109], v[110:113], v[48:63]
	s_waitcnt vmcnt(5)
	ds_write_b128 v68, v[94:97] offset:23040
	s_waitcnt vmcnt(4)
	ds_write_b128 v68, v[130:133] offset:59904
	v_mfma_f32_32x32x16_bf16 v[32:47], v[106:109], v[118:121], v[32:47]
	s_waitcnt lgkmcnt(8)
	v_mfma_f32_32x32x16_bf16 v[16:31], v[122:125], v[110:113], v[16:31]
	v_mfma_f32_32x32x16_bf16 v[0:15], v[122:125], v[118:121], v[0:15]
	s_waitcnt lgkmcnt(3)
	v_mfma_f32_32x32x16_bf16 v[48:63], v[74:77], v[86:89], v[48:63]
	s_waitcnt lgkmcnt(2)
	v_mfma_f32_32x32x16_bf16 v[32:47], v[74:77], v[98:101], v[32:47]
	v_mfma_f32_32x32x16_bf16 v[16:31], v[78:81], v[86:89], v[16:31]
	ds_read_b128 v[74:77], v66 offset:96
	ds_read_b128 v[86:89], v66 offset:4704
	ds_read_b128 v[94:97], v64 offset:36960
	ds_read_b128 v[106:109], v64 offset:41568
	s_waitcnt vmcnt(3)
	ds_write_b128 v68, v[102:105] offset:27648
	s_waitcnt vmcnt(2)
	ds_write_b128 v68, v[82:85] offset:64512
	v_mfma_f32_32x32x16_bf16 v[0:15], v[78:81], v[98:101], v[0:15]
	s_waitcnt lgkmcnt(3)
	v_mfma_f32_32x32x16_bf16 v[48:63], v[74:77], v[94:97], v[48:63]
	s_waitcnt vmcnt(1)
	ds_write_b128 v68, v[70:73] offset:32256
	s_waitcnt vmcnt(0)
	ds_write_b128 v67, v[90:93] offset:32256
	s_waitcnt lgkmcnt(4)
	v_mfma_f32_32x32x16_bf16 v[32:47], v[74:77], v[106:109], v[32:47]
	v_mfma_f32_32x32x16_bf16 v[16:31], v[86:89], v[94:97], v[16:31]
	v_mfma_f32_32x32x16_bf16 v[0:15], v[86:89], v[106:109], v[0:15]
	s_waitcnt lgkmcnt(0)
	s_barrier
; DI u16 f2bf(float x) { return (u16)(pack2(x, 0.f) & 0xffffu); }
; DI int opaque_tid() { int t = threadIdx.x; asm volatile("" : "+v"(t)); return t; }
; DI int crow(int i, int h) { return (i & 3) + 8 * (i >> 2) + 4 * h; }
; template <class AL, class BL>
; DI void gemm_core(AL al, BL bl, int m0, int n0, int K, char* smem, f32x16 (&acc)[2][2]) {
;     ...
;   for (int kt = 0; kt < nk; kt += 2) {
;     G_TILE(0, x, true, (kt + 3 < nk), kt + 3);
;     __syncthreads();
;     G_TILE(1, y, (kt + 2 < nk), (kt + 4 < nk), kt + 4);
;     __syncthreads();
;   }
; template <class F>
; DI void epi_bf16_tile(const f32x16 (&acc)[2][2], int m0, int n0, u16* dst0, long ld, char* smem, F f) {
;   const int tid = opaque_tid(), lane = tid & 63, w = tid >> 6, wm = w >> 1, wn = w & 1, h = lane >> 5;
;   u16* T = (u16*)smem;
; #pragma unroll
;   for (int mt = 0; mt < 2; mt++)
; #pragma unroll
;     for (int nt = 0; nt < 2; nt++)
; #pragma unroll
;       for (int i = 0; i < 16; i++) {
;         const int ml = wm * 64 + mt * 32 + crow(i, h), nl = wn * 64 + nt * 32 + (lane & 31);
;         T[ml * 136 + nl] = f2bf(f(m0 + ml, n0 + nl, acc[mt][nt][i]));
	ds_read_b128 v[68:71], v66 offset:18432
	ds_read_b128 v[72:75], v64 offset:55296
	ds_read_b128 v[76:79], v66 offset:18464
	ds_read_b128 v[80:83], v64 offset:55328
	ds_read_b128 v[84:87], v64 offset:59904
	ds_read_b128 v[88:91], v64 offset:59936
	s_waitcnt lgkmcnt(4)
	v_mfma_f32_32x32x16_bf16 v[48:63], v[68:71], v[72:75], v[48:63]
	s_waitcnt lgkmcnt(1)
	v_mfma_f32_32x32x16_bf16 v[32:47], v[68:71], v[84:87], v[32:47]
	ds_read_b128 v[68:71], v66 offset:23040
	ds_read_b128 v[92:95], v66 offset:23072
	s_waitcnt lgkmcnt(1)
	v_mfma_f32_32x32x16_bf16 v[16:31], v[68:71], v[72:75], v[16:31]
	v_mfma_f32_32x32x16_bf16 v[0:15], v[68:71], v[84:87], v[0:15]
	v_mfma_f32_32x32x16_bf16 v[48:63], v[76:79], v[80:83], v[48:63]
	v_mfma_f32_32x32x16_bf16 v[32:47], v[76:79], v[88:91], v[32:47]
	s_waitcnt lgkmcnt(0)
	v_mfma_f32_32x32x16_bf16 v[16:31], v[92:95], v[80:83], v[16:31]
	ds_read_b128 v[68:71], v66 offset:18496
	ds_read_b128 v[72:75], v66 offset:23104
	ds_read_b128 v[76:79], v64 offset:55360
	ds_read_b128 v[80:83], v64 offset:59968
	v_mfma_f32_32x32x16_bf16 v[0:15], v[92:95], v[88:91], v[0:15]
	s_waitcnt lgkmcnt(1)
	v_mfma_f32_32x32x16_bf16 v[48:63], v[68:71], v[76:79], v[48:63]
	s_waitcnt lgkmcnt(0)
	v_mfma_f32_32x32x16_bf16 v[32:47], v[68:71], v[80:83], v[32:47]
	v_mfma_f32_32x32x16_bf16 v[16:31], v[72:75], v[76:79], v[16:31]
	ds_read_b128 v[68:71], v66 offset:18528
	ds_read_b128 v[76:79], v66 offset:23136
	ds_read_b128 v[84:87], v64 offset:55392
	ds_read_b128 v[88:91], v64 offset:60000
	v_mfma_f32_32x32x16_bf16 v[0:15], v[72:75], v[80:83], v[0:15]
	s_waitcnt lgkmcnt(1)
	v_mfma_f32_32x32x16_bf16 v[48:63], v[68:71], v[84:87], v[48:63]
	s_waitcnt lgkmcnt(0)
	v_mfma_f32_32x32x16_bf16 v[32:47], v[68:71], v[88:91], v[32:47]
	v_mfma_f32_32x32x16_bf16 v[16:31], v[76:79], v[84:87], v[16:31]
	v_mfma_f32_32x32x16_bf16 v[0:15], v[76:79], v[88:91], v[0:15]
	v_mov_b32_e32 v64, v202
	s_barrier
	s_ashr_i32 s19, s18, 31
	s_lshl_b64 s[2:3], s[18:19], 13
	v_ashrrev_i32_e32 v66, 1, v64
	v_lshrrev_b32_e32 v67, 3, v64
	v_lshlrev_b32_e32 v69, 4, v64
	v_lshlrev_b32_e32 v68, 1, v64
	v_ashrrev_i32_e32 v70, 4, v64
	v_add_u32_e32 v72, 0x100, v64
	v_add_u32_e32 v73, 0x200, v64
	v_add_u32_e32 v74, 0x300, v64
	v_add_u32_e32 v75, 0x400, v64
	v_add_u32_e32 v76, 0x500, v64
	v_add_u32_e32 v77, 0x600, v64
	v_add_u32_e32 v78, 0x700, v64
	v_and_b32_e32 v98, 0xffffffc0, v66
	v_and_b32_e32 v99, 4, v67
	v_and_b32_e32 v64, 0xf0, v69
	s_add_u32 s2, s20, s2
	v_or_b32_e32 v82, v99, v98
	v_mad_u64_u32 v[66:67], s[18:19], v70, s29, v[64:65]
	s_addc_u32 s33, s21, s3
	s_ashr_i32 s1, s0, 31
	v_subrev_u32_e32 v67, s31, v82
	s_lshl_b64 s[0:1], s[0:1], 1
	v_add_u32_e32 v162, s22, v67
	v_and_b32_e32 v114, 0xbe, v68
	v_ashrrev_i32_e32 v71, 31, v70
	v_ashrrev_i32_e32 v84, 4, v72
	v_ashrrev_i32_e32 v86, 4, v73
	v_ashrrev_i32_e32 v88, 4, v74
	v_ashrrev_i32_e32 v90, 4, v75
	v_ashrrev_i32_e32 v92, 4, v76
	v_ashrrev_i32_e32 v94, 4, v77
	v_ashrrev_i32_e32 v96, 4, v78
	v_or_b32_e32 v115, 27, v99
	s_add_u32 s0, s2, s0
	v_subrev_u32_e32 v166, 48, v162
	v_subrev_u32_e32 v168, 40, v162
	v_subrev_u32_e32 v170, 32, v162
	v_subrev_u32_e32 v172, 24, v162
	v_add_u32_e32 v174, -16, v162
	v_add_u32_e32 v176, -8, v162
	v_add_u32_e32 v178, 8, v162
	v_or_b32_e32 v100, 1, v99
	v_or_b32_e32 v101, 2, v99
	v_or_b32_e32 v102, 3, v99
	v_or_b32_e32 v103, 8, v99
	v_or_b32_e32 v104, 9, v99
	v_or_b32_e32 v105, 10, v99
	v_or_b32_e32 v106, 11, v99
	v_or_b32_e32 v107, 16, v99
	v_or_b32_e32 v108, 17, v99
	v_or_b32_e32 v109, 18, v99
	v_or_b32_e32 v110, 19, v99
	v_or_b32_e32 v111, 24, v99
	v_or_b32_e32 v112, 25, v99
	v_or_b32_e32 v113, 26, v99
	v_or_b32_e32 v118, 32, v98
	v_lshlrev_b64 v[116:117], 13, v[70:71]
	v_mad_u64_u32 v[68:69], s[18:19], v84, s29, v[64:65]
	v_ashrrev_i32_e32 v85, 31, v84
	v_mad_u64_u32 v[70:71], s[18:19], v86, s29, v[64:65]
	v_ashrrev_i32_e32 v87, 31, v86
	v_mad_u64_u32 v[72:73], s[18:19], v88, s29, v[64:65]
	v_ashrrev_i32_e32 v89, 31, v88
	v_mad_u64_u32 v[74:75], s[18:19], v90, s29, v[64:65]
	v_ashrrev_i32_e32 v91, 31, v90
	v_mad_u64_u32 v[76:77], s[18:19], v92, s29, v[64:65]
	v_ashrrev_i32_e32 v93, 31, v92
	v_mad_u64_u32 v[78:79], s[18:19], v94, s29, v[64:65]
	v_ashrrev_i32_e32 v95, 31, v94
	v_mad_u64_u32 v[80:81], s[18:19], v96, s29, v[64:65]
	v_ashrrev_i32_e32 v97, 31, v96
	v_mad_u64_u32 v[82:83], s[2:3], v82, s29, v[114:115]
	s_addc_u32 s1, s33, s1
	v_ashrrev_i32_e32 v163, 31, v162
	v_ashrrev_i32_e32 v167, 31, v166
	v_ashrrev_i32_e32 v169, 31, v168
	v_ashrrev_i32_e32 v171, 31, v170
	v_ashrrev_i32_e32 v173, 31, v172
	v_ashrrev_i32_e32 v175, 31, v174
	v_ashrrev_i32_e32 v177, 31, v176
	v_ashrrev_i32_e32 v179, 31, v178
	v_or_b32_e32 v69, v100, v98
	v_or_b32_e32 v71, v101, v98
	v_or_b32_e32 v73, v102, v98
	v_or_b32_e32 v75, v103, v98
	v_or_b32_e32 v77, v104, v98
	v_or_b32_e32 v79, v105, v98
	v_or_b32_e32 v81, v106, v98
	v_or_b32_e32 v83, v107, v98
	v_or_b32_e32 v148, v108, v98
	v_or_b32_e32 v150, v109, v98
	v_or_b32_e32 v152, v110, v98
	v_or_b32_e32 v154, v111, v98
	v_or_b32_e32 v156, v112, v98
	v_or_b32_e32 v158, v113, v98
	v_or_b32_e32 v98, v115, v98
	v_or_b32_e32 v99, v118, v99
	v_or_b32_e32 v100, v100, v118
	v_or_b32_e32 v101, v101, v118
	v_or_b32_e32 v102, v102, v118
	v_or_b32_e32 v103, v103, v118
	v_or_b32_e32 v104, v104, v118
	v_or_b32_e32 v105, v105, v118
	v_or_b32_e32 v106, v106, v118
	v_or_b32_e32 v107, v107, v118
	v_or_b32_e32 v108, v108, v118
	v_or_b32_e32 v109, v109, v118
	v_or_b32_e32 v110, v110, v118
	v_or_b32_e32 v111, v111, v118
	v_or_b32_e32 v112, v112, v118
	v_or_b32_e32 v113, v113, v118
	v_or_b32_e32 v115, v115, v118
	v_lshlrev_b64 v[118:119], 13, v[84:85]
	v_lshlrev_b64 v[120:121], 13, v[86:87]
; DI u16 f2bf(float x) { return (u16)(pack2(x, 0.f) & 0xffffu); }
; DI int crow(int i, int h) { return (i & 3) + 8 * (i >> 2) + 4 * h; }
; template <class F>
; DI void epi_bf16_tile(const f32x16 (&acc)[2][2], int m0, int n0, u16* dst0, long ld, char* smem, F f) {
;     ...
;   for (int mt = 0; mt < 2; mt++)
; #pragma unroll
;     for (int nt = 0; nt < 2; nt++)
; #pragma unroll
;       for (int i = 0; i < 16; i++) {
;         const int ml = wm * 64 + mt * 32 + crow(i, h), nl = wn * 64 + nt * 32 + (lane & 31);
;         T[ml * 136 + nl] = f2bf(f(m0 + ml, n0 + nl, acc[mt][nt][i]));
; DI void ffn_up_phase(const Params& p, const u16* xb, int ldx, const u16* wupT, u16* hid, char* smem) {
;     ...
;                epi_bf16_tile(acc, m0, n0, hid + (long)m0 * 4096 + n0, 4096, smem, [=](int m, int n, float v) {
;                  const float a = fmaxf(v * rs[m], 0.f);
;                  return a * a;
	v_lshlrev_b64 v[122:123], 13, v[88:89]
	v_lshlrev_b64 v[124:125], 13, v[90:91]
	v_lshlrev_b64 v[126:127], 13, v[92:93]
	v_lshlrev_b64 v[128:129], 13, v[94:95]
	v_lshlrev_b64 v[130:131], 13, v[96:97]
	v_lshl_add_u64 v[164:165], s[0:1], 0, v[64:65]
	v_lshl_add_u64 v[162:163], v[162:163], 2, s[12:13]
	v_lshl_add_u64 v[166:167], v[166:167], 2, s[12:13]
	v_lshl_add_u64 v[180:181], v[168:169], 2, s[12:13]
	v_lshl_add_u64 v[182:183], v[170:171], 2, s[12:13]
	v_lshl_add_u64 v[184:185], v[172:173], 2, s[12:13]
	v_lshl_add_u64 v[186:187], v[174:175], 2, s[12:13]
	v_lshl_add_u64 v[188:189], v[176:177], 2, s[12:13]
	v_lshl_add_u64 v[190:191], v[178:179], 2, s[12:13]
	v_lshl_add_u64 v[116:117], v[164:165], 0, v[116:117]
	v_lshl_add_u64 v[118:119], v[164:165], 0, v[118:119]
	v_lshl_add_u64 v[120:121], v[164:165], 0, v[120:121]
	v_lshl_add_u64 v[122:123], v[164:165], 0, v[122:123]
	v_lshl_add_u64 v[124:125], v[164:165], 0, v[124:125]
	v_lshl_add_u64 v[126:127], v[164:165], 0, v[126:127]
	v_lshl_add_u64 v[128:129], v[164:165], 0, v[128:129]
	v_lshl_add_u64 v[130:131], v[164:165], 0, v[130:131]
	global_load_dwordx4 v[162:165], v[162:163], off
	s_nop 0
	global_load_dwordx4 v[166:169], v[166:167], off
	s_nop 0
	global_load_dwordx4 v[170:173], v[180:181], off
	global_load_dwordx4 v[174:177], v[182:183], off
	s_nop 0
	global_load_dwordx4 v[178:181], v[184:185], off
	s_nop 0
	global_load_dwordx4 v[182:185], v[186:187], off
	s_nop 0
	global_load_dwordx4 v[186:189], v[188:189], off
	s_nop 0
	global_load_dwordx4 v[190:193], v[190:191], off
	v_mad_u64_u32 v[132:133], s[2:3], v69, s29, v[114:115]
	v_mad_u64_u32 v[134:135], s[2:3], v71, s29, v[114:115]
	v_mad_u64_u32 v[136:137], s[2:3], v73, s29, v[114:115]
	v_mad_u64_u32 v[138:139], s[2:3], v75, s29, v[114:115]
	v_mad_u64_u32 v[140:141], s[2:3], v77, s29, v[114:115]
	v_mad_u64_u32 v[142:143], s[2:3], v79, s29, v[114:115]
	v_mad_u64_u32 v[144:145], s[2:3], v81, s29, v[114:115]
	v_mad_u64_u32 v[146:147], s[2:3], v83, s29, v[114:115]
	v_mad_u64_u32 v[148:149], s[2:3], v148, s29, v[114:115]
	v_mad_u64_u32 v[150:151], s[2:3], v150, s29, v[114:115]
	v_mad_u64_u32 v[152:153], s[2:3], v152, s29, v[114:115]
	v_mad_u64_u32 v[154:155], s[2:3], v154, s29, v[114:115]
	v_mad_u64_u32 v[156:157], s[2:3], v156, s29, v[114:115]
	v_mad_u64_u32 v[158:159], s[2:3], v158, s29, v[114:115]
	v_mad_u64_u32 v[160:161], s[2:3], v98, s29, v[114:115]
	v_mad_u64_u32 v[84:85], s[2:3], v99, s29, v[114:115]
	v_mad_u64_u32 v[86:87], s[2:3], v100, s29, v[114:115]
	v_mad_u64_u32 v[88:89], s[2:3], v101, s29, v[114:115]
	v_mad_u64_u32 v[90:91], s[2:3], v102, s29, v[114:115]
	v_mad_u64_u32 v[92:93], s[2:3], v103, s29, v[114:115]
	v_mad_u64_u32 v[94:95], s[2:3], v104, s29, v[114:115]
	v_mad_u64_u32 v[96:97], s[2:3], v105, s29, v[114:115]
	v_mad_u64_u32 v[98:99], s[2:3], v106, s29, v[114:115]
	v_mad_u64_u32 v[100:101], s[2:3], v107, s29, v[114:115]
	v_mad_u64_u32 v[102:103], s[2:3], v108, s29, v[114:115]
	v_mad_u64_u32 v[104:105], s[2:3], v109, s29, v[114:115]
	v_mad_u64_u32 v[106:107], s[2:3], v110, s29, v[114:115]
	v_mad_u64_u32 v[108:109], s[2:3], v111, s29, v[114:115]
	v_mad_u64_u32 v[110:111], s[2:3], v112, s29, v[114:115]
	v_mad_u64_u32 v[112:113], s[2:3], v113, s29, v[114:115]
	v_mad_u64_u32 v[114:115], s[2:3], v115, s29, v[114:115]
	s_add_i32 s30, s30, s50
	s_add_i32 s22, s22, s23
	s_cmpk_lt_i32 s30, 0x1200
	s_waitcnt vmcnt(6)
	v_mul_f32_e32 v48, v48, v166
	v_mul_f32_e32 v49, v49, v167
	v_mul_f32_e32 v50, v50, v168
	v_mul_f32_e32 v51, v51, v169
	s_waitcnt vmcnt(2)
	v_mul_f32_e32 v16, v16, v182
	v_mul_f32_e32 v24, v24, v162
	v_mul_f32_e32 v25, v25, v163
	v_mul_f32_e32 v26, v26, v164
	v_mul_f32_e32 v27, v27, v165
	v_mul_f32_e32 v8, v8, v162
	v_mul_f32_e32 v9, v9, v163
	v_mul_f32_e32 v10, v10, v164
	v_mul_f32_e32 v11, v11, v165
	v_mul_f32_e32 v17, v17, v183
	v_mul_f32_e32 v18, v18, v184
	v_mul_f32_e32 v19, v19, v185
	s_waitcnt vmcnt(1)
	v_mul_f32_e32 v20, v20, v186
	v_mul_f32_e32 v21, v21, v187
	v_mul_f32_e32 v22, v22, v188
	v_mul_f32_e32 v23, v23, v189
	s_waitcnt vmcnt(0)
	v_mul_f32_e32 v28, v28, v190
	v_mul_f32_e32 v29, v29, v191
	v_mul_f32_e32 v30, v30, v192
	v_mul_f32_e32 v31, v31, v193
	v_mul_f32_e32 v0, v0, v182
	v_mul_f32_e32 v1, v1, v183
	v_mul_f32_e32 v2, v2, v184
	v_mul_f32_e32 v3, v3, v185
	v_mul_f32_e32 v4, v4, v186
	v_mul_f32_e32 v5, v5, v187
	v_mul_f32_e32 v6, v6, v188
	v_mul_f32_e32 v7, v7, v189
	v_mul_f32_e32 v12, v12, v190
	v_mul_f32_e32 v13, v13, v191
	v_mul_f32_e32 v14, v14, v192
	v_mul_f32_e32 v15, v15, v193
	v_mul_f32_e32 v52, v52, v170
	v_mul_f32_e32 v53, v53, v171
	v_mul_f32_e32 v54, v54, v172
	v_mul_f32_e32 v55, v55, v173
	v_mul_f32_e32 v56, v56, v174
	v_mul_f32_e32 v57, v57, v175
	v_mul_f32_e32 v58, v58, v176
	v_mul_f32_e32 v59, v59, v177
	v_mul_f32_e32 v60, v60, v178
	v_mul_f32_e32 v61, v61, v179
	v_mul_f32_e32 v62, v62, v180
	v_mul_f32_e32 v63, v63, v181
	v_mul_f32_e32 v32, v32, v166
	v_mul_f32_e32 v33, v33, v167
	v_mul_f32_e32 v34, v34, v168
	v_mul_f32_e32 v35, v35, v169
	v_mul_f32_e32 v36, v36, v170
	v_mul_f32_e32 v37, v37, v171
	v_mul_f32_e32 v38, v38, v172
	v_mul_f32_e32 v39, v39, v173
	v_mul_f32_e32 v40, v40, v174
	v_mul_f32_e32 v41, v41, v175
	v_mul_f32_e32 v42, v42, v176
	v_mul_f32_e32 v43, v43, v177
	v_mul_f32_e32 v44, v44, v178
	v_mul_f32_e32 v45, v45, v179
	v_mul_f32_e32 v46, v46, v180
	v_mul_f32_e32 v47, v47, v181
	v_max_f32_e32 v24, 0, v24
	v_max_f32_e32 v25, 0, v25
	v_max_f32_e32 v26, 0, v26
	v_max_f32_e32 v27, 0, v27
	v_max_f32_e32 v8, 0, v8
	v_max_f32_e32 v9, 0, v9
	v_max_f32_e32 v10, 0, v10
	v_max_f32_e32 v11, 0, v11
	v_max_f32_e32 v48, 0, v48
	v_max_f32_e32 v16, 0, v16
	v_max_f32_e32 v17, 0, v17
; DI u16 f2bf(float x) { return (u16)(pack2(x, 0.f) & 0xffffu); }
; template <class F>
; DI void epi_bf16_tile(const f32x16 (&acc)[2][2], int m0, int n0, u16* dst0, long ld, char* smem, F f) {
;     ...
;         T[ml * 136 + nl] = f2bf(f(m0 + ml, n0 + nl, acc[mt][nt][i]));
; DI void ffn_up_phase(const Params& p, const u16* xb, int ldx, const u16* wupT, u16* hid, char* smem) {
;     ...
;                epi_bf16_tile(acc, m0, n0, hid + (long)m0 * 4096 + n0, 4096, smem, [=](int m, int n, float v) {
;                  const float a = fmaxf(v * rs[m], 0.f);
;                  return a * a;
	v_max_f32_e32 v18, 0, v18
	v_max_f32_e32 v19, 0, v19
	v_max_f32_e32 v20, 0, v20
	v_max_f32_e32 v21, 0, v21
	v_max_f32_e32 v22, 0, v22
	v_max_f32_e32 v23, 0, v23
	v_max_f32_e32 v28, 0, v28
	v_max_f32_e32 v29, 0, v29
	v_max_f32_e32 v30, 0, v30
	v_max_f32_e32 v31, 0, v31
	v_max_f32_e32 v0, 0, v0
	v_max_f32_e32 v1, 0, v1
	v_max_f32_e32 v2, 0, v2
	v_max_f32_e32 v3, 0, v3
	v_max_f32_e32 v4, 0, v4
	v_max_f32_e32 v5, 0, v5
	v_max_f32_e32 v6, 0, v6
	v_max_f32_e32 v7, 0, v7
	v_max_f32_e32 v12, 0, v12
	v_max_f32_e32 v13, 0, v13
	v_max_f32_e32 v14, 0, v14
	v_max_f32_e32 v15, 0, v15
	v_max_f32_e32 v49, 0, v49
	v_max_f32_e32 v50, 0, v50
	v_max_f32_e32 v51, 0, v51
	v_max_f32_e32 v52, 0, v52
	v_max_f32_e32 v53, 0, v53
	v_max_f32_e32 v54, 0, v54
	v_max_f32_e32 v55, 0, v55
	v_max_f32_e32 v56, 0, v56
	v_max_f32_e32 v57, 0, v57
	v_max_f32_e32 v58, 0, v58
	v_max_f32_e32 v59, 0, v59
	v_max_f32_e32 v60, 0, v60
	v_max_f32_e32 v61, 0, v61
	v_max_f32_e32 v62, 0, v62
	v_max_f32_e32 v63, 0, v63
	v_max_f32_e32 v32, 0, v32
	v_max_f32_e32 v33, 0, v33
	v_max_f32_e32 v34, 0, v34
	v_max_f32_e32 v35, 0, v35
	v_max_f32_e32 v36, 0, v36
	v_max_f32_e32 v37, 0, v37
	v_max_f32_e32 v38, 0, v38
	v_max_f32_e32 v39, 0, v39
	v_max_f32_e32 v40, 0, v40
	v_max_f32_e32 v41, 0, v41
	v_max_f32_e32 v42, 0, v42
	v_max_f32_e32 v43, 0, v43
	v_max_f32_e32 v44, 0, v44
	v_max_f32_e32 v45, 0, v45
	v_max_f32_e32 v46, 0, v46
	v_max_f32_e32 v47, 0, v47
	v_mul_f32_e32 v24, v24, v24
	v_mul_f32_e32 v25, v25, v25
	v_mul_f32_e32 v26, v26, v26
	v_mul_f32_e32 v27, v27, v27
	v_mul_f32_e32 v8, v8, v8
	v_mul_f32_e32 v9, v9, v9
	v_mul_f32_e32 v10, v10, v10
	v_mul_f32_e32 v11, v11, v11
	v_mul_f32_e32 v48, v48, v48
	v_mul_f32_e32 v16, v16, v16
	v_mul_f32_e32 v17, v17, v17
	v_mul_f32_e32 v18, v18, v18
	v_mul_f32_e32 v19, v19, v19
	v_mul_f32_e32 v20, v20, v20
	v_mul_f32_e32 v21, v21, v21
	v_mul_f32_e32 v22, v22, v22
	v_mul_f32_e32 v23, v23, v23
	v_mul_f32_e32 v28, v28, v28
	v_mul_f32_e32 v29, v29, v29
	v_mul_f32_e32 v30, v30, v30
	v_mul_f32_e32 v31, v31, v31
	v_mul_f32_e32 v0, v0, v0
	v_mul_f32_e32 v1, v1, v1
	v_mul_f32_e32 v2, v2, v2
	v_mul_f32_e32 v3, v3, v3
	v_mul_f32_e32 v4, v4, v4
	v_mul_f32_e32 v5, v5, v5
	v_mul_f32_e32 v6, v6, v6
	v_mul_f32_e32 v7, v7, v7
	v_mul_f32_e32 v12, v12, v12
	v_mul_f32_e32 v13, v13, v13
	v_mul_f32_e32 v14, v14, v14
	v_mul_f32_e32 v15, v15, v15
	v_mul_f32_e32 v49, v49, v49
	v_mul_f32_e32 v50, v50, v50
	v_mul_f32_e32 v51, v51, v51
	v_mul_f32_e32 v52, v52, v52
	v_mul_f32_e32 v53, v53, v53
	v_mul_f32_e32 v54, v54, v54
	v_mul_f32_e32 v55, v55, v55
	v_mul_f32_e32 v56, v56, v56
	v_mul_f32_e32 v57, v57, v57
	v_mul_f32_e32 v58, v58, v58
	v_mul_f32_e32 v59, v59, v59
	v_mul_f32_e32 v60, v60, v60
	v_mul_f32_e32 v61, v61, v61
	v_mul_f32_e32 v62, v62, v62
	v_mul_f32_e32 v63, v63, v63
	v_mul_f32_e32 v32, v32, v32
	v_mul_f32_e32 v33, v33, v33
	v_mul_f32_e32 v34, v34, v34
	v_mul_f32_e32 v35, v35, v35
	v_mul_f32_e32 v36, v36, v36
	v_mul_f32_e32 v37, v37, v37
	v_mul_f32_e32 v38, v38, v38
	v_mul_f32_e32 v39, v39, v39
	v_mul_f32_e32 v40, v40, v40
	v_mul_f32_e32 v41, v41, v41
	v_mul_f32_e32 v42, v42, v42
	v_mul_f32_e32 v43, v43, v43
	v_mul_f32_e32 v44, v44, v44
	v_mul_f32_e32 v45, v45, v45
	v_mul_f32_e32 v46, v46, v46
	v_mul_f32_e32 v47, v47, v47
	v_cvt_pk_bf16_f32 v24, v24, s0
	v_cvt_pk_bf16_f32 v25, v25, s0
	v_cvt_pk_bf16_f32 v26, v26, s0
	v_cvt_pk_bf16_f32 v27, v27, s0
	v_cvt_pk_bf16_f32 v8, v8, s0
	v_cvt_pk_bf16_f32 v9, v9, s0
	v_cvt_pk_bf16_f32 v10, v10, s0
	v_cvt_pk_bf16_f32 v11, v11, s0
	v_cvt_pk_bf16_f32 v48, v48, s0
	v_cvt_pk_bf16_f32 v16, v16, s0
	v_cvt_pk_bf16_f32 v17, v17, s0
	v_cvt_pk_bf16_f32 v18, v18, s0
	v_cvt_pk_bf16_f32 v19, v19, s0
	v_cvt_pk_bf16_f32 v20, v20, s0
	v_cvt_pk_bf16_f32 v21, v21, s0
	v_cvt_pk_bf16_f32 v22, v22, s0
	v_cvt_pk_bf16_f32 v23, v23, s0
	v_cvt_pk_bf16_f32 v28, v28, s0
	v_cvt_pk_bf16_f32 v29, v29, s0
	v_cvt_pk_bf16_f32 v30, v30, s0
	v_cvt_pk_bf16_f32 v31, v31, s0
	v_cvt_pk_bf16_f32 v0, v0, s0
	v_cvt_pk_bf16_f32 v1, v1, s0
; DI u16 f2bf(float x) { return (u16)(pack2(x, 0.f) & 0xffffu); }
; DI int crow(int i, int h) { return (i & 3) + 8 * (i >> 2) + 4 * h; }
; template <class F>
; DI void epi_bf16_tile(const f32x16 (&acc)[2][2], int m0, int n0, u16* dst0, long ld, char* smem, F f) {
;     ...
;       for (int i = 0; i < 16; i++) {
;         const int ml = wm * 64 + mt * 32 + crow(i, h), nl = wn * 64 + nt * 32 + (lane & 31);
;         T[ml * 136 + nl] = f2bf(f(m0 + ml, n0 + nl, acc[mt][nt][i]));
;       }
;   __syncthreads();
; #pragma unroll
;   for (int j = 0; j < 8; j++) {
;     const int idx = tid + 256 * j, row = idx >> 4, ch = idx & 15;
;     *(uint4*)(dst0 + (long)row * ld + ch * 8) = *(const uint4*)(T + row * 136 + ch * 8);
;   }
;   __syncthreads();
; template <class AL, class BL, class EP>
; DI void gemm_phase(int MT, int NTL, int K, AL al, BL bl, EP ep, char* smem) {
;   for (int t = blockIdx.x; t < MT * NTL; t += gridDim.x) {
	v_cvt_pk_bf16_f32 v2, v2, s0
	v_cvt_pk_bf16_f32 v3, v3, s0
	v_cvt_pk_bf16_f32 v4, v4, s0
	v_cvt_pk_bf16_f32 v5, v5, s0
	v_cvt_pk_bf16_f32 v6, v6, s0
	v_cvt_pk_bf16_f32 v7, v7, s0
	v_cvt_pk_bf16_f32 v12, v12, s0
	v_cvt_pk_bf16_f32 v13, v13, s0
	v_cvt_pk_bf16_f32 v14, v14, s0
	v_cvt_pk_bf16_f32 v15, v15, s0
	v_cvt_pk_bf16_f32 v49, v49, s0
	v_cvt_pk_bf16_f32 v50, v50, s0
	v_cvt_pk_bf16_f32 v51, v51, s0
	v_cvt_pk_bf16_f32 v52, v52, s0
	v_cvt_pk_bf16_f32 v53, v53, s0
	v_cvt_pk_bf16_f32 v54, v54, s0
	v_cvt_pk_bf16_f32 v55, v55, s0
	v_cvt_pk_bf16_f32 v56, v56, s0
	v_cvt_pk_bf16_f32 v57, v57, s0
	v_cvt_pk_bf16_f32 v58, v58, s0
	v_cvt_pk_bf16_f32 v59, v59, s0
	v_cvt_pk_bf16_f32 v60, v60, s0
	v_cvt_pk_bf16_f32 v61, v61, s0
	v_cvt_pk_bf16_f32 v62, v62, s0
	v_cvt_pk_bf16_f32 v63, v63, s0
	v_cvt_pk_bf16_f32 v32, v32, s0
	v_cvt_pk_bf16_f32 v33, v33, s0
	v_cvt_pk_bf16_f32 v34, v34, s0
	v_cvt_pk_bf16_f32 v35, v35, s0
	v_cvt_pk_bf16_f32 v36, v36, s0
	v_cvt_pk_bf16_f32 v37, v37, s0
	v_cvt_pk_bf16_f32 v38, v38, s0
	v_cvt_pk_bf16_f32 v39, v39, s0
	v_cvt_pk_bf16_f32 v40, v40, s0
	v_cvt_pk_bf16_f32 v41, v41, s0
	v_cvt_pk_bf16_f32 v42, v42, s0
	v_cvt_pk_bf16_f32 v43, v43, s0
	v_cvt_pk_bf16_f32 v44, v44, s0
	v_cvt_pk_bf16_f32 v45, v45, s0
	v_cvt_pk_bf16_f32 v46, v46, s0
	v_cvt_pk_bf16_f32 v47, v47, s0
	ds_write_b16 v82, v48
	ds_write_b16 v132, v49
	ds_write_b16 v134, v50
	ds_write_b16 v136, v51
	ds_write_b16 v138, v52
	ds_write_b16 v140, v53
	ds_write_b16 v142, v54
	ds_write_b16 v144, v55
	ds_write_b16 v146, v56
	ds_write_b16 v148, v57
	ds_write_b16 v150, v58
	ds_write_b16 v152, v59
	ds_write_b16 v154, v60
	ds_write_b16 v156, v61
	ds_write_b16 v158, v62
	ds_write_b16 v160, v63
	ds_write_b16 v82, v32 offset:64
	ds_write_b16 v132, v33 offset:64
	ds_write_b16 v134, v34 offset:64
	ds_write_b16 v136, v35 offset:64
	ds_write_b16 v138, v36 offset:64
	ds_write_b16 v140, v37 offset:64
	ds_write_b16 v142, v38 offset:64
	ds_write_b16 v144, v39 offset:64
	ds_write_b16 v146, v40 offset:64
	ds_write_b16 v148, v41 offset:64
	ds_write_b16 v150, v42 offset:64
	ds_write_b16 v152, v43 offset:64
	ds_write_b16 v154, v44 offset:64
	ds_write_b16 v156, v45 offset:64
	ds_write_b16 v158, v46 offset:64
	ds_write_b16 v160, v47 offset:64
	ds_write_b16 v84, v16
	ds_write_b16 v86, v17
	ds_write_b16 v88, v18
	ds_write_b16 v90, v19
	ds_write_b16 v92, v20
	ds_write_b16 v94, v21
	ds_write_b16 v96, v22
	ds_write_b16 v98, v23
	ds_write_b16 v100, v24
	ds_write_b16 v102, v25
	ds_write_b16 v104, v26
	ds_write_b16 v106, v27
	ds_write_b16 v108, v28
	ds_write_b16 v110, v29
	ds_write_b16 v112, v30
	ds_write_b16 v114, v31
	ds_write_b16 v84, v0 offset:64
	ds_write_b16 v86, v1 offset:64
	ds_write_b16 v88, v2 offset:64
	ds_write_b16 v90, v3 offset:64
	ds_write_b16 v92, v4 offset:64
	ds_write_b16 v94, v5 offset:64
	ds_write_b16 v96, v6 offset:64
	ds_write_b16 v98, v7 offset:64
	ds_write_b16 v100, v8 offset:64
	ds_write_b16 v102, v9 offset:64
	ds_write_b16 v104, v10 offset:64
	ds_write_b16 v106, v11 offset:64
	ds_write_b16 v108, v12 offset:64
	ds_write_b16 v110, v13 offset:64
	ds_write_b16 v112, v14 offset:64
	ds_write_b16 v114, v15 offset:64
	s_waitcnt lgkmcnt(0)
	s_barrier
	ds_read_b128 v[0:3], v66
	ds_read_b128 v[4:7], v68
	ds_read_b128 v[8:11], v70
	ds_read_b128 v[12:15], v72
	ds_read_b128 v[16:19], v74
	ds_read_b128 v[20:23], v76
	ds_read_b128 v[24:27], v78
	ds_read_b128 v[28:31], v80
	s_waitcnt lgkmcnt(7)
	global_store_dwordx4 v[116:117], v[0:3], off
	s_waitcnt lgkmcnt(6)
	global_store_dwordx4 v[118:119], v[4:7], off
	s_waitcnt lgkmcnt(5)
	global_store_dwordx4 v[120:121], v[8:11], off
	s_waitcnt lgkmcnt(4)
	global_store_dwordx4 v[122:123], v[12:15], off
	s_waitcnt lgkmcnt(3)
	global_store_dwordx4 v[124:125], v[16:19], off
	s_waitcnt lgkmcnt(2)
	global_store_dwordx4 v[126:127], v[20:23], off
	s_waitcnt lgkmcnt(1)
	global_store_dwordx4 v[128:129], v[24:27], off
	s_waitcnt lgkmcnt(0)
	global_store_dwordx4 v[130:131], v[28:31], off
	s_barrier
	s_mov_b64 s[70:71], s[48:49]
